# GEMM units: first K iteration peeled with C=0 in each accumulator's first MFMA; the 128 per-unit accumulator zeroing moves removed
# speedup vs baseline: 1.0055x; 1.0055x over previous
; DEVI size_t gemm_offB(const Gemm& g, const Unit& u) { return (g.split ? (size_t)(u.b >> 2) * g.sB + (size_t)(u.b & 3) * g.sB_lo : (size_t)u.b * g.sB) + (size_t)(u.pm >> g.pmsh) * g.sBpm; }
; #define PG8_STAGE(bufoff, gbase, voff) do { _Pragma("unroll") for (int _i = 0; _i < 2; ++_i) \
;         __builtin_amdgcn_global_load_lds((const unsigned*)((const char*)(gbase) + (voff)[_i]), (LAS unsigned*)(lds + (bufoff) + ldsw + _i * 8192), 16, 0, 0); } while (0)
; #define PG8_LDA(dst, b, h) do { _Pragma("unroll") for (int m = 0; m < 4; ++m) _Pragma("unroll") for (int k = 0; k < 2; ++k) dst[m][k] = *(const LAS bf16x8*)(lds + PG8_SA(b, h) + aoff + m * 2048 + k * 1024); } while (0)
; #define PG8_LDB(dst, b, h) do { _Pragma("unroll") for (int n = 0; n < 2; ++n) _Pragma("unroll") for (int k = 0; k < 2; ++k) dst[n][k] = *(const LAS bf16x8*)(lds + PG8_SB(b, h) + boff + n * 2048 + k * 1024); } while (0)
; #define PG8_WAIT_V(n) asm volatile("s_waitcnt vmcnt(" #n ")" ::: "memory")
; #define PG8_BAR __builtin_amdgcn_s_barrier()
; template <class Epi>
; DEVI void gemm_phase(LAS unsigned char* lds, const Gemm g, const Epi& E) {
;     ...
;         const bool has_next = unit_next(g, ui + 1, nxt);
;         const char* nA = has_next ? (const char*)g.A + gemm_offA(g, nxt) * 2 + (size_t)nxt.pm * tstepA : cA;
;         const char* nB = has_next ? (const char*)g.Bt + gemm_offB(g, nxt) * 2 + (size_t)nxt.pn * tstepB : cB;
;         for (int t = 0; t < nt; t += 2) {
;             const bool last = (t == nt - 2);
;             const char* a1 = cA + (size_t)(t + 1) * kstep;
;             const char* a2 = last ? nA : cA + (size_t)(t + 2) * kstep; const char* b2 = last ? nB : cB + (size_t)(t + 2) * kstep;
;             const char* a3 = a2 + kstep; const char* b3 = b2 + kstep;
;             PG8_LDB(B0, 0, 0); PG8_SCHED; PG8_LDA(At, 0, 0); PG8_STAGE(PG8_SA(1, 1), a1 + hstepA, voffA);
;             PG8_WAIT_L(8); PG8_BAR; PG8_WAIT_L(0); PG8_MMA(0, 0, At, B0); PG8_BAR; PG8_SCHED;
;             PG8_LDB(B1, 0, 1); PG8_STAGE(PG8_SB(0, 0), b2, voffB);
;             PG8_BAR; PG8_WAIT_L(0); PG8_MMA(0, 1, At, B1); PG8_BAR;
;             PG8_LDA(At, 0, 1); PG8_STAGE(PG8_SA(0, 0), a2, voffA);
;             PG8_BAR; PG8_WAIT_L(0); PG8_MMA(1, 0, At, B0); PG8_BAR; PG8_SCHED;
;             PG8_STAGE(PG8_SB(0, 1), b2 + hstepB, voffB);
;             PG8_WAIT_V(6); PG8_BAR; PG8_MMA(1, 1, At, B1); PG8_BAR;
.LBB0_186:
	s_ashr_i32 s17, s16, 31
	s_lshl_b64 s[24:25], s[16:17], 19
	s_add_u32 s24, s36, s24
	s_addc_u32 s25, s37, s25
	s_and_b64 s[0:1], s[0:1], exec
	s_cselect_b32 s13, s25, s27
	s_cselect_b32 s15, s24, s26
	s_add_u32 s0, s26, 0x40080
	s_addc_u32 s1, s27, 0
	s_add_u32 s17, s28, 0x100
	s_addc_u32 s49, s29, 0
	s_mov_b32 s50, -2
	ds_read_b128 v[156:159], v150
	ds_read_b128 v[160:163], v150 offset:1024
	ds_read_b128 v[164:167], v150 offset:2048
	ds_read_b128 v[168:171], v150 offset:3072
	s_add_u32 s26, s0, 0xfffc0080
	s_addc_u32 s27, s1, -1
	s_cmp_eq_u32 s50, 12
	s_cselect_b32 s29, s13, s27
	s_cselect_b32 s28, s15, s26
	s_cselect_b32 s27, s19, s49
	s_cselect_b32 s26, s18, s17
	v_lshl_add_u64 v[204:205], s[0:1], 0, v[138:139]
	s_add_i32 m0, s38, 0xc000
	ds_read_b128 v[172:175], v151
	ds_read_b128 v[176:179], v151 offset:1024
	ds_read_b128 v[180:183], v151 offset:2048
	ds_read_b128 v[184:187], v151 offset:3072
	ds_read_b128 v[188:191], v151 offset:4096
	ds_read_b128 v[192:195], v151 offset:5120
	ds_read_b128 v[196:199], v151 offset:6144
	ds_read_b128 v[200:203], v151 offset:7168
	global_load_lds_dwordx4 v[204:205], off
	s_add_i32 m0, s38, 0xe000
	v_lshl_add_u64 v[204:205], s[0:1], 0, v[140:141]
	global_load_lds_dwordx4 v[204:205], off
	s_waitcnt lgkmcnt(8)
	s_barrier
	s_waitcnt lgkmcnt(0)
	v_mfma_f32_16x16x32_bf16 v[124:127], v[156:159], v[172:175], 0
	v_mfma_f32_16x16x32_bf16 v[120:123], v[164:167], v[172:175], 0
	v_mfma_f32_16x16x32_bf16 v[116:119], v[156:159], v[180:183], 0
	v_mfma_f32_16x16x32_bf16 v[108:111], v[164:167], v[180:183], 0
	v_mfma_f32_16x16x32_bf16 v[100:103], v[156:159], v[188:191], 0
	v_mfma_f32_16x16x32_bf16 v[96:99], v[164:167], v[188:191], 0
	v_mfma_f32_16x16x32_bf16 v[84:87], v[156:159], v[196:199], 0
	v_mfma_f32_16x16x32_bf16 v[80:83], v[164:167], v[196:199], 0
	v_mfma_f32_16x16x32_bf16 v[124:127], v[160:163], v[176:179], v[124:127]
	v_mfma_f32_16x16x32_bf16 v[120:123], v[168:171], v[176:179], v[120:123]
	v_mfma_f32_16x16x32_bf16 v[116:119], v[160:163], v[184:187], v[116:119]
	v_mfma_f32_16x16x32_bf16 v[108:111], v[168:171], v[184:187], v[108:111]
	v_mfma_f32_16x16x32_bf16 v[100:103], v[160:163], v[192:195], v[100:103]
	v_mfma_f32_16x16x32_bf16 v[96:99], v[168:171], v[192:195], v[96:99]
	v_mfma_f32_16x16x32_bf16 v[84:87], v[160:163], v[200:203], v[84:87]
	v_mfma_f32_16x16x32_bf16 v[80:83], v[168:171], v[200:203], v[80:83]
	s_barrier
	s_add_i32 s51, s46, s35
	v_lshl_add_u64 v[220:221], s[26:27], 0, v[130:131]
	s_mov_b32 m0, s51
	ds_read_b128 v[204:207], v152
	ds_read_b128 v[208:211], v152 offset:1024
	ds_read_b128 v[212:215], v152 offset:2048
	ds_read_b128 v[216:219], v152 offset:3072
	global_load_lds_dwordx4 v[220:221], off
	s_add_i32 m0, s51, 0x2000
	v_lshl_add_u64 v[222:223], s[26:27], 0, v[134:135]
	global_load_lds_dwordx4 v[222:223], off
	s_barrier
	s_waitcnt lgkmcnt(0)
	v_mfma_f32_16x16x32_bf16 v[112:115], v[204:207], v[172:175], 0
	v_mfma_f32_16x16x32_bf16 v[104:107], v[212:215], v[172:175], 0
	v_mfma_f32_16x16x32_bf16 v[92:95], v[204:207], v[180:183], 0
	v_mfma_f32_16x16x32_bf16 v[88:91], v[212:215], v[180:183], 0
	v_mfma_f32_16x16x32_bf16 v[76:79], v[204:207], v[188:191], 0
	v_mfma_f32_16x16x32_bf16 v[72:75], v[212:215], v[188:191], 0
	v_mfma_f32_16x16x32_bf16 v[68:71], v[204:207], v[196:199], 0
	v_mfma_f32_16x16x32_bf16 v[64:67], v[212:215], v[196:199], 0
	v_mfma_f32_16x16x32_bf16 v[112:115], v[208:211], v[176:179], v[112:115]
	v_mfma_f32_16x16x32_bf16 v[104:107], v[216:219], v[176:179], v[104:107]
	v_mfma_f32_16x16x32_bf16 v[92:95], v[208:211], v[184:187], v[92:95]
	v_mfma_f32_16x16x32_bf16 v[88:91], v[216:219], v[184:187], v[88:91]
	v_mfma_f32_16x16x32_bf16 v[76:79], v[208:211], v[192:195], v[76:79]
	v_mfma_f32_16x16x32_bf16 v[72:75], v[216:219], v[192:195], v[72:75]
	v_mfma_f32_16x16x32_bf16 v[68:71], v[208:211], v[200:203], v[68:71]
	v_mfma_f32_16x16x32_bf16 v[64:67], v[216:219], v[200:203], v[64:67]
	s_mov_b32 m0, s38
	v_lshl_add_u64 v[224:225], s[28:29], 0, v[128:129]
	s_barrier
	ds_read_b128 v[172:175], v151 offset:16384
	ds_read_b128 v[176:179], v151 offset:17408
	ds_read_b128 v[180:183], v151 offset:18432
	ds_read_b128 v[184:187], v151 offset:19456
	ds_read_b128 v[188:191], v151 offset:20480
	ds_read_b128 v[192:195], v151 offset:21504
	ds_read_b128 v[196:199], v151 offset:22528
	ds_read_b128 v[200:203], v151 offset:23552
	global_load_lds_dwordx4 v[224:225], off
	s_mov_b32 m0, s39
	v_lshl_add_u64 v[226:227], s[28:29], 0, v[132:133]
	global_load_lds_dwordx4 v[226:227], off
	s_barrier
	s_waitcnt lgkmcnt(0)
	v_mfma_f32_16x16x32_bf16 v[60:63], v[156:159], v[172:175], 0
	v_mfma_f32_16x16x32_bf16 v[56:59], v[164:167], v[172:175], 0
	v_mfma_f32_16x16x32_bf16 v[52:55], v[156:159], v[180:183], 0
	v_mfma_f32_16x16x32_bf16 v[48:51], v[164:167], v[180:183], 0
	v_mfma_f32_16x16x32_bf16 v[36:39], v[156:159], v[188:191], 0
	v_mfma_f32_16x16x32_bf16 v[32:35], v[164:167], v[188:191], 0
	v_mfma_f32_16x16x32_bf16 v[20:23], v[156:159], v[196:199], 0
	v_mfma_f32_16x16x32_bf16 v[16:19], v[164:167], v[196:199], 0
	v_mfma_f32_16x16x32_bf16 v[60:63], v[160:163], v[176:179], v[60:63]
	v_mfma_f32_16x16x32_bf16 v[56:59], v[168:171], v[176:179], v[56:59]
	v_mfma_f32_16x16x32_bf16 v[52:55], v[160:163], v[184:187], v[52:55]
	v_mfma_f32_16x16x32_bf16 v[48:51], v[168:171], v[184:187], v[48:51]
	v_mfma_f32_16x16x32_bf16 v[36:39], v[160:163], v[192:195], v[36:39]
	v_mfma_f32_16x16x32_bf16 v[32:35], v[168:171], v[192:195], v[32:35]
	v_mfma_f32_16x16x32_bf16 v[20:23], v[160:163], v[200:203], v[20:23]
	v_mfma_f32_16x16x32_bf16 v[16:19], v[168:171], v[200:203], v[16:19]
	s_barrier
; #define PG8_STAGE(bufoff, gbase, voff) do { _Pragma("unroll") for (int _i = 0; _i < 2; ++_i) \
;         __builtin_amdgcn_global_load_lds((const unsigned*)((const char*)(gbase) + (voff)[_i]), (LAS unsigned*)(lds + (bufoff) + ldsw + _i * 8192), 16, 0, 0); } while (0)
; #define PG8_LDA(dst, b, h) do { _Pragma("unroll") for (int m = 0; m < 4; ++m) _Pragma("unroll") for (int k = 0; k < 2; ++k) dst[m][k] = *(const LAS bf16x8*)(lds + PG8_SA(b, h) + aoff + m * 2048 + k * 1024); } while (0)
; #define PG8_LDB(dst, b, h) do { _Pragma("unroll") for (int n = 0; n < 2; ++n) _Pragma("unroll") for (int k = 0; k < 2; ++k) dst[n][k] = *(const LAS bf16x8*)(lds + PG8_SB(b, h) + boff + n * 2048 + k * 1024); } while (0)
; #define PG8_MMA(ai, bj, At, Bt) do { __builtin_amdgcn_s_setprio(1); _Pragma("unroll") for (int m = 0; m < 4; ++m) _Pragma("unroll") for (int n = 0; n < 2; ++n) _Pragma("unroll") for (int k = 0; k < 2; ++k) \
;         acc[ai][bj][m][n] = __builtin_amdgcn_mfma_f32_16x16x32_bf16(Bt[n][k], At[m][k], acc[ai][bj][m][n], 0, 0, 0); __builtin_amdgcn_s_setprio(0); } while (0)
; #define PG8_WAIT_V(n) asm volatile("s_waitcnt vmcnt(" #n ")" ::: "memory")
; #define PG8_WAIT_L(n) asm volatile("s_waitcnt lgkmcnt(" #n ")" ::: "memory")
; #define PG8_BAR __builtin_amdgcn_s_barrier()
; #define PG8_SCHED __builtin_amdgcn_sched_barrier(0)
; template <class Epi>
; DEVI void gemm_phase(LAS unsigned char* lds, const Gemm g, const Epi& E) {
;     ...
;             PG8_STAGE(PG8_SB(0, 1), b2 + hstepB, voffB);
;             PG8_WAIT_V(6); PG8_BAR; PG8_MMA(1, 1, At, B1); PG8_BAR;
;             PG8_LDB(B0, 1, 0); PG8_SCHED; PG8_LDA(At, 1, 0); PG8_STAGE(PG8_SA(0, 1), a2 + hstepA, voffA);
;             PG8_WAIT_L(8); PG8_BAR; PG8_WAIT_L(0); PG8_MMA(0, 0, At, B0); PG8_BAR; PG8_SCHED;
;             PG8_LDB(B1, 1, 1); PG8_STAGE(PG8_SB(1, 0), b3, voffB);
;             PG8_BAR; PG8_WAIT_L(0); PG8_MMA(0, 1, At, B1); PG8_BAR;
;             PG8_LDA(At, 1, 1); PG8_STAGE(PG8_SA(1, 0), a3, voffA);
	s_add_u32 s52, s26, 0x40000
	s_addc_u32 s53, s27, 0
	s_add_i32 s51, s47, s35
	s_mov_b32 m0, s51
	v_lshl_add_u64 v[156:157], s[52:53], 0, v[130:131]
	global_load_lds_dwordx4 v[156:157], off
	s_add_i32 m0, s51, 0x2000
	v_lshl_add_u64 v[156:157], s[52:53], 0, v[134:135]
	global_load_lds_dwordx4 v[156:157], off
	s_waitcnt vmcnt(6)
	s_barrier
	v_mfma_f32_16x16x32_bf16 v[44:47], v[204:207], v[172:175], 0
	v_mfma_f32_16x16x32_bf16 v[40:43], v[212:215], v[172:175], 0
	v_mfma_f32_16x16x32_bf16 v[28:31], v[204:207], v[180:183], 0
	v_mfma_f32_16x16x32_bf16 v[24:27], v[212:215], v[180:183], 0
	v_mfma_f32_16x16x32_bf16 v[12:15], v[204:207], v[188:191], 0
	v_mfma_f32_16x16x32_bf16 v[8:11], v[212:215], v[188:191], 0
	v_mfma_f32_16x16x32_bf16 v[4:7], v[204:207], v[196:199], 0
	v_mfma_f32_16x16x32_bf16 v[0:3], v[212:215], v[196:199], 0
	v_mfma_f32_16x16x32_bf16 v[44:47], v[208:211], v[176:179], v[44:47]
	v_mfma_f32_16x16x32_bf16 v[40:43], v[216:219], v[176:179], v[40:43]
	v_mfma_f32_16x16x32_bf16 v[28:31], v[208:211], v[184:187], v[28:31]
	v_mfma_f32_16x16x32_bf16 v[24:27], v[216:219], v[184:187], v[24:27]
	v_mfma_f32_16x16x32_bf16 v[12:15], v[208:211], v[192:195], v[12:15]
	v_mfma_f32_16x16x32_bf16 v[8:11], v[216:219], v[192:195], v[8:11]
	v_mfma_f32_16x16x32_bf16 v[4:7], v[208:211], v[200:203], v[4:7]
	v_mfma_f32_16x16x32_bf16 v[0:3], v[216:219], v[200:203], v[0:3]
	s_add_i32 s51, 0, 0x18000
	v_add_u32_e32 v136, s51, v148
	s_barrier
	ds_read_b128 v[156:159], v136
	ds_read_b128 v[160:163], v136 offset:1024
	ds_read_b128 v[164:167], v136 offset:2048
	ds_read_b128 v[168:171], v136 offset:3072
	s_add_u32 s28, s28, 0x40000
	s_addc_u32 s29, s29, 0
	s_mov_b32 m0, s40
	v_lshl_add_u64 v[204:205], s[28:29], 0, v[128:129]
	ds_read_b128 v[172:175], v151 offset:32768
	ds_read_b128 v[176:179], v151 offset:33792
	ds_read_b128 v[180:183], v151 offset:34816
	ds_read_b128 v[184:187], v151 offset:35840
	ds_read_b128 v[188:191], v151 offset:36864
	ds_read_b128 v[192:195], v151 offset:37888
	ds_read_b128 v[196:199], v151 offset:38912
	ds_read_b128 v[200:203], v151 offset:39936
	global_load_lds_dwordx4 v[204:205], off
	s_mov_b32 m0, s41
	v_lshl_add_u64 v[204:205], s[28:29], 0, v[132:133]
	global_load_lds_dwordx4 v[204:205], off
	s_waitcnt lgkmcnt(8)
	s_barrier
	s_waitcnt lgkmcnt(0)
	v_mfma_f32_16x16x32_bf16 v[124:127], v[156:159], v[172:175], v[124:127]
	v_mfma_f32_16x16x32_bf16 v[120:123], v[164:167], v[172:175], v[120:123]
	v_mfma_f32_16x16x32_bf16 v[116:119], v[156:159], v[180:183], v[116:119]
	v_mfma_f32_16x16x32_bf16 v[108:111], v[164:167], v[180:183], v[108:111]
	v_mfma_f32_16x16x32_bf16 v[100:103], v[156:159], v[188:191], v[100:103]
	v_mfma_f32_16x16x32_bf16 v[96:99], v[164:167], v[188:191], v[96:99]
	v_mfma_f32_16x16x32_bf16 v[84:87], v[156:159], v[196:199], v[84:87]
	v_mfma_f32_16x16x32_bf16 v[80:83], v[164:167], v[196:199], v[80:83]
	v_mfma_f32_16x16x32_bf16 v[124:127], v[160:163], v[176:179], v[124:127]
	v_mfma_f32_16x16x32_bf16 v[120:123], v[168:171], v[176:179], v[120:123]
	v_mfma_f32_16x16x32_bf16 v[116:119], v[160:163], v[184:187], v[116:119]
	v_mfma_f32_16x16x32_bf16 v[108:111], v[168:171], v[184:187], v[108:111]
	v_mfma_f32_16x16x32_bf16 v[100:103], v[160:163], v[192:195], v[100:103]
	v_mfma_f32_16x16x32_bf16 v[96:99], v[168:171], v[192:195], v[96:99]
	v_mfma_f32_16x16x32_bf16 v[84:87], v[160:163], v[200:203], v[84:87]
	v_mfma_f32_16x16x32_bf16 v[80:83], v[168:171], v[200:203], v[80:83]
	s_barrier
	s_add_i32 s28, 0, 0x1c000
	s_add_i32 s29, s51, s35
	v_add_u32_e32 v136, s28, v148
	v_lshl_add_u64 v[220:221], v[220:221], 0, s[8:9]
	s_mov_b32 m0, s29
	ds_read_b128 v[204:207], v136
	ds_read_b128 v[208:211], v136 offset:1024
	ds_read_b128 v[212:215], v136 offset:2048
	ds_read_b128 v[216:219], v136 offset:3072
	global_load_lds_dwordx4 v[220:221], off
	s_add_i32 m0, s29, 0x2000
	v_lshl_add_u64 v[220:221], v[222:223], 0, s[8:9]
	global_load_lds_dwordx4 v[220:221], off
	s_barrier
; #define PG8_STAGE(bufoff, gbase, voff) do { _Pragma("unroll") for (int _i = 0; _i < 2; ++_i) \
;         __builtin_amdgcn_global_load_lds((const unsigned*)((const char*)(gbase) + (voff)[_i]), (LAS unsigned*)(lds + (bufoff) + ldsw + _i * 8192), 16, 0, 0); } while (0)
; #define PG8_LDA(dst, b, h) do { _Pragma("unroll") for (int m = 0; m < 4; ++m) _Pragma("unroll") for (int k = 0; k < 2; ++k) dst[m][k] = *(const LAS bf16x8*)(lds + PG8_SA(b, h) + aoff + m * 2048 + k * 1024); } while (0)
; #define PG8_MMA(ai, bj, At, Bt) do { __builtin_amdgcn_s_setprio(1); _Pragma("unroll") for (int m = 0; m < 4; ++m) _Pragma("unroll") for (int n = 0; n < 2; ++n) _Pragma("unroll") for (int k = 0; k < 2; ++k) \
;         acc[ai][bj][m][n] = __builtin_amdgcn_mfma_f32_16x16x32_bf16(Bt[n][k], At[m][k], acc[ai][bj][m][n], 0, 0, 0); __builtin_amdgcn_s_setprio(0); } while (0)
; #define PG8_WAIT_V(n) asm volatile("s_waitcnt vmcnt(" #n ")" ::: "memory")
; #define PG8_WAIT_L(n) asm volatile("s_waitcnt lgkmcnt(" #n ")" ::: "memory")
; #define PG8_BAR __builtin_amdgcn_s_barrier()
; #define PG8_SCHED __builtin_amdgcn_sched_barrier(0)
; template <class Epi>
; DEVI void gemm_phase(LAS unsigned char* lds, const Gemm g, const Epi& E) {
;     ...
;             PG8_LDA(At, 1, 1); PG8_STAGE(PG8_SA(1, 0), a3, voffA);
;             PG8_BAR; PG8_WAIT_L(0); PG8_MMA(1, 0, At, B0); PG8_BAR; PG8_SCHED;
;             PG8_STAGE(PG8_SB(1, 1), b3 + hstepB, voffB);
;             PG8_WAIT_V(6); PG8_BAR; PG8_MMA(1, 1, At, B1); PG8_BAR;
	s_waitcnt lgkmcnt(0)
	v_mfma_f32_16x16x32_bf16 v[112:115], v[204:207], v[172:175], v[112:115]
	v_mfma_f32_16x16x32_bf16 v[104:107], v[212:215], v[172:175], v[104:107]
	v_mfma_f32_16x16x32_bf16 v[92:95], v[204:207], v[180:183], v[92:95]
	v_mfma_f32_16x16x32_bf16 v[88:91], v[212:215], v[180:183], v[88:91]
	v_mfma_f32_16x16x32_bf16 v[76:79], v[204:207], v[188:191], v[76:79]
	v_mfma_f32_16x16x32_bf16 v[72:75], v[212:215], v[188:191], v[72:75]
	v_mfma_f32_16x16x32_bf16 v[68:71], v[204:207], v[196:199], v[68:71]
	v_mfma_f32_16x16x32_bf16 v[64:67], v[212:215], v[196:199], v[64:67]
	v_mfma_f32_16x16x32_bf16 v[112:115], v[208:211], v[176:179], v[112:115]
	v_mfma_f32_16x16x32_bf16 v[104:107], v[216:219], v[176:179], v[104:107]
	v_mfma_f32_16x16x32_bf16 v[92:95], v[208:211], v[184:187], v[92:95]
	v_mfma_f32_16x16x32_bf16 v[88:91], v[216:219], v[184:187], v[88:91]
	v_mfma_f32_16x16x32_bf16 v[76:79], v[208:211], v[192:195], v[76:79]
	v_mfma_f32_16x16x32_bf16 v[72:75], v[216:219], v[192:195], v[72:75]
	v_mfma_f32_16x16x32_bf16 v[68:71], v[208:211], v[200:203], v[68:71]
	v_mfma_f32_16x16x32_bf16 v[64:67], v[216:219], v[200:203], v[64:67]
	s_mov_b32 m0, s44
	v_lshl_add_u64 v[220:221], v[224:225], 0, s[8:9]
	s_barrier
	ds_read_b128 v[172:175], v151 offset:49152
	ds_read_b128 v[176:179], v151 offset:50176
	ds_read_b128 v[180:183], v151 offset:51200
	ds_read_b128 v[184:187], v151 offset:52224
	ds_read_b128 v[188:191], v151 offset:53248
	ds_read_b128 v[192:195], v151 offset:54272
	ds_read_b128 v[196:199], v151 offset:55296
	ds_read_b128 v[200:203], v151 offset:56320
	global_load_lds_dwordx4 v[220:221], off
	s_mov_b32 m0, s45
	v_lshl_add_u64 v[220:221], v[226:227], 0, s[8:9]
	global_load_lds_dwordx4 v[220:221], off
	s_barrier
	s_waitcnt lgkmcnt(0)
	v_mfma_f32_16x16x32_bf16 v[60:63], v[156:159], v[172:175], v[60:63]
	v_mfma_f32_16x16x32_bf16 v[56:59], v[164:167], v[172:175], v[56:59]
	v_mfma_f32_16x16x32_bf16 v[52:55], v[156:159], v[180:183], v[52:55]
	v_mfma_f32_16x16x32_bf16 v[48:51], v[164:167], v[180:183], v[48:51]
	v_mfma_f32_16x16x32_bf16 v[36:39], v[156:159], v[188:191], v[36:39]
	v_mfma_f32_16x16x32_bf16 v[32:35], v[164:167], v[188:191], v[32:35]
	v_mfma_f32_16x16x32_bf16 v[20:23], v[156:159], v[196:199], v[20:23]
	v_mfma_f32_16x16x32_bf16 v[16:19], v[164:167], v[196:199], v[16:19]
	v_mfma_f32_16x16x32_bf16 v[60:63], v[160:163], v[176:179], v[60:63]
	v_mfma_f32_16x16x32_bf16 v[56:59], v[168:171], v[176:179], v[56:59]
	v_mfma_f32_16x16x32_bf16 v[52:55], v[160:163], v[184:187], v[52:55]
	v_mfma_f32_16x16x32_bf16 v[48:51], v[168:171], v[184:187], v[48:51]
	v_mfma_f32_16x16x32_bf16 v[36:39], v[160:163], v[192:195], v[36:39]
	v_mfma_f32_16x16x32_bf16 v[32:35], v[168:171], v[192:195], v[32:35]
	v_mfma_f32_16x16x32_bf16 v[20:23], v[160:163], v[200:203], v[20:23]
	v_mfma_f32_16x16x32_bf16 v[16:19], v[168:171], v[200:203], v[16:19]
	s_barrier
	s_add_u32 s26, s26, 0x40080
	s_addc_u32 s27, s27, 0
	s_add_i32 s28, s28, s35
	s_mov_b32 m0, s28
	v_lshl_add_u64 v[156:157], s[26:27], 0, v[130:131]
	global_load_lds_dwordx4 v[156:157], off
	s_add_i32 m0, s28, 0x2000
	v_lshl_add_u64 v[156:157], s[26:27], 0, v[134:135]
	global_load_lds_dwordx4 v[156:157], off
	s_waitcnt vmcnt(6)
	s_barrier
	v_mfma_f32_16x16x32_bf16 v[44:47], v[204:207], v[172:175], v[44:47]
	v_mfma_f32_16x16x32_bf16 v[40:43], v[212:215], v[172:175], v[40:43]
	v_mfma_f32_16x16x32_bf16 v[28:31], v[204:207], v[180:183], v[28:31]
	v_mfma_f32_16x16x32_bf16 v[24:27], v[212:215], v[180:183], v[24:27]
	v_mfma_f32_16x16x32_bf16 v[12:15], v[204:207], v[188:191], v[12:15]
	v_mfma_f32_16x16x32_bf16 v[8:11], v[212:215], v[188:191], v[8:11]
	v_mfma_f32_16x16x32_bf16 v[4:7], v[204:207], v[196:199], v[4:7]
	v_mfma_f32_16x16x32_bf16 v[0:3], v[212:215], v[196:199], v[0:3]
	v_mfma_f32_16x16x32_bf16 v[44:47], v[208:211], v[176:179], v[44:47]
	v_mfma_f32_16x16x32_bf16 v[40:43], v[216:219], v[176:179], v[40:43]
	v_mfma_f32_16x16x32_bf16 v[28:31], v[208:211], v[184:187], v[28:31]
	v_mfma_f32_16x16x32_bf16 v[24:27], v[216:219], v[184:187], v[24:27]
	v_mfma_f32_16x16x32_bf16 v[12:15], v[208:211], v[192:195], v[12:15]
	v_mfma_f32_16x16x32_bf16 v[8:11], v[216:219], v[192:195], v[8:11]
	v_mfma_f32_16x16x32_bf16 v[4:7], v[208:211], v[200:203], v[4:7]
	v_mfma_f32_16x16x32_bf16 v[0:3], v[216:219], v[200:203], v[0:3]
	s_add_i32 s50, s50, 2
	s_add_u32 s0, s0, 0x100
	s_addc_u32 s1, s1, 0
	s_add_u32 s17, s17, 0x100
	s_addc_u32 s49, s49, 0
	s_cmp_gt_u32 s50, 13
	s_barrier

; DEVI size_t gemm_offB(const Gemm& g, const Unit& u) { return (g.split ? (size_t)(u.b >> 2) * g.sB + (size_t)(u.b & 3) * g.sB_lo : (size_t)u.b * g.sB) + (size_t)(u.pm >> g.pmsh) * g.sBpm; }
; #define PG8_STAGE(bufoff, gbase, voff) do { _Pragma("unroll") for (int _i = 0; _i < 2; ++_i) \
;         __builtin_amdgcn_global_load_lds((const unsigned*)((const char*)(gbase) + (voff)[_i]), (LAS unsigned*)(lds + (bufoff) + ldsw + _i * 8192), 16, 0, 0); } while (0)
; #define PG8_LDA(dst, b, h) do { _Pragma("unroll") for (int m = 0; m < 4; ++m) _Pragma("unroll") for (int k = 0; k < 2; ++k) dst[m][k] = *(const LAS bf16x8*)(lds + PG8_SA(b, h) + aoff + m * 2048 + k * 1024); } while (0)
; #define PG8_LDB(dst, b, h) do { _Pragma("unroll") for (int n = 0; n < 2; ++n) _Pragma("unroll") for (int k = 0; k < 2; ++k) dst[n][k] = *(const LAS bf16x8*)(lds + PG8_SB(b, h) + boff + n * 2048 + k * 1024); } while (0)
; #define PG8_WAIT_V(n) asm volatile("s_waitcnt vmcnt(" #n ")" ::: "memory")
; #define PG8_BAR __builtin_amdgcn_s_barrier()
; template <class Epi>
; DEVI void gemm_phase(LAS unsigned char* lds, const Gemm g, const Epi& E) {
;     ...
;         const bool has_next = unit_next(g, ui + 1, nxt);
;         const char* nA = has_next ? (const char*)g.A + gemm_offA(g, nxt) * 2 + (size_t)nxt.pm * tstepA : cA;
;         const char* nB = has_next ? (const char*)g.Bt + gemm_offB(g, nxt) * 2 + (size_t)nxt.pn * tstepB : cB;
;         for (int t = 0; t < nt; t += 2) {
;             const bool last = (t == nt - 2);
;             const char* a1 = cA + (size_t)(t + 1) * kstep;
;             const char* a2 = last ? nA : cA + (size_t)(t + 2) * kstep; const char* b2 = last ? nB : cB + (size_t)(t + 2) * kstep;
;             const char* a3 = a2 + kstep; const char* b3 = b2 + kstep;
;             PG8_LDB(B0, 0, 0); PG8_SCHED; PG8_LDA(At, 0, 0); PG8_STAGE(PG8_SA(1, 1), a1 + hstepA, voffA);
;             PG8_WAIT_L(8); PG8_BAR; PG8_WAIT_L(0); PG8_MMA(0, 0, At, B0); PG8_BAR; PG8_SCHED;
;             PG8_LDB(B1, 0, 1); PG8_STAGE(PG8_SB(0, 0), b2, voffB);
;             PG8_BAR; PG8_WAIT_L(0); PG8_MMA(0, 1, At, B1); PG8_BAR;
;             PG8_LDA(At, 0, 1); PG8_STAGE(PG8_SA(0, 0), a2, voffA);
;             PG8_BAR; PG8_WAIT_L(0); PG8_MMA(1, 0, At, B0); PG8_BAR; PG8_SCHED;
;             PG8_STAGE(PG8_SB(0, 1), b2 + hstepB, voffB);
;             PG8_WAIT_V(6); PG8_BAR; PG8_MMA(1, 1, At, B1); PG8_BAR;
.LBB0_275:
	s_and_b32 s101, s66, 0xc0
	s_cmp_eq_u32 s4, 12
	s_cselect_b32 s100, 1, 0
	s_cselect_b32 s101, s101, 0
	s_ashr_i32 s13, s12, 31
	v_mov_b64_e32 v[0:1], 0x680
	s_lshl_b64 s[0:1], s[12:13], 19
	v_cmp_lt_i64_e32 vcc, s[16:17], v[0:1]
	s_add_u32 s16, s24, s0
	s_addc_u32 s17, s25, s1
	s_and_b64 s[0:1], vcc, exec
	s_cselect_b32 s0, s17, s9
	s_cselect_b32 s1, s16, s8
	s_ashr_i32 s15, s14, 31
	s_lshl_b64 s[18:19], s[14:15], 19
	s_add_u32 s36, s40, s18
	s_addc_u32 s37, s41, s19
	s_and_b64 s[18:19], vcc, exec
	s_cselect_b32 s5, s37, s47
	s_cselect_b32 s7, s36, s46
	s_add_u32 s8, s8, 0x40080
	s_addc_u32 s9, s9, 0
	s_add_u32 s13, s46, 0x100
	s_addc_u32 s15, s47, 0
	s_mov_b32 s18, -2
	s_add_u32 s19, s8, 0xfffc0080
	s_addc_u32 s26, s9, -1
	s_add_i32 s27, 0, 0x10000
	v_add_u32_e32 v8, s27, v214
	ds_read_b128 v[130:133], v8
	ds_read_b128 v[134:137], v8 offset:1024
	ds_read_b128 v[138:141], v8 offset:2048
	ds_read_b128 v[142:145], v8 offset:3072
	s_cmp_eq_u32 s18, 12
	s_cselect_b32 s69, s0, s26
	s_cselect_b32 s68, s1, s19
	s_cselect_b32 s47, s5, s15
	s_cselect_b32 s46, s7, s13
	v_lshl_add_u64 v[208:209], s[8:9], 0, v[184:185]
	s_add_i32 m0, s81, 0xc000
	ds_read_b128 v[146:149], v216
	ds_read_b128 v[150:153], v216 offset:1024
	ds_read_b128 v[188:191], v216 offset:2048
	ds_read_b128 v[192:195], v216 offset:3072
	ds_read_b128 v[196:199], v216 offset:4096
	ds_read_b128 v[200:203], v216 offset:5120
	ds_read_b128 v[204:207], v216 offset:6144
	ds_read_b128 v[218:221], v216 offset:7168
	global_load_lds_dwordx4 v[208:209], off
	s_add_i32 m0, s81, 0xe000
	v_lshl_add_u64 v[208:209], s[8:9], 0, v[186:187]
	global_load_lds_dwordx4 v[208:209], off
	s_waitcnt lgkmcnt(8)
	s_barrier
	s_waitcnt lgkmcnt(0)
	s_cmp_lg_u32 s101, 0
	s_cbranch_scc1 .Lip13_a_0_p
	v_mfma_f32_16x16x32_bf16 v[126:129], v[130:133], v[146:149], 0
	v_mfma_f32_16x16x32_bf16 v[122:125], v[138:141], v[146:149], 0
	v_mfma_f32_16x16x32_bf16 v[114:117], v[130:133], v[188:191], 0
	v_mfma_f32_16x16x32_bf16 v[106:109], v[138:141], v[188:191], 0
	v_mfma_f32_16x16x32_bf16 v[94:97], v[130:133], v[196:199], 0
	v_mfma_f32_16x16x32_bf16 v[90:93], v[138:141], v[196:199], 0
	v_mfma_f32_16x16x32_bf16 v[82:85], v[130:133], v[204:207], 0
	v_mfma_f32_16x16x32_bf16 v[74:77], v[138:141], v[204:207], 0
	v_mfma_f32_16x16x32_bf16 v[126:129], v[134:137], v[150:153], v[126:129]
	v_mfma_f32_16x16x32_bf16 v[122:125], v[142:145], v[150:153], v[122:125]
	v_mfma_f32_16x16x32_bf16 v[114:117], v[134:137], v[192:195], v[114:117]
	v_mfma_f32_16x16x32_bf16 v[106:109], v[142:145], v[192:195], v[106:109]
	v_mfma_f32_16x16x32_bf16 v[94:97], v[134:137], v[200:203], v[94:97]
	v_mfma_f32_16x16x32_bf16 v[90:93], v[142:145], v[200:203], v[90:93]
	v_mfma_f32_16x16x32_bf16 v[82:85], v[134:137], v[218:221], v[82:85]
	v_mfma_f32_16x16x32_bf16 v[74:77], v[142:145], v[218:221], v[74:77]
.Lip13_a_0_p:
	s_barrier
	s_add_i32 s19, 0, 0x14000
	s_add_i32 s26, s27, s80
	v_add_u32_e32 v8, s19, v214
	v_lshl_add_u64 v[208:209], s[46:47], 0, v[178:179]
	s_mov_b32 m0, s26
	ds_read_b128 v[222:225], v8
	ds_read_b128 v[226:229], v8 offset:1024
	ds_read_b128 v[230:233], v8 offset:2048
	ds_read_b128 v[234:237], v8 offset:3072
	global_load_lds_dwordx4 v[208:209], off
	s_add_i32 m0, s26, 0x2000
	v_lshl_add_u64 v[238:239], s[46:47], 0, v[182:183]
	global_load_lds_dwordx4 v[238:239], off
	s_barrier
	s_waitcnt lgkmcnt(0)
	s_cmp_lg_u32 s100, 0
	s_cbranch_scc1 .Lip13_a_1_p
	v_mfma_f32_16x16x32_bf16 v[118:121], v[222:225], v[146:149], 0
	v_mfma_f32_16x16x32_bf16 v[110:113], v[230:233], v[146:149], 0
	v_mfma_f32_16x16x32_bf16 v[102:105], v[222:225], v[188:191], 0
	v_mfma_f32_16x16x32_bf16 v[98:101], v[230:233], v[188:191], 0
	v_mfma_f32_16x16x32_bf16 v[86:89], v[222:225], v[196:199], 0
	v_mfma_f32_16x16x32_bf16 v[78:81], v[230:233], v[196:199], 0
	v_mfma_f32_16x16x32_bf16 v[62:65], v[222:225], v[204:207], 0
	v_mfma_f32_16x16x32_bf16 v[58:61], v[230:233], v[204:207], 0
	v_mfma_f32_16x16x32_bf16 v[118:121], v[226:229], v[150:153], v[118:121]
	v_mfma_f32_16x16x32_bf16 v[110:113], v[234:237], v[150:153], v[110:113]
	v_mfma_f32_16x16x32_bf16 v[102:105], v[226:229], v[192:195], v[102:105]
	v_mfma_f32_16x16x32_bf16 v[98:101], v[234:237], v[192:195], v[98:101]
	v_mfma_f32_16x16x32_bf16 v[86:89], v[226:229], v[200:203], v[86:89]
	v_mfma_f32_16x16x32_bf16 v[78:81], v[234:237], v[200:203], v[78:81]
	v_mfma_f32_16x16x32_bf16 v[62:65], v[226:229], v[218:221], v[62:65]
	v_mfma_f32_16x16x32_bf16 v[58:61], v[234:237], v[218:221], v[58:61]
.Lip13_a_1_p:
	s_mov_b32 m0, s81
	v_lshl_add_u64 v[240:241], s[68:69], 0, v[176:177]
	s_barrier
	ds_read_b128 v[146:149], v216 offset:16384
	ds_read_b128 v[150:153], v216 offset:17408
	ds_read_b128 v[188:191], v216 offset:18432
	ds_read_b128 v[192:195], v216 offset:19456
	ds_read_b128 v[196:199], v216 offset:20480
	ds_read_b128 v[200:203], v216 offset:21504
	ds_read_b128 v[204:207], v216 offset:22528
	ds_read_b128 v[218:221], v216 offset:23552
	global_load_lds_dwordx4 v[240:241], off
	s_mov_b32 m0, s82
	v_lshl_add_u64 v[242:243], s[68:69], 0, v[180:181]
	global_load_lds_dwordx4 v[242:243], off
	s_barrier
	s_waitcnt lgkmcnt(0)
	s_cmp_lg_u32 s101, 0
	s_cbranch_scc1 .Lip13_a_2_p
	v_mfma_f32_16x16x32_bf16 v[70:73], v[130:133], v[146:149], 0
	v_mfma_f32_16x16x32_bf16 v[66:69], v[138:141], v[146:149], 0
	v_mfma_f32_16x16x32_bf16 v[46:49], v[130:133], v[188:191], 0
	v_mfma_f32_16x16x32_bf16 v[42:45], v[138:141], v[188:191], 0
	v_mfma_f32_16x16x32_bf16 v[30:33], v[130:133], v[196:199], 0
	v_mfma_f32_16x16x32_bf16 v[26:29], v[138:141], v[196:199], 0
	v_mfma_f32_16x16x32_bf16 v[14:17], v[130:133], v[204:207], 0
	v_mfma_f32_16x16x32_bf16 v[10:13], v[138:141], v[204:207], 0
	v_mfma_f32_16x16x32_bf16 v[70:73], v[134:137], v[150:153], v[70:73]
	v_mfma_f32_16x16x32_bf16 v[66:69], v[142:145], v[150:153], v[66:69]
	v_mfma_f32_16x16x32_bf16 v[46:49], v[134:137], v[192:195], v[46:49]
	v_mfma_f32_16x16x32_bf16 v[42:45], v[142:145], v[192:195], v[42:45]
	v_mfma_f32_16x16x32_bf16 v[30:33], v[134:137], v[200:203], v[30:33]
	v_mfma_f32_16x16x32_bf16 v[26:29], v[142:145], v[200:203], v[26:29]
	v_mfma_f32_16x16x32_bf16 v[14:17], v[134:137], v[218:221], v[14:17]
	v_mfma_f32_16x16x32_bf16 v[10:13], v[142:145], v[218:221], v[10:13]
; #define PG8_STAGE(bufoff, gbase, voff) do { _Pragma("unroll") for (int _i = 0; _i < 2; ++_i) \
;         __builtin_amdgcn_global_load_lds((const unsigned*)((const char*)(gbase) + (voff)[_i]), (LAS unsigned*)(lds + (bufoff) + ldsw + _i * 8192), 16, 0, 0); } while (0)
; #define PG8_LDA(dst, b, h) do { _Pragma("unroll") for (int m = 0; m < 4; ++m) _Pragma("unroll") for (int k = 0; k < 2; ++k) dst[m][k] = *(const LAS bf16x8*)(lds + PG8_SA(b, h) + aoff + m * 2048 + k * 1024); } while (0)
; #define PG8_LDB(dst, b, h) do { _Pragma("unroll") for (int n = 0; n < 2; ++n) _Pragma("unroll") for (int k = 0; k < 2; ++k) dst[n][k] = *(const LAS bf16x8*)(lds + PG8_SB(b, h) + boff + n * 2048 + k * 1024); } while (0)
; #define PG8_MMA(ai, bj, At, Bt) do { __builtin_amdgcn_s_setprio(1); _Pragma("unroll") for (int m = 0; m < 4; ++m) _Pragma("unroll") for (int n = 0; n < 2; ++n) _Pragma("unroll") for (int k = 0; k < 2; ++k) \
;         acc[ai][bj][m][n] = __builtin_amdgcn_mfma_f32_16x16x32_bf16(Bt[n][k], At[m][k], acc[ai][bj][m][n], 0, 0, 0); __builtin_amdgcn_s_setprio(0); } while (0)
; #define PG8_WAIT_V(n) asm volatile("s_waitcnt vmcnt(" #n ")" ::: "memory")
; #define PG8_WAIT_L(n) asm volatile("s_waitcnt lgkmcnt(" #n ")" ::: "memory")
; #define PG8_BAR __builtin_amdgcn_s_barrier()
; #define PG8_SCHED __builtin_amdgcn_sched_barrier(0)
; template <class Epi>
; DEVI void gemm_phase(LAS unsigned char* lds, const Gemm g, const Epi& E) {
;     ...
;             PG8_STAGE(PG8_SB(0, 1), b2 + hstepB, voffB);
;             PG8_WAIT_V(6); PG8_BAR; PG8_MMA(1, 1, At, B1); PG8_BAR;
;             PG8_LDB(B0, 1, 0); PG8_SCHED; PG8_LDA(At, 1, 0); PG8_STAGE(PG8_SA(0, 1), a2 + hstepA, voffA);
;             PG8_WAIT_L(8); PG8_BAR; PG8_WAIT_L(0); PG8_MMA(0, 0, At, B0); PG8_BAR; PG8_SCHED;
;             PG8_LDB(B1, 1, 1); PG8_STAGE(PG8_SB(1, 0), b3, voffB);
;             PG8_BAR; PG8_WAIT_L(0); PG8_MMA(0, 1, At, B1); PG8_BAR;
;             PG8_LDA(At, 1, 1); PG8_STAGE(PG8_SA(1, 0), a3, voffA);
.Lip13_a_2_p:
	s_barrier
	s_add_u32 s26, s46, 0x40000
	s_addc_u32 s27, s47, 0
	s_add_i32 s19, s19, s80
	s_mov_b32 m0, s19
	v_lshl_add_u64 v[130:131], s[26:27], 0, v[178:179]
	global_load_lds_dwordx4 v[130:131], off
	s_add_i32 m0, s19, 0x2000
	v_lshl_add_u64 v[130:131], s[26:27], 0, v[182:183]
	global_load_lds_dwordx4 v[130:131], off
	s_waitcnt vmcnt(6)
	s_barrier
	s_cmp_lg_u32 s100, 0
	s_cbranch_scc1 .Lip13_a_3_p
	v_mfma_f32_16x16x32_bf16 v[50:53], v[222:225], v[146:149], 0
	v_mfma_f32_16x16x32_bf16 v[54:57], v[230:233], v[146:149], 0
	v_mfma_f32_16x16x32_bf16 v[34:37], v[222:225], v[188:191], 0
	v_mfma_f32_16x16x32_bf16 v[38:41], v[230:233], v[188:191], 0
	v_mfma_f32_16x16x32_bf16 v[18:21], v[222:225], v[196:199], 0
	v_mfma_f32_16x16x32_bf16 v[22:25], v[230:233], v[196:199], 0
	v_mfma_f32_16x16x32_bf16 v[0:3], v[222:225], v[204:207], 0
	v_mfma_f32_16x16x32_bf16 v[4:7], v[230:233], v[204:207], 0
	v_mfma_f32_16x16x32_bf16 v[50:53], v[226:229], v[150:153], v[50:53]
	v_mfma_f32_16x16x32_bf16 v[54:57], v[234:237], v[150:153], v[54:57]
	v_mfma_f32_16x16x32_bf16 v[34:37], v[226:229], v[192:195], v[34:37]
	v_mfma_f32_16x16x32_bf16 v[38:41], v[234:237], v[192:195], v[38:41]
	v_mfma_f32_16x16x32_bf16 v[18:21], v[226:229], v[200:203], v[18:21]
	v_mfma_f32_16x16x32_bf16 v[22:25], v[234:237], v[200:203], v[22:25]
	v_mfma_f32_16x16x32_bf16 v[0:3], v[226:229], v[218:221], v[0:3]
	v_mfma_f32_16x16x32_bf16 v[4:7], v[234:237], v[218:221], v[4:7]
.Lip13_a_3_p:
	s_add_i32 s19, 0, 0x18000
	v_add_u32_e32 v8, s19, v214
	s_barrier
	ds_read_b128 v[130:133], v8
	ds_read_b128 v[134:137], v8 offset:1024
	ds_read_b128 v[138:141], v8 offset:2048
	ds_read_b128 v[142:145], v8 offset:3072
	s_add_u32 s26, s68, 0x40000
	s_addc_u32 s27, s69, 0
	s_mov_b32 m0, s83
	v_lshl_add_u64 v[222:223], s[26:27], 0, v[176:177]
	ds_read_b128 v[146:149], v216 offset:32768
	ds_read_b128 v[150:153], v216 offset:33792
	ds_read_b128 v[188:191], v216 offset:34816
	ds_read_b128 v[192:195], v216 offset:35840
	ds_read_b128 v[196:199], v216 offset:36864
	ds_read_b128 v[200:203], v216 offset:37888
	ds_read_b128 v[204:207], v216 offset:38912
	ds_read_b128 v[218:221], v216 offset:39936
	global_load_lds_dwordx4 v[222:223], off
	s_mov_b32 m0, s84
	v_lshl_add_u64 v[222:223], s[26:27], 0, v[180:181]
	global_load_lds_dwordx4 v[222:223], off
	s_waitcnt lgkmcnt(8)
	s_barrier
	s_waitcnt lgkmcnt(0)
	s_cmp_lg_u32 s101, 0
	s_cbranch_scc1 .Lip13_a_4_p
	v_mfma_f32_16x16x32_bf16 v[126:129], v[130:133], v[146:149], v[126:129]
	v_mfma_f32_16x16x32_bf16 v[122:125], v[138:141], v[146:149], v[122:125]
	v_mfma_f32_16x16x32_bf16 v[114:117], v[130:133], v[188:191], v[114:117]
	v_mfma_f32_16x16x32_bf16 v[106:109], v[138:141], v[188:191], v[106:109]
	v_mfma_f32_16x16x32_bf16 v[94:97], v[130:133], v[196:199], v[94:97]
	v_mfma_f32_16x16x32_bf16 v[90:93], v[138:141], v[196:199], v[90:93]
	v_mfma_f32_16x16x32_bf16 v[82:85], v[130:133], v[204:207], v[82:85]
	v_mfma_f32_16x16x32_bf16 v[74:77], v[138:141], v[204:207], v[74:77]
	v_mfma_f32_16x16x32_bf16 v[126:129], v[134:137], v[150:153], v[126:129]
	v_mfma_f32_16x16x32_bf16 v[122:125], v[142:145], v[150:153], v[122:125]
	v_mfma_f32_16x16x32_bf16 v[114:117], v[134:137], v[192:195], v[114:117]
	v_mfma_f32_16x16x32_bf16 v[106:109], v[142:145], v[192:195], v[106:109]
	v_mfma_f32_16x16x32_bf16 v[94:97], v[134:137], v[200:203], v[94:97]
	v_mfma_f32_16x16x32_bf16 v[90:93], v[142:145], v[200:203], v[90:93]
	v_mfma_f32_16x16x32_bf16 v[82:85], v[134:137], v[218:221], v[82:85]
	v_mfma_f32_16x16x32_bf16 v[74:77], v[142:145], v[218:221], v[74:77]
; #define PG8_STAGE(bufoff, gbase, voff) do { _Pragma("unroll") for (int _i = 0; _i < 2; ++_i) \
;         __builtin_amdgcn_global_load_lds((const unsigned*)((const char*)(gbase) + (voff)[_i]), (LAS unsigned*)(lds + (bufoff) + ldsw + _i * 8192), 16, 0, 0); } while (0)
; #define PG8_LDA(dst, b, h) do { _Pragma("unroll") for (int m = 0; m < 4; ++m) _Pragma("unroll") for (int k = 0; k < 2; ++k) dst[m][k] = *(const LAS bf16x8*)(lds + PG8_SA(b, h) + aoff + m * 2048 + k * 1024); } while (0)
; #define PG8_MMA(ai, bj, At, Bt) do { __builtin_amdgcn_s_setprio(1); _Pragma("unroll") for (int m = 0; m < 4; ++m) _Pragma("unroll") for (int n = 0; n < 2; ++n) _Pragma("unroll") for (int k = 0; k < 2; ++k) \
;         acc[ai][bj][m][n] = __builtin_amdgcn_mfma_f32_16x16x32_bf16(Bt[n][k], At[m][k], acc[ai][bj][m][n], 0, 0, 0); __builtin_amdgcn_s_setprio(0); } while (0)
; #define PG8_WAIT_V(n) asm volatile("s_waitcnt vmcnt(" #n ")" ::: "memory")
; #define PG8_WAIT_L(n) asm volatile("s_waitcnt lgkmcnt(" #n ")" ::: "memory")
; #define PG8_BAR __builtin_amdgcn_s_barrier()
; #define PG8_SCHED __builtin_amdgcn_sched_barrier(0)
; template <class Epi>
; DEVI void gemm_phase(LAS unsigned char* lds, const Gemm g, const Epi& E) {
;     ...
;             PG8_LDA(At, 1, 1); PG8_STAGE(PG8_SA(1, 0), a3, voffA);
;             PG8_BAR; PG8_WAIT_L(0); PG8_MMA(1, 0, At, B0); PG8_BAR; PG8_SCHED;
;             PG8_STAGE(PG8_SB(1, 1), b3 + hstepB, voffB);
;             PG8_WAIT_V(6); PG8_BAR; PG8_MMA(1, 1, At, B1); PG8_BAR;
.Lip13_a_4_p:
	s_barrier
	s_add_i32 s38, 0, 0x1c000
	s_add_i32 s19, s19, s80
	v_add_u32_e32 v8, s38, v214
	v_lshl_add_u64 v[208:209], v[208:209], 0, s[70:71]
	s_mov_b32 m0, s19
	ds_read_b128 v[222:225], v8
	ds_read_b128 v[226:229], v8 offset:1024
	ds_read_b128 v[230:233], v8 offset:2048
	ds_read_b128 v[234:237], v8 offset:3072
	global_load_lds_dwordx4 v[208:209], off
	s_add_i32 m0, s19, 0x2000
	v_lshl_add_u64 v[208:209], v[238:239], 0, s[70:71]
	global_load_lds_dwordx4 v[208:209], off
	s_barrier
	s_waitcnt lgkmcnt(0)
	s_cmp_lg_u32 s100, 0
	s_cbranch_scc1 .Lip13_a_5_p
	v_mfma_f32_16x16x32_bf16 v[118:121], v[222:225], v[146:149], v[118:121]
	v_mfma_f32_16x16x32_bf16 v[110:113], v[230:233], v[146:149], v[110:113]
	v_mfma_f32_16x16x32_bf16 v[102:105], v[222:225], v[188:191], v[102:105]
	v_mfma_f32_16x16x32_bf16 v[98:101], v[230:233], v[188:191], v[98:101]
	v_mfma_f32_16x16x32_bf16 v[86:89], v[222:225], v[196:199], v[86:89]
	v_mfma_f32_16x16x32_bf16 v[78:81], v[230:233], v[196:199], v[78:81]
	v_mfma_f32_16x16x32_bf16 v[62:65], v[222:225], v[204:207], v[62:65]
	v_mfma_f32_16x16x32_bf16 v[58:61], v[230:233], v[204:207], v[58:61]
	v_mfma_f32_16x16x32_bf16 v[118:121], v[226:229], v[150:153], v[118:121]
	v_mfma_f32_16x16x32_bf16 v[110:113], v[234:237], v[150:153], v[110:113]
	v_mfma_f32_16x16x32_bf16 v[102:105], v[226:229], v[192:195], v[102:105]
	v_mfma_f32_16x16x32_bf16 v[98:101], v[234:237], v[192:195], v[98:101]
	v_mfma_f32_16x16x32_bf16 v[86:89], v[226:229], v[200:203], v[86:89]
	v_mfma_f32_16x16x32_bf16 v[78:81], v[234:237], v[200:203], v[78:81]
	v_mfma_f32_16x16x32_bf16 v[62:65], v[226:229], v[218:221], v[62:65]
	v_mfma_f32_16x16x32_bf16 v[58:61], v[234:237], v[218:221], v[58:61]
.Lip13_a_5_p:
	s_mov_b32 m0, s85
	v_lshl_add_u64 v[208:209], v[240:241], 0, s[70:71]
	s_barrier
	ds_read_b128 v[146:149], v216 offset:49152
	ds_read_b128 v[150:153], v216 offset:50176
	ds_read_b128 v[188:191], v216 offset:51200
	ds_read_b128 v[192:195], v216 offset:52224
	ds_read_b128 v[196:199], v216 offset:53248
	ds_read_b128 v[200:203], v216 offset:54272
	ds_read_b128 v[204:207], v216 offset:55296
	ds_read_b128 v[218:221], v216 offset:56320
	global_load_lds_dwordx4 v[208:209], off
	s_mov_b32 m0, s86
	v_lshl_add_u64 v[208:209], v[242:243], 0, s[70:71]
	global_load_lds_dwordx4 v[208:209], off
	s_barrier
	s_waitcnt lgkmcnt(0)
	s_cmp_lg_u32 s101, 0
	s_cbranch_scc1 .Lip13_a_6_p
	v_mfma_f32_16x16x32_bf16 v[70:73], v[130:133], v[146:149], v[70:73]
	v_mfma_f32_16x16x32_bf16 v[66:69], v[138:141], v[146:149], v[66:69]
	v_mfma_f32_16x16x32_bf16 v[46:49], v[130:133], v[188:191], v[46:49]
	v_mfma_f32_16x16x32_bf16 v[42:45], v[138:141], v[188:191], v[42:45]
	v_mfma_f32_16x16x32_bf16 v[30:33], v[130:133], v[196:199], v[30:33]
	v_mfma_f32_16x16x32_bf16 v[26:29], v[138:141], v[196:199], v[26:29]
	v_mfma_f32_16x16x32_bf16 v[14:17], v[130:133], v[204:207], v[14:17]
	v_mfma_f32_16x16x32_bf16 v[10:13], v[138:141], v[204:207], v[10:13]
	v_mfma_f32_16x16x32_bf16 v[70:73], v[134:137], v[150:153], v[70:73]
	v_mfma_f32_16x16x32_bf16 v[66:69], v[142:145], v[150:153], v[66:69]
	v_mfma_f32_16x16x32_bf16 v[46:49], v[134:137], v[192:195], v[46:49]
	v_mfma_f32_16x16x32_bf16 v[42:45], v[142:145], v[192:195], v[42:45]
	v_mfma_f32_16x16x32_bf16 v[30:33], v[134:137], v[200:203], v[30:33]
	v_mfma_f32_16x16x32_bf16 v[26:29], v[142:145], v[200:203], v[26:29]
	v_mfma_f32_16x16x32_bf16 v[14:17], v[134:137], v[218:221], v[14:17]
	v_mfma_f32_16x16x32_bf16 v[10:13], v[142:145], v[218:221], v[10:13]

; #define PG8_STAGE(bufoff, gbase, voff) do { _Pragma("unroll") for (int _i = 0; _i < 2; ++_i) \
;         __builtin_amdgcn_global_load_lds((const unsigned*)((const char*)(gbase) + (voff)[_i]), (LAS unsigned*)(lds + (bufoff) + ldsw + _i * 8192), 16, 0, 0); } while (0)
; #define PG8_LDA(dst, b, h) do { _Pragma("unroll") for (int m = 0; m < 4; ++m) _Pragma("unroll") for (int k = 0; k < 2; ++k) dst[m][k] = *(const LAS bf16x8*)(lds + PG8_SA(b, h) + aoff + m * 2048 + k * 1024); } while (0)
; #define PG8_LDB(dst, b, h) do { _Pragma("unroll") for (int n = 0; n < 2; ++n) _Pragma("unroll") for (int k = 0; k < 2; ++k) dst[n][k] = *(const LAS bf16x8*)(lds + PG8_SB(b, h) + boff + n * 2048 + k * 1024); } while (0)
; #define PG8_MMA(ai, bj, At, Bt) do { __builtin_amdgcn_s_setprio(1); _Pragma("unroll") for (int m = 0; m < 4; ++m) _Pragma("unroll") for (int n = 0; n < 2; ++n) _Pragma("unroll") for (int k = 0; k < 2; ++k) \
;         acc[ai][bj][m][n] = __builtin_amdgcn_mfma_f32_16x16x32_bf16(Bt[n][k], At[m][k], acc[ai][bj][m][n], 0, 0, 0); __builtin_amdgcn_s_setprio(0); } while (0)
; template <class Epi>
; DEVI void gemm_phase(LAS unsigned char* lds, const Gemm g, const Epi& E) {
;     ...
;         for (int t = 0; t < nt; t += 2) {
;             const bool last = (t == nt - 2);
;             const char* a1 = cA + (size_t)(t + 1) * kstep;
;             const char* a2 = last ? nA : cA + (size_t)(t + 2) * kstep; const char* b2 = last ? nB : cB + (size_t)(t + 2) * kstep;
;             const char* a3 = a2 + kstep; const char* b3 = b2 + kstep;
;             PG8_LDB(B0, 0, 0); PG8_SCHED; PG8_LDA(At, 0, 0); PG8_STAGE(PG8_SA(1, 1), a1 + hstepA, voffA);
;             PG8_WAIT_L(8); PG8_BAR; PG8_WAIT_L(0); PG8_MMA(0, 0, At, B0); PG8_BAR; PG8_SCHED;
;             PG8_LDB(B1, 0, 1); PG8_STAGE(PG8_SB(0, 0), b2, voffB);
;             PG8_BAR; PG8_WAIT_L(0); PG8_MMA(0, 1, At, B1); PG8_BAR;
;             PG8_LDA(At, 0, 1); PG8_STAGE(PG8_SA(0, 0), a2, voffA);
;             PG8_BAR; PG8_WAIT_L(0); PG8_MMA(1, 0, At, B0); PG8_BAR; PG8_SCHED;
;             PG8_STAGE(PG8_SB(0, 1), b2 + hstepB, voffB);
;             PG8_WAIT_V(6); PG8_BAR; PG8_MMA(1, 1, At, B1); PG8_BAR;
;             PG8_LDB(B0, 1, 0); PG8_SCHED; PG8_LDA(At, 1, 0); PG8_STAGE(PG8_SA(0, 1), a2 + hstepA, voffA);
;             PG8_WAIT_L(8); PG8_BAR; PG8_WAIT_L(0); PG8_MMA(0, 0, At, B0); PG8_BAR; PG8_SCHED;
.Lip13_a_7_p:
	s_add_i32 s18, s18, 2
	s_add_u32 s8, s8, 0x100
	s_addc_u32 s9, s9, 0
	s_add_u32 s13, s13, 0x100
	s_addc_u32 s15, s15, 0
	s_cmp_gt_u32 s18, 13
	s_barrier
.LBB0_276:
	s_add_u32 s19, s8, 0xfffc0080
	s_addc_u32 s26, s9, -1
	s_add_i32 s27, 0, 0x10000
	v_add_u32_e32 v8, s27, v214
	ds_read_b128 v[130:133], v8
	ds_read_b128 v[134:137], v8 offset:1024
	ds_read_b128 v[138:141], v8 offset:2048
	ds_read_b128 v[142:145], v8 offset:3072
	s_cmp_eq_u32 s18, 12
	s_cselect_b32 s69, s0, s26
	s_cselect_b32 s68, s1, s19
	s_cselect_b32 s47, s5, s15
	s_cselect_b32 s46, s7, s13
	v_lshl_add_u64 v[208:209], s[8:9], 0, v[184:185]
	s_add_i32 m0, s81, 0xc000
	ds_read_b128 v[146:149], v216
	ds_read_b128 v[150:153], v216 offset:1024
	ds_read_b128 v[188:191], v216 offset:2048
	ds_read_b128 v[192:195], v216 offset:3072
	ds_read_b128 v[196:199], v216 offset:4096
	ds_read_b128 v[200:203], v216 offset:5120
	ds_read_b128 v[204:207], v216 offset:6144
	ds_read_b128 v[218:221], v216 offset:7168
	global_load_lds_dwordx4 v[208:209], off
	s_add_i32 m0, s81, 0xe000
	v_lshl_add_u64 v[208:209], s[8:9], 0, v[186:187]
	global_load_lds_dwordx4 v[208:209], off
	s_waitcnt lgkmcnt(8)
	s_barrier
	s_waitcnt lgkmcnt(0)
	s_cmp_lg_u32 s101, 0
	s_cbranch_scc1 .Lip13_a_0
	v_mfma_f32_16x16x32_bf16 v[126:129], v[130:133], v[146:149], v[126:129]
	v_mfma_f32_16x16x32_bf16 v[122:125], v[138:141], v[146:149], v[122:125]
	v_mfma_f32_16x16x32_bf16 v[114:117], v[130:133], v[188:191], v[114:117]
	v_mfma_f32_16x16x32_bf16 v[106:109], v[138:141], v[188:191], v[106:109]
	v_mfma_f32_16x16x32_bf16 v[94:97], v[130:133], v[196:199], v[94:97]
	v_mfma_f32_16x16x32_bf16 v[90:93], v[138:141], v[196:199], v[90:93]
	v_mfma_f32_16x16x32_bf16 v[82:85], v[130:133], v[204:207], v[82:85]
	v_mfma_f32_16x16x32_bf16 v[74:77], v[138:141], v[204:207], v[74:77]
	v_mfma_f32_16x16x32_bf16 v[126:129], v[134:137], v[150:153], v[126:129]
	v_mfma_f32_16x16x32_bf16 v[122:125], v[142:145], v[150:153], v[122:125]
	v_mfma_f32_16x16x32_bf16 v[114:117], v[134:137], v[192:195], v[114:117]
	v_mfma_f32_16x16x32_bf16 v[106:109], v[142:145], v[192:195], v[106:109]
	v_mfma_f32_16x16x32_bf16 v[94:97], v[134:137], v[200:203], v[94:97]
	v_mfma_f32_16x16x32_bf16 v[90:93], v[142:145], v[200:203], v[90:93]
	v_mfma_f32_16x16x32_bf16 v[82:85], v[134:137], v[218:221], v[82:85]
	v_mfma_f32_16x16x32_bf16 v[74:77], v[142:145], v[218:221], v[74:77]
.Lip13_a_0:
	s_barrier
	s_add_i32 s19, 0, 0x14000
	s_add_i32 s26, s27, s80
	v_add_u32_e32 v8, s19, v214
	v_lshl_add_u64 v[208:209], s[46:47], 0, v[178:179]
	s_mov_b32 m0, s26
	ds_read_b128 v[222:225], v8
	ds_read_b128 v[226:229], v8 offset:1024
	ds_read_b128 v[230:233], v8 offset:2048
	ds_read_b128 v[234:237], v8 offset:3072
	global_load_lds_dwordx4 v[208:209], off
	s_add_i32 m0, s26, 0x2000
	v_lshl_add_u64 v[238:239], s[46:47], 0, v[182:183]
	global_load_lds_dwordx4 v[238:239], off
	s_barrier
	s_waitcnt lgkmcnt(0)
	s_cmp_lg_u32 s100, 0
	s_cbranch_scc1 .Lip13_a_1
	v_mfma_f32_16x16x32_bf16 v[118:121], v[222:225], v[146:149], v[118:121]
	v_mfma_f32_16x16x32_bf16 v[110:113], v[230:233], v[146:149], v[110:113]
	v_mfma_f32_16x16x32_bf16 v[102:105], v[222:225], v[188:191], v[102:105]
	v_mfma_f32_16x16x32_bf16 v[98:101], v[230:233], v[188:191], v[98:101]
	v_mfma_f32_16x16x32_bf16 v[86:89], v[222:225], v[196:199], v[86:89]
	v_mfma_f32_16x16x32_bf16 v[78:81], v[230:233], v[196:199], v[78:81]
	v_mfma_f32_16x16x32_bf16 v[62:65], v[222:225], v[204:207], v[62:65]
	v_mfma_f32_16x16x32_bf16 v[58:61], v[230:233], v[204:207], v[58:61]
	v_mfma_f32_16x16x32_bf16 v[118:121], v[226:229], v[150:153], v[118:121]
	v_mfma_f32_16x16x32_bf16 v[110:113], v[234:237], v[150:153], v[110:113]
	v_mfma_f32_16x16x32_bf16 v[102:105], v[226:229], v[192:195], v[102:105]
	v_mfma_f32_16x16x32_bf16 v[98:101], v[234:237], v[192:195], v[98:101]
	v_mfma_f32_16x16x32_bf16 v[86:89], v[226:229], v[200:203], v[86:89]
	v_mfma_f32_16x16x32_bf16 v[78:81], v[234:237], v[200:203], v[78:81]
	v_mfma_f32_16x16x32_bf16 v[62:65], v[226:229], v[218:221], v[62:65]
	v_mfma_f32_16x16x32_bf16 v[58:61], v[234:237], v[218:221], v[58:61]
.Lip13_a_1:
	s_mov_b32 m0, s81
	v_lshl_add_u64 v[240:241], s[68:69], 0, v[176:177]
	s_barrier
	ds_read_b128 v[146:149], v216 offset:16384
	ds_read_b128 v[150:153], v216 offset:17408
	ds_read_b128 v[188:191], v216 offset:18432
	ds_read_b128 v[192:195], v216 offset:19456
	ds_read_b128 v[196:199], v216 offset:20480
	ds_read_b128 v[200:203], v216 offset:21504
	ds_read_b128 v[204:207], v216 offset:22528
	ds_read_b128 v[218:221], v216 offset:23552
	global_load_lds_dwordx4 v[240:241], off
	s_mov_b32 m0, s82
	v_lshl_add_u64 v[242:243], s[68:69], 0, v[180:181]
	global_load_lds_dwordx4 v[242:243], off
	s_barrier
	s_waitcnt lgkmcnt(0)
	s_cmp_lg_u32 s101, 0
	s_cbranch_scc1 .Lip13_a_2
	v_mfma_f32_16x16x32_bf16 v[70:73], v[130:133], v[146:149], v[70:73]
	v_mfma_f32_16x16x32_bf16 v[66:69], v[138:141], v[146:149], v[66:69]
	v_mfma_f32_16x16x32_bf16 v[46:49], v[130:133], v[188:191], v[46:49]
	v_mfma_f32_16x16x32_bf16 v[42:45], v[138:141], v[188:191], v[42:45]
	v_mfma_f32_16x16x32_bf16 v[30:33], v[130:133], v[196:199], v[30:33]
	v_mfma_f32_16x16x32_bf16 v[26:29], v[138:141], v[196:199], v[26:29]
	v_mfma_f32_16x16x32_bf16 v[14:17], v[130:133], v[204:207], v[14:17]
	v_mfma_f32_16x16x32_bf16 v[10:13], v[138:141], v[204:207], v[10:13]
	v_mfma_f32_16x16x32_bf16 v[70:73], v[134:137], v[150:153], v[70:73]
	v_mfma_f32_16x16x32_bf16 v[66:69], v[142:145], v[150:153], v[66:69]
	v_mfma_f32_16x16x32_bf16 v[46:49], v[134:137], v[192:195], v[46:49]
	v_mfma_f32_16x16x32_bf16 v[42:45], v[142:145], v[192:195], v[42:45]
	v_mfma_f32_16x16x32_bf16 v[30:33], v[134:137], v[200:203], v[30:33]
	v_mfma_f32_16x16x32_bf16 v[26:29], v[142:145], v[200:203], v[26:29]
	v_mfma_f32_16x16x32_bf16 v[14:17], v[134:137], v[218:221], v[14:17]
	v_mfma_f32_16x16x32_bf16 v[10:13], v[142:145], v[218:221], v[10:13]

; DEVI size_t gemm_offB(const Gemm& g, const Unit& u) { return (g.split ? (size_t)(u.b >> 2) * g.sB + (size_t)(u.b & 3) * g.sB_lo : (size_t)u.b * g.sB) + (size_t)(u.pm >> g.pmsh) * g.sBpm; }
; #define PG8_STAGE(bufoff, gbase, voff) do { _Pragma("unroll") for (int _i = 0; _i < 2; ++_i) \
;         __builtin_amdgcn_global_load_lds((const unsigned*)((const char*)(gbase) + (voff)[_i]), (LAS unsigned*)(lds + (bufoff) + ldsw + _i * 8192), 16, 0, 0); } while (0)
; #define PG8_LDA(dst, b, h) do { _Pragma("unroll") for (int m = 0; m < 4; ++m) _Pragma("unroll") for (int k = 0; k < 2; ++k) dst[m][k] = *(const LAS bf16x8*)(lds + PG8_SA(b, h) + aoff + m * 2048 + k * 1024); } while (0)
; #define PG8_LDB(dst, b, h) do { _Pragma("unroll") for (int n = 0; n < 2; ++n) _Pragma("unroll") for (int k = 0; k < 2; ++k) dst[n][k] = *(const LAS bf16x8*)(lds + PG8_SB(b, h) + boff + n * 2048 + k * 1024); } while (0)
; #define PG8_WAIT_V(n) asm volatile("s_waitcnt vmcnt(" #n ")" ::: "memory")
; #define PG8_BAR __builtin_amdgcn_s_barrier()
; template <class Epi>
; DEVI void gemm_phase(LAS unsigned char* lds, const Gemm g, const Epi& E) {
;     ...
;         const bool has_next = unit_next(g, ui + 1, nxt);
;         const char* nA = has_next ? (const char*)g.A + gemm_offA(g, nxt) * 2 + (size_t)nxt.pm * tstepA : cA;
;         const char* nB = has_next ? (const char*)g.Bt + gemm_offB(g, nxt) * 2 + (size_t)nxt.pn * tstepB : cB;
;         for (int t = 0; t < nt; t += 2) {
;             const bool last = (t == nt - 2);
;             const char* a1 = cA + (size_t)(t + 1) * kstep;
;             const char* a2 = last ? nA : cA + (size_t)(t + 2) * kstep; const char* b2 = last ? nB : cB + (size_t)(t + 2) * kstep;
;             const char* a3 = a2 + kstep; const char* b3 = b2 + kstep;
;             PG8_LDB(B0, 0, 0); PG8_SCHED; PG8_LDA(At, 0, 0); PG8_STAGE(PG8_SA(1, 1), a1 + hstepA, voffA);
;             PG8_WAIT_L(8); PG8_BAR; PG8_WAIT_L(0); PG8_MMA(0, 0, At, B0); PG8_BAR; PG8_SCHED;
;             PG8_LDB(B1, 0, 1); PG8_STAGE(PG8_SB(0, 0), b2, voffB);
;             PG8_BAR; PG8_WAIT_L(0); PG8_MMA(0, 1, At, B1); PG8_BAR;
;             PG8_LDA(At, 0, 1); PG8_STAGE(PG8_SA(0, 0), a2, voffA);
;             PG8_BAR; PG8_WAIT_L(0); PG8_MMA(1, 0, At, B0); PG8_BAR; PG8_SCHED;
;             PG8_STAGE(PG8_SB(0, 1), b2 + hstepB, voffB);
;             PG8_WAIT_V(6); PG8_BAR; PG8_MMA(1, 1, At, B1); PG8_BAR;
.LBB0_355:
	s_and_b32 s101, s66, 0xc0
	s_cmp_eq_u32 s4, 12
	s_cselect_b32 s100, 1, 0
	s_cselect_b32 s101, s101, 0
	s_ashr_i32 s11, s10, 31
	v_mov_b64_e32 v[0:1], 0x680
	s_lshl_b64 s[0:1], s[10:11], 19
	v_cmp_lt_i64_e32 vcc, s[14:15], v[0:1]
	s_add_u32 s14, s24, s0
	s_addc_u32 s15, s25, s1
	s_and_b64 s[0:1], vcc, exec
	s_cselect_b32 s0, s15, s9
	s_cselect_b32 s1, s14, s8
	s_ashr_i32 s13, s12, 31
	s_lshl_b64 s[16:17], s[12:13], 19
	s_add_u32 s16, s82, s16
	s_addc_u32 s17, s83, s17
	s_and_b64 s[18:19], vcc, exec
	s_cselect_b32 s5, s17, s47
	s_cselect_b32 s7, s16, s46
	s_add_u32 s8, s8, 0x40080
	s_addc_u32 s9, s9, 0
	s_add_u32 s11, s46, 0x100
	s_addc_u32 s13, s47, 0
	s_mov_b32 s18, -2
	s_add_u32 s19, s8, 0xfffc0080
	s_addc_u32 s26, s9, -1
	s_add_i32 s27, 0, 0x10000
	v_add_u32_e32 v142, s27, v209
	ds_read_b128 v[130:133], v142
	ds_read_b128 v[134:137], v142 offset:1024
	ds_read_b128 v[138:141], v142 offset:2048
	ds_read_b128 v[142:145], v142 offset:3072
	s_cmp_eq_u32 s18, 12
	s_cselect_b32 s69, s0, s26
	s_cselect_b32 s68, s1, s19
	s_cselect_b32 s47, s5, s13
	s_cselect_b32 s46, s7, s11
	v_lshl_add_u64 v[206:207], s[8:9], 0, v[182:183]
	s_add_i32 m0, s85, 0xc000
	ds_read_b128 v[146:149], v214
	ds_read_b128 v[150:153], v214 offset:1024
	ds_read_b128 v[186:189], v214 offset:2048
	ds_read_b128 v[190:193], v214 offset:3072
	ds_read_b128 v[194:197], v214 offset:4096
	ds_read_b128 v[198:201], v214 offset:5120
	ds_read_b128 v[202:205], v214 offset:6144
	ds_read_b128 v[216:219], v214 offset:7168
	global_load_lds_dwordx4 v[206:207], off
	s_add_i32 m0, s85, 0xe000
	v_lshl_add_u64 v[206:207], s[8:9], 0, v[184:185]
	global_load_lds_dwordx4 v[206:207], off
	s_waitcnt lgkmcnt(8)
	s_barrier
	s_waitcnt lgkmcnt(0)
	s_cmp_lg_u32 s101, 0
	s_cbranch_scc1 .Lip13_b_0_p
	v_mfma_f32_16x16x32_bf16 v[126:129], v[130:133], v[146:149], 0
	v_mfma_f32_16x16x32_bf16 v[122:125], v[138:141], v[146:149], 0
	v_mfma_f32_16x16x32_bf16 v[114:117], v[130:133], v[186:189], 0
	v_mfma_f32_16x16x32_bf16 v[106:109], v[138:141], v[186:189], 0
	v_mfma_f32_16x16x32_bf16 v[94:97], v[130:133], v[194:197], 0
	v_mfma_f32_16x16x32_bf16 v[90:93], v[138:141], v[194:197], 0
	v_mfma_f32_16x16x32_bf16 v[82:85], v[130:133], v[202:205], 0
	v_mfma_f32_16x16x32_bf16 v[74:77], v[138:141], v[202:205], 0
	v_mfma_f32_16x16x32_bf16 v[126:129], v[134:137], v[150:153], v[126:129]
	v_mfma_f32_16x16x32_bf16 v[122:125], v[142:145], v[150:153], v[122:125]
	v_mfma_f32_16x16x32_bf16 v[114:117], v[134:137], v[190:193], v[114:117]
	v_mfma_f32_16x16x32_bf16 v[106:109], v[142:145], v[190:193], v[106:109]
	v_mfma_f32_16x16x32_bf16 v[94:97], v[134:137], v[198:201], v[94:97]
	v_mfma_f32_16x16x32_bf16 v[90:93], v[142:145], v[198:201], v[90:93]
	v_mfma_f32_16x16x32_bf16 v[82:85], v[134:137], v[216:219], v[82:85]
	v_mfma_f32_16x16x32_bf16 v[74:77], v[142:145], v[216:219], v[74:77]
.Lip13_b_0_p:
	s_barrier
	s_add_i32 s19, 0, 0x14000
	s_add_i32 s26, s27, s84
	v_add_u32_e32 v162, s19, v209
	v_lshl_add_u64 v[206:207], s[46:47], 0, v[8:9]
	s_mov_b32 m0, s26
	ds_read_b128 v[220:223], v162
	ds_read_b128 v[224:227], v162 offset:1024
	ds_read_b128 v[228:231], v162 offset:2048
	ds_read_b128 v[232:235], v162 offset:3072
	global_load_lds_dwordx4 v[206:207], off
	s_add_i32 m0, s26, 0x2000
	v_lshl_add_u64 v[236:237], s[46:47], 0, v[180:181]
	global_load_lds_dwordx4 v[236:237], off
	s_barrier
	s_waitcnt lgkmcnt(0)
	s_cmp_lg_u32 s100, 0
	s_cbranch_scc1 .Lip13_b_1_p
	v_mfma_f32_16x16x32_bf16 v[118:121], v[220:223], v[146:149], 0
	v_mfma_f32_16x16x32_bf16 v[110:113], v[228:231], v[146:149], 0
	v_mfma_f32_16x16x32_bf16 v[102:105], v[220:223], v[186:189], 0
	v_mfma_f32_16x16x32_bf16 v[98:101], v[228:231], v[186:189], 0
	v_mfma_f32_16x16x32_bf16 v[86:89], v[220:223], v[194:197], 0
	v_mfma_f32_16x16x32_bf16 v[78:81], v[228:231], v[194:197], 0
	v_mfma_f32_16x16x32_bf16 v[62:65], v[220:223], v[202:205], 0
	v_mfma_f32_16x16x32_bf16 v[58:61], v[228:231], v[202:205], 0
	v_mfma_f32_16x16x32_bf16 v[118:121], v[224:227], v[150:153], v[118:121]
	v_mfma_f32_16x16x32_bf16 v[110:113], v[232:235], v[150:153], v[110:113]
	v_mfma_f32_16x16x32_bf16 v[102:105], v[224:227], v[190:193], v[102:105]
	v_mfma_f32_16x16x32_bf16 v[98:101], v[232:235], v[190:193], v[98:101]
	v_mfma_f32_16x16x32_bf16 v[86:89], v[224:227], v[198:201], v[86:89]
	v_mfma_f32_16x16x32_bf16 v[78:81], v[232:235], v[198:201], v[78:81]
	v_mfma_f32_16x16x32_bf16 v[62:65], v[224:227], v[216:219], v[62:65]
	v_mfma_f32_16x16x32_bf16 v[58:61], v[232:235], v[216:219], v[58:61]
.Lip13_b_1_p:
	s_mov_b32 m0, s85
	v_lshl_add_u64 v[238:239], s[68:69], 0, v[176:177]
	s_barrier
	ds_read_b128 v[146:149], v214 offset:16384
	ds_read_b128 v[150:153], v214 offset:17408
	ds_read_b128 v[186:189], v214 offset:18432
	ds_read_b128 v[190:193], v214 offset:19456
	ds_read_b128 v[194:197], v214 offset:20480
	ds_read_b128 v[198:201], v214 offset:21504
	ds_read_b128 v[202:205], v214 offset:22528
	ds_read_b128 v[216:219], v214 offset:23552
	global_load_lds_dwordx4 v[238:239], off
	s_mov_b32 m0, s86
	v_lshl_add_u64 v[240:241], s[68:69], 0, v[178:179]
	global_load_lds_dwordx4 v[240:241], off
	s_barrier
	s_waitcnt lgkmcnt(0)
	s_cmp_lg_u32 s101, 0
	s_cbranch_scc1 .Lip13_b_2_p
	v_mfma_f32_16x16x32_bf16 v[70:73], v[130:133], v[146:149], 0
	v_mfma_f32_16x16x32_bf16 v[66:69], v[138:141], v[146:149], 0
	v_mfma_f32_16x16x32_bf16 v[46:49], v[130:133], v[186:189], 0
	v_mfma_f32_16x16x32_bf16 v[42:45], v[138:141], v[186:189], 0
	v_mfma_f32_16x16x32_bf16 v[30:33], v[130:133], v[194:197], 0
	v_mfma_f32_16x16x32_bf16 v[26:29], v[138:141], v[194:197], 0
	v_mfma_f32_16x16x32_bf16 v[14:17], v[130:133], v[202:205], 0
	v_mfma_f32_16x16x32_bf16 v[10:13], v[138:141], v[202:205], 0
	v_mfma_f32_16x16x32_bf16 v[70:73], v[134:137], v[150:153], v[70:73]
	v_mfma_f32_16x16x32_bf16 v[66:69], v[142:145], v[150:153], v[66:69]
	v_mfma_f32_16x16x32_bf16 v[46:49], v[134:137], v[190:193], v[46:49]
	v_mfma_f32_16x16x32_bf16 v[42:45], v[142:145], v[190:193], v[42:45]
	v_mfma_f32_16x16x32_bf16 v[30:33], v[134:137], v[198:201], v[30:33]
	v_mfma_f32_16x16x32_bf16 v[26:29], v[142:145], v[198:201], v[26:29]
	v_mfma_f32_16x16x32_bf16 v[14:17], v[134:137], v[216:219], v[14:17]
	v_mfma_f32_16x16x32_bf16 v[10:13], v[142:145], v[216:219], v[10:13]
; #define PG8_STAGE(bufoff, gbase, voff) do { _Pragma("unroll") for (int _i = 0; _i < 2; ++_i) \
;         __builtin_amdgcn_global_load_lds((const unsigned*)((const char*)(gbase) + (voff)[_i]), (LAS unsigned*)(lds + (bufoff) + ldsw + _i * 8192), 16, 0, 0); } while (0)
; #define PG8_LDA(dst, b, h) do { _Pragma("unroll") for (int m = 0; m < 4; ++m) _Pragma("unroll") for (int k = 0; k < 2; ++k) dst[m][k] = *(const LAS bf16x8*)(lds + PG8_SA(b, h) + aoff + m * 2048 + k * 1024); } while (0)
; #define PG8_LDB(dst, b, h) do { _Pragma("unroll") for (int n = 0; n < 2; ++n) _Pragma("unroll") for (int k = 0; k < 2; ++k) dst[n][k] = *(const LAS bf16x8*)(lds + PG8_SB(b, h) + boff + n * 2048 + k * 1024); } while (0)
; #define PG8_MMA(ai, bj, At, Bt) do { __builtin_amdgcn_s_setprio(1); _Pragma("unroll") for (int m = 0; m < 4; ++m) _Pragma("unroll") for (int n = 0; n < 2; ++n) _Pragma("unroll") for (int k = 0; k < 2; ++k) \
;         acc[ai][bj][m][n] = __builtin_amdgcn_mfma_f32_16x16x32_bf16(Bt[n][k], At[m][k], acc[ai][bj][m][n], 0, 0, 0); __builtin_amdgcn_s_setprio(0); } while (0)
; #define PG8_WAIT_V(n) asm volatile("s_waitcnt vmcnt(" #n ")" ::: "memory")
; #define PG8_WAIT_L(n) asm volatile("s_waitcnt lgkmcnt(" #n ")" ::: "memory")
; #define PG8_BAR __builtin_amdgcn_s_barrier()
; #define PG8_SCHED __builtin_amdgcn_sched_barrier(0)
; template <class Epi>
; DEVI void gemm_phase(LAS unsigned char* lds, const Gemm g, const Epi& E) {
;     ...
;             PG8_STAGE(PG8_SB(0, 1), b2 + hstepB, voffB);
;             PG8_WAIT_V(6); PG8_BAR; PG8_MMA(1, 1, At, B1); PG8_BAR;
;             PG8_LDB(B0, 1, 0); PG8_SCHED; PG8_LDA(At, 1, 0); PG8_STAGE(PG8_SA(0, 1), a2 + hstepA, voffA);
;             PG8_WAIT_L(8); PG8_BAR; PG8_WAIT_L(0); PG8_MMA(0, 0, At, B0); PG8_BAR; PG8_SCHED;
;             PG8_LDB(B1, 1, 1); PG8_STAGE(PG8_SB(1, 0), b3, voffB);
;             PG8_BAR; PG8_WAIT_L(0); PG8_MMA(0, 1, At, B1); PG8_BAR;
;             PG8_LDA(At, 1, 1); PG8_STAGE(PG8_SA(1, 0), a3, voffA);
.Lip13_b_2_p:
	s_barrier
	s_add_u32 s26, s46, 0x40000
	s_addc_u32 s27, s47, 0
	s_add_i32 s19, s19, s84
	s_mov_b32 m0, s19
	v_lshl_add_u64 v[130:131], s[26:27], 0, v[8:9]
	global_load_lds_dwordx4 v[130:131], off
	s_add_i32 m0, s19, 0x2000
	v_lshl_add_u64 v[130:131], s[26:27], 0, v[180:181]
	global_load_lds_dwordx4 v[130:131], off
	s_waitcnt vmcnt(6)
	s_barrier
	s_cmp_lg_u32 s100, 0
	s_cbranch_scc1 .Lip13_b_3_p
	v_mfma_f32_16x16x32_bf16 v[50:53], v[220:223], v[146:149], 0
	v_mfma_f32_16x16x32_bf16 v[54:57], v[228:231], v[146:149], 0
	v_mfma_f32_16x16x32_bf16 v[34:37], v[220:223], v[186:189], 0
	v_mfma_f32_16x16x32_bf16 v[38:41], v[228:231], v[186:189], 0
	v_mfma_f32_16x16x32_bf16 v[18:21], v[220:223], v[194:197], 0
	v_mfma_f32_16x16x32_bf16 v[22:25], v[228:231], v[194:197], 0
	v_mfma_f32_16x16x32_bf16 v[0:3], v[220:223], v[202:205], 0
	v_mfma_f32_16x16x32_bf16 v[4:7], v[228:231], v[202:205], 0
	v_mfma_f32_16x16x32_bf16 v[50:53], v[224:227], v[150:153], v[50:53]
	v_mfma_f32_16x16x32_bf16 v[54:57], v[232:235], v[150:153], v[54:57]
	v_mfma_f32_16x16x32_bf16 v[34:37], v[224:227], v[190:193], v[34:37]
	v_mfma_f32_16x16x32_bf16 v[38:41], v[232:235], v[190:193], v[38:41]
	v_mfma_f32_16x16x32_bf16 v[18:21], v[224:227], v[198:201], v[18:21]
	v_mfma_f32_16x16x32_bf16 v[22:25], v[232:235], v[198:201], v[22:25]
	v_mfma_f32_16x16x32_bf16 v[0:3], v[224:227], v[216:219], v[0:3]
	v_mfma_f32_16x16x32_bf16 v[4:7], v[232:235], v[216:219], v[4:7]
.Lip13_b_3_p:
	s_add_i32 s19, 0, 0x18000
	v_add_u32_e32 v142, s19, v209
	s_barrier
	ds_read_b128 v[130:133], v142
	ds_read_b128 v[134:137], v142 offset:1024
	ds_read_b128 v[138:141], v142 offset:2048
	ds_read_b128 v[142:145], v142 offset:3072
	s_add_u32 s26, s68, 0x40000
	s_addc_u32 s27, s69, 0
	s_mov_b32 m0, s87
	v_lshl_add_u64 v[220:221], s[26:27], 0, v[176:177]
	ds_read_b128 v[146:149], v214 offset:32768
	ds_read_b128 v[150:153], v214 offset:33792
	ds_read_b128 v[186:189], v214 offset:34816
	ds_read_b128 v[190:193], v214 offset:35840
	ds_read_b128 v[194:197], v214 offset:36864
	ds_read_b128 v[198:201], v214 offset:37888
	ds_read_b128 v[202:205], v214 offset:38912
	ds_read_b128 v[216:219], v214 offset:39936
	global_load_lds_dwordx4 v[220:221], off
	s_mov_b32 m0, s88
	v_lshl_add_u64 v[220:221], s[26:27], 0, v[178:179]
	global_load_lds_dwordx4 v[220:221], off
	s_waitcnt lgkmcnt(8)
	s_barrier
	s_waitcnt lgkmcnt(0)
	s_cmp_lg_u32 s101, 0
	s_cbranch_scc1 .Lip13_b_4_p
	v_mfma_f32_16x16x32_bf16 v[126:129], v[130:133], v[146:149], v[126:129]
	v_mfma_f32_16x16x32_bf16 v[122:125], v[138:141], v[146:149], v[122:125]
	v_mfma_f32_16x16x32_bf16 v[114:117], v[130:133], v[186:189], v[114:117]
	v_mfma_f32_16x16x32_bf16 v[106:109], v[138:141], v[186:189], v[106:109]
	v_mfma_f32_16x16x32_bf16 v[94:97], v[130:133], v[194:197], v[94:97]
	v_mfma_f32_16x16x32_bf16 v[90:93], v[138:141], v[194:197], v[90:93]
	v_mfma_f32_16x16x32_bf16 v[82:85], v[130:133], v[202:205], v[82:85]
	v_mfma_f32_16x16x32_bf16 v[74:77], v[138:141], v[202:205], v[74:77]
	v_mfma_f32_16x16x32_bf16 v[126:129], v[134:137], v[150:153], v[126:129]
	v_mfma_f32_16x16x32_bf16 v[122:125], v[142:145], v[150:153], v[122:125]
	v_mfma_f32_16x16x32_bf16 v[114:117], v[134:137], v[190:193], v[114:117]
	v_mfma_f32_16x16x32_bf16 v[106:109], v[142:145], v[190:193], v[106:109]
	v_mfma_f32_16x16x32_bf16 v[94:97], v[134:137], v[198:201], v[94:97]
	v_mfma_f32_16x16x32_bf16 v[90:93], v[142:145], v[198:201], v[90:93]
	v_mfma_f32_16x16x32_bf16 v[82:85], v[134:137], v[216:219], v[82:85]
	v_mfma_f32_16x16x32_bf16 v[74:77], v[142:145], v[216:219], v[74:77]
; #define PG8_STAGE(bufoff, gbase, voff) do { _Pragma("unroll") for (int _i = 0; _i < 2; ++_i) \
;         __builtin_amdgcn_global_load_lds((const unsigned*)((const char*)(gbase) + (voff)[_i]), (LAS unsigned*)(lds + (bufoff) + ldsw + _i * 8192), 16, 0, 0); } while (0)
; #define PG8_LDA(dst, b, h) do { _Pragma("unroll") for (int m = 0; m < 4; ++m) _Pragma("unroll") for (int k = 0; k < 2; ++k) dst[m][k] = *(const LAS bf16x8*)(lds + PG8_SA(b, h) + aoff + m * 2048 + k * 1024); } while (0)
; #define PG8_MMA(ai, bj, At, Bt) do { __builtin_amdgcn_s_setprio(1); _Pragma("unroll") for (int m = 0; m < 4; ++m) _Pragma("unroll") for (int n = 0; n < 2; ++n) _Pragma("unroll") for (int k = 0; k < 2; ++k) \
;         acc[ai][bj][m][n] = __builtin_amdgcn_mfma_f32_16x16x32_bf16(Bt[n][k], At[m][k], acc[ai][bj][m][n], 0, 0, 0); __builtin_amdgcn_s_setprio(0); } while (0)
; #define PG8_WAIT_V(n) asm volatile("s_waitcnt vmcnt(" #n ")" ::: "memory")
; #define PG8_WAIT_L(n) asm volatile("s_waitcnt lgkmcnt(" #n ")" ::: "memory")
; #define PG8_BAR __builtin_amdgcn_s_barrier()
; #define PG8_SCHED __builtin_amdgcn_sched_barrier(0)
; template <class Epi>
; DEVI void gemm_phase(LAS unsigned char* lds, const Gemm g, const Epi& E) {
;     ...
;             PG8_LDA(At, 1, 1); PG8_STAGE(PG8_SA(1, 0), a3, voffA);
;             PG8_BAR; PG8_WAIT_L(0); PG8_MMA(1, 0, At, B0); PG8_BAR; PG8_SCHED;
;             PG8_STAGE(PG8_SB(1, 1), b3 + hstepB, voffB);
;             PG8_WAIT_V(6); PG8_BAR; PG8_MMA(1, 1, At, B1); PG8_BAR;
.Lip13_b_4_p:
	s_barrier
	s_add_i32 s38, 0, 0x1c000
	s_add_i32 s19, s19, s84
	v_add_u32_e32 v162, s38, v209
	v_lshl_add_u64 v[206:207], v[206:207], 0, s[70:71]
	s_mov_b32 m0, s19
	ds_read_b128 v[220:223], v162
	ds_read_b128 v[224:227], v162 offset:1024
	ds_read_b128 v[228:231], v162 offset:2048
	ds_read_b128 v[232:235], v162 offset:3072
	global_load_lds_dwordx4 v[206:207], off
	s_add_i32 m0, s19, 0x2000
	v_lshl_add_u64 v[206:207], v[236:237], 0, s[70:71]
	global_load_lds_dwordx4 v[206:207], off
	s_barrier
	s_waitcnt lgkmcnt(0)
	s_cmp_lg_u32 s100, 0
	s_cbranch_scc1 .Lip13_b_5_p
	v_mfma_f32_16x16x32_bf16 v[118:121], v[220:223], v[146:149], v[118:121]
	v_mfma_f32_16x16x32_bf16 v[110:113], v[228:231], v[146:149], v[110:113]
	v_mfma_f32_16x16x32_bf16 v[102:105], v[220:223], v[186:189], v[102:105]
	v_mfma_f32_16x16x32_bf16 v[98:101], v[228:231], v[186:189], v[98:101]
	v_mfma_f32_16x16x32_bf16 v[86:89], v[220:223], v[194:197], v[86:89]
	v_mfma_f32_16x16x32_bf16 v[78:81], v[228:231], v[194:197], v[78:81]
	v_mfma_f32_16x16x32_bf16 v[62:65], v[220:223], v[202:205], v[62:65]
	v_mfma_f32_16x16x32_bf16 v[58:61], v[228:231], v[202:205], v[58:61]
	v_mfma_f32_16x16x32_bf16 v[118:121], v[224:227], v[150:153], v[118:121]
	v_mfma_f32_16x16x32_bf16 v[110:113], v[232:235], v[150:153], v[110:113]
	v_mfma_f32_16x16x32_bf16 v[102:105], v[224:227], v[190:193], v[102:105]
	v_mfma_f32_16x16x32_bf16 v[98:101], v[232:235], v[190:193], v[98:101]
	v_mfma_f32_16x16x32_bf16 v[86:89], v[224:227], v[198:201], v[86:89]
	v_mfma_f32_16x16x32_bf16 v[78:81], v[232:235], v[198:201], v[78:81]
	v_mfma_f32_16x16x32_bf16 v[62:65], v[224:227], v[216:219], v[62:65]
	v_mfma_f32_16x16x32_bf16 v[58:61], v[232:235], v[216:219], v[58:61]
.Lip13_b_5_p:
	s_mov_b32 m0, s89
	v_lshl_add_u64 v[206:207], v[238:239], 0, s[70:71]
	s_barrier
	ds_read_b128 v[146:149], v214 offset:49152
	ds_read_b128 v[150:153], v214 offset:50176
	ds_read_b128 v[186:189], v214 offset:51200
	ds_read_b128 v[190:193], v214 offset:52224
	ds_read_b128 v[194:197], v214 offset:53248
	ds_read_b128 v[198:201], v214 offset:54272
	ds_read_b128 v[202:205], v214 offset:55296
	ds_read_b128 v[216:219], v214 offset:56320
	global_load_lds_dwordx4 v[206:207], off
	s_mov_b32 m0, s90
	v_lshl_add_u64 v[206:207], v[240:241], 0, s[70:71]
	global_load_lds_dwordx4 v[206:207], off
	s_barrier
	s_waitcnt lgkmcnt(0)
	s_cmp_lg_u32 s101, 0
	s_cbranch_scc1 .Lip13_b_6_p
	v_mfma_f32_16x16x32_bf16 v[70:73], v[130:133], v[146:149], v[70:73]
	v_mfma_f32_16x16x32_bf16 v[66:69], v[138:141], v[146:149], v[66:69]
	v_mfma_f32_16x16x32_bf16 v[46:49], v[130:133], v[186:189], v[46:49]
	v_mfma_f32_16x16x32_bf16 v[42:45], v[138:141], v[186:189], v[42:45]
	v_mfma_f32_16x16x32_bf16 v[30:33], v[130:133], v[194:197], v[30:33]
	v_mfma_f32_16x16x32_bf16 v[26:29], v[138:141], v[194:197], v[26:29]
	v_mfma_f32_16x16x32_bf16 v[14:17], v[130:133], v[202:205], v[14:17]
	v_mfma_f32_16x16x32_bf16 v[10:13], v[138:141], v[202:205], v[10:13]
	v_mfma_f32_16x16x32_bf16 v[70:73], v[134:137], v[150:153], v[70:73]
	v_mfma_f32_16x16x32_bf16 v[66:69], v[142:145], v[150:153], v[66:69]
	v_mfma_f32_16x16x32_bf16 v[46:49], v[134:137], v[190:193], v[46:49]
	v_mfma_f32_16x16x32_bf16 v[42:45], v[142:145], v[190:193], v[42:45]
	v_mfma_f32_16x16x32_bf16 v[30:33], v[134:137], v[198:201], v[30:33]
	v_mfma_f32_16x16x32_bf16 v[26:29], v[142:145], v[198:201], v[26:29]
	v_mfma_f32_16x16x32_bf16 v[14:17], v[134:137], v[216:219], v[14:17]
	v_mfma_f32_16x16x32_bf16 v[10:13], v[142:145], v[216:219], v[10:13]

; #define PG8_STAGE(bufoff, gbase, voff) do { _Pragma("unroll") for (int _i = 0; _i < 2; ++_i) \
;         __builtin_amdgcn_global_load_lds((const unsigned*)((const char*)(gbase) + (voff)[_i]), (LAS unsigned*)(lds + (bufoff) + ldsw + _i * 8192), 16, 0, 0); } while (0)
; #define PG8_LDA(dst, b, h) do { _Pragma("unroll") for (int m = 0; m < 4; ++m) _Pragma("unroll") for (int k = 0; k < 2; ++k) dst[m][k] = *(const LAS bf16x8*)(lds + PG8_SA(b, h) + aoff + m * 2048 + k * 1024); } while (0)
; #define PG8_LDB(dst, b, h) do { _Pragma("unroll") for (int n = 0; n < 2; ++n) _Pragma("unroll") for (int k = 0; k < 2; ++k) dst[n][k] = *(const LAS bf16x8*)(lds + PG8_SB(b, h) + boff + n * 2048 + k * 1024); } while (0)
; #define PG8_MMA(ai, bj, At, Bt) do { __builtin_amdgcn_s_setprio(1); _Pragma("unroll") for (int m = 0; m < 4; ++m) _Pragma("unroll") for (int n = 0; n < 2; ++n) _Pragma("unroll") for (int k = 0; k < 2; ++k) \
;         acc[ai][bj][m][n] = __builtin_amdgcn_mfma_f32_16x16x32_bf16(Bt[n][k], At[m][k], acc[ai][bj][m][n], 0, 0, 0); __builtin_amdgcn_s_setprio(0); } while (0)
; template <class Epi>
; DEVI void gemm_phase(LAS unsigned char* lds, const Gemm g, const Epi& E) {
;     ...
;         for (int t = 0; t < nt; t += 2) {
;             const bool last = (t == nt - 2);
;             const char* a1 = cA + (size_t)(t + 1) * kstep;
;             const char* a2 = last ? nA : cA + (size_t)(t + 2) * kstep; const char* b2 = last ? nB : cB + (size_t)(t + 2) * kstep;
;             const char* a3 = a2 + kstep; const char* b3 = b2 + kstep;
;             PG8_LDB(B0, 0, 0); PG8_SCHED; PG8_LDA(At, 0, 0); PG8_STAGE(PG8_SA(1, 1), a1 + hstepA, voffA);
;             PG8_WAIT_L(8); PG8_BAR; PG8_WAIT_L(0); PG8_MMA(0, 0, At, B0); PG8_BAR; PG8_SCHED;
;             PG8_LDB(B1, 0, 1); PG8_STAGE(PG8_SB(0, 0), b2, voffB);
;             PG8_BAR; PG8_WAIT_L(0); PG8_MMA(0, 1, At, B1); PG8_BAR;
;             PG8_LDA(At, 0, 1); PG8_STAGE(PG8_SA(0, 0), a2, voffA);
;             PG8_BAR; PG8_WAIT_L(0); PG8_MMA(1, 0, At, B0); PG8_BAR; PG8_SCHED;
;             PG8_STAGE(PG8_SB(0, 1), b2 + hstepB, voffB);
;             PG8_WAIT_V(6); PG8_BAR; PG8_MMA(1, 1, At, B1); PG8_BAR;
;             PG8_LDB(B0, 1, 0); PG8_SCHED; PG8_LDA(At, 1, 0); PG8_STAGE(PG8_SA(0, 1), a2 + hstepA, voffA);
;             PG8_WAIT_L(8); PG8_BAR; PG8_WAIT_L(0); PG8_MMA(0, 0, At, B0); PG8_BAR; PG8_SCHED;
.Lip13_b_7_p:
	s_add_i32 s18, s18, 2
	s_add_u32 s8, s8, 0x100
	s_addc_u32 s9, s9, 0
	s_add_u32 s11, s11, 0x100
	s_addc_u32 s13, s13, 0
	s_cmp_gt_u32 s18, 13
	s_barrier
.LBB0_356:
	s_add_u32 s19, s8, 0xfffc0080
	s_addc_u32 s26, s9, -1
	s_add_i32 s27, 0, 0x10000
	v_add_u32_e32 v142, s27, v209
	ds_read_b128 v[130:133], v142
	ds_read_b128 v[134:137], v142 offset:1024
	ds_read_b128 v[138:141], v142 offset:2048
	ds_read_b128 v[142:145], v142 offset:3072
	s_cmp_eq_u32 s18, 12
	s_cselect_b32 s69, s0, s26
	s_cselect_b32 s68, s1, s19
	s_cselect_b32 s47, s5, s13
	s_cselect_b32 s46, s7, s11
	v_lshl_add_u64 v[206:207], s[8:9], 0, v[182:183]
	s_add_i32 m0, s85, 0xc000
	ds_read_b128 v[146:149], v214
	ds_read_b128 v[150:153], v214 offset:1024
	ds_read_b128 v[186:189], v214 offset:2048
	ds_read_b128 v[190:193], v214 offset:3072
	ds_read_b128 v[194:197], v214 offset:4096
	ds_read_b128 v[198:201], v214 offset:5120
	ds_read_b128 v[202:205], v214 offset:6144
	ds_read_b128 v[216:219], v214 offset:7168
	global_load_lds_dwordx4 v[206:207], off
	s_add_i32 m0, s85, 0xe000
	v_lshl_add_u64 v[206:207], s[8:9], 0, v[184:185]
	global_load_lds_dwordx4 v[206:207], off
	s_waitcnt lgkmcnt(8)
	s_barrier
	s_waitcnt lgkmcnt(0)
	s_cmp_lg_u32 s101, 0
	s_cbranch_scc1 .Lip13_b_0
	v_mfma_f32_16x16x32_bf16 v[126:129], v[130:133], v[146:149], v[126:129]
	v_mfma_f32_16x16x32_bf16 v[122:125], v[138:141], v[146:149], v[122:125]
	v_mfma_f32_16x16x32_bf16 v[114:117], v[130:133], v[186:189], v[114:117]
	v_mfma_f32_16x16x32_bf16 v[106:109], v[138:141], v[186:189], v[106:109]
	v_mfma_f32_16x16x32_bf16 v[94:97], v[130:133], v[194:197], v[94:97]
	v_mfma_f32_16x16x32_bf16 v[90:93], v[138:141], v[194:197], v[90:93]
	v_mfma_f32_16x16x32_bf16 v[82:85], v[130:133], v[202:205], v[82:85]
	v_mfma_f32_16x16x32_bf16 v[74:77], v[138:141], v[202:205], v[74:77]
	v_mfma_f32_16x16x32_bf16 v[126:129], v[134:137], v[150:153], v[126:129]
	v_mfma_f32_16x16x32_bf16 v[122:125], v[142:145], v[150:153], v[122:125]
	v_mfma_f32_16x16x32_bf16 v[114:117], v[134:137], v[190:193], v[114:117]
	v_mfma_f32_16x16x32_bf16 v[106:109], v[142:145], v[190:193], v[106:109]
	v_mfma_f32_16x16x32_bf16 v[94:97], v[134:137], v[198:201], v[94:97]
	v_mfma_f32_16x16x32_bf16 v[90:93], v[142:145], v[198:201], v[90:93]
	v_mfma_f32_16x16x32_bf16 v[82:85], v[134:137], v[216:219], v[82:85]
	v_mfma_f32_16x16x32_bf16 v[74:77], v[142:145], v[216:219], v[74:77]
.Lip13_b_0:
	s_barrier
	s_add_i32 s19, 0, 0x14000
	s_add_i32 s26, s27, s84
	v_add_u32_e32 v162, s19, v209
	v_lshl_add_u64 v[206:207], s[46:47], 0, v[8:9]
	s_mov_b32 m0, s26
	ds_read_b128 v[220:223], v162
	ds_read_b128 v[224:227], v162 offset:1024
	ds_read_b128 v[228:231], v162 offset:2048
	ds_read_b128 v[232:235], v162 offset:3072
	global_load_lds_dwordx4 v[206:207], off
	s_add_i32 m0, s26, 0x2000
	v_lshl_add_u64 v[236:237], s[46:47], 0, v[180:181]
	global_load_lds_dwordx4 v[236:237], off
	s_barrier
	s_waitcnt lgkmcnt(0)
	s_cmp_lg_u32 s100, 0
	s_cbranch_scc1 .Lip13_b_1
	v_mfma_f32_16x16x32_bf16 v[118:121], v[220:223], v[146:149], v[118:121]
	v_mfma_f32_16x16x32_bf16 v[110:113], v[228:231], v[146:149], v[110:113]
	v_mfma_f32_16x16x32_bf16 v[102:105], v[220:223], v[186:189], v[102:105]
	v_mfma_f32_16x16x32_bf16 v[98:101], v[228:231], v[186:189], v[98:101]
	v_mfma_f32_16x16x32_bf16 v[86:89], v[220:223], v[194:197], v[86:89]
	v_mfma_f32_16x16x32_bf16 v[78:81], v[228:231], v[194:197], v[78:81]
	v_mfma_f32_16x16x32_bf16 v[62:65], v[220:223], v[202:205], v[62:65]
	v_mfma_f32_16x16x32_bf16 v[58:61], v[228:231], v[202:205], v[58:61]
	v_mfma_f32_16x16x32_bf16 v[118:121], v[224:227], v[150:153], v[118:121]
	v_mfma_f32_16x16x32_bf16 v[110:113], v[232:235], v[150:153], v[110:113]
	v_mfma_f32_16x16x32_bf16 v[102:105], v[224:227], v[190:193], v[102:105]
	v_mfma_f32_16x16x32_bf16 v[98:101], v[232:235], v[190:193], v[98:101]
	v_mfma_f32_16x16x32_bf16 v[86:89], v[224:227], v[198:201], v[86:89]
	v_mfma_f32_16x16x32_bf16 v[78:81], v[232:235], v[198:201], v[78:81]
	v_mfma_f32_16x16x32_bf16 v[62:65], v[224:227], v[216:219], v[62:65]
	v_mfma_f32_16x16x32_bf16 v[58:61], v[232:235], v[216:219], v[58:61]
.Lip13_b_1:
	s_mov_b32 m0, s85
	v_lshl_add_u64 v[238:239], s[68:69], 0, v[176:177]
	s_barrier
	ds_read_b128 v[146:149], v214 offset:16384
	ds_read_b128 v[150:153], v214 offset:17408
	ds_read_b128 v[186:189], v214 offset:18432
	ds_read_b128 v[190:193], v214 offset:19456
	ds_read_b128 v[194:197], v214 offset:20480
	ds_read_b128 v[198:201], v214 offset:21504
	ds_read_b128 v[202:205], v214 offset:22528
	ds_read_b128 v[216:219], v214 offset:23552
	global_load_lds_dwordx4 v[238:239], off
	s_mov_b32 m0, s86
	v_lshl_add_u64 v[240:241], s[68:69], 0, v[178:179]
	global_load_lds_dwordx4 v[240:241], off
	s_barrier
	s_waitcnt lgkmcnt(0)
	s_cmp_lg_u32 s101, 0
	s_cbranch_scc1 .Lip13_b_2
	v_mfma_f32_16x16x32_bf16 v[70:73], v[130:133], v[146:149], v[70:73]
	v_mfma_f32_16x16x32_bf16 v[66:69], v[138:141], v[146:149], v[66:69]
	v_mfma_f32_16x16x32_bf16 v[46:49], v[130:133], v[186:189], v[46:49]
	v_mfma_f32_16x16x32_bf16 v[42:45], v[138:141], v[186:189], v[42:45]
	v_mfma_f32_16x16x32_bf16 v[30:33], v[130:133], v[194:197], v[30:33]
	v_mfma_f32_16x16x32_bf16 v[26:29], v[138:141], v[194:197], v[26:29]
	v_mfma_f32_16x16x32_bf16 v[14:17], v[130:133], v[202:205], v[14:17]
	v_mfma_f32_16x16x32_bf16 v[10:13], v[138:141], v[202:205], v[10:13]
	v_mfma_f32_16x16x32_bf16 v[70:73], v[134:137], v[150:153], v[70:73]
	v_mfma_f32_16x16x32_bf16 v[66:69], v[142:145], v[150:153], v[66:69]
	v_mfma_f32_16x16x32_bf16 v[46:49], v[134:137], v[190:193], v[46:49]
	v_mfma_f32_16x16x32_bf16 v[42:45], v[142:145], v[190:193], v[42:45]
	v_mfma_f32_16x16x32_bf16 v[30:33], v[134:137], v[198:201], v[30:33]
	v_mfma_f32_16x16x32_bf16 v[26:29], v[142:145], v[198:201], v[26:29]
	v_mfma_f32_16x16x32_bf16 v[14:17], v[134:137], v[216:219], v[14:17]
	v_mfma_f32_16x16x32_bf16 v[10:13], v[142:145], v[216:219], v[10:13]

; DEVI size_t gemm_offB(const Gemm& g, const Unit& u) { return (g.split ? (size_t)(u.b >> 2) * g.sB + (size_t)(u.b & 3) * g.sB_lo : (size_t)u.b * g.sB) + (size_t)(u.pm >> g.pmsh) * g.sBpm; }
; #define PG8_STAGE(bufoff, gbase, voff) do { _Pragma("unroll") for (int _i = 0; _i < 2; ++_i) \
;         __builtin_amdgcn_global_load_lds((const unsigned*)((const char*)(gbase) + (voff)[_i]), (LAS unsigned*)(lds + (bufoff) + ldsw + _i * 8192), 16, 0, 0); } while (0)
; #define PG8_LDA(dst, b, h) do { _Pragma("unroll") for (int m = 0; m < 4; ++m) _Pragma("unroll") for (int k = 0; k < 2; ++k) dst[m][k] = *(const LAS bf16x8*)(lds + PG8_SA(b, h) + aoff + m * 2048 + k * 1024); } while (0)
; #define PG8_LDB(dst, b, h) do { _Pragma("unroll") for (int n = 0; n < 2; ++n) _Pragma("unroll") for (int k = 0; k < 2; ++k) dst[n][k] = *(const LAS bf16x8*)(lds + PG8_SB(b, h) + boff + n * 2048 + k * 1024); } while (0)
; #define PG8_WAIT_V(n) asm volatile("s_waitcnt vmcnt(" #n ")" ::: "memory")
; #define PG8_BAR __builtin_amdgcn_s_barrier()
; template <class Epi>
; DEVI void gemm_phase(LAS unsigned char* lds, const Gemm g, const Epi& E) {
;     ...
;         const bool has_next = unit_next(g, ui + 1, nxt);
;         const char* nA = has_next ? (const char*)g.A + gemm_offA(g, nxt) * 2 + (size_t)nxt.pm * tstepA : cA;
;         const char* nB = has_next ? (const char*)g.Bt + gemm_offB(g, nxt) * 2 + (size_t)nxt.pn * tstepB : cB;
;         for (int t = 0; t < nt; t += 2) {
;             const bool last = (t == nt - 2);
;             const char* a1 = cA + (size_t)(t + 1) * kstep;
;             const char* a2 = last ? nA : cA + (size_t)(t + 2) * kstep; const char* b2 = last ? nB : cB + (size_t)(t + 2) * kstep;
;             const char* a3 = a2 + kstep; const char* b3 = b2 + kstep;
;             PG8_LDB(B0, 0, 0); PG8_SCHED; PG8_LDA(At, 0, 0); PG8_STAGE(PG8_SA(1, 1), a1 + hstepA, voffA);
;             PG8_WAIT_L(8); PG8_BAR; PG8_WAIT_L(0); PG8_MMA(0, 0, At, B0); PG8_BAR; PG8_SCHED;
;             PG8_LDB(B1, 0, 1); PG8_STAGE(PG8_SB(0, 0), b2, voffB);
;             PG8_BAR; PG8_WAIT_L(0); PG8_MMA(0, 1, At, B1); PG8_BAR;
;             PG8_LDA(At, 0, 1); PG8_STAGE(PG8_SA(0, 0), a2, voffA);
;             PG8_BAR; PG8_WAIT_L(0); PG8_MMA(1, 0, At, B0); PG8_BAR; PG8_SCHED;
;             PG8_STAGE(PG8_SB(0, 1), b2 + hstepB, voffB);
;             PG8_WAIT_V(6); PG8_BAR; PG8_MMA(1, 1, At, B1); PG8_BAR;
.LBB0_967:
	s_ashr_i32 s13, s12, 31
	s_lshl_b64 s[0:1], s[12:13], 19
	v_cmp_lt_i64_e32 vcc, s[16:17], v[168:169]
	s_add_u32 s16, s24, s0
	s_addc_u32 s17, s25, s1
	s_and_b64 s[0:1], vcc, exec
	s_cselect_b32 s0, s17, s69
	s_cselect_b32 s1, s16, s68
	s_ashr_i32 s15, s14, 31
	s_lshl_b64 s[18:19], s[14:15], 19
	v_readlane_b32 s26, v254, 9
	v_readlane_b32 s27, v254, 10
	s_add_u32 s36, s26, s18
	s_addc_u32 s37, s27, s19
	s_and_b64 s[18:19], vcc, exec
	s_cselect_b32 s9, s37, s81
	s_cselect_b32 s13, s36, s80
	s_add_u32 s68, s68, 0x40080
	s_addc_u32 s69, s69, 0
	s_add_u32 s15, s80, 0x100
	s_addc_u32 s18, s81, 0
	s_mov_b32 s19, -2
	s_waitcnt lgkmcnt(0)
	s_add_u32 s26, s68, 0xfffc0080
	s_addc_u32 s27, s69, -1
	s_add_i32 s38, 0, 0x10000
	v_add_u32_e32 v142, s38, v193
	ds_read_b128 v[130:133], v142
	ds_read_b128 v[134:137], v142 offset:1024
	ds_read_b128 v[138:141], v142 offset:2048
	ds_read_b128 v[142:145], v142 offset:3072
	s_cmp_eq_u32 s19, 12
	s_cselect_b32 s83, s0, s27
	s_cselect_b32 s82, s1, s26
	s_cselect_b32 s81, s9, s18
	s_cselect_b32 s80, s13, s15
	v_lshl_add_u64 v[162:163], s[68:69], 0, v[178:179]
	s_add_i32 m0, s85, 0xc000
	ds_read_b128 v[146:149], v198
	ds_read_b128 v[182:185], v198 offset:1024
	ds_read_b128 v[186:189], v198 offset:2048
	ds_read_b128 v[200:203], v198 offset:3072
	ds_read_b128 v[204:207], v198 offset:4096
	ds_read_b128 v[214:217], v198 offset:5120
	ds_read_b128 v[218:221], v198 offset:6144
	ds_read_b128 v[222:225], v198 offset:7168
	global_load_lds_dwordx4 v[162:163], off
	s_add_i32 m0, s85, 0xe000
	v_lshl_add_u64 v[162:163], s[68:69], 0, v[180:181]
	global_load_lds_dwordx4 v[162:163], off
	s_waitcnt lgkmcnt(8)
	s_barrier
	s_waitcnt lgkmcnt(0)
	v_mfma_f32_16x16x32_bf16 v[126:129], v[130:133], v[146:149], 0
	v_mfma_f32_16x16x32_bf16 v[122:125], v[138:141], v[146:149], 0
	v_mfma_f32_16x16x32_bf16 v[110:113], v[130:133], v[186:189], 0
	v_mfma_f32_16x16x32_bf16 v[106:109], v[138:141], v[186:189], 0
	v_mfma_f32_16x16x32_bf16 v[94:97], v[130:133], v[204:207], 0
	v_mfma_f32_16x16x32_bf16 v[90:93], v[138:141], v[204:207], 0
	v_mfma_f32_16x16x32_bf16 v[78:81], v[130:133], v[218:221], 0
	v_mfma_f32_16x16x32_bf16 v[74:77], v[138:141], v[218:221], 0
	v_mfma_f32_16x16x32_bf16 v[126:129], v[134:137], v[182:185], v[126:129]
	v_mfma_f32_16x16x32_bf16 v[122:125], v[142:145], v[182:185], v[122:125]
	v_mfma_f32_16x16x32_bf16 v[110:113], v[134:137], v[200:203], v[110:113]
	v_mfma_f32_16x16x32_bf16 v[106:109], v[142:145], v[200:203], v[106:109]
	v_mfma_f32_16x16x32_bf16 v[94:97], v[134:137], v[214:217], v[94:97]
	v_mfma_f32_16x16x32_bf16 v[90:93], v[142:145], v[214:217], v[90:93]
	v_mfma_f32_16x16x32_bf16 v[78:81], v[134:137], v[222:225], v[78:81]
	v_mfma_f32_16x16x32_bf16 v[74:77], v[142:145], v[222:225], v[74:77]
	s_barrier
	s_add_i32 s39, 0, 0x14000
	v_add_u32_e32 v162, s39, v193
	s_add_i32 s26, s38, s84
	ds_read_b128 v[226:229], v162
	ds_read_b128 v[230:233], v162 offset:1024
	ds_read_b128 v[234:237], v162 offset:2048
	ds_read_b128 v[238:241], v162 offset:3072
	v_lshl_add_u64 v[162:163], s[80:81], 0, v[8:9]
	s_mov_b32 m0, s26
	v_lshl_add_u64 v[164:165], s[80:81], 0, v[176:177]
	global_load_lds_dwordx4 v[162:163], off
	s_add_i32 m0, s26, 0x2000
	s_nop 0
	global_load_lds_dwordx4 v[164:165], off
	s_barrier
	s_waitcnt lgkmcnt(0)
	v_mfma_f32_16x16x32_bf16 v[118:121], v[226:229], v[146:149], 0
	v_mfma_f32_16x16x32_bf16 v[114:117], v[234:237], v[146:149], 0
	v_mfma_f32_16x16x32_bf16 v[102:105], v[226:229], v[186:189], 0
	v_mfma_f32_16x16x32_bf16 v[98:101], v[234:237], v[186:189], 0
	v_mfma_f32_16x16x32_bf16 v[86:89], v[226:229], v[204:207], 0
	v_mfma_f32_16x16x32_bf16 v[82:85], v[234:237], v[204:207], 0
	v_mfma_f32_16x16x32_bf16 v[70:73], v[226:229], v[218:221], 0
	v_mfma_f32_16x16x32_bf16 v[66:69], v[234:237], v[218:221], 0
	v_mfma_f32_16x16x32_bf16 v[118:121], v[230:233], v[182:185], v[118:121]
	v_mfma_f32_16x16x32_bf16 v[114:117], v[238:241], v[182:185], v[114:117]
	v_mfma_f32_16x16x32_bf16 v[102:105], v[230:233], v[200:203], v[102:105]
	v_mfma_f32_16x16x32_bf16 v[98:101], v[238:241], v[200:203], v[98:101]
	v_mfma_f32_16x16x32_bf16 v[86:89], v[230:233], v[214:217], v[86:89]
	v_mfma_f32_16x16x32_bf16 v[82:85], v[238:241], v[214:217], v[82:85]
	v_mfma_f32_16x16x32_bf16 v[70:73], v[230:233], v[222:225], v[70:73]
	v_mfma_f32_16x16x32_bf16 v[66:69], v[238:241], v[222:225], v[66:69]
	s_mov_b32 m0, s85
	v_lshl_add_u64 v[190:191], s[82:83], 0, v[150:151]
	s_barrier
	ds_read_b128 v[146:149], v198 offset:16384
	ds_read_b128 v[182:185], v198 offset:17408
	ds_read_b128 v[186:189], v198 offset:18432
	ds_read_b128 v[200:203], v198 offset:19456
	ds_read_b128 v[204:207], v198 offset:20480
	ds_read_b128 v[214:217], v198 offset:21504
	ds_read_b128 v[218:221], v198 offset:22528
	ds_read_b128 v[222:225], v198 offset:23552
	global_load_lds_dwordx4 v[190:191], off
	s_mov_b32 m0, s86
	v_lshl_add_u64 v[208:209], s[82:83], 0, v[152:153]
	global_load_lds_dwordx4 v[208:209], off
	s_barrier
	s_waitcnt lgkmcnt(0)
	v_mfma_f32_16x16x32_bf16 v[62:65], v[130:133], v[146:149], 0
	v_mfma_f32_16x16x32_bf16 v[58:61], v[138:141], v[146:149], 0
	v_mfma_f32_16x16x32_bf16 v[46:49], v[130:133], v[186:189], 0
	v_mfma_f32_16x16x32_bf16 v[42:45], v[138:141], v[186:189], 0
	v_mfma_f32_16x16x32_bf16 v[30:33], v[130:133], v[204:207], 0
	v_mfma_f32_16x16x32_bf16 v[26:29], v[138:141], v[204:207], 0
	v_mfma_f32_16x16x32_bf16 v[14:17], v[130:133], v[218:221], 0
	v_mfma_f32_16x16x32_bf16 v[10:13], v[138:141], v[218:221], 0
	v_mfma_f32_16x16x32_bf16 v[62:65], v[134:137], v[182:185], v[62:65]
	v_mfma_f32_16x16x32_bf16 v[58:61], v[142:145], v[182:185], v[58:61]
	v_mfma_f32_16x16x32_bf16 v[46:49], v[134:137], v[200:203], v[46:49]
	v_mfma_f32_16x16x32_bf16 v[42:45], v[142:145], v[200:203], v[42:45]
	v_mfma_f32_16x16x32_bf16 v[30:33], v[134:137], v[214:217], v[30:33]
	v_mfma_f32_16x16x32_bf16 v[26:29], v[142:145], v[214:217], v[26:29]
	v_mfma_f32_16x16x32_bf16 v[14:17], v[134:137], v[222:225], v[14:17]
	v_mfma_f32_16x16x32_bf16 v[10:13], v[142:145], v[222:225], v[10:13]
	s_barrier
; #define PG8_STAGE(bufoff, gbase, voff) do { _Pragma("unroll") for (int _i = 0; _i < 2; ++_i) \
;         __builtin_amdgcn_global_load_lds((const unsigned*)((const char*)(gbase) + (voff)[_i]), (LAS unsigned*)(lds + (bufoff) + ldsw + _i * 8192), 16, 0, 0); } while (0)
; #define PG8_LDA(dst, b, h) do { _Pragma("unroll") for (int m = 0; m < 4; ++m) _Pragma("unroll") for (int k = 0; k < 2; ++k) dst[m][k] = *(const LAS bf16x8*)(lds + PG8_SA(b, h) + aoff + m * 2048 + k * 1024); } while (0)
; #define PG8_LDB(dst, b, h) do { _Pragma("unroll") for (int n = 0; n < 2; ++n) _Pragma("unroll") for (int k = 0; k < 2; ++k) dst[n][k] = *(const LAS bf16x8*)(lds + PG8_SB(b, h) + boff + n * 2048 + k * 1024); } while (0)
; #define PG8_MMA(ai, bj, At, Bt) do { __builtin_amdgcn_s_setprio(1); _Pragma("unroll") for (int m = 0; m < 4; ++m) _Pragma("unroll") for (int n = 0; n < 2; ++n) _Pragma("unroll") for (int k = 0; k < 2; ++k) \
;         acc[ai][bj][m][n] = __builtin_amdgcn_mfma_f32_16x16x32_bf16(Bt[n][k], At[m][k], acc[ai][bj][m][n], 0, 0, 0); __builtin_amdgcn_s_setprio(0); } while (0)
; #define PG8_WAIT_V(n) asm volatile("s_waitcnt vmcnt(" #n ")" ::: "memory")
; #define PG8_WAIT_L(n) asm volatile("s_waitcnt lgkmcnt(" #n ")" ::: "memory")
; #define PG8_BAR __builtin_amdgcn_s_barrier()
; #define PG8_SCHED __builtin_amdgcn_sched_barrier(0)
; template <class Epi>
; DEVI void gemm_phase(LAS unsigned char* lds, const Gemm g, const Epi& E) {
;     ...
;             PG8_STAGE(PG8_SB(0, 1), b2 + hstepB, voffB);
;             PG8_WAIT_V(6); PG8_BAR; PG8_MMA(1, 1, At, B1); PG8_BAR;
;             PG8_LDB(B0, 1, 0); PG8_SCHED; PG8_LDA(At, 1, 0); PG8_STAGE(PG8_SA(0, 1), a2 + hstepA, voffA);
;             PG8_WAIT_L(8); PG8_BAR; PG8_WAIT_L(0); PG8_MMA(0, 0, At, B0); PG8_BAR; PG8_SCHED;
;             PG8_LDB(B1, 1, 1); PG8_STAGE(PG8_SB(1, 0), b3, voffB);
;             PG8_BAR; PG8_WAIT_L(0); PG8_MMA(0, 1, At, B1); PG8_BAR;
;             PG8_LDA(At, 1, 1); PG8_STAGE(PG8_SA(1, 0), a3, voffA);
	s_add_u32 s26, s80, 0x40000
	s_addc_u32 s27, s81, 0
	s_add_i32 s38, s39, s84
	s_mov_b32 m0, s38
	v_lshl_add_u64 v[130:131], s[26:27], 0, v[8:9]
	global_load_lds_dwordx4 v[130:131], off
	s_add_i32 m0, s38, 0x2000
	v_lshl_add_u64 v[130:131], s[26:27], 0, v[176:177]
	global_load_lds_dwordx4 v[130:131], off
	s_waitcnt vmcnt(6)
	s_barrier
	v_mfma_f32_16x16x32_bf16 v[54:57], v[226:229], v[146:149], 0
	v_mfma_f32_16x16x32_bf16 v[50:53], v[234:237], v[146:149], 0
	v_mfma_f32_16x16x32_bf16 v[38:41], v[226:229], v[186:189], 0
	v_mfma_f32_16x16x32_bf16 v[34:37], v[234:237], v[186:189], 0
	v_mfma_f32_16x16x32_bf16 v[22:25], v[226:229], v[204:207], 0
	v_mfma_f32_16x16x32_bf16 v[18:21], v[234:237], v[204:207], 0
	v_mfma_f32_16x16x32_bf16 v[4:7], v[226:229], v[218:221], 0
	v_mfma_f32_16x16x32_bf16 v[0:3], v[234:237], v[218:221], 0
	v_mfma_f32_16x16x32_bf16 v[54:57], v[230:233], v[182:185], v[54:57]
	v_mfma_f32_16x16x32_bf16 v[50:53], v[238:241], v[182:185], v[50:53]
	v_mfma_f32_16x16x32_bf16 v[38:41], v[230:233], v[200:203], v[38:41]
	v_mfma_f32_16x16x32_bf16 v[34:37], v[238:241], v[200:203], v[34:37]
	v_mfma_f32_16x16x32_bf16 v[22:25], v[230:233], v[214:217], v[22:25]
	v_mfma_f32_16x16x32_bf16 v[18:21], v[238:241], v[214:217], v[18:21]
	v_mfma_f32_16x16x32_bf16 v[4:7], v[230:233], v[222:225], v[4:7]
	v_mfma_f32_16x16x32_bf16 v[0:3], v[238:241], v[222:225], v[0:3]
	s_add_i32 s38, 0, 0x18000
	v_add_u32_e32 v142, s38, v193
	s_barrier
	ds_read_b128 v[130:133], v142
	ds_read_b128 v[134:137], v142 offset:1024
	ds_read_b128 v[138:141], v142 offset:2048
	ds_read_b128 v[142:145], v142 offset:3072
	s_add_u32 s26, s82, 0x40000
	s_addc_u32 s27, s83, 0
	s_mov_b32 m0, s87
	v_lshl_add_u64 v[226:227], s[26:27], 0, v[150:151]
	ds_read_b128 v[146:149], v198 offset:32768
	ds_read_b128 v[182:185], v198 offset:33792
	ds_read_b128 v[186:189], v198 offset:34816
	ds_read_b128 v[200:203], v198 offset:35840
	ds_read_b128 v[204:207], v198 offset:36864
	ds_read_b128 v[214:217], v198 offset:37888
	ds_read_b128 v[218:221], v198 offset:38912
	ds_read_b128 v[222:225], v198 offset:39936
	global_load_lds_dwordx4 v[226:227], off
	s_mov_b32 m0, s88
	v_lshl_add_u64 v[226:227], s[26:27], 0, v[152:153]
	global_load_lds_dwordx4 v[226:227], off
	s_waitcnt lgkmcnt(8)
	s_barrier
	s_waitcnt lgkmcnt(0)
	v_mfma_f32_16x16x32_bf16 v[126:129], v[130:133], v[146:149], v[126:129]
	v_mfma_f32_16x16x32_bf16 v[122:125], v[138:141], v[146:149], v[122:125]
	v_mfma_f32_16x16x32_bf16 v[110:113], v[130:133], v[186:189], v[110:113]
	v_mfma_f32_16x16x32_bf16 v[106:109], v[138:141], v[186:189], v[106:109]
	v_mfma_f32_16x16x32_bf16 v[94:97], v[130:133], v[204:207], v[94:97]
	v_mfma_f32_16x16x32_bf16 v[90:93], v[138:141], v[204:207], v[90:93]
	v_mfma_f32_16x16x32_bf16 v[78:81], v[130:133], v[218:221], v[78:81]
	v_mfma_f32_16x16x32_bf16 v[74:77], v[138:141], v[218:221], v[74:77]
	v_mfma_f32_16x16x32_bf16 v[126:129], v[134:137], v[182:185], v[126:129]
	v_mfma_f32_16x16x32_bf16 v[122:125], v[142:145], v[182:185], v[122:125]
	v_mfma_f32_16x16x32_bf16 v[110:113], v[134:137], v[200:203], v[110:113]
	v_mfma_f32_16x16x32_bf16 v[106:109], v[142:145], v[200:203], v[106:109]
	v_mfma_f32_16x16x32_bf16 v[94:97], v[134:137], v[214:217], v[94:97]
	v_mfma_f32_16x16x32_bf16 v[90:93], v[142:145], v[214:217], v[90:93]
	v_mfma_f32_16x16x32_bf16 v[78:81], v[134:137], v[222:225], v[78:81]
	v_mfma_f32_16x16x32_bf16 v[74:77], v[142:145], v[222:225], v[74:77]
	s_barrier
	s_add_i32 s39, 0, 0x1c000
	s_add_i32 s26, s38, s84
	v_add_u32_e32 v199, s39, v193
	v_lshl_add_u64 v[162:163], v[162:163], 0, s[70:71]
	s_mov_b32 m0, s26
	ds_read_b128 v[226:229], v199
	ds_read_b128 v[230:233], v199 offset:1024
	ds_read_b128 v[234:237], v199 offset:2048
	ds_read_b128 v[238:241], v199 offset:3072
	global_load_lds_dwordx4 v[162:163], off
	s_add_i32 m0, s26, 0x2000
	v_lshl_add_u64 v[162:163], v[164:165], 0, s[70:71]
	global_load_lds_dwordx4 v[162:163], off
	s_barrier
; #define PG8_STAGE(bufoff, gbase, voff) do { _Pragma("unroll") for (int _i = 0; _i < 2; ++_i) \
;         __builtin_amdgcn_global_load_lds((const unsigned*)((const char*)(gbase) + (voff)[_i]), (LAS unsigned*)(lds + (bufoff) + ldsw + _i * 8192), 16, 0, 0); } while (0)
; #define PG8_LDA(dst, b, h) do { _Pragma("unroll") for (int m = 0; m < 4; ++m) _Pragma("unroll") for (int k = 0; k < 2; ++k) dst[m][k] = *(const LAS bf16x8*)(lds + PG8_SA(b, h) + aoff + m * 2048 + k * 1024); } while (0)
; #define PG8_MMA(ai, bj, At, Bt) do { __builtin_amdgcn_s_setprio(1); _Pragma("unroll") for (int m = 0; m < 4; ++m) _Pragma("unroll") for (int n = 0; n < 2; ++n) _Pragma("unroll") for (int k = 0; k < 2; ++k) \
;         acc[ai][bj][m][n] = __builtin_amdgcn_mfma_f32_16x16x32_bf16(Bt[n][k], At[m][k], acc[ai][bj][m][n], 0, 0, 0); __builtin_amdgcn_s_setprio(0); } while (0)
; #define PG8_WAIT_V(n) asm volatile("s_waitcnt vmcnt(" #n ")" ::: "memory")
; #define PG8_WAIT_L(n) asm volatile("s_waitcnt lgkmcnt(" #n ")" ::: "memory")
; #define PG8_BAR __builtin_amdgcn_s_barrier()
; #define PG8_SCHED __builtin_amdgcn_sched_barrier(0)
; template <class Epi>
; DEVI void gemm_phase(LAS unsigned char* lds, const Gemm g, const Epi& E) {
;     ...
;             PG8_LDA(At, 1, 1); PG8_STAGE(PG8_SA(1, 0), a3, voffA);
;             PG8_BAR; PG8_WAIT_L(0); PG8_MMA(1, 0, At, B0); PG8_BAR; PG8_SCHED;
;             PG8_STAGE(PG8_SB(1, 1), b3 + hstepB, voffB);
;             PG8_WAIT_V(6); PG8_BAR; PG8_MMA(1, 1, At, B1); PG8_BAR;
	s_waitcnt lgkmcnt(0)
	v_mfma_f32_16x16x32_bf16 v[118:121], v[226:229], v[146:149], v[118:121]
	v_mfma_f32_16x16x32_bf16 v[114:117], v[234:237], v[146:149], v[114:117]
	v_mfma_f32_16x16x32_bf16 v[102:105], v[226:229], v[186:189], v[102:105]
	v_mfma_f32_16x16x32_bf16 v[98:101], v[234:237], v[186:189], v[98:101]
	v_mfma_f32_16x16x32_bf16 v[86:89], v[226:229], v[204:207], v[86:89]
	v_mfma_f32_16x16x32_bf16 v[82:85], v[234:237], v[204:207], v[82:85]
	v_mfma_f32_16x16x32_bf16 v[70:73], v[226:229], v[218:221], v[70:73]
	v_mfma_f32_16x16x32_bf16 v[66:69], v[234:237], v[218:221], v[66:69]
	v_mfma_f32_16x16x32_bf16 v[118:121], v[230:233], v[182:185], v[118:121]
	v_mfma_f32_16x16x32_bf16 v[114:117], v[238:241], v[182:185], v[114:117]
	v_mfma_f32_16x16x32_bf16 v[102:105], v[230:233], v[200:203], v[102:105]
	v_mfma_f32_16x16x32_bf16 v[98:101], v[238:241], v[200:203], v[98:101]
	v_mfma_f32_16x16x32_bf16 v[86:89], v[230:233], v[214:217], v[86:89]
	v_mfma_f32_16x16x32_bf16 v[82:85], v[238:241], v[214:217], v[82:85]
	v_mfma_f32_16x16x32_bf16 v[70:73], v[230:233], v[222:225], v[70:73]
	v_mfma_f32_16x16x32_bf16 v[66:69], v[238:241], v[222:225], v[66:69]
	s_mov_b32 m0, s89
	v_lshl_add_u64 v[162:163], v[190:191], 0, s[70:71]
	s_barrier
	ds_read_b128 v[146:149], v198 offset:49152
	ds_read_b128 v[182:185], v198 offset:50176
	ds_read_b128 v[186:189], v198 offset:51200
	ds_read_b128 v[200:203], v198 offset:52224
	ds_read_b128 v[204:207], v198 offset:53248
	ds_read_b128 v[214:217], v198 offset:54272
	ds_read_b128 v[218:221], v198 offset:55296
	ds_read_b128 v[222:225], v198 offset:56320
	global_load_lds_dwordx4 v[162:163], off
	s_mov_b32 m0, s90
	v_lshl_add_u64 v[162:163], v[208:209], 0, s[70:71]
	global_load_lds_dwordx4 v[162:163], off
	s_barrier
	s_waitcnt lgkmcnt(0)
	v_mfma_f32_16x16x32_bf16 v[62:65], v[130:133], v[146:149], v[62:65]
	v_mfma_f32_16x16x32_bf16 v[58:61], v[138:141], v[146:149], v[58:61]
	v_mfma_f32_16x16x32_bf16 v[46:49], v[130:133], v[186:189], v[46:49]
	v_mfma_f32_16x16x32_bf16 v[42:45], v[138:141], v[186:189], v[42:45]
	v_mfma_f32_16x16x32_bf16 v[30:33], v[130:133], v[204:207], v[30:33]
	v_mfma_f32_16x16x32_bf16 v[26:29], v[138:141], v[204:207], v[26:29]
	v_mfma_f32_16x16x32_bf16 v[14:17], v[130:133], v[218:221], v[14:17]
	v_mfma_f32_16x16x32_bf16 v[10:13], v[138:141], v[218:221], v[10:13]
	v_mfma_f32_16x16x32_bf16 v[62:65], v[134:137], v[182:185], v[62:65]
	v_mfma_f32_16x16x32_bf16 v[58:61], v[142:145], v[182:185], v[58:61]
	v_mfma_f32_16x16x32_bf16 v[46:49], v[134:137], v[200:203], v[46:49]
	v_mfma_f32_16x16x32_bf16 v[42:45], v[142:145], v[200:203], v[42:45]
	v_mfma_f32_16x16x32_bf16 v[30:33], v[134:137], v[214:217], v[30:33]
	v_mfma_f32_16x16x32_bf16 v[26:29], v[142:145], v[214:217], v[26:29]
	v_mfma_f32_16x16x32_bf16 v[14:17], v[134:137], v[222:225], v[14:17]
	v_mfma_f32_16x16x32_bf16 v[10:13], v[142:145], v[222:225], v[10:13]
	s_barrier
	s_add_u32 s26, s80, 0x40080
	s_addc_u32 s27, s81, 0
	s_add_i32 s38, s39, s84
	s_mov_b32 m0, s38
	v_lshl_add_u64 v[130:131], s[26:27], 0, v[8:9]
	global_load_lds_dwordx4 v[130:131], off
	s_add_i32 m0, s38, 0x2000
	v_lshl_add_u64 v[130:131], s[26:27], 0, v[176:177]
	global_load_lds_dwordx4 v[130:131], off
	s_waitcnt vmcnt(6)
	s_barrier
	v_mfma_f32_16x16x32_bf16 v[54:57], v[226:229], v[146:149], v[54:57]
	v_mfma_f32_16x16x32_bf16 v[50:53], v[234:237], v[146:149], v[50:53]
	v_mfma_f32_16x16x32_bf16 v[38:41], v[226:229], v[186:189], v[38:41]
	v_mfma_f32_16x16x32_bf16 v[34:37], v[234:237], v[186:189], v[34:37]
	v_mfma_f32_16x16x32_bf16 v[22:25], v[226:229], v[204:207], v[22:25]
	v_mfma_f32_16x16x32_bf16 v[18:21], v[234:237], v[204:207], v[18:21]
	v_mfma_f32_16x16x32_bf16 v[4:7], v[226:229], v[218:221], v[4:7]
	v_mfma_f32_16x16x32_bf16 v[0:3], v[234:237], v[218:221], v[0:3]
	v_mfma_f32_16x16x32_bf16 v[54:57], v[230:233], v[182:185], v[54:57]
	v_mfma_f32_16x16x32_bf16 v[50:53], v[238:241], v[182:185], v[50:53]
	v_mfma_f32_16x16x32_bf16 v[38:41], v[230:233], v[200:203], v[38:41]
	v_mfma_f32_16x16x32_bf16 v[34:37], v[238:241], v[200:203], v[34:37]
	v_mfma_f32_16x16x32_bf16 v[22:25], v[230:233], v[214:217], v[22:25]
	v_mfma_f32_16x16x32_bf16 v[18:21], v[238:241], v[214:217], v[18:21]
	v_mfma_f32_16x16x32_bf16 v[4:7], v[230:233], v[222:225], v[4:7]
	v_mfma_f32_16x16x32_bf16 v[0:3], v[238:241], v[222:225], v[0:3]
	s_add_i32 s19, s19, 2
	s_add_u32 s68, s68, 0x100
	s_addc_u32 s69, s69, 0
	s_add_u32 s15, s15, 0x100
	s_addc_u32 s18, s18, 0
	s_cmp_gt_u32 s19, 13
	s_barrier

; DEVI size_t gemm_offB(const Gemm& g, const Unit& u) { return (g.split ? (size_t)(u.b >> 2) * g.sB + (size_t)(u.b & 3) * g.sB_lo : (size_t)u.b * g.sB) + (size_t)(u.pm >> g.pmsh) * g.sBpm; }
; #define PG8_STAGE(bufoff, gbase, voff) do { _Pragma("unroll") for (int _i = 0; _i < 2; ++_i) \
;         __builtin_amdgcn_global_load_lds((const unsigned*)((const char*)(gbase) + (voff)[_i]), (LAS unsigned*)(lds + (bufoff) + ldsw + _i * 8192), 16, 0, 0); } while (0)
; #define PG8_LDA(dst, b, h) do { _Pragma("unroll") for (int m = 0; m < 4; ++m) _Pragma("unroll") for (int k = 0; k < 2; ++k) dst[m][k] = *(const LAS bf16x8*)(lds + PG8_SA(b, h) + aoff + m * 2048 + k * 1024); } while (0)
; #define PG8_LDB(dst, b, h) do { _Pragma("unroll") for (int n = 0; n < 2; ++n) _Pragma("unroll") for (int k = 0; k < 2; ++k) dst[n][k] = *(const LAS bf16x8*)(lds + PG8_SB(b, h) + boff + n * 2048 + k * 1024); } while (0)
; #define PG8_WAIT_V(n) asm volatile("s_waitcnt vmcnt(" #n ")" ::: "memory")
; #define PG8_BAR __builtin_amdgcn_s_barrier()
; template <class Epi>
; DEVI void gemm_phase(LAS unsigned char* lds, const Gemm g, const Epi& E) {
;     ...
;         const bool has_next = unit_next(g, ui + 1, nxt);
;         const char* nA = has_next ? (const char*)g.A + gemm_offA(g, nxt) * 2 + (size_t)nxt.pm * tstepA : cA;
;         const char* nB = has_next ? (const char*)g.Bt + gemm_offB(g, nxt) * 2 + (size_t)nxt.pn * tstepB : cB;
;         for (int t = 0; t < nt; t += 2) {
;             const bool last = (t == nt - 2);
;             const char* a1 = cA + (size_t)(t + 1) * kstep;
;             const char* a2 = last ? nA : cA + (size_t)(t + 2) * kstep; const char* b2 = last ? nB : cB + (size_t)(t + 2) * kstep;
;             const char* a3 = a2 + kstep; const char* b3 = b2 + kstep;
;             PG8_LDB(B0, 0, 0); PG8_SCHED; PG8_LDA(At, 0, 0); PG8_STAGE(PG8_SA(1, 1), a1 + hstepA, voffA);
;             PG8_WAIT_L(8); PG8_BAR; PG8_WAIT_L(0); PG8_MMA(0, 0, At, B0); PG8_BAR; PG8_SCHED;
;             PG8_LDB(B1, 0, 1); PG8_STAGE(PG8_SB(0, 0), b2, voffB);
;             PG8_BAR; PG8_WAIT_L(0); PG8_MMA(0, 1, At, B1); PG8_BAR;
;             PG8_LDA(At, 0, 1); PG8_STAGE(PG8_SA(0, 0), a2, voffA);
;             PG8_BAR; PG8_WAIT_L(0); PG8_MMA(1, 0, At, B0); PG8_BAR; PG8_SCHED;
;             PG8_STAGE(PG8_SB(0, 1), b2 + hstepB, voffB);
;             PG8_WAIT_V(6); PG8_BAR; PG8_MMA(1, 1, At, B1); PG8_BAR;
.LBB0_1006:
	s_ashr_i32 s7, s6, 31
	s_lshl_b64 s[0:1], s[6:7], 19
	v_cmp_lt_i64_e32 vcc, s[10:11], v[168:169]
	s_add_u32 s10, s24, s0
	s_addc_u32 s11, s25, s1
	s_and_b64 s[0:1], vcc, exec
	s_cselect_b32 s0, s11, s15
	s_cselect_b32 s1, s10, s14
	s_ashr_i32 s9, s8, 31
	s_lshl_b64 s[12:13], s[8:9], 19
	v_readlane_b32 s18, v251, 60
	v_readlane_b32 s19, v251, 61
	s_add_u32 s12, s18, s12
	s_addc_u32 s13, s19, s13
	s_and_b64 s[18:19], vcc, exec
	s_cselect_b32 s5, s13, s17
	s_cselect_b32 s7, s12, s16
	s_add_u32 s14, s14, 0x40080
	s_addc_u32 s15, s15, 0
	s_add_u32 s9, s16, 0x100
	s_addc_u32 s18, s17, 0
	s_mov_b32 s19, -2
	s_add_u32 s16, s14, 0xfffc0080
	s_addc_u32 s17, s15, -1
	s_add_i32 s26, 0, 0x10000
	v_add_u32_e32 v8, s26, v199
	ds_read_b128 v[130:133], v8
	ds_read_b128 v[134:137], v8 offset:1024
	ds_read_b128 v[138:141], v8 offset:2048
	ds_read_b128 v[142:145], v8 offset:3072
	s_cmp_eq_u32 s19, 12
	s_cselect_b32 s37, s0, s17
	s_cselect_b32 s36, s1, s16
	s_cselect_b32 s17, s5, s18
	s_cselect_b32 s16, s7, s9
	v_lshl_add_u64 v[162:163], s[14:15], 0, v[180:181]
	s_add_i32 m0, s66, 0xc000
	ds_read_b128 v[184:187], v204
	ds_read_b128 v[188:191], v204 offset:1024
	ds_read_b128 v[192:195], v204 offset:2048
	ds_read_b128 v[206:209], v204 offset:3072
	ds_read_b128 v[214:217], v204 offset:4096
	ds_read_b128 v[218:221], v204 offset:5120
	ds_read_b128 v[222:225], v204 offset:6144
	ds_read_b128 v[226:229], v204 offset:7168
	global_load_lds_dwordx4 v[162:163], off
	s_add_i32 m0, s66, 0xe000
	v_lshl_add_u64 v[162:163], s[14:15], 0, v[182:183]
	global_load_lds_dwordx4 v[162:163], off
	s_waitcnt lgkmcnt(8)
	s_barrier
	s_waitcnt lgkmcnt(0)
	v_mfma_f32_16x16x32_bf16 v[126:129], v[130:133], v[184:187], 0
	v_mfma_f32_16x16x32_bf16 v[122:125], v[138:141], v[184:187], 0
	v_mfma_f32_16x16x32_bf16 v[114:117], v[130:133], v[192:195], 0
	v_mfma_f32_16x16x32_bf16 v[106:109], v[138:141], v[192:195], 0
	v_mfma_f32_16x16x32_bf16 v[102:105], v[130:133], v[214:217], 0
	v_mfma_f32_16x16x32_bf16 v[94:97], v[138:141], v[214:217], 0
	v_mfma_f32_16x16x32_bf16 v[82:85], v[130:133], v[222:225], 0
	v_mfma_f32_16x16x32_bf16 v[74:77], v[138:141], v[222:225], 0
	v_mfma_f32_16x16x32_bf16 v[126:129], v[134:137], v[188:191], v[126:129]
	v_mfma_f32_16x16x32_bf16 v[122:125], v[142:145], v[188:191], v[122:125]
	v_mfma_f32_16x16x32_bf16 v[114:117], v[134:137], v[206:209], v[114:117]
	v_mfma_f32_16x16x32_bf16 v[106:109], v[142:145], v[206:209], v[106:109]
	v_mfma_f32_16x16x32_bf16 v[102:105], v[134:137], v[218:221], v[102:105]
	v_mfma_f32_16x16x32_bf16 v[94:97], v[142:145], v[218:221], v[94:97]
	v_mfma_f32_16x16x32_bf16 v[82:85], v[134:137], v[226:229], v[82:85]
	v_mfma_f32_16x16x32_bf16 v[74:77], v[142:145], v[226:229], v[74:77]
	s_barrier
	s_add_i32 s38, 0, 0x14000
	s_add_i32 s26, s26, s47
	v_add_u32_e32 v8, s38, v199
	v_lshl_add_u64 v[162:163], s[16:17], 0, v[148:149]
	s_mov_b32 m0, s26
	ds_read_b128 v[230:233], v8
	ds_read_b128 v[234:237], v8 offset:1024
	ds_read_b128 v[238:241], v8 offset:2048
	ds_read_b128 v[242:245], v8 offset:3072
	global_load_lds_dwordx4 v[162:163], off
	s_add_i32 m0, s26, 0x2000
	v_lshl_add_u64 v[164:165], s[16:17], 0, v[152:153]
	global_load_lds_dwordx4 v[164:165], off
	s_barrier
	s_waitcnt lgkmcnt(0)
	v_mfma_f32_16x16x32_bf16 v[118:121], v[230:233], v[184:187], 0
	v_mfma_f32_16x16x32_bf16 v[110:113], v[238:241], v[184:187], 0
	v_mfma_f32_16x16x32_bf16 v[98:101], v[230:233], v[192:195], 0
	v_mfma_f32_16x16x32_bf16 v[90:93], v[238:241], v[192:195], 0
	v_mfma_f32_16x16x32_bf16 v[86:89], v[230:233], v[214:217], 0
	v_mfma_f32_16x16x32_bf16 v[78:81], v[238:241], v[214:217], 0
	v_mfma_f32_16x16x32_bf16 v[54:57], v[230:233], v[222:225], 0
	v_mfma_f32_16x16x32_bf16 v[34:37], v[238:241], v[222:225], 0
	v_mfma_f32_16x16x32_bf16 v[118:121], v[234:237], v[188:191], v[118:121]
	v_mfma_f32_16x16x32_bf16 v[110:113], v[242:245], v[188:191], v[110:113]
	v_mfma_f32_16x16x32_bf16 v[98:101], v[234:237], v[206:209], v[98:101]
	v_mfma_f32_16x16x32_bf16 v[90:93], v[242:245], v[206:209], v[90:93]
	v_mfma_f32_16x16x32_bf16 v[86:89], v[234:237], v[218:221], v[86:89]
	v_mfma_f32_16x16x32_bf16 v[78:81], v[242:245], v[218:221], v[78:81]
	v_mfma_f32_16x16x32_bf16 v[54:57], v[234:237], v[226:229], v[54:57]
	v_mfma_f32_16x16x32_bf16 v[34:37], v[242:245], v[226:229], v[34:37]
	s_mov_b32 m0, s66
	v_lshl_add_u64 v[202:203], s[36:37], 0, v[146:147]
	s_barrier
	ds_read_b128 v[184:187], v204 offset:16384
	ds_read_b128 v[188:191], v204 offset:17408
	ds_read_b128 v[192:195], v204 offset:18432
	ds_read_b128 v[206:209], v204 offset:19456
	ds_read_b128 v[214:217], v204 offset:20480
	ds_read_b128 v[218:221], v204 offset:21504
	ds_read_b128 v[222:225], v204 offset:22528
	ds_read_b128 v[226:229], v204 offset:23552
	global_load_lds_dwordx4 v[202:203], off
	s_mov_b32 m0, s68
	v_lshl_add_u64 v[246:247], s[36:37], 0, v[150:151]
	global_load_lds_dwordx4 v[246:247], off
	s_barrier
	s_waitcnt lgkmcnt(0)
	v_mfma_f32_16x16x32_bf16 v[58:61], v[130:133], v[184:187], 0
	v_mfma_f32_16x16x32_bf16 v[62:65], v[138:141], v[184:187], 0
	v_mfma_f32_16x16x32_bf16 v[38:41], v[130:133], v[192:195], 0
	v_mfma_f32_16x16x32_bf16 v[42:45], v[138:141], v[192:195], 0
	v_mfma_f32_16x16x32_bf16 v[18:21], v[130:133], v[214:217], 0
	v_mfma_f32_16x16x32_bf16 v[22:25], v[138:141], v[214:217], 0
	v_mfma_f32_16x16x32_bf16 v[0:3], v[130:133], v[222:225], 0
	v_mfma_f32_16x16x32_bf16 v[4:7], v[138:141], v[222:225], 0
	v_mfma_f32_16x16x32_bf16 v[58:61], v[134:137], v[188:191], v[58:61]
	v_mfma_f32_16x16x32_bf16 v[62:65], v[142:145], v[188:191], v[62:65]
	v_mfma_f32_16x16x32_bf16 v[38:41], v[134:137], v[206:209], v[38:41]
	v_mfma_f32_16x16x32_bf16 v[42:45], v[142:145], v[206:209], v[42:45]
	v_mfma_f32_16x16x32_bf16 v[18:21], v[134:137], v[218:221], v[18:21]
	v_mfma_f32_16x16x32_bf16 v[22:25], v[142:145], v[218:221], v[22:25]
	v_mfma_f32_16x16x32_bf16 v[0:3], v[134:137], v[226:229], v[0:3]
	v_mfma_f32_16x16x32_bf16 v[4:7], v[142:145], v[226:229], v[4:7]
	s_barrier
; #define PG8_STAGE(bufoff, gbase, voff) do { _Pragma("unroll") for (int _i = 0; _i < 2; ++_i) \
;         __builtin_amdgcn_global_load_lds((const unsigned*)((const char*)(gbase) + (voff)[_i]), (LAS unsigned*)(lds + (bufoff) + ldsw + _i * 8192), 16, 0, 0); } while (0)
; #define PG8_LDA(dst, b, h) do { _Pragma("unroll") for (int m = 0; m < 4; ++m) _Pragma("unroll") for (int k = 0; k < 2; ++k) dst[m][k] = *(const LAS bf16x8*)(lds + PG8_SA(b, h) + aoff + m * 2048 + k * 1024); } while (0)
; #define PG8_LDB(dst, b, h) do { _Pragma("unroll") for (int n = 0; n < 2; ++n) _Pragma("unroll") for (int k = 0; k < 2; ++k) dst[n][k] = *(const LAS bf16x8*)(lds + PG8_SB(b, h) + boff + n * 2048 + k * 1024); } while (0)
; #define PG8_MMA(ai, bj, At, Bt) do { __builtin_amdgcn_s_setprio(1); _Pragma("unroll") for (int m = 0; m < 4; ++m) _Pragma("unroll") for (int n = 0; n < 2; ++n) _Pragma("unroll") for (int k = 0; k < 2; ++k) \
;         acc[ai][bj][m][n] = __builtin_amdgcn_mfma_f32_16x16x32_bf16(Bt[n][k], At[m][k], acc[ai][bj][m][n], 0, 0, 0); __builtin_amdgcn_s_setprio(0); } while (0)
; #define PG8_WAIT_V(n) asm volatile("s_waitcnt vmcnt(" #n ")" ::: "memory")
; #define PG8_WAIT_L(n) asm volatile("s_waitcnt lgkmcnt(" #n ")" ::: "memory")
; #define PG8_BAR __builtin_amdgcn_s_barrier()
; #define PG8_SCHED __builtin_amdgcn_sched_barrier(0)
; template <class Epi>
; DEVI void gemm_phase(LAS unsigned char* lds, const Gemm g, const Epi& E) {
;     ...
;             PG8_STAGE(PG8_SB(0, 1), b2 + hstepB, voffB);
;             PG8_WAIT_V(6); PG8_BAR; PG8_MMA(1, 1, At, B1); PG8_BAR;
;             PG8_LDB(B0, 1, 0); PG8_SCHED; PG8_LDA(At, 1, 0); PG8_STAGE(PG8_SA(0, 1), a2 + hstepA, voffA);
;             PG8_WAIT_L(8); PG8_BAR; PG8_WAIT_L(0); PG8_MMA(0, 0, At, B0); PG8_BAR; PG8_SCHED;
;             PG8_LDB(B1, 1, 1); PG8_STAGE(PG8_SB(1, 0), b3, voffB);
;             PG8_BAR; PG8_WAIT_L(0); PG8_MMA(0, 1, At, B1); PG8_BAR;
;             PG8_LDA(At, 1, 1); PG8_STAGE(PG8_SA(1, 0), a3, voffA);
	s_add_u32 s26, s16, 0x40000
	s_addc_u32 s27, s17, 0
	s_add_i32 s38, s38, s47
	s_mov_b32 m0, s38
	v_lshl_add_u64 v[130:131], s[26:27], 0, v[148:149]
	global_load_lds_dwordx4 v[130:131], off
	s_add_i32 m0, s38, 0x2000
	v_lshl_add_u64 v[130:131], s[26:27], 0, v[152:153]
	global_load_lds_dwordx4 v[130:131], off
	s_waitcnt vmcnt(6)
	s_barrier
	v_mfma_f32_16x16x32_bf16 v[66:69], v[230:233], v[184:187], 0
	v_mfma_f32_16x16x32_bf16 v[70:73], v[238:241], v[184:187], 0
	v_mfma_f32_16x16x32_bf16 v[46:49], v[230:233], v[192:195], 0
	v_mfma_f32_16x16x32_bf16 v[50:53], v[238:241], v[192:195], 0
	v_mfma_f32_16x16x32_bf16 v[26:29], v[230:233], v[214:217], 0
	v_mfma_f32_16x16x32_bf16 v[30:33], v[238:241], v[214:217], 0
	v_mfma_f32_16x16x32_bf16 v[10:13], v[230:233], v[222:225], 0
	v_mfma_f32_16x16x32_bf16 v[14:17], v[238:241], v[222:225], 0
	v_mfma_f32_16x16x32_bf16 v[66:69], v[234:237], v[188:191], v[66:69]
	v_mfma_f32_16x16x32_bf16 v[70:73], v[242:245], v[188:191], v[70:73]
	v_mfma_f32_16x16x32_bf16 v[46:49], v[234:237], v[206:209], v[46:49]
	v_mfma_f32_16x16x32_bf16 v[50:53], v[242:245], v[206:209], v[50:53]
	v_mfma_f32_16x16x32_bf16 v[26:29], v[234:237], v[218:221], v[26:29]
	v_mfma_f32_16x16x32_bf16 v[30:33], v[242:245], v[218:221], v[30:33]
	v_mfma_f32_16x16x32_bf16 v[10:13], v[234:237], v[226:229], v[10:13]
	v_mfma_f32_16x16x32_bf16 v[14:17], v[242:245], v[226:229], v[14:17]
	s_add_i32 s38, 0, 0x18000
	v_add_u32_e32 v8, s38, v199
	s_barrier
	ds_read_b128 v[130:133], v8
	ds_read_b128 v[134:137], v8 offset:1024
	ds_read_b128 v[138:141], v8 offset:2048
	ds_read_b128 v[142:145], v8 offset:3072
	s_add_u32 s26, s36, 0x40000
	s_addc_u32 s27, s37, 0
	s_mov_b32 m0, s69
	v_lshl_add_u64 v[230:231], s[26:27], 0, v[146:147]
	ds_read_b128 v[184:187], v204 offset:32768
	ds_read_b128 v[188:191], v204 offset:33792
	ds_read_b128 v[192:195], v204 offset:34816
	ds_read_b128 v[206:209], v204 offset:35840
	ds_read_b128 v[214:217], v204 offset:36864
	ds_read_b128 v[218:221], v204 offset:37888
	ds_read_b128 v[222:225], v204 offset:38912
	ds_read_b128 v[226:229], v204 offset:39936
	global_load_lds_dwordx4 v[230:231], off
	s_mov_b32 m0, s80
	v_lshl_add_u64 v[230:231], s[26:27], 0, v[150:151]
	global_load_lds_dwordx4 v[230:231], off
	s_waitcnt lgkmcnt(8)
	s_barrier
	s_waitcnt lgkmcnt(0)
	v_mfma_f32_16x16x32_bf16 v[126:129], v[130:133], v[184:187], v[126:129]
	v_mfma_f32_16x16x32_bf16 v[122:125], v[138:141], v[184:187], v[122:125]
	v_mfma_f32_16x16x32_bf16 v[114:117], v[130:133], v[192:195], v[114:117]
	v_mfma_f32_16x16x32_bf16 v[106:109], v[138:141], v[192:195], v[106:109]
	v_mfma_f32_16x16x32_bf16 v[102:105], v[130:133], v[214:217], v[102:105]
	v_mfma_f32_16x16x32_bf16 v[94:97], v[138:141], v[214:217], v[94:97]
	v_mfma_f32_16x16x32_bf16 v[82:85], v[130:133], v[222:225], v[82:85]
	v_mfma_f32_16x16x32_bf16 v[74:77], v[138:141], v[222:225], v[74:77]
	v_mfma_f32_16x16x32_bf16 v[126:129], v[134:137], v[188:191], v[126:129]
	v_mfma_f32_16x16x32_bf16 v[122:125], v[142:145], v[188:191], v[122:125]
	v_mfma_f32_16x16x32_bf16 v[114:117], v[134:137], v[206:209], v[114:117]
	v_mfma_f32_16x16x32_bf16 v[106:109], v[142:145], v[206:209], v[106:109]
	v_mfma_f32_16x16x32_bf16 v[102:105], v[134:137], v[218:221], v[102:105]
	v_mfma_f32_16x16x32_bf16 v[94:97], v[142:145], v[218:221], v[94:97]
	v_mfma_f32_16x16x32_bf16 v[82:85], v[134:137], v[226:229], v[82:85]
	v_mfma_f32_16x16x32_bf16 v[74:77], v[142:145], v[226:229], v[74:77]
	s_barrier
	s_add_i32 s26, 0, 0x1c000
	s_add_i32 s27, s38, s47
	v_add_u32_e32 v8, s26, v199
	v_lshl_add_u64 v[162:163], v[162:163], 0, s[70:71]
	s_mov_b32 m0, s27
	ds_read_b128 v[230:233], v8
	ds_read_b128 v[234:237], v8 offset:1024
	ds_read_b128 v[238:241], v8 offset:2048
	ds_read_b128 v[242:245], v8 offset:3072
	global_load_lds_dwordx4 v[162:163], off
	s_add_i32 m0, s27, 0x2000
	v_lshl_add_u64 v[162:163], v[164:165], 0, s[70:71]
	global_load_lds_dwordx4 v[162:163], off
	s_barrier
; #define PG8_STAGE(bufoff, gbase, voff) do { _Pragma("unroll") for (int _i = 0; _i < 2; ++_i) \
;         __builtin_amdgcn_global_load_lds((const unsigned*)((const char*)(gbase) + (voff)[_i]), (LAS unsigned*)(lds + (bufoff) + ldsw + _i * 8192), 16, 0, 0); } while (0)
; #define PG8_LDA(dst, b, h) do { _Pragma("unroll") for (int m = 0; m < 4; ++m) _Pragma("unroll") for (int k = 0; k < 2; ++k) dst[m][k] = *(const LAS bf16x8*)(lds + PG8_SA(b, h) + aoff + m * 2048 + k * 1024); } while (0)
; #define PG8_MMA(ai, bj, At, Bt) do { __builtin_amdgcn_s_setprio(1); _Pragma("unroll") for (int m = 0; m < 4; ++m) _Pragma("unroll") for (int n = 0; n < 2; ++n) _Pragma("unroll") for (int k = 0; k < 2; ++k) \
;         acc[ai][bj][m][n] = __builtin_amdgcn_mfma_f32_16x16x32_bf16(Bt[n][k], At[m][k], acc[ai][bj][m][n], 0, 0, 0); __builtin_amdgcn_s_setprio(0); } while (0)
; #define PG8_WAIT_V(n) asm volatile("s_waitcnt vmcnt(" #n ")" ::: "memory")
; #define PG8_WAIT_L(n) asm volatile("s_waitcnt lgkmcnt(" #n ")" ::: "memory")
; #define PG8_BAR __builtin_amdgcn_s_barrier()
; #define PG8_SCHED __builtin_amdgcn_sched_barrier(0)
; template <class Epi>
; DEVI void gemm_phase(LAS unsigned char* lds, const Gemm g, const Epi& E) {
;     ...
;             PG8_LDA(At, 1, 1); PG8_STAGE(PG8_SA(1, 0), a3, voffA);
;             PG8_BAR; PG8_WAIT_L(0); PG8_MMA(1, 0, At, B0); PG8_BAR; PG8_SCHED;
;             PG8_STAGE(PG8_SB(1, 1), b3 + hstepB, voffB);
;             PG8_WAIT_V(6); PG8_BAR; PG8_MMA(1, 1, At, B1); PG8_BAR;
	s_waitcnt lgkmcnt(0)
	v_mfma_f32_16x16x32_bf16 v[118:121], v[230:233], v[184:187], v[118:121]
	v_mfma_f32_16x16x32_bf16 v[110:113], v[238:241], v[184:187], v[110:113]
	v_mfma_f32_16x16x32_bf16 v[98:101], v[230:233], v[192:195], v[98:101]
	v_mfma_f32_16x16x32_bf16 v[90:93], v[238:241], v[192:195], v[90:93]
	v_mfma_f32_16x16x32_bf16 v[86:89], v[230:233], v[214:217], v[86:89]
	v_mfma_f32_16x16x32_bf16 v[78:81], v[238:241], v[214:217], v[78:81]
	v_mfma_f32_16x16x32_bf16 v[54:57], v[230:233], v[222:225], v[54:57]
	v_mfma_f32_16x16x32_bf16 v[34:37], v[238:241], v[222:225], v[34:37]
	v_mfma_f32_16x16x32_bf16 v[118:121], v[234:237], v[188:191], v[118:121]
	v_mfma_f32_16x16x32_bf16 v[110:113], v[242:245], v[188:191], v[110:113]
	v_mfma_f32_16x16x32_bf16 v[98:101], v[234:237], v[206:209], v[98:101]
	v_mfma_f32_16x16x32_bf16 v[90:93], v[242:245], v[206:209], v[90:93]
	v_mfma_f32_16x16x32_bf16 v[86:89], v[234:237], v[218:221], v[86:89]
	v_mfma_f32_16x16x32_bf16 v[78:81], v[242:245], v[218:221], v[78:81]
	v_mfma_f32_16x16x32_bf16 v[54:57], v[234:237], v[226:229], v[54:57]
	v_mfma_f32_16x16x32_bf16 v[34:37], v[242:245], v[226:229], v[34:37]
	s_mov_b32 m0, s81
	v_lshl_add_u64 v[162:163], v[202:203], 0, s[70:71]
	s_barrier
	ds_read_b128 v[184:187], v204 offset:49152
	ds_read_b128 v[188:191], v204 offset:50176
	ds_read_b128 v[192:195], v204 offset:51200
	ds_read_b128 v[206:209], v204 offset:52224
	ds_read_b128 v[214:217], v204 offset:53248
	ds_read_b128 v[218:221], v204 offset:54272
	ds_read_b128 v[222:225], v204 offset:55296
	ds_read_b128 v[226:229], v204 offset:56320
	global_load_lds_dwordx4 v[162:163], off
	s_mov_b32 m0, s82
	v_lshl_add_u64 v[162:163], v[246:247], 0, s[70:71]
	global_load_lds_dwordx4 v[162:163], off
	s_barrier
	s_waitcnt lgkmcnt(0)
	v_mfma_f32_16x16x32_bf16 v[58:61], v[130:133], v[184:187], v[58:61]
	v_mfma_f32_16x16x32_bf16 v[62:65], v[138:141], v[184:187], v[62:65]
	v_mfma_f32_16x16x32_bf16 v[38:41], v[130:133], v[192:195], v[38:41]
	v_mfma_f32_16x16x32_bf16 v[42:45], v[138:141], v[192:195], v[42:45]
	v_mfma_f32_16x16x32_bf16 v[18:21], v[130:133], v[214:217], v[18:21]
	v_mfma_f32_16x16x32_bf16 v[22:25], v[138:141], v[214:217], v[22:25]
	v_mfma_f32_16x16x32_bf16 v[0:3], v[130:133], v[222:225], v[0:3]
	v_mfma_f32_16x16x32_bf16 v[4:7], v[138:141], v[222:225], v[4:7]
	v_mfma_f32_16x16x32_bf16 v[58:61], v[134:137], v[188:191], v[58:61]
	v_mfma_f32_16x16x32_bf16 v[62:65], v[142:145], v[188:191], v[62:65]
	v_mfma_f32_16x16x32_bf16 v[38:41], v[134:137], v[206:209], v[38:41]
	v_mfma_f32_16x16x32_bf16 v[42:45], v[142:145], v[206:209], v[42:45]
	v_mfma_f32_16x16x32_bf16 v[18:21], v[134:137], v[218:221], v[18:21]
	v_mfma_f32_16x16x32_bf16 v[22:25], v[142:145], v[218:221], v[22:25]
	v_mfma_f32_16x16x32_bf16 v[0:3], v[134:137], v[226:229], v[0:3]
	v_mfma_f32_16x16x32_bf16 v[4:7], v[142:145], v[226:229], v[4:7]
	s_barrier
	s_add_u32 s16, s16, 0x40080
	s_addc_u32 s17, s17, 0
	s_add_i32 s26, s26, s47
	s_mov_b32 m0, s26
	v_lshl_add_u64 v[130:131], s[16:17], 0, v[148:149]
	global_load_lds_dwordx4 v[130:131], off
	s_add_i32 m0, s26, 0x2000
	v_lshl_add_u64 v[130:131], s[16:17], 0, v[152:153]
	global_load_lds_dwordx4 v[130:131], off
	s_waitcnt vmcnt(6)
	s_barrier
	v_mfma_f32_16x16x32_bf16 v[66:69], v[230:233], v[184:187], v[66:69]
	v_mfma_f32_16x16x32_bf16 v[70:73], v[238:241], v[184:187], v[70:73]
	v_mfma_f32_16x16x32_bf16 v[46:49], v[230:233], v[192:195], v[46:49]
	v_mfma_f32_16x16x32_bf16 v[50:53], v[238:241], v[192:195], v[50:53]
	v_mfma_f32_16x16x32_bf16 v[26:29], v[230:233], v[214:217], v[26:29]
	v_mfma_f32_16x16x32_bf16 v[30:33], v[238:241], v[214:217], v[30:33]
	v_mfma_f32_16x16x32_bf16 v[10:13], v[230:233], v[222:225], v[10:13]
	v_mfma_f32_16x16x32_bf16 v[14:17], v[238:241], v[222:225], v[14:17]
	v_mfma_f32_16x16x32_bf16 v[66:69], v[234:237], v[188:191], v[66:69]
	v_mfma_f32_16x16x32_bf16 v[70:73], v[242:245], v[188:191], v[70:73]
	v_mfma_f32_16x16x32_bf16 v[46:49], v[234:237], v[206:209], v[46:49]
	v_mfma_f32_16x16x32_bf16 v[50:53], v[242:245], v[206:209], v[50:53]
	v_mfma_f32_16x16x32_bf16 v[26:29], v[234:237], v[218:221], v[26:29]
	v_mfma_f32_16x16x32_bf16 v[30:33], v[242:245], v[218:221], v[30:33]
	v_mfma_f32_16x16x32_bf16 v[10:13], v[234:237], v[226:229], v[10:13]
	v_mfma_f32_16x16x32_bf16 v[14:17], v[242:245], v[226:229], v[14:17]
	s_add_i32 s19, s19, 2
	s_add_u32 s14, s14, 0x100
	s_addc_u32 s15, s15, 0
	s_add_u32 s9, s9, 0x100
	s_addc_u32 s18, s18, 0
	s_cmp_gt_u32 s19, 13
	s_barrier

; #define PG8_STAGE(bufoff, gbase, voff) do { _Pragma("unroll") for (int _i = 0; _i < 2; ++_i) \
;         __builtin_amdgcn_global_load_lds((const unsigned*)((const char*)(gbase) + (voff)[_i]), (LAS unsigned*)(lds + (bufoff) + ldsw + _i * 8192), 16, 0, 0); } while (0)
; #define PG8_LDA(dst, b, h) do { _Pragma("unroll") for (int m = 0; m < 4; ++m) _Pragma("unroll") for (int k = 0; k < 2; ++k) dst[m][k] = *(const LAS bf16x8*)(lds + PG8_SA(b, h) + aoff + m * 2048 + k * 1024); } while (0)
; #define PG8_LDB(dst, b, h) do { _Pragma("unroll") for (int n = 0; n < 2; ++n) _Pragma("unroll") for (int k = 0; k < 2; ++k) dst[n][k] = *(const LAS bf16x8*)(lds + PG8_SB(b, h) + boff + n * 2048 + k * 1024); } while (0)
; #define PG8_MMA(ai, bj, At, Bt) do { __builtin_amdgcn_s_setprio(1); _Pragma("unroll") for (int m = 0; m < 4; ++m) _Pragma("unroll") for (int n = 0; n < 2; ++n) _Pragma("unroll") for (int k = 0; k < 2; ++k) \
;         acc[ai][bj][m][n] = __builtin_amdgcn_mfma_f32_16x16x32_bf16(Bt[n][k], At[m][k], acc[ai][bj][m][n], 0, 0, 0); __builtin_amdgcn_s_setprio(0); } while (0)
; #define PG8_WAIT_V(n) asm volatile("s_waitcnt vmcnt(" #n ")" ::: "memory")
; #define PG8_WAIT_L(n) asm volatile("s_waitcnt lgkmcnt(" #n ")" ::: "memory")
; #define PG8_BAR __builtin_amdgcn_s_barrier()
; #define PG8_SCHED __builtin_amdgcn_sched_barrier(0)
; template <class Epi>
; DEVI void gemm_phase(LAS unsigned char* lds, const Gemm g, const Epi& E) {
;     ...
;             const bool last = (t == nt - 2);
;             const char* a1 = cA + (size_t)(t + 1) * kstep;
;             const char* a2 = last ? nA : cA + (size_t)(t + 2) * kstep; const char* b2 = last ? nB : cB + (size_t)(t + 2) * kstep;
;             const char* a3 = a2 + kstep; const char* b3 = b2 + kstep;
;             PG8_LDB(B0, 0, 0); PG8_SCHED; PG8_LDA(At, 0, 0); PG8_STAGE(PG8_SA(1, 1), a1 + hstepA, voffA);
;             PG8_WAIT_L(8); PG8_BAR; PG8_WAIT_L(0); PG8_MMA(0, 0, At, B0); PG8_BAR; PG8_SCHED;
;             PG8_LDB(B1, 0, 1); PG8_STAGE(PG8_SB(0, 0), b2, voffB);
;             PG8_BAR; PG8_WAIT_L(0); PG8_MMA(0, 1, At, B1); PG8_BAR;
;             PG8_LDA(At, 0, 1); PG8_STAGE(PG8_SA(0, 0), a2, voffA);
;             PG8_BAR; PG8_WAIT_L(0); PG8_MMA(1, 0, At, B0); PG8_BAR; PG8_SCHED;
;             PG8_STAGE(PG8_SB(0, 1), b2 + hstepB, voffB);
;             PG8_WAIT_V(6); PG8_BAR; PG8_MMA(1, 1, At, B1); PG8_BAR;
.LBB0_1126:
	v_cmp_lt_i64_e32 vcc, s[10:11], v[170:171]
	s_lshl_b64 s[10:11], s[6:7], 18
	v_readlane_b32 s16, v253, 48
	v_readlane_b32 s17, v253, 49
	s_add_u32 s5, s16, s10
	s_addc_u32 s7, s17, s11
	s_and_b64 s[10:11], vcc, exec
	s_cselect_b32 s11, s7, s15
	s_cselect_b32 s10, s5, s14
	s_add_u32 s5, s14, 0x100
	s_addc_u32 s7, s15, 0
	s_mov_b32 s47, -2
	s_add_u32 s14, s12, 0x100
	s_addc_u32 s15, s13, 0
	s_add_i32 s48, 0, 0x10000
	v_add_u32_e32 v81, s48, v79
	ds_read_b128 v[82:85], v81
	ds_read_b128 v[86:89], v81 offset:1024
	ds_read_b128 v[90:93], v81 offset:2048
	ds_read_b128 v[94:97], v81 offset:3072
	s_cmp_eq_u32 s47, 4
	s_cselect_b32 s37, s9, s15
	s_cselect_b32 s36, s8, s14
	s_cselect_b32 s17, s11, s7
	s_cselect_b32 s16, s10, s5
	v_lshl_add_u64 v[130:131], s[12:13], 0, v[74:75]
	s_add_i32 m0, s18, 0xc000
	ds_read_b128 v[98:101], v80
	ds_read_b128 v[102:105], v80 offset:1024
	ds_read_b128 v[106:109], v80 offset:2048
	ds_read_b128 v[110:113], v80 offset:3072
	ds_read_b128 v[114:117], v80 offset:4096
	ds_read_b128 v[118:121], v80 offset:5120
	ds_read_b128 v[122:125], v80 offset:6144
	ds_read_b128 v[126:129], v80 offset:7168
	global_load_lds_dwordx4 v[130:131], off
	s_add_i32 m0, s18, 0xe000
	v_lshl_add_u64 v[130:131], s[12:13], 0, v[76:77]
	global_load_lds_dwordx4 v[130:131], off
	s_waitcnt lgkmcnt(8)
	s_barrier
	s_waitcnt lgkmcnt(0)
	v_mfma_f32_16x16x32_bf16 v[62:65], v[82:85], v[98:101], 0
	v_mfma_f32_16x16x32_bf16 v[58:61], v[90:93], v[98:101], 0
	v_mfma_f32_16x16x32_bf16 v[54:57], v[82:85], v[106:109], 0
	v_mfma_f32_16x16x32_bf16 v[50:53], v[90:93], v[106:109], 0
	v_mfma_f32_16x16x32_bf16 v[46:49], v[82:85], v[114:117], 0
	v_mfma_f32_16x16x32_bf16 v[42:45], v[90:93], v[114:117], 0
	v_mfma_f32_16x16x32_bf16 v[38:41], v[82:85], v[122:125], 0
	v_mfma_f32_16x16x32_bf16 v[34:37], v[90:93], v[122:125], 0
	v_mfma_f32_16x16x32_bf16 v[62:65], v[86:89], v[102:105], v[62:65]
	v_mfma_f32_16x16x32_bf16 v[58:61], v[94:97], v[102:105], v[58:61]
	v_mfma_f32_16x16x32_bf16 v[54:57], v[86:89], v[110:113], v[54:57]
	v_mfma_f32_16x16x32_bf16 v[50:53], v[94:97], v[110:113], v[50:53]
	v_mfma_f32_16x16x32_bf16 v[46:49], v[86:89], v[118:121], v[46:49]
	v_mfma_f32_16x16x32_bf16 v[42:45], v[94:97], v[118:121], v[42:45]
	v_mfma_f32_16x16x32_bf16 v[38:41], v[86:89], v[126:129], v[38:41]
	v_mfma_f32_16x16x32_bf16 v[34:37], v[94:97], v[126:129], v[34:37]
	s_barrier
	s_add_i32 s12, s48, s1
	v_lshl_add_u64 v[130:131], s[16:17], 0, v[70:71]
	s_mov_b32 m0, s12
	v_lshl_add_u64 v[132:133], s[16:17], 0, v[66:67]
	global_load_lds_dwordx4 v[130:131], off
	s_add_i32 m0, s12, 0x2000
	s_nop 0
	global_load_lds_dwordx4 v[132:133], off
	s_barrier
	s_waitcnt lgkmcnt(0)
	s_mov_b32 m0, s18
	v_lshl_add_u64 v[134:135], s[36:37], 0, v[72:73]
	s_barrier
	ds_read_b128 v[98:101], v80 offset:16384
	ds_read_b128 v[102:105], v80 offset:17408
	ds_read_b128 v[106:109], v80 offset:18432
	ds_read_b128 v[110:113], v80 offset:19456
	ds_read_b128 v[114:117], v80 offset:20480
	ds_read_b128 v[118:121], v80 offset:21504
	ds_read_b128 v[122:125], v80 offset:22528
	ds_read_b128 v[126:129], v80 offset:23552
	global_load_lds_dwordx4 v[134:135], off
	s_mov_b32 m0, s19
	v_lshl_add_u64 v[136:137], s[36:37], 0, v[68:69]
	global_load_lds_dwordx4 v[136:137], off
	s_barrier
	s_waitcnt lgkmcnt(0)
	v_mfma_f32_16x16x32_bf16 v[30:33], v[82:85], v[98:101], 0
	v_mfma_f32_16x16x32_bf16 v[26:29], v[90:93], v[98:101], 0
	v_mfma_f32_16x16x32_bf16 v[22:25], v[82:85], v[106:109], 0
	v_mfma_f32_16x16x32_bf16 v[18:21], v[90:93], v[106:109], 0
	v_mfma_f32_16x16x32_bf16 v[14:17], v[82:85], v[114:117], 0
	v_mfma_f32_16x16x32_bf16 v[10:13], v[90:93], v[114:117], 0
	v_mfma_f32_16x16x32_bf16 v[4:7], v[82:85], v[122:125], 0
	v_mfma_f32_16x16x32_bf16 v[0:3], v[90:93], v[122:125], 0
	v_mfma_f32_16x16x32_bf16 v[30:33], v[86:89], v[102:105], v[30:33]
	v_mfma_f32_16x16x32_bf16 v[26:29], v[94:97], v[102:105], v[26:29]
	v_mfma_f32_16x16x32_bf16 v[22:25], v[86:89], v[110:113], v[22:25]
	v_mfma_f32_16x16x32_bf16 v[18:21], v[94:97], v[110:113], v[18:21]
	v_mfma_f32_16x16x32_bf16 v[14:17], v[86:89], v[118:121], v[14:17]
	v_mfma_f32_16x16x32_bf16 v[10:13], v[94:97], v[118:121], v[10:13]
	v_mfma_f32_16x16x32_bf16 v[4:7], v[86:89], v[126:129], v[4:7]
	v_mfma_f32_16x16x32_bf16 v[0:3], v[94:97], v[126:129], v[0:3]
	s_barrier
	s_add_u32 s12, s16, 0x20000
	s_addc_u32 s13, s17, 0
	s_mov_b32 m0, s26
	v_lshl_add_u64 v[82:83], s[12:13], 0, v[70:71]
	global_load_lds_dwordx4 v[82:83], off
	s_mov_b32 m0, s27
	v_lshl_add_u64 v[82:83], s[12:13], 0, v[66:67]
	global_load_lds_dwordx4 v[82:83], off
	s_waitcnt vmcnt(6)
	s_barrier
; #define PG8_STAGE(bufoff, gbase, voff) do { _Pragma("unroll") for (int _i = 0; _i < 2; ++_i) \
;         __builtin_amdgcn_global_load_lds((const unsigned*)((const char*)(gbase) + (voff)[_i]), (LAS unsigned*)(lds + (bufoff) + ldsw + _i * 8192), 16, 0, 0); } while (0)
; #define PG8_LDA(dst, b, h) do { _Pragma("unroll") for (int m = 0; m < 4; ++m) _Pragma("unroll") for (int k = 0; k < 2; ++k) dst[m][k] = *(const LAS bf16x8*)(lds + PG8_SA(b, h) + aoff + m * 2048 + k * 1024); } while (0)
; #define PG8_LDB(dst, b, h) do { _Pragma("unroll") for (int n = 0; n < 2; ++n) _Pragma("unroll") for (int k = 0; k < 2; ++k) dst[n][k] = *(const LAS bf16x8*)(lds + PG8_SB(b, h) + boff + n * 2048 + k * 1024); } while (0)
; #define PG8_MMA(ai, bj, At, Bt) do { __builtin_amdgcn_s_setprio(1); _Pragma("unroll") for (int m = 0; m < 4; ++m) _Pragma("unroll") for (int n = 0; n < 2; ++n) _Pragma("unroll") for (int k = 0; k < 2; ++k) \
;         acc[ai][bj][m][n] = __builtin_amdgcn_mfma_f32_16x16x32_bf16(Bt[n][k], At[m][k], acc[ai][bj][m][n], 0, 0, 0); __builtin_amdgcn_s_setprio(0); } while (0)
; #define PG8_WAIT_V(n) asm volatile("s_waitcnt vmcnt(" #n ")" ::: "memory")
; #define PG8_WAIT_L(n) asm volatile("s_waitcnt lgkmcnt(" #n ")" ::: "memory")
; #define PG8_BAR __builtin_amdgcn_s_barrier()
; #define PG8_SCHED __builtin_amdgcn_sched_barrier(0)
; template <class Epi>
; DEVI void gemm_phase(LAS unsigned char* lds, const Gemm g, const Epi& E) {
;     ...
;             PG8_LDB(B0, 1, 0); PG8_SCHED; PG8_LDA(At, 1, 0); PG8_STAGE(PG8_SA(0, 1), a2 + hstepA, voffA);
;             PG8_WAIT_L(8); PG8_BAR; PG8_WAIT_L(0); PG8_MMA(0, 0, At, B0); PG8_BAR; PG8_SCHED;
;             PG8_LDB(B1, 1, 1); PG8_STAGE(PG8_SB(1, 0), b3, voffB);
;             PG8_BAR; PG8_WAIT_L(0); PG8_MMA(0, 1, At, B1); PG8_BAR;
;             PG8_LDA(At, 1, 1); PG8_STAGE(PG8_SA(1, 0), a3, voffA);
;             PG8_BAR; PG8_WAIT_L(0); PG8_MMA(1, 0, At, B0); PG8_BAR; PG8_SCHED;
;             PG8_STAGE(PG8_SB(1, 1), b3 + hstepB, voffB);
;             PG8_WAIT_V(6); PG8_BAR; PG8_MMA(1, 1, At, B1); PG8_BAR;
	s_add_i32 s48, 0, 0x18000
	v_add_u32_e32 v81, s48, v79
	s_barrier
	ds_read_b128 v[82:85], v81
	ds_read_b128 v[86:89], v81 offset:1024
	ds_read_b128 v[90:93], v81 offset:2048
	ds_read_b128 v[94:97], v81 offset:3072
	s_add_u32 s12, s36, 0x28000
	s_addc_u32 s13, s37, 0
	s_mov_b32 m0, s38
	v_lshl_add_u64 v[138:139], s[12:13], 0, v[72:73]
	ds_read_b128 v[98:101], v80 offset:32768
	ds_read_b128 v[102:105], v80 offset:33792
	ds_read_b128 v[106:109], v80 offset:34816
	ds_read_b128 v[110:113], v80 offset:35840
	ds_read_b128 v[114:117], v80 offset:36864
	ds_read_b128 v[118:121], v80 offset:37888
	ds_read_b128 v[122:125], v80 offset:38912
	ds_read_b128 v[126:129], v80 offset:39936
	global_load_lds_dwordx4 v[138:139], off
	s_mov_b32 m0, s39
	v_lshl_add_u64 v[138:139], s[12:13], 0, v[68:69]
	global_load_lds_dwordx4 v[138:139], off
	s_waitcnt lgkmcnt(8)
	s_barrier
	s_waitcnt lgkmcnt(0)
	v_mfma_f32_16x16x32_bf16 v[62:65], v[82:85], v[98:101], v[62:65]
	v_mfma_f32_16x16x32_bf16 v[58:61], v[90:93], v[98:101], v[58:61]
	v_mfma_f32_16x16x32_bf16 v[54:57], v[82:85], v[106:109], v[54:57]
	v_mfma_f32_16x16x32_bf16 v[50:53], v[90:93], v[106:109], v[50:53]
	v_mfma_f32_16x16x32_bf16 v[46:49], v[82:85], v[114:117], v[46:49]
	v_mfma_f32_16x16x32_bf16 v[42:45], v[90:93], v[114:117], v[42:45]
	v_mfma_f32_16x16x32_bf16 v[38:41], v[82:85], v[122:125], v[38:41]
	v_mfma_f32_16x16x32_bf16 v[34:37], v[90:93], v[122:125], v[34:37]
	v_mfma_f32_16x16x32_bf16 v[62:65], v[86:89], v[102:105], v[62:65]
	v_mfma_f32_16x16x32_bf16 v[58:61], v[94:97], v[102:105], v[58:61]
	v_mfma_f32_16x16x32_bf16 v[54:57], v[86:89], v[110:113], v[54:57]
	v_mfma_f32_16x16x32_bf16 v[50:53], v[94:97], v[110:113], v[50:53]
	v_mfma_f32_16x16x32_bf16 v[46:49], v[86:89], v[118:121], v[46:49]
	v_mfma_f32_16x16x32_bf16 v[42:45], v[94:97], v[118:121], v[42:45]
	v_mfma_f32_16x16x32_bf16 v[38:41], v[86:89], v[126:129], v[38:41]
	v_mfma_f32_16x16x32_bf16 v[34:37], v[94:97], v[126:129], v[34:37]
	s_barrier
	s_add_i32 s12, s48, s1
	s_mov_b32 m0, s12
	v_lshl_add_u64 v[98:99], v[130:131], 0, s[70:71]
	global_load_lds_dwordx4 v[98:99], off
	s_add_i32 m0, s12, 0x2000
	v_lshl_add_u64 v[98:99], v[132:133], 0, s[70:71]
	global_load_lds_dwordx4 v[98:99], off
	s_barrier
	s_waitcnt lgkmcnt(0)
	s_mov_b32 m0, s41
	v_lshl_add_u64 v[130:131], v[134:135], 0, s[70:71]
	s_barrier
	ds_read_b128 v[98:101], v80 offset:49152
	ds_read_b128 v[102:105], v80 offset:50176
	ds_read_b128 v[106:109], v80 offset:51200
	ds_read_b128 v[110:113], v80 offset:52224
	ds_read_b128 v[114:117], v80 offset:53248
	ds_read_b128 v[118:121], v80 offset:54272
	ds_read_b128 v[122:125], v80 offset:55296
	ds_read_b128 v[126:129], v80 offset:56320
	global_load_lds_dwordx4 v[130:131], off
	s_mov_b32 m0, s42
	v_lshl_add_u64 v[130:131], v[136:137], 0, s[70:71]
	global_load_lds_dwordx4 v[130:131], off
	s_barrier
	s_waitcnt lgkmcnt(0)
	v_mfma_f32_16x16x32_bf16 v[30:33], v[82:85], v[98:101], v[30:33]
	v_mfma_f32_16x16x32_bf16 v[26:29], v[90:93], v[98:101], v[26:29]
	v_mfma_f32_16x16x32_bf16 v[22:25], v[82:85], v[106:109], v[22:25]
	v_mfma_f32_16x16x32_bf16 v[18:21], v[90:93], v[106:109], v[18:21]
	v_mfma_f32_16x16x32_bf16 v[14:17], v[82:85], v[114:117], v[14:17]
	v_mfma_f32_16x16x32_bf16 v[10:13], v[90:93], v[114:117], v[10:13]
	v_mfma_f32_16x16x32_bf16 v[4:7], v[82:85], v[122:125], v[4:7]
	v_mfma_f32_16x16x32_bf16 v[0:3], v[90:93], v[122:125], v[0:3]
	v_mfma_f32_16x16x32_bf16 v[30:33], v[86:89], v[102:105], v[30:33]
	v_mfma_f32_16x16x32_bf16 v[26:29], v[94:97], v[102:105], v[26:29]
	v_mfma_f32_16x16x32_bf16 v[22:25], v[86:89], v[110:113], v[22:25]
	v_mfma_f32_16x16x32_bf16 v[18:21], v[94:97], v[110:113], v[18:21]
	v_mfma_f32_16x16x32_bf16 v[14:17], v[86:89], v[118:121], v[14:17]
	v_mfma_f32_16x16x32_bf16 v[10:13], v[94:97], v[118:121], v[10:13]
	v_mfma_f32_16x16x32_bf16 v[4:7], v[86:89], v[126:129], v[4:7]
	v_mfma_f32_16x16x32_bf16 v[0:3], v[94:97], v[126:129], v[0:3]
	s_barrier
	s_add_u32 s12, s16, 0x20080
	s_addc_u32 s13, s17, 0
	s_mov_b32 m0, s43
	v_lshl_add_u64 v[82:83], s[12:13], 0, v[70:71]
	global_load_lds_dwordx4 v[82:83], off
	s_mov_b32 m0, s44
	v_lshl_add_u64 v[82:83], s[12:13], 0, v[66:67]
	global_load_lds_dwordx4 v[82:83], off
	s_waitcnt vmcnt(6)
	s_barrier
	s_add_i32 s47, s47, 2
	s_add_u32 s5, s5, 0x100
	s_addc_u32 s7, s7, 0
	s_cmp_gt_u32 s47, 5
	s_mov_b64 s[12:13], s[14:15]
	s_barrier

; DEVI size_t gemm_offB(const Gemm& g, const Unit& u) { return (g.split ? (size_t)(u.b >> 2) * g.sB + (size_t)(u.b & 3) * g.sB_lo : (size_t)u.b * g.sB) + (size_t)(u.pm >> g.pmsh) * g.sBpm; }
; #define PG8_STAGE(bufoff, gbase, voff) do { _Pragma("unroll") for (int _i = 0; _i < 2; ++_i) \
;         __builtin_amdgcn_global_load_lds((const unsigned*)((const char*)(gbase) + (voff)[_i]), (LAS unsigned*)(lds + (bufoff) + ldsw + _i * 8192), 16, 0, 0); } while (0)
; #define PG8_LDA(dst, b, h) do { _Pragma("unroll") for (int m = 0; m < 4; ++m) _Pragma("unroll") for (int k = 0; k < 2; ++k) dst[m][k] = *(const LAS bf16x8*)(lds + PG8_SA(b, h) + aoff + m * 2048 + k * 1024); } while (0)
; #define PG8_LDB(dst, b, h) do { _Pragma("unroll") for (int n = 0; n < 2; ++n) _Pragma("unroll") for (int k = 0; k < 2; ++k) dst[n][k] = *(const LAS bf16x8*)(lds + PG8_SB(b, h) + boff + n * 2048 + k * 1024); } while (0)
; #define PG8_WAIT_V(n) asm volatile("s_waitcnt vmcnt(" #n ")" ::: "memory")
; #define PG8_BAR __builtin_amdgcn_s_barrier()
; template <class Epi>
; DEVI void gemm_phase(LAS unsigned char* lds, const Gemm g, const Epi& E) {
;     ...
;         const bool has_next = unit_next(g, ui + 1, nxt);
;         const char* nA = has_next ? (const char*)g.A + gemm_offA(g, nxt) * 2 + (size_t)nxt.pm * tstepA : cA;
;         const char* nB = has_next ? (const char*)g.Bt + gemm_offB(g, nxt) * 2 + (size_t)nxt.pn * tstepB : cB;
;         for (int t = 0; t < nt; t += 2) {
;             const bool last = (t == nt - 2);
;             const char* a1 = cA + (size_t)(t + 1) * kstep;
;             const char* a2 = last ? nA : cA + (size_t)(t + 2) * kstep; const char* b2 = last ? nB : cB + (size_t)(t + 2) * kstep;
;             const char* a3 = a2 + kstep; const char* b3 = b2 + kstep;
;             PG8_LDB(B0, 0, 0); PG8_SCHED; PG8_LDA(At, 0, 0); PG8_STAGE(PG8_SA(1, 1), a1 + hstepA, voffA);
;             PG8_WAIT_L(8); PG8_BAR; PG8_WAIT_L(0); PG8_MMA(0, 0, At, B0); PG8_BAR; PG8_SCHED;
;             PG8_LDB(B1, 0, 1); PG8_STAGE(PG8_SB(0, 0), b2, voffB);
;             PG8_BAR; PG8_WAIT_L(0); PG8_MMA(0, 1, At, B1); PG8_BAR;
;             PG8_LDA(At, 0, 1); PG8_STAGE(PG8_SA(0, 0), a2, voffA);
;             PG8_BAR; PG8_WAIT_L(0); PG8_MMA(1, 0, At, B0); PG8_BAR; PG8_SCHED;
;             PG8_STAGE(PG8_SB(0, 1), b2 + hstepB, voffB);
;             PG8_WAIT_V(6); PG8_BAR; PG8_MMA(1, 1, At, B1); PG8_BAR;
.LBB0_1277:
	s_add_u32 s19, s12, 0x100
	s_addc_u32 s26, s13, 0
	s_mov_b32 s27, -2
	s_add_u32 s12, s10, 0x100
	s_addc_u32 s13, s11, 0
	s_add_i32 s38, 0, 0x10000
	v_add_u32_e32 v146, s38, v149
	ds_read_b128 v[142:145], v146
	ds_read_b128 v[176:179], v146 offset:1024
	ds_read_b128 v[180:183], v146 offset:2048
	ds_read_b128 v[184:187], v146 offset:3072
	s_cmp_eq_u32 s27, 6
	s_cselect_b32 s17, s5, s13
	s_cselect_b32 s16, s4, s12
	s_cselect_b32 s15, s7, s26
	s_cselect_b32 s14, s6, s19
	v_lshl_add_u64 v[146:147], s[10:11], 0, v[138:139]
	s_add_i32 m0, s46, 0xc000
	ds_read_b128 v[188:191], v151
	ds_read_b128 v[192:195], v151 offset:1024
	ds_read_b128 v[196:199], v151 offset:2048
	ds_read_b128 v[200:203], v151 offset:3072
	ds_read_b128 v[204:207], v151 offset:4096
	ds_read_b128 v[214:217], v151 offset:5120
	ds_read_b128 v[218:221], v151 offset:6144
	ds_read_b128 v[222:225], v151 offset:7168
	global_load_lds_dwordx4 v[146:147], off
	s_add_i32 m0, s46, 0xe000
	v_lshl_add_u64 v[146:147], s[10:11], 0, v[140:141]
	global_load_lds_dwordx4 v[146:147], off
	s_waitcnt lgkmcnt(8)
	s_barrier
	s_waitcnt lgkmcnt(0)
	v_mfma_f32_16x16x32_bf16 v[126:129], v[142:145], v[188:191], 0
	v_mfma_f32_16x16x32_bf16 v[122:125], v[180:183], v[188:191], 0
	v_mfma_f32_16x16x32_bf16 v[110:113], v[142:145], v[196:199], 0
	v_mfma_f32_16x16x32_bf16 v[106:109], v[180:183], v[196:199], 0
	v_mfma_f32_16x16x32_bf16 v[94:97], v[142:145], v[204:207], 0
	v_mfma_f32_16x16x32_bf16 v[90:93], v[180:183], v[204:207], 0
	v_mfma_f32_16x16x32_bf16 v[78:81], v[142:145], v[218:221], 0
	v_mfma_f32_16x16x32_bf16 v[74:77], v[180:183], v[218:221], 0
	v_mfma_f32_16x16x32_bf16 v[126:129], v[176:179], v[192:195], v[126:129]
	v_mfma_f32_16x16x32_bf16 v[122:125], v[184:187], v[192:195], v[122:125]
	v_mfma_f32_16x16x32_bf16 v[110:113], v[176:179], v[200:203], v[110:113]
	v_mfma_f32_16x16x32_bf16 v[106:109], v[184:187], v[200:203], v[106:109]
	v_mfma_f32_16x16x32_bf16 v[94:97], v[176:179], v[214:217], v[94:97]
	v_mfma_f32_16x16x32_bf16 v[90:93], v[184:187], v[214:217], v[90:93]
	v_mfma_f32_16x16x32_bf16 v[78:81], v[176:179], v[222:225], v[78:81]
	v_mfma_f32_16x16x32_bf16 v[74:77], v[184:187], v[222:225], v[74:77]
	s_barrier
	s_add_i32 s39, 0, 0x14000
	v_add_u32_e32 v146, s39, v149
	s_add_i32 s10, s38, s37
	ds_read_b128 v[226:229], v146
	ds_read_b128 v[230:233], v146 offset:1024
	ds_read_b128 v[234:237], v146 offset:2048
	ds_read_b128 v[238:241], v146 offset:3072
	v_lshl_add_u64 v[146:147], s[14:15], 0, v[8:9]
	s_mov_b32 m0, s10
	v_lshl_add_u64 v[152:153], s[14:15], 0, v[130:131]
	global_load_lds_dwordx4 v[146:147], off
	s_add_i32 m0, s10, 0x2000
	s_nop 0
	global_load_lds_dwordx4 v[152:153], off
	s_barrier
	s_waitcnt lgkmcnt(0)
	v_mfma_f32_16x16x32_bf16 v[118:121], v[226:229], v[188:191], 0
	v_mfma_f32_16x16x32_bf16 v[114:117], v[234:237], v[188:191], 0
	v_mfma_f32_16x16x32_bf16 v[102:105], v[226:229], v[196:199], 0
	v_mfma_f32_16x16x32_bf16 v[98:101], v[234:237], v[196:199], 0
	v_mfma_f32_16x16x32_bf16 v[86:89], v[226:229], v[204:207], 0
	v_mfma_f32_16x16x32_bf16 v[82:85], v[234:237], v[204:207], 0
	v_mfma_f32_16x16x32_bf16 v[70:73], v[226:229], v[218:221], 0
	v_mfma_f32_16x16x32_bf16 v[66:69], v[234:237], v[218:221], 0
	v_mfma_f32_16x16x32_bf16 v[118:121], v[230:233], v[192:195], v[118:121]
	v_mfma_f32_16x16x32_bf16 v[114:117], v[238:241], v[192:195], v[114:117]
	v_mfma_f32_16x16x32_bf16 v[102:105], v[230:233], v[200:203], v[102:105]
	v_mfma_f32_16x16x32_bf16 v[98:101], v[238:241], v[200:203], v[98:101]
	v_mfma_f32_16x16x32_bf16 v[86:89], v[230:233], v[214:217], v[86:89]
	v_mfma_f32_16x16x32_bf16 v[82:85], v[238:241], v[214:217], v[82:85]
	v_mfma_f32_16x16x32_bf16 v[70:73], v[230:233], v[222:225], v[70:73]
	v_mfma_f32_16x16x32_bf16 v[66:69], v[238:241], v[222:225], v[66:69]
	s_mov_b32 m0, s46
	v_lshl_add_u64 v[162:163], s[16:17], 0, v[134:135]
	s_barrier
	ds_read_b128 v[188:191], v151 offset:16384
	ds_read_b128 v[192:195], v151 offset:17408
	ds_read_b128 v[196:199], v151 offset:18432
	ds_read_b128 v[200:203], v151 offset:19456
	ds_read_b128 v[204:207], v151 offset:20480
	ds_read_b128 v[214:217], v151 offset:21504
	ds_read_b128 v[218:221], v151 offset:22528
	ds_read_b128 v[222:225], v151 offset:23552
	global_load_lds_dwordx4 v[162:163], off
	s_mov_b32 m0, s47
	v_lshl_add_u64 v[164:165], s[16:17], 0, v[132:133]
	global_load_lds_dwordx4 v[164:165], off
	s_barrier
	s_waitcnt lgkmcnt(0)
	v_mfma_f32_16x16x32_bf16 v[62:65], v[142:145], v[188:191], 0
	v_mfma_f32_16x16x32_bf16 v[58:61], v[180:183], v[188:191], 0
	v_mfma_f32_16x16x32_bf16 v[46:49], v[142:145], v[196:199], 0
	v_mfma_f32_16x16x32_bf16 v[42:45], v[180:183], v[196:199], 0
	v_mfma_f32_16x16x32_bf16 v[30:33], v[142:145], v[204:207], 0
	v_mfma_f32_16x16x32_bf16 v[26:29], v[180:183], v[204:207], 0
	v_mfma_f32_16x16x32_bf16 v[14:17], v[142:145], v[218:221], 0
	v_mfma_f32_16x16x32_bf16 v[10:13], v[180:183], v[218:221], 0
	v_mfma_f32_16x16x32_bf16 v[62:65], v[176:179], v[192:195], v[62:65]
	v_mfma_f32_16x16x32_bf16 v[58:61], v[184:187], v[192:195], v[58:61]
	v_mfma_f32_16x16x32_bf16 v[46:49], v[176:179], v[200:203], v[46:49]
	v_mfma_f32_16x16x32_bf16 v[42:45], v[184:187], v[200:203], v[42:45]
	v_mfma_f32_16x16x32_bf16 v[30:33], v[176:179], v[214:217], v[30:33]
	v_mfma_f32_16x16x32_bf16 v[26:29], v[184:187], v[214:217], v[26:29]
	v_mfma_f32_16x16x32_bf16 v[14:17], v[176:179], v[222:225], v[14:17]
	v_mfma_f32_16x16x32_bf16 v[10:13], v[184:187], v[222:225], v[10:13]
	s_barrier
	s_add_u32 s10, s14, 0x28000
	s_addc_u32 s11, s15, 0
	s_add_i32 s38, s39, s37
	s_mov_b32 m0, s38
	v_lshl_add_u64 v[142:143], s[10:11], 0, v[8:9]
	global_load_lds_dwordx4 v[142:143], off
	s_add_i32 m0, s38, 0x2000
	v_lshl_add_u64 v[142:143], s[10:11], 0, v[130:131]
	global_load_lds_dwordx4 v[142:143], off
	s_waitcnt vmcnt(6)
	s_barrier
; #define PG8_STAGE(bufoff, gbase, voff) do { _Pragma("unroll") for (int _i = 0; _i < 2; ++_i) \
;         __builtin_amdgcn_global_load_lds((const unsigned*)((const char*)(gbase) + (voff)[_i]), (LAS unsigned*)(lds + (bufoff) + ldsw + _i * 8192), 16, 0, 0); } while (0)
; #define PG8_LDA(dst, b, h) do { _Pragma("unroll") for (int m = 0; m < 4; ++m) _Pragma("unroll") for (int k = 0; k < 2; ++k) dst[m][k] = *(const LAS bf16x8*)(lds + PG8_SA(b, h) + aoff + m * 2048 + k * 1024); } while (0)
; #define PG8_LDB(dst, b, h) do { _Pragma("unroll") for (int n = 0; n < 2; ++n) _Pragma("unroll") for (int k = 0; k < 2; ++k) dst[n][k] = *(const LAS bf16x8*)(lds + PG8_SB(b, h) + boff + n * 2048 + k * 1024); } while (0)
; #define PG8_MMA(ai, bj, At, Bt) do { __builtin_amdgcn_s_setprio(1); _Pragma("unroll") for (int m = 0; m < 4; ++m) _Pragma("unroll") for (int n = 0; n < 2; ++n) _Pragma("unroll") for (int k = 0; k < 2; ++k) \
;         acc[ai][bj][m][n] = __builtin_amdgcn_mfma_f32_16x16x32_bf16(Bt[n][k], At[m][k], acc[ai][bj][m][n], 0, 0, 0); __builtin_amdgcn_s_setprio(0); } while (0)
; #define PG8_WAIT_V(n) asm volatile("s_waitcnt vmcnt(" #n ")" ::: "memory")
; #define PG8_WAIT_L(n) asm volatile("s_waitcnt lgkmcnt(" #n ")" ::: "memory")
; #define PG8_BAR __builtin_amdgcn_s_barrier()
; #define PG8_SCHED __builtin_amdgcn_sched_barrier(0)
; template <class Epi>
; DEVI void gemm_phase(LAS unsigned char* lds, const Gemm g, const Epi& E) {
;     ...
;             PG8_WAIT_V(6); PG8_BAR; PG8_MMA(1, 1, At, B1); PG8_BAR;
;             PG8_LDB(B0, 1, 0); PG8_SCHED; PG8_LDA(At, 1, 0); PG8_STAGE(PG8_SA(0, 1), a2 + hstepA, voffA);
;             PG8_WAIT_L(8); PG8_BAR; PG8_WAIT_L(0); PG8_MMA(0, 0, At, B0); PG8_BAR; PG8_SCHED;
;             PG8_LDB(B1, 1, 1); PG8_STAGE(PG8_SB(1, 0), b3, voffB);
;             PG8_BAR; PG8_WAIT_L(0); PG8_MMA(0, 1, At, B1); PG8_BAR;
;             PG8_LDA(At, 1, 1); PG8_STAGE(PG8_SA(1, 0), a3, voffA);
	v_mfma_f32_16x16x32_bf16 v[54:57], v[226:229], v[188:191], 0
	v_mfma_f32_16x16x32_bf16 v[50:53], v[234:237], v[188:191], 0
	v_mfma_f32_16x16x32_bf16 v[38:41], v[226:229], v[196:199], 0
	v_mfma_f32_16x16x32_bf16 v[34:37], v[234:237], v[196:199], 0
	v_mfma_f32_16x16x32_bf16 v[22:25], v[226:229], v[204:207], 0
	v_mfma_f32_16x16x32_bf16 v[18:21], v[234:237], v[204:207], 0
	v_mfma_f32_16x16x32_bf16 v[4:7], v[226:229], v[218:221], 0
	v_mfma_f32_16x16x32_bf16 v[0:3], v[234:237], v[218:221], 0
	v_mfma_f32_16x16x32_bf16 v[54:57], v[230:233], v[192:195], v[54:57]
	v_mfma_f32_16x16x32_bf16 v[50:53], v[238:241], v[192:195], v[50:53]
	v_mfma_f32_16x16x32_bf16 v[38:41], v[230:233], v[200:203], v[38:41]
	v_mfma_f32_16x16x32_bf16 v[34:37], v[238:241], v[200:203], v[34:37]
	v_mfma_f32_16x16x32_bf16 v[22:25], v[230:233], v[214:217], v[22:25]
	v_mfma_f32_16x16x32_bf16 v[18:21], v[238:241], v[214:217], v[18:21]
	v_mfma_f32_16x16x32_bf16 v[4:7], v[230:233], v[222:225], v[4:7]
	v_mfma_f32_16x16x32_bf16 v[0:3], v[238:241], v[222:225], v[0:3]
	s_add_i32 s38, 0, 0x18000
	v_add_u32_e32 v184, s38, v149
	s_barrier
	ds_read_b128 v[142:145], v184
	ds_read_b128 v[176:179], v184 offset:1024
	ds_read_b128 v[180:183], v184 offset:2048
	ds_read_b128 v[184:187], v184 offset:3072
	s_add_u32 s10, s16, 0x28000
	s_addc_u32 s11, s17, 0
	s_mov_b32 m0, s66
	v_lshl_add_u64 v[208:209], s[10:11], 0, v[134:135]
	ds_read_b128 v[188:191], v151 offset:32768
	ds_read_b128 v[192:195], v151 offset:33792
	ds_read_b128 v[196:199], v151 offset:34816
	ds_read_b128 v[200:203], v151 offset:35840
	ds_read_b128 v[204:207], v151 offset:36864
	ds_read_b128 v[214:217], v151 offset:37888
	ds_read_b128 v[218:221], v151 offset:38912
	ds_read_b128 v[222:225], v151 offset:39936
	global_load_lds_dwordx4 v[208:209], off
	s_mov_b32 m0, s68
	v_lshl_add_u64 v[208:209], s[10:11], 0, v[132:133]
	global_load_lds_dwordx4 v[208:209], off
	s_waitcnt lgkmcnt(8)
	s_barrier
	s_waitcnt lgkmcnt(0)
	v_mfma_f32_16x16x32_bf16 v[126:129], v[142:145], v[188:191], v[126:129]
	v_mfma_f32_16x16x32_bf16 v[122:125], v[180:183], v[188:191], v[122:125]
	v_mfma_f32_16x16x32_bf16 v[110:113], v[142:145], v[196:199], v[110:113]
	v_mfma_f32_16x16x32_bf16 v[106:109], v[180:183], v[196:199], v[106:109]
	v_mfma_f32_16x16x32_bf16 v[94:97], v[142:145], v[204:207], v[94:97]
	v_mfma_f32_16x16x32_bf16 v[90:93], v[180:183], v[204:207], v[90:93]
	v_mfma_f32_16x16x32_bf16 v[78:81], v[142:145], v[218:221], v[78:81]
	v_mfma_f32_16x16x32_bf16 v[74:77], v[180:183], v[218:221], v[74:77]
	v_mfma_f32_16x16x32_bf16 v[126:129], v[176:179], v[192:195], v[126:129]
	v_mfma_f32_16x16x32_bf16 v[122:125], v[184:187], v[192:195], v[122:125]
	v_mfma_f32_16x16x32_bf16 v[110:113], v[176:179], v[200:203], v[110:113]
	v_mfma_f32_16x16x32_bf16 v[106:109], v[184:187], v[200:203], v[106:109]
	v_mfma_f32_16x16x32_bf16 v[94:97], v[176:179], v[214:217], v[94:97]
	v_mfma_f32_16x16x32_bf16 v[90:93], v[184:187], v[214:217], v[90:93]
	v_mfma_f32_16x16x32_bf16 v[78:81], v[176:179], v[222:225], v[78:81]
	v_mfma_f32_16x16x32_bf16 v[74:77], v[184:187], v[222:225], v[74:77]
	s_barrier
	s_add_i32 s16, 0, 0x1c000
	s_add_i32 s10, s38, s37
	v_add_u32_e32 v208, s16, v149
	v_lshl_add_u64 v[146:147], v[146:147], 0, s[70:71]
	s_mov_b32 m0, s10
	ds_read_b128 v[226:229], v208
	ds_read_b128 v[230:233], v208 offset:1024
	ds_read_b128 v[234:237], v208 offset:2048
	ds_read_b128 v[238:241], v208 offset:3072
	global_load_lds_dwordx4 v[146:147], off
	s_add_i32 m0, s10, 0x2000
	v_lshl_add_u64 v[146:147], v[152:153], 0, s[70:71]
	global_load_lds_dwordx4 v[146:147], off
	s_barrier
; #define PG8_STAGE(bufoff, gbase, voff) do { _Pragma("unroll") for (int _i = 0; _i < 2; ++_i) \
;         __builtin_amdgcn_global_load_lds((const unsigned*)((const char*)(gbase) + (voff)[_i]), (LAS unsigned*)(lds + (bufoff) + ldsw + _i * 8192), 16, 0, 0); } while (0)
; #define PG8_LDA(dst, b, h) do { _Pragma("unroll") for (int m = 0; m < 4; ++m) _Pragma("unroll") for (int k = 0; k < 2; ++k) dst[m][k] = *(const LAS bf16x8*)(lds + PG8_SA(b, h) + aoff + m * 2048 + k * 1024); } while (0)
; #define PG8_MMA(ai, bj, At, Bt) do { __builtin_amdgcn_s_setprio(1); _Pragma("unroll") for (int m = 0; m < 4; ++m) _Pragma("unroll") for (int n = 0; n < 2; ++n) _Pragma("unroll") for (int k = 0; k < 2; ++k) \
;         acc[ai][bj][m][n] = __builtin_amdgcn_mfma_f32_16x16x32_bf16(Bt[n][k], At[m][k], acc[ai][bj][m][n], 0, 0, 0); __builtin_amdgcn_s_setprio(0); } while (0)
; #define PG8_WAIT_V(n) asm volatile("s_waitcnt vmcnt(" #n ")" ::: "memory")
; #define PG8_WAIT_L(n) asm volatile("s_waitcnt lgkmcnt(" #n ")" ::: "memory")
; #define PG8_BAR __builtin_amdgcn_s_barrier()
; #define PG8_SCHED __builtin_amdgcn_sched_barrier(0)
; template <class Epi>
; DEVI void gemm_phase(LAS unsigned char* lds, const Gemm g, const Epi& E) {
;     ...
;             PG8_BAR; PG8_WAIT_L(0); PG8_MMA(0, 1, At, B1); PG8_BAR;
;             PG8_LDA(At, 1, 1); PG8_STAGE(PG8_SA(1, 0), a3, voffA);
;             PG8_BAR; PG8_WAIT_L(0); PG8_MMA(1, 0, At, B0); PG8_BAR; PG8_SCHED;
;             PG8_STAGE(PG8_SB(1, 1), b3 + hstepB, voffB);
;             PG8_WAIT_V(6); PG8_BAR; PG8_MMA(1, 1, At, B1); PG8_BAR;
;         }
	s_waitcnt lgkmcnt(0)
	v_mfma_f32_16x16x32_bf16 v[118:121], v[226:229], v[188:191], v[118:121]
	v_mfma_f32_16x16x32_bf16 v[114:117], v[234:237], v[188:191], v[114:117]
	v_mfma_f32_16x16x32_bf16 v[102:105], v[226:229], v[196:199], v[102:105]
	v_mfma_f32_16x16x32_bf16 v[98:101], v[234:237], v[196:199], v[98:101]
	v_mfma_f32_16x16x32_bf16 v[86:89], v[226:229], v[204:207], v[86:89]
	v_mfma_f32_16x16x32_bf16 v[82:85], v[234:237], v[204:207], v[82:85]
	v_mfma_f32_16x16x32_bf16 v[70:73], v[226:229], v[218:221], v[70:73]
	v_mfma_f32_16x16x32_bf16 v[66:69], v[234:237], v[218:221], v[66:69]
	v_mfma_f32_16x16x32_bf16 v[118:121], v[230:233], v[192:195], v[118:121]
	v_mfma_f32_16x16x32_bf16 v[114:117], v[238:241], v[192:195], v[114:117]
	v_mfma_f32_16x16x32_bf16 v[102:105], v[230:233], v[200:203], v[102:105]
	v_mfma_f32_16x16x32_bf16 v[98:101], v[238:241], v[200:203], v[98:101]
	v_mfma_f32_16x16x32_bf16 v[86:89], v[230:233], v[214:217], v[86:89]
	v_mfma_f32_16x16x32_bf16 v[82:85], v[238:241], v[214:217], v[82:85]
	v_mfma_f32_16x16x32_bf16 v[70:73], v[230:233], v[222:225], v[70:73]
	v_mfma_f32_16x16x32_bf16 v[66:69], v[238:241], v[222:225], v[66:69]
	s_mov_b32 m0, s69
	v_lshl_add_u64 v[146:147], v[162:163], 0, s[70:71]
	s_barrier
	ds_read_b128 v[188:191], v151 offset:49152
	ds_read_b128 v[192:195], v151 offset:50176
	ds_read_b128 v[196:199], v151 offset:51200
	ds_read_b128 v[200:203], v151 offset:52224
	ds_read_b128 v[204:207], v151 offset:53248
	ds_read_b128 v[214:217], v151 offset:54272
	ds_read_b128 v[218:221], v151 offset:55296
	ds_read_b128 v[222:225], v151 offset:56320
	global_load_lds_dwordx4 v[146:147], off
	s_mov_b32 m0, s80
	v_lshl_add_u64 v[146:147], v[164:165], 0, s[70:71]
	global_load_lds_dwordx4 v[146:147], off
	s_barrier
	s_waitcnt lgkmcnt(0)
	v_mfma_f32_16x16x32_bf16 v[62:65], v[142:145], v[188:191], v[62:65]
	v_mfma_f32_16x16x32_bf16 v[58:61], v[180:183], v[188:191], v[58:61]
	v_mfma_f32_16x16x32_bf16 v[46:49], v[142:145], v[196:199], v[46:49]
	v_mfma_f32_16x16x32_bf16 v[42:45], v[180:183], v[196:199], v[42:45]
	v_mfma_f32_16x16x32_bf16 v[30:33], v[142:145], v[204:207], v[30:33]
	v_mfma_f32_16x16x32_bf16 v[26:29], v[180:183], v[204:207], v[26:29]
	v_mfma_f32_16x16x32_bf16 v[14:17], v[142:145], v[218:221], v[14:17]
	v_mfma_f32_16x16x32_bf16 v[10:13], v[180:183], v[218:221], v[10:13]
	v_mfma_f32_16x16x32_bf16 v[62:65], v[176:179], v[192:195], v[62:65]
	v_mfma_f32_16x16x32_bf16 v[58:61], v[184:187], v[192:195], v[58:61]
	v_mfma_f32_16x16x32_bf16 v[46:49], v[176:179], v[200:203], v[46:49]
	v_mfma_f32_16x16x32_bf16 v[42:45], v[184:187], v[200:203], v[42:45]
	v_mfma_f32_16x16x32_bf16 v[30:33], v[176:179], v[214:217], v[30:33]
	v_mfma_f32_16x16x32_bf16 v[26:29], v[184:187], v[214:217], v[26:29]
	v_mfma_f32_16x16x32_bf16 v[14:17], v[176:179], v[222:225], v[14:17]
	v_mfma_f32_16x16x32_bf16 v[10:13], v[184:187], v[222:225], v[10:13]
	s_barrier
	s_add_u32 s10, s14, 0x28080
	s_addc_u32 s11, s15, 0
	s_add_i32 s14, s16, s37
	s_mov_b32 m0, s14
	v_lshl_add_u64 v[142:143], s[10:11], 0, v[8:9]
	global_load_lds_dwordx4 v[142:143], off
	s_add_i32 m0, s14, 0x2000
	v_lshl_add_u64 v[142:143], s[10:11], 0, v[130:131]
	global_load_lds_dwordx4 v[142:143], off
	s_waitcnt vmcnt(6)
	s_barrier
	v_mfma_f32_16x16x32_bf16 v[54:57], v[226:229], v[188:191], v[54:57]
	v_mfma_f32_16x16x32_bf16 v[50:53], v[234:237], v[188:191], v[50:53]
	v_mfma_f32_16x16x32_bf16 v[38:41], v[226:229], v[196:199], v[38:41]
	v_mfma_f32_16x16x32_bf16 v[34:37], v[234:237], v[196:199], v[34:37]
	v_mfma_f32_16x16x32_bf16 v[22:25], v[226:229], v[204:207], v[22:25]
	v_mfma_f32_16x16x32_bf16 v[18:21], v[234:237], v[204:207], v[18:21]
	v_mfma_f32_16x16x32_bf16 v[4:7], v[226:229], v[218:221], v[4:7]
	v_mfma_f32_16x16x32_bf16 v[0:3], v[234:237], v[218:221], v[0:3]
	v_mfma_f32_16x16x32_bf16 v[54:57], v[230:233], v[192:195], v[54:57]
	v_mfma_f32_16x16x32_bf16 v[50:53], v[238:241], v[192:195], v[50:53]
	v_mfma_f32_16x16x32_bf16 v[38:41], v[230:233], v[200:203], v[38:41]
	v_mfma_f32_16x16x32_bf16 v[34:37], v[238:241], v[200:203], v[34:37]
	v_mfma_f32_16x16x32_bf16 v[22:25], v[230:233], v[214:217], v[22:25]
	v_mfma_f32_16x16x32_bf16 v[18:21], v[238:241], v[214:217], v[18:21]
	v_mfma_f32_16x16x32_bf16 v[4:7], v[230:233], v[222:225], v[4:7]
	v_mfma_f32_16x16x32_bf16 v[0:3], v[238:241], v[222:225], v[0:3]
	s_add_i32 s27, s27, 2
	s_add_u32 s19, s19, 0x100
	s_addc_u32 s26, s26, 0
	s_cmp_gt_u32 s27, 7
	s_mov_b64 s[10:11], s[12:13]
	s_barrier

; DEVI size_t gemm_offB(const Gemm& g, const Unit& u) { return (g.split ? (size_t)(u.b >> 2) * g.sB + (size_t)(u.b & 3) * g.sB_lo : (size_t)u.b * g.sB) + (size_t)(u.pm >> g.pmsh) * g.sBpm; }
; #define PG8_STAGE(bufoff, gbase, voff) do { _Pragma("unroll") for (int _i = 0; _i < 2; ++_i) \
;         __builtin_amdgcn_global_load_lds((const unsigned*)((const char*)(gbase) + (voff)[_i]), (LAS unsigned*)(lds + (bufoff) + ldsw + _i * 8192), 16, 0, 0); } while (0)
; #define PG8_LDA(dst, b, h) do { _Pragma("unroll") for (int m = 0; m < 4; ++m) _Pragma("unroll") for (int k = 0; k < 2; ++k) dst[m][k] = *(const LAS bf16x8*)(lds + PG8_SA(b, h) + aoff + m * 2048 + k * 1024); } while (0)
; #define PG8_WAIT_L(n) asm volatile("s_waitcnt lgkmcnt(" #n ")" ::: "memory")
; #define PG8_BAR __builtin_amdgcn_s_barrier()
; #define PG8_SCHED __builtin_amdgcn_sched_barrier(0)
; template <class Epi>
; DEVI void gemm_phase(LAS unsigned char* lds, const Gemm g, const Epi& E) {
;     ...
;         const char* nA = has_next ? (const char*)g.A + gemm_offA(g, nxt) * 2 + (size_t)nxt.pm * tstepA : cA;
;         const char* nB = has_next ? (const char*)g.Bt + gemm_offB(g, nxt) * 2 + (size_t)nxt.pn * tstepB : cB;
;         for (int t = 0; t < nt; t += 2) {
;             const bool last = (t == nt - 2);
;             const char* a1 = cA + (size_t)(t + 1) * kstep;
;             const char* a2 = last ? nA : cA + (size_t)(t + 2) * kstep; const char* b2 = last ? nB : cB + (size_t)(t + 2) * kstep;
;             const char* a3 = a2 + kstep; const char* b3 = b2 + kstep;
;             PG8_LDB(B0, 0, 0); PG8_SCHED; PG8_LDA(At, 0, 0); PG8_STAGE(PG8_SA(1, 1), a1 + hstepA, voffA);
;             PG8_WAIT_L(8); PG8_BAR; PG8_WAIT_L(0); PG8_MMA(0, 0, At, B0); PG8_BAR; PG8_SCHED;
;             PG8_LDB(B1, 0, 1); PG8_STAGE(PG8_SB(0, 0), b2, voffB);
;             PG8_BAR; PG8_WAIT_L(0); PG8_MMA(0, 1, At, B1); PG8_BAR;
;             PG8_LDA(At, 0, 1); PG8_STAGE(PG8_SA(0, 0), a2, voffA);
;             PG8_BAR; PG8_WAIT_L(0); PG8_MMA(1, 0, At, B0); PG8_BAR; PG8_SCHED;
;     ...
; #pragma unroll
;         for (int a = 0; a < 2; ++a)
; #pragma unroll
;             for (int b = 0; b < 2; ++b)
; #pragma unroll
;                 for (int m = 0; m < 4; ++m)
; #pragma unroll
;                     for (int n = 0; n < 2; ++n) acc[a][b][m][n] = (f32x4){0.f, 0.f, 0.f, 0.f};
;         cur = nxt; cA = nA; cB = nB; ++ui;
.LBB0_1345:
	s_ashr_i32 s3, s2, 31
	v_cmp_lt_i64_e32 vcc, s[6:7], v[168:169]
	s_lshl_b64 s[6:7], s[2:3], 19
	s_add_u32 s6, s24, s6
	s_addc_u32 s7, s25, s7
	s_and_b64 s[8:9], vcc, exec
	s_cselect_b32 s1, s7, s13
	s_cselect_b32 s3, s6, s12
	s_ashr_i32 s5, s4, 31
	s_lshl_b64 s[8:9], s[4:5], 19
	v_readlane_b32 s16, v251, 58
	v_readlane_b32 s17, v251, 59
	s_add_u32 s8, s16, s8
	s_addc_u32 s9, s17, s9
	s_and_b64 s[16:17], vcc, exec
	s_cselect_b32 s5, s9, s15
	s_cselect_b32 s18, s8, s14
	s_add_u32 s12, s12, 0x40080
	s_addc_u32 s13, s13, 0
	s_add_u32 s19, s14, 0x100
	s_mov_b32 s85, s63
	s_mov_b32 s84, s62
	s_mov_b32 s83, s61
	s_mov_b32 s41, s60
	s_mov_b64 s[44:45], s[58:59]
	s_mov_b64 s[42:43], s[56:57]
	s_addc_u32 s26, s15, 0
	s_mov_b32 s27, -2
	s_add_u32 s14, s12, 0xfffc0080
	s_addc_u32 s15, s13, -1
	s_add_i32 s38, 0, 0x10000
	v_add_u32_e32 v152, s38, v185
	ds_read_b128 v[114:117], v152
	ds_read_b128 v[126:129], v152 offset:1024
	ds_read_b128 v[130:133], v152 offset:2048
	ds_read_b128 v[176:179], v152 offset:3072
	s_cmp_eq_u32 s27, 12
	s_cselect_b32 s17, s1, s15
	s_cselect_b32 s16, s3, s14
	s_cselect_b32 s15, s5, s26
	s_cselect_b32 s14, s18, s19
	v_lshl_add_u64 v[152:153], s[12:13], 0, v[148:149]
	s_add_i32 m0, s11, 0xc000
	ds_read_b128 v[180:183], v187
	ds_read_b128 v[188:191], v187 offset:1024
	ds_read_b128 v[192:195], v187 offset:2048
	ds_read_b128 v[196:199], v187 offset:3072
	ds_read_b128 v[200:203], v187 offset:4096
	ds_read_b128 v[204:207], v187 offset:5120
	ds_read_b128 v[214:217], v187 offset:6144
	ds_read_b128 v[218:221], v187 offset:7168
	global_load_lds_dwordx4 v[152:153], off
	s_add_i32 m0, s11, 0xe000
	v_lshl_add_u64 v[152:153], s[12:13], 0, v[150:151]
	global_load_lds_dwordx4 v[152:153], off
	s_waitcnt lgkmcnt(8)
	s_barrier
	s_waitcnt lgkmcnt(0)
	v_mfma_f32_16x16x32_bf16 v[138:141], v[114:117], v[180:183], 0
	v_mfma_f32_16x16x32_bf16 v[134:137], v[130:133], v[180:183], 0
	v_mfma_f32_16x16x32_bf16 v[110:113], v[114:117], v[192:195], 0
	v_mfma_f32_16x16x32_bf16 v[106:109], v[130:133], v[192:195], 0
	v_mfma_f32_16x16x32_bf16 v[94:97], v[114:117], v[200:203], 0
	v_mfma_f32_16x16x32_bf16 v[90:93], v[130:133], v[200:203], 0
	v_mfma_f32_16x16x32_bf16 v[78:81], v[114:117], v[214:217], 0
	v_mfma_f32_16x16x32_bf16 v[74:77], v[130:133], v[214:217], 0
	v_mfma_f32_16x16x32_bf16 v[138:141], v[126:129], v[188:191], v[138:141]
	v_mfma_f32_16x16x32_bf16 v[134:137], v[176:179], v[188:191], v[134:137]
	v_mfma_f32_16x16x32_bf16 v[110:113], v[126:129], v[196:199], v[110:113]
	v_mfma_f32_16x16x32_bf16 v[106:109], v[176:179], v[196:199], v[106:109]
	v_mfma_f32_16x16x32_bf16 v[94:97], v[126:129], v[204:207], v[94:97]
	v_mfma_f32_16x16x32_bf16 v[90:93], v[176:179], v[204:207], v[90:93]
	v_mfma_f32_16x16x32_bf16 v[78:81], v[126:129], v[218:221], v[78:81]
	v_mfma_f32_16x16x32_bf16 v[74:77], v[176:179], v[218:221], v[74:77]
	s_barrier
	s_add_i32 s40, 0, 0x14000
	v_add_u32_e32 v152, s40, v185
	s_add_i32 s38, s38, s47
	ds_read_b128 v[222:225], v152
	ds_read_b128 v[226:229], v152 offset:1024
	ds_read_b128 v[230:233], v152 offset:2048
	ds_read_b128 v[234:237], v152 offset:3072
	v_lshl_add_u64 v[152:153], s[14:15], 0, v[8:9]
	s_mov_b32 m0, s38
	v_lshl_add_u64 v[162:163], s[14:15], 0, v[146:147]
	global_load_lds_dwordx4 v[152:153], off
	s_add_i32 m0, s38, 0x2000
	s_nop 0
	global_load_lds_dwordx4 v[162:163], off
	s_barrier
	s_waitcnt lgkmcnt(0)
	v_mfma_f32_16x16x32_bf16 v[122:125], v[222:225], v[180:183], 0
	v_mfma_f32_16x16x32_bf16 v[118:121], v[230:233], v[180:183], 0
	v_mfma_f32_16x16x32_bf16 v[102:105], v[222:225], v[192:195], 0
	v_mfma_f32_16x16x32_bf16 v[98:101], v[230:233], v[192:195], 0
	v_mfma_f32_16x16x32_bf16 v[86:89], v[222:225], v[200:203], 0
	v_mfma_f32_16x16x32_bf16 v[82:85], v[230:233], v[200:203], 0
	v_mfma_f32_16x16x32_bf16 v[70:73], v[222:225], v[214:217], 0
	v_mfma_f32_16x16x32_bf16 v[66:69], v[230:233], v[214:217], 0
	v_mfma_f32_16x16x32_bf16 v[122:125], v[226:229], v[188:191], v[122:125]
	v_mfma_f32_16x16x32_bf16 v[118:121], v[234:237], v[188:191], v[118:121]
	v_mfma_f32_16x16x32_bf16 v[102:105], v[226:229], v[196:199], v[102:105]
	v_mfma_f32_16x16x32_bf16 v[98:101], v[234:237], v[196:199], v[98:101]
	v_mfma_f32_16x16x32_bf16 v[86:89], v[226:229], v[204:207], v[86:89]
	v_mfma_f32_16x16x32_bf16 v[82:85], v[234:237], v[204:207], v[82:85]
	v_mfma_f32_16x16x32_bf16 v[70:73], v[226:229], v[218:221], v[70:73]
	v_mfma_f32_16x16x32_bf16 v[66:69], v[234:237], v[218:221], v[66:69]
	s_mov_b32 m0, s11
	v_lshl_add_u64 v[164:165], s[16:17], 0, v[142:143]
	s_barrier
	ds_read_b128 v[180:183], v187 offset:16384
	ds_read_b128 v[188:191], v187 offset:17408
	ds_read_b128 v[192:195], v187 offset:18432
	ds_read_b128 v[196:199], v187 offset:19456
	ds_read_b128 v[200:203], v187 offset:20480
	ds_read_b128 v[204:207], v187 offset:21504
	ds_read_b128 v[214:217], v187 offset:22528
	ds_read_b128 v[218:221], v187 offset:23552
	global_load_lds_dwordx4 v[164:165], off
	s_mov_b32 m0, s66
	v_lshl_add_u64 v[208:209], s[16:17], 0, v[144:145]
	global_load_lds_dwordx4 v[208:209], off
	s_barrier
	s_waitcnt lgkmcnt(0)
	v_mfma_f32_16x16x32_bf16 v[62:65], v[114:117], v[180:183], 0
	v_mfma_f32_16x16x32_bf16 v[58:61], v[130:133], v[180:183], 0
	v_mfma_f32_16x16x32_bf16 v[46:49], v[114:117], v[192:195], 0
	v_mfma_f32_16x16x32_bf16 v[42:45], v[130:133], v[192:195], 0
	v_mfma_f32_16x16x32_bf16 v[30:33], v[114:117], v[200:203], 0
	v_mfma_f32_16x16x32_bf16 v[26:29], v[130:133], v[200:203], 0
	v_mfma_f32_16x16x32_bf16 v[14:17], v[114:117], v[214:217], 0
	v_mfma_f32_16x16x32_bf16 v[10:13], v[130:133], v[214:217], 0
	v_mfma_f32_16x16x32_bf16 v[62:65], v[126:129], v[188:191], v[62:65]
	v_mfma_f32_16x16x32_bf16 v[58:61], v[176:179], v[188:191], v[58:61]
	v_mfma_f32_16x16x32_bf16 v[46:49], v[126:129], v[196:199], v[46:49]
	v_mfma_f32_16x16x32_bf16 v[42:45], v[176:179], v[196:199], v[42:45]
	v_mfma_f32_16x16x32_bf16 v[30:33], v[126:129], v[204:207], v[30:33]
	v_mfma_f32_16x16x32_bf16 v[26:29], v[176:179], v[204:207], v[26:29]
	v_mfma_f32_16x16x32_bf16 v[14:17], v[126:129], v[218:221], v[14:17]
	v_mfma_f32_16x16x32_bf16 v[10:13], v[176:179], v[218:221], v[10:13]
	s_barrier
; #define PG8_STAGE(bufoff, gbase, voff) do { _Pragma("unroll") for (int _i = 0; _i < 2; ++_i) \
;         __builtin_amdgcn_global_load_lds((const unsigned*)((const char*)(gbase) + (voff)[_i]), (LAS unsigned*)(lds + (bufoff) + ldsw + _i * 8192), 16, 0, 0); } while (0)
; #define PG8_LDA(dst, b, h) do { _Pragma("unroll") for (int m = 0; m < 4; ++m) _Pragma("unroll") for (int k = 0; k < 2; ++k) dst[m][k] = *(const LAS bf16x8*)(lds + PG8_SA(b, h) + aoff + m * 2048 + k * 1024); } while (0)
; #define PG8_LDB(dst, b, h) do { _Pragma("unroll") for (int n = 0; n < 2; ++n) _Pragma("unroll") for (int k = 0; k < 2; ++k) dst[n][k] = *(const LAS bf16x8*)(lds + PG8_SB(b, h) + boff + n * 2048 + k * 1024); } while (0)
; #define PG8_MMA(ai, bj, At, Bt) do { __builtin_amdgcn_s_setprio(1); _Pragma("unroll") for (int m = 0; m < 4; ++m) _Pragma("unroll") for (int n = 0; n < 2; ++n) _Pragma("unroll") for (int k = 0; k < 2; ++k) \
;         acc[ai][bj][m][n] = __builtin_amdgcn_mfma_f32_16x16x32_bf16(Bt[n][k], At[m][k], acc[ai][bj][m][n], 0, 0, 0); __builtin_amdgcn_s_setprio(0); } while (0)
; #define PG8_WAIT_V(n) asm volatile("s_waitcnt vmcnt(" #n ")" ::: "memory")
; #define PG8_WAIT_L(n) asm volatile("s_waitcnt lgkmcnt(" #n ")" ::: "memory")
; #define PG8_BAR __builtin_amdgcn_s_barrier()
; #define PG8_SCHED __builtin_amdgcn_sched_barrier(0)
; template <class Epi>
; DEVI void gemm_phase(LAS unsigned char* lds, const Gemm g, const Epi& E) {
;     ...
;             PG8_STAGE(PG8_SB(0, 1), b2 + hstepB, voffB);
;             PG8_WAIT_V(6); PG8_BAR; PG8_MMA(1, 1, At, B1); PG8_BAR;
;             PG8_LDB(B0, 1, 0); PG8_SCHED; PG8_LDA(At, 1, 0); PG8_STAGE(PG8_SA(0, 1), a2 + hstepA, voffA);
;             PG8_WAIT_L(8); PG8_BAR; PG8_WAIT_L(0); PG8_MMA(0, 0, At, B0); PG8_BAR; PG8_SCHED;
;             PG8_LDB(B1, 1, 1); PG8_STAGE(PG8_SB(1, 0), b3, voffB);
	s_add_u32 s38, s14, 0x40000
	s_addc_u32 s39, s15, 0
	s_add_i32 s40, s40, s47
	s_mov_b32 m0, s40
	v_lshl_add_u64 v[114:115], s[38:39], 0, v[8:9]
	global_load_lds_dwordx4 v[114:115], off
	s_add_i32 m0, s40, 0x2000
	v_lshl_add_u64 v[114:115], s[38:39], 0, v[146:147]
	global_load_lds_dwordx4 v[114:115], off
	s_waitcnt vmcnt(6)
	s_barrier
	v_mfma_f32_16x16x32_bf16 v[54:57], v[222:225], v[180:183], 0
	v_mfma_f32_16x16x32_bf16 v[50:53], v[230:233], v[180:183], 0
	v_mfma_f32_16x16x32_bf16 v[38:41], v[222:225], v[192:195], 0
	v_mfma_f32_16x16x32_bf16 v[34:37], v[230:233], v[192:195], 0
	v_mfma_f32_16x16x32_bf16 v[22:25], v[222:225], v[200:203], 0
	v_mfma_f32_16x16x32_bf16 v[18:21], v[230:233], v[200:203], 0
	v_mfma_f32_16x16x32_bf16 v[4:7], v[222:225], v[214:217], 0
	v_mfma_f32_16x16x32_bf16 v[0:3], v[230:233], v[214:217], 0
	v_mfma_f32_16x16x32_bf16 v[54:57], v[226:229], v[188:191], v[54:57]
	v_mfma_f32_16x16x32_bf16 v[50:53], v[234:237], v[188:191], v[50:53]
	v_mfma_f32_16x16x32_bf16 v[38:41], v[226:229], v[196:199], v[38:41]
	v_mfma_f32_16x16x32_bf16 v[34:37], v[234:237], v[196:199], v[34:37]
	v_mfma_f32_16x16x32_bf16 v[22:25], v[226:229], v[204:207], v[22:25]
	v_mfma_f32_16x16x32_bf16 v[18:21], v[234:237], v[204:207], v[18:21]
	v_mfma_f32_16x16x32_bf16 v[4:7], v[226:229], v[218:221], v[4:7]
	v_mfma_f32_16x16x32_bf16 v[0:3], v[234:237], v[218:221], v[0:3]
	s_add_i32 s38, 0, 0x18000
	v_add_u32_e32 v176, s38, v185
	s_barrier
	ds_read_b128 v[114:117], v176
	ds_read_b128 v[126:129], v176 offset:1024
	ds_read_b128 v[130:133], v176 offset:2048
	ds_read_b128 v[176:179], v176 offset:3072
	s_add_u32 s16, s16, 0x40000
	s_addc_u32 s17, s17, 0
	s_mov_b32 m0, s68
	v_lshl_add_u64 v[222:223], s[16:17], 0, v[142:143]
	ds_read_b128 v[180:183], v187 offset:32768
	ds_read_b128 v[188:191], v187 offset:33792
	ds_read_b128 v[192:195], v187 offset:34816
	ds_read_b128 v[196:199], v187 offset:35840
	ds_read_b128 v[200:203], v187 offset:36864
	ds_read_b128 v[204:207], v187 offset:37888
	ds_read_b128 v[214:217], v187 offset:38912
	ds_read_b128 v[218:221], v187 offset:39936
	global_load_lds_dwordx4 v[222:223], off
	s_mov_b32 m0, s69
	v_lshl_add_u64 v[222:223], s[16:17], 0, v[144:145]
	global_load_lds_dwordx4 v[222:223], off
	s_waitcnt lgkmcnt(8)
	s_barrier
	s_waitcnt lgkmcnt(0)
	v_mfma_f32_16x16x32_bf16 v[138:141], v[114:117], v[180:183], v[138:141]
	v_mfma_f32_16x16x32_bf16 v[134:137], v[130:133], v[180:183], v[134:137]
	v_mfma_f32_16x16x32_bf16 v[110:113], v[114:117], v[192:195], v[110:113]
	v_mfma_f32_16x16x32_bf16 v[106:109], v[130:133], v[192:195], v[106:109]
	v_mfma_f32_16x16x32_bf16 v[94:97], v[114:117], v[200:203], v[94:97]
	v_mfma_f32_16x16x32_bf16 v[90:93], v[130:133], v[200:203], v[90:93]
	v_mfma_f32_16x16x32_bf16 v[78:81], v[114:117], v[214:217], v[78:81]
	v_mfma_f32_16x16x32_bf16 v[74:77], v[130:133], v[214:217], v[74:77]
	v_mfma_f32_16x16x32_bf16 v[138:141], v[126:129], v[188:191], v[138:141]
	v_mfma_f32_16x16x32_bf16 v[134:137], v[176:179], v[188:191], v[134:137]
	v_mfma_f32_16x16x32_bf16 v[110:113], v[126:129], v[196:199], v[110:113]
	v_mfma_f32_16x16x32_bf16 v[106:109], v[176:179], v[196:199], v[106:109]
	v_mfma_f32_16x16x32_bf16 v[94:97], v[126:129], v[204:207], v[94:97]
	v_mfma_f32_16x16x32_bf16 v[90:93], v[176:179], v[204:207], v[90:93]
	v_mfma_f32_16x16x32_bf16 v[78:81], v[126:129], v[218:221], v[78:81]
	v_mfma_f32_16x16x32_bf16 v[74:77], v[176:179], v[218:221], v[74:77]
	s_barrier
	s_add_i32 s16, 0, 0x1c000
	s_add_i32 s17, s38, s47
	v_add_u32_e32 v213, s16, v185
	v_lshl_add_u64 v[152:153], v[152:153], 0, s[70:71]
	s_mov_b32 m0, s17
	ds_read_b128 v[222:225], v213
	ds_read_b128 v[226:229], v213 offset:1024
	ds_read_b128 v[230:233], v213 offset:2048
	ds_read_b128 v[234:237], v213 offset:3072
	global_load_lds_dwordx4 v[152:153], off
	s_add_i32 m0, s17, 0x2000
	v_lshl_add_u64 v[152:153], v[162:163], 0, s[70:71]
	global_load_lds_dwordx4 v[152:153], off
	s_barrier
; #define PG8_STAGE(bufoff, gbase, voff) do { _Pragma("unroll") for (int _i = 0; _i < 2; ++_i) \
;         __builtin_amdgcn_global_load_lds((const unsigned*)((const char*)(gbase) + (voff)[_i]), (LAS unsigned*)(lds + (bufoff) + ldsw + _i * 8192), 16, 0, 0); } while (0)
; #define PG8_LDA(dst, b, h) do { _Pragma("unroll") for (int m = 0; m < 4; ++m) _Pragma("unroll") for (int k = 0; k < 2; ++k) dst[m][k] = *(const LAS bf16x8*)(lds + PG8_SA(b, h) + aoff + m * 2048 + k * 1024); } while (0)
; #define PG8_MMA(ai, bj, At, Bt) do { __builtin_amdgcn_s_setprio(1); _Pragma("unroll") for (int m = 0; m < 4; ++m) _Pragma("unroll") for (int n = 0; n < 2; ++n) _Pragma("unroll") for (int k = 0; k < 2; ++k) \
;         acc[ai][bj][m][n] = __builtin_amdgcn_mfma_f32_16x16x32_bf16(Bt[n][k], At[m][k], acc[ai][bj][m][n], 0, 0, 0); __builtin_amdgcn_s_setprio(0); } while (0)
; #define PG8_WAIT_V(n) asm volatile("s_waitcnt vmcnt(" #n ")" ::: "memory")
; #define PG8_WAIT_L(n) asm volatile("s_waitcnt lgkmcnt(" #n ")" ::: "memory")
; #define PG8_BAR __builtin_amdgcn_s_barrier()
; #define PG8_SCHED __builtin_amdgcn_sched_barrier(0)
; template <class Epi>
; DEVI void gemm_phase(LAS unsigned char* lds, const Gemm g, const Epi& E) {
;     ...
;             PG8_BAR; PG8_WAIT_L(0); PG8_MMA(0, 1, At, B1); PG8_BAR;
;             PG8_LDA(At, 1, 1); PG8_STAGE(PG8_SA(1, 0), a3, voffA);
;             PG8_BAR; PG8_WAIT_L(0); PG8_MMA(1, 0, At, B0); PG8_BAR; PG8_SCHED;
;             PG8_STAGE(PG8_SB(1, 1), b3 + hstepB, voffB);
;             PG8_WAIT_V(6); PG8_BAR; PG8_MMA(1, 1, At, B1); PG8_BAR;
;         }
	s_waitcnt lgkmcnt(0)
	v_mfma_f32_16x16x32_bf16 v[122:125], v[222:225], v[180:183], v[122:125]
	v_mfma_f32_16x16x32_bf16 v[118:121], v[230:233], v[180:183], v[118:121]
	v_mfma_f32_16x16x32_bf16 v[102:105], v[222:225], v[192:195], v[102:105]
	v_mfma_f32_16x16x32_bf16 v[98:101], v[230:233], v[192:195], v[98:101]
	v_mfma_f32_16x16x32_bf16 v[86:89], v[222:225], v[200:203], v[86:89]
	v_mfma_f32_16x16x32_bf16 v[82:85], v[230:233], v[200:203], v[82:85]
	v_mfma_f32_16x16x32_bf16 v[70:73], v[222:225], v[214:217], v[70:73]
	v_mfma_f32_16x16x32_bf16 v[66:69], v[230:233], v[214:217], v[66:69]
	v_mfma_f32_16x16x32_bf16 v[122:125], v[226:229], v[188:191], v[122:125]
	v_mfma_f32_16x16x32_bf16 v[118:121], v[234:237], v[188:191], v[118:121]
	v_mfma_f32_16x16x32_bf16 v[102:105], v[226:229], v[196:199], v[102:105]
	v_mfma_f32_16x16x32_bf16 v[98:101], v[234:237], v[196:199], v[98:101]
	v_mfma_f32_16x16x32_bf16 v[86:89], v[226:229], v[204:207], v[86:89]
	v_mfma_f32_16x16x32_bf16 v[82:85], v[234:237], v[204:207], v[82:85]
	v_mfma_f32_16x16x32_bf16 v[70:73], v[226:229], v[218:221], v[70:73]
	v_mfma_f32_16x16x32_bf16 v[66:69], v[234:237], v[218:221], v[66:69]
	s_mov_b32 m0, s80
	v_lshl_add_u64 v[152:153], v[164:165], 0, s[70:71]
	s_barrier
	ds_read_b128 v[180:183], v187 offset:49152
	ds_read_b128 v[188:191], v187 offset:50176
	ds_read_b128 v[192:195], v187 offset:51200
	ds_read_b128 v[196:199], v187 offset:52224
	ds_read_b128 v[200:203], v187 offset:53248
	ds_read_b128 v[204:207], v187 offset:54272
	ds_read_b128 v[214:217], v187 offset:55296
	ds_read_b128 v[218:221], v187 offset:56320
	global_load_lds_dwordx4 v[152:153], off
	s_mov_b32 m0, s81
	v_lshl_add_u64 v[152:153], v[208:209], 0, s[70:71]
	global_load_lds_dwordx4 v[152:153], off
	s_barrier
	s_waitcnt lgkmcnt(0)
	v_mfma_f32_16x16x32_bf16 v[62:65], v[114:117], v[180:183], v[62:65]
	v_mfma_f32_16x16x32_bf16 v[58:61], v[130:133], v[180:183], v[58:61]
	v_mfma_f32_16x16x32_bf16 v[46:49], v[114:117], v[192:195], v[46:49]
	v_mfma_f32_16x16x32_bf16 v[42:45], v[130:133], v[192:195], v[42:45]
	v_mfma_f32_16x16x32_bf16 v[30:33], v[114:117], v[200:203], v[30:33]
	v_mfma_f32_16x16x32_bf16 v[26:29], v[130:133], v[200:203], v[26:29]
	v_mfma_f32_16x16x32_bf16 v[14:17], v[114:117], v[214:217], v[14:17]
	v_mfma_f32_16x16x32_bf16 v[10:13], v[130:133], v[214:217], v[10:13]
	v_mfma_f32_16x16x32_bf16 v[62:65], v[126:129], v[188:191], v[62:65]
	v_mfma_f32_16x16x32_bf16 v[58:61], v[176:179], v[188:191], v[58:61]
	v_mfma_f32_16x16x32_bf16 v[46:49], v[126:129], v[196:199], v[46:49]
	v_mfma_f32_16x16x32_bf16 v[42:45], v[176:179], v[196:199], v[42:45]
	v_mfma_f32_16x16x32_bf16 v[30:33], v[126:129], v[204:207], v[30:33]
	v_mfma_f32_16x16x32_bf16 v[26:29], v[176:179], v[204:207], v[26:29]
	v_mfma_f32_16x16x32_bf16 v[14:17], v[126:129], v[218:221], v[14:17]
	v_mfma_f32_16x16x32_bf16 v[10:13], v[176:179], v[218:221], v[10:13]
	s_barrier
	s_add_u32 s14, s14, 0x40080
	s_addc_u32 s15, s15, 0
	s_add_i32 s16, s16, s47
	s_mov_b32 m0, s16
	v_lshl_add_u64 v[114:115], s[14:15], 0, v[8:9]
	global_load_lds_dwordx4 v[114:115], off
	s_add_i32 m0, s16, 0x2000
	v_lshl_add_u64 v[114:115], s[14:15], 0, v[146:147]
	global_load_lds_dwordx4 v[114:115], off
	s_waitcnt vmcnt(6)
	s_barrier
	v_mfma_f32_16x16x32_bf16 v[54:57], v[222:225], v[180:183], v[54:57]
	v_mfma_f32_16x16x32_bf16 v[50:53], v[230:233], v[180:183], v[50:53]
	v_mfma_f32_16x16x32_bf16 v[38:41], v[222:225], v[192:195], v[38:41]
	v_mfma_f32_16x16x32_bf16 v[34:37], v[230:233], v[192:195], v[34:37]
	v_mfma_f32_16x16x32_bf16 v[22:25], v[222:225], v[200:203], v[22:25]
	v_mfma_f32_16x16x32_bf16 v[18:21], v[230:233], v[200:203], v[18:21]
	v_mfma_f32_16x16x32_bf16 v[4:7], v[222:225], v[214:217], v[4:7]
	v_mfma_f32_16x16x32_bf16 v[0:3], v[230:233], v[214:217], v[0:3]
	v_mfma_f32_16x16x32_bf16 v[54:57], v[226:229], v[188:191], v[54:57]
	v_mfma_f32_16x16x32_bf16 v[50:53], v[234:237], v[188:191], v[50:53]
	v_mfma_f32_16x16x32_bf16 v[38:41], v[226:229], v[196:199], v[38:41]
	v_mfma_f32_16x16x32_bf16 v[34:37], v[234:237], v[196:199], v[34:37]
	v_mfma_f32_16x16x32_bf16 v[22:25], v[226:229], v[204:207], v[22:25]
	v_mfma_f32_16x16x32_bf16 v[18:21], v[234:237], v[204:207], v[18:21]
	v_mfma_f32_16x16x32_bf16 v[4:7], v[226:229], v[218:221], v[4:7]
	v_mfma_f32_16x16x32_bf16 v[0:3], v[234:237], v[218:221], v[0:3]
	s_add_i32 s27, s27, 2
	s_add_u32 s12, s12, 0x100
	s_addc_u32 s13, s13, 0
	s_add_u32 s19, s19, 0x100
	s_addc_u32 s26, s26, 0
	s_cmp_gt_u32 s27, 13
	s_barrier

; DEVI size_t gemm_offB(const Gemm& g, const Unit& u) { return (g.split ? (size_t)(u.b >> 2) * g.sB + (size_t)(u.b & 3) * g.sB_lo : (size_t)u.b * g.sB) + (size_t)(u.pm >> g.pmsh) * g.sBpm; }
; #define PG8_STAGE(bufoff, gbase, voff) do { _Pragma("unroll") for (int _i = 0; _i < 2; ++_i) \
;         __builtin_amdgcn_global_load_lds((const unsigned*)((const char*)(gbase) + (voff)[_i]), (LAS unsigned*)(lds + (bufoff) + ldsw + _i * 8192), 16, 0, 0); } while (0)
; #define PG8_LDA(dst, b, h) do { _Pragma("unroll") for (int m = 0; m < 4; ++m) _Pragma("unroll") for (int k = 0; k < 2; ++k) dst[m][k] = *(const LAS bf16x8*)(lds + PG8_SA(b, h) + aoff + m * 2048 + k * 1024); } while (0)
; #define PG8_WAIT_L(n) asm volatile("s_waitcnt lgkmcnt(" #n ")" ::: "memory")
; #define PG8_BAR __builtin_amdgcn_s_barrier()
; #define PG8_SCHED __builtin_amdgcn_sched_barrier(0)
; template <class Epi>
; DEVI void gemm_phase(LAS unsigned char* lds, const Gemm g, const Epi& E) {
;     ...
;         const char* nA = has_next ? (const char*)g.A + gemm_offA(g, nxt) * 2 + (size_t)nxt.pm * tstepA : cA;
;         const char* nB = has_next ? (const char*)g.Bt + gemm_offB(g, nxt) * 2 + (size_t)nxt.pn * tstepB : cB;
;         for (int t = 0; t < nt; t += 2) {
;             const bool last = (t == nt - 2);
;             const char* a1 = cA + (size_t)(t + 1) * kstep;
;             const char* a2 = last ? nA : cA + (size_t)(t + 2) * kstep; const char* b2 = last ? nB : cB + (size_t)(t + 2) * kstep;
;             const char* a3 = a2 + kstep; const char* b3 = b2 + kstep;
;             PG8_LDB(B0, 0, 0); PG8_SCHED; PG8_LDA(At, 0, 0); PG8_STAGE(PG8_SA(1, 1), a1 + hstepA, voffA);
;             PG8_WAIT_L(8); PG8_BAR; PG8_WAIT_L(0); PG8_MMA(0, 0, At, B0); PG8_BAR; PG8_SCHED;
;             PG8_LDB(B1, 0, 1); PG8_STAGE(PG8_SB(0, 0), b2, voffB);
;             PG8_BAR; PG8_WAIT_L(0); PG8_MMA(0, 1, At, B1); PG8_BAR;
;             PG8_LDA(At, 0, 1); PG8_STAGE(PG8_SA(0, 0), a2, voffA);
;             PG8_BAR; PG8_WAIT_L(0); PG8_MMA(1, 0, At, B0); PG8_BAR; PG8_SCHED;
;     ...
; #pragma unroll
;         for (int a = 0; a < 2; ++a)
; #pragma unroll
;             for (int b = 0; b < 2; ++b)
; #pragma unroll
;                 for (int m = 0; m < 4; ++m)
; #pragma unroll
;                     for (int n = 0; n < 2; ++n) acc[a][b][m][n] = (f32x4){0.f, 0.f, 0.f, 0.f};
;         cur = nxt; cA = nA; cB = nB; ++ui;
.LBB0_1416:
	s_ashr_i32 s13, s12, 31
	s_lshl_b64 s[0:1], s[12:13], 19
	v_cmp_lt_i64_e32 vcc, s[16:17], v[168:169]
	s_add_u32 s16, s64, s0
	s_addc_u32 s17, s65, s1
	s_and_b64 s[0:1], vcc, exec
	s_cselect_b32 s0, s17, s69
	s_cselect_b32 s1, s16, s68
	s_ashr_i32 s15, s14, 31
	s_lshl_b64 s[18:19], s[14:15], 19
	v_readlane_b32 s26, v251, 56
	v_readlane_b32 s27, v251, 57
	s_add_u32 s36, s26, s18
	s_addc_u32 s37, s27, s19
	s_and_b64 s[18:19], vcc, exec
	s_cselect_b32 s9, s37, s81
	s_cselect_b32 s13, s36, s80
	s_add_u32 s68, s68, 0x40080
	s_addc_u32 s69, s69, 0
	s_add_u32 s15, s80, 0x100
	s_addc_u32 s18, s81, 0
	s_mov_b32 s19, -2
	s_waitcnt lgkmcnt(0)
	s_add_u32 s26, s68, 0xfffc0080
	s_addc_u32 s27, s69, -1
	s_add_i32 s38, 0, 0x10000
	v_add_u32_e32 v142, s38, v193
	ds_read_b128 v[130:133], v142
	ds_read_b128 v[134:137], v142 offset:1024
	ds_read_b128 v[138:141], v142 offset:2048
	ds_read_b128 v[142:145], v142 offset:3072
	s_cmp_eq_u32 s19, 12
	s_cselect_b32 s83, s0, s27
	s_cselect_b32 s82, s1, s26
	s_cselect_b32 s81, s9, s18
	s_cselect_b32 s80, s13, s15
	v_lshl_add_u64 v[162:163], s[68:69], 0, v[178:179]
	s_add_i32 m0, s85, 0xc000
	ds_read_b128 v[146:149], v198
	ds_read_b128 v[182:185], v198 offset:1024
	ds_read_b128 v[186:189], v198 offset:2048
	ds_read_b128 v[200:203], v198 offset:3072
	ds_read_b128 v[204:207], v198 offset:4096
	ds_read_b128 v[214:217], v198 offset:5120
	ds_read_b128 v[218:221], v198 offset:6144
	ds_read_b128 v[222:225], v198 offset:7168
	global_load_lds_dwordx4 v[162:163], off
	s_add_i32 m0, s85, 0xe000
	v_lshl_add_u64 v[162:163], s[68:69], 0, v[180:181]
	global_load_lds_dwordx4 v[162:163], off
	s_waitcnt lgkmcnt(8)
	s_barrier
	s_waitcnt lgkmcnt(0)
	v_mfma_f32_16x16x32_bf16 v[126:129], v[130:133], v[146:149], 0
	v_mfma_f32_16x16x32_bf16 v[122:125], v[138:141], v[146:149], 0
	v_mfma_f32_16x16x32_bf16 v[110:113], v[130:133], v[186:189], 0
	v_mfma_f32_16x16x32_bf16 v[106:109], v[138:141], v[186:189], 0
	v_mfma_f32_16x16x32_bf16 v[94:97], v[130:133], v[204:207], 0
	v_mfma_f32_16x16x32_bf16 v[90:93], v[138:141], v[204:207], 0
	v_mfma_f32_16x16x32_bf16 v[78:81], v[130:133], v[218:221], 0
	v_mfma_f32_16x16x32_bf16 v[74:77], v[138:141], v[218:221], 0
	v_mfma_f32_16x16x32_bf16 v[126:129], v[134:137], v[182:185], v[126:129]
	v_mfma_f32_16x16x32_bf16 v[122:125], v[142:145], v[182:185], v[122:125]
	v_mfma_f32_16x16x32_bf16 v[110:113], v[134:137], v[200:203], v[110:113]
	v_mfma_f32_16x16x32_bf16 v[106:109], v[142:145], v[200:203], v[106:109]
	v_mfma_f32_16x16x32_bf16 v[94:97], v[134:137], v[214:217], v[94:97]
	v_mfma_f32_16x16x32_bf16 v[90:93], v[142:145], v[214:217], v[90:93]
	v_mfma_f32_16x16x32_bf16 v[78:81], v[134:137], v[222:225], v[78:81]
	v_mfma_f32_16x16x32_bf16 v[74:77], v[142:145], v[222:225], v[74:77]
	s_barrier
	s_add_i32 s39, 0, 0x14000
	v_add_u32_e32 v162, s39, v193
	s_add_i32 s26, s38, s84
	ds_read_b128 v[226:229], v162
	ds_read_b128 v[230:233], v162 offset:1024
	ds_read_b128 v[234:237], v162 offset:2048
	ds_read_b128 v[238:241], v162 offset:3072
	v_lshl_add_u64 v[162:163], s[80:81], 0, v[8:9]
	s_mov_b32 m0, s26
	v_lshl_add_u64 v[164:165], s[80:81], 0, v[176:177]
	global_load_lds_dwordx4 v[162:163], off
	s_add_i32 m0, s26, 0x2000
	s_nop 0
	global_load_lds_dwordx4 v[164:165], off
	s_barrier
	s_waitcnt lgkmcnt(0)
	v_mfma_f32_16x16x32_bf16 v[118:121], v[226:229], v[146:149], 0
	v_mfma_f32_16x16x32_bf16 v[114:117], v[234:237], v[146:149], 0
	v_mfma_f32_16x16x32_bf16 v[102:105], v[226:229], v[186:189], 0
	v_mfma_f32_16x16x32_bf16 v[98:101], v[234:237], v[186:189], 0
	v_mfma_f32_16x16x32_bf16 v[86:89], v[226:229], v[204:207], 0
	v_mfma_f32_16x16x32_bf16 v[82:85], v[234:237], v[204:207], 0
	v_mfma_f32_16x16x32_bf16 v[70:73], v[226:229], v[218:221], 0
	v_mfma_f32_16x16x32_bf16 v[66:69], v[234:237], v[218:221], 0
	v_mfma_f32_16x16x32_bf16 v[118:121], v[230:233], v[182:185], v[118:121]
	v_mfma_f32_16x16x32_bf16 v[114:117], v[238:241], v[182:185], v[114:117]
	v_mfma_f32_16x16x32_bf16 v[102:105], v[230:233], v[200:203], v[102:105]
	v_mfma_f32_16x16x32_bf16 v[98:101], v[238:241], v[200:203], v[98:101]
	v_mfma_f32_16x16x32_bf16 v[86:89], v[230:233], v[214:217], v[86:89]
	v_mfma_f32_16x16x32_bf16 v[82:85], v[238:241], v[214:217], v[82:85]
	v_mfma_f32_16x16x32_bf16 v[70:73], v[230:233], v[222:225], v[70:73]
	v_mfma_f32_16x16x32_bf16 v[66:69], v[238:241], v[222:225], v[66:69]
	s_mov_b32 m0, s85
	v_lshl_add_u64 v[190:191], s[82:83], 0, v[150:151]
	s_barrier
	ds_read_b128 v[146:149], v198 offset:16384
	ds_read_b128 v[182:185], v198 offset:17408
	ds_read_b128 v[186:189], v198 offset:18432
	ds_read_b128 v[200:203], v198 offset:19456
	ds_read_b128 v[204:207], v198 offset:20480
	ds_read_b128 v[214:217], v198 offset:21504
	ds_read_b128 v[218:221], v198 offset:22528
	ds_read_b128 v[222:225], v198 offset:23552
	global_load_lds_dwordx4 v[190:191], off
	s_mov_b32 m0, s86
	v_lshl_add_u64 v[208:209], s[82:83], 0, v[152:153]
	global_load_lds_dwordx4 v[208:209], off
	s_barrier
	s_waitcnt lgkmcnt(0)
	v_mfma_f32_16x16x32_bf16 v[62:65], v[130:133], v[146:149], 0
	v_mfma_f32_16x16x32_bf16 v[58:61], v[138:141], v[146:149], 0
	v_mfma_f32_16x16x32_bf16 v[46:49], v[130:133], v[186:189], 0
	v_mfma_f32_16x16x32_bf16 v[42:45], v[138:141], v[186:189], 0
	v_mfma_f32_16x16x32_bf16 v[30:33], v[130:133], v[204:207], 0
	v_mfma_f32_16x16x32_bf16 v[26:29], v[138:141], v[204:207], 0
	v_mfma_f32_16x16x32_bf16 v[14:17], v[130:133], v[218:221], 0
	v_mfma_f32_16x16x32_bf16 v[10:13], v[138:141], v[218:221], 0
	v_mfma_f32_16x16x32_bf16 v[62:65], v[134:137], v[182:185], v[62:65]
	v_mfma_f32_16x16x32_bf16 v[58:61], v[142:145], v[182:185], v[58:61]
	v_mfma_f32_16x16x32_bf16 v[46:49], v[134:137], v[200:203], v[46:49]
	v_mfma_f32_16x16x32_bf16 v[42:45], v[142:145], v[200:203], v[42:45]
	v_mfma_f32_16x16x32_bf16 v[30:33], v[134:137], v[214:217], v[30:33]
	v_mfma_f32_16x16x32_bf16 v[26:29], v[142:145], v[214:217], v[26:29]
	v_mfma_f32_16x16x32_bf16 v[14:17], v[134:137], v[222:225], v[14:17]
	v_mfma_f32_16x16x32_bf16 v[10:13], v[142:145], v[222:225], v[10:13]
	s_barrier
; #define PG8_STAGE(bufoff, gbase, voff) do { _Pragma("unroll") for (int _i = 0; _i < 2; ++_i) \
;         __builtin_amdgcn_global_load_lds((const unsigned*)((const char*)(gbase) + (voff)[_i]), (LAS unsigned*)(lds + (bufoff) + ldsw + _i * 8192), 16, 0, 0); } while (0)
; #define PG8_LDA(dst, b, h) do { _Pragma("unroll") for (int m = 0; m < 4; ++m) _Pragma("unroll") for (int k = 0; k < 2; ++k) dst[m][k] = *(const LAS bf16x8*)(lds + PG8_SA(b, h) + aoff + m * 2048 + k * 1024); } while (0)
; #define PG8_LDB(dst, b, h) do { _Pragma("unroll") for (int n = 0; n < 2; ++n) _Pragma("unroll") for (int k = 0; k < 2; ++k) dst[n][k] = *(const LAS bf16x8*)(lds + PG8_SB(b, h) + boff + n * 2048 + k * 1024); } while (0)
; #define PG8_MMA(ai, bj, At, Bt) do { __builtin_amdgcn_s_setprio(1); _Pragma("unroll") for (int m = 0; m < 4; ++m) _Pragma("unroll") for (int n = 0; n < 2; ++n) _Pragma("unroll") for (int k = 0; k < 2; ++k) \
;         acc[ai][bj][m][n] = __builtin_amdgcn_mfma_f32_16x16x32_bf16(Bt[n][k], At[m][k], acc[ai][bj][m][n], 0, 0, 0); __builtin_amdgcn_s_setprio(0); } while (0)
; #define PG8_WAIT_V(n) asm volatile("s_waitcnt vmcnt(" #n ")" ::: "memory")
; #define PG8_WAIT_L(n) asm volatile("s_waitcnt lgkmcnt(" #n ")" ::: "memory")
; #define PG8_BAR __builtin_amdgcn_s_barrier()
; #define PG8_SCHED __builtin_amdgcn_sched_barrier(0)
; template <class Epi>
; DEVI void gemm_phase(LAS unsigned char* lds, const Gemm g, const Epi& E) {
;     ...
;             PG8_STAGE(PG8_SB(0, 1), b2 + hstepB, voffB);
;             PG8_WAIT_V(6); PG8_BAR; PG8_MMA(1, 1, At, B1); PG8_BAR;
;             PG8_LDB(B0, 1, 0); PG8_SCHED; PG8_LDA(At, 1, 0); PG8_STAGE(PG8_SA(0, 1), a2 + hstepA, voffA);
;             PG8_WAIT_L(8); PG8_BAR; PG8_WAIT_L(0); PG8_MMA(0, 0, At, B0); PG8_BAR; PG8_SCHED;
;             PG8_LDB(B1, 1, 1); PG8_STAGE(PG8_SB(1, 0), b3, voffB);
	s_add_u32 s26, s80, 0x40000
	s_addc_u32 s27, s81, 0
	s_add_i32 s38, s39, s84
	s_mov_b32 m0, s38
	v_lshl_add_u64 v[130:131], s[26:27], 0, v[8:9]
	global_load_lds_dwordx4 v[130:131], off
	s_add_i32 m0, s38, 0x2000
	v_lshl_add_u64 v[130:131], s[26:27], 0, v[176:177]
	global_load_lds_dwordx4 v[130:131], off
	s_waitcnt vmcnt(6)
	s_barrier
	v_mfma_f32_16x16x32_bf16 v[54:57], v[226:229], v[146:149], 0
	v_mfma_f32_16x16x32_bf16 v[50:53], v[234:237], v[146:149], 0
	v_mfma_f32_16x16x32_bf16 v[38:41], v[226:229], v[186:189], 0
	v_mfma_f32_16x16x32_bf16 v[34:37], v[234:237], v[186:189], 0
	v_mfma_f32_16x16x32_bf16 v[22:25], v[226:229], v[204:207], 0
	v_mfma_f32_16x16x32_bf16 v[18:21], v[234:237], v[204:207], 0
	v_mfma_f32_16x16x32_bf16 v[4:7], v[226:229], v[218:221], 0
	v_mfma_f32_16x16x32_bf16 v[0:3], v[234:237], v[218:221], 0
	v_mfma_f32_16x16x32_bf16 v[54:57], v[230:233], v[182:185], v[54:57]
	v_mfma_f32_16x16x32_bf16 v[50:53], v[238:241], v[182:185], v[50:53]
	v_mfma_f32_16x16x32_bf16 v[38:41], v[230:233], v[200:203], v[38:41]
	v_mfma_f32_16x16x32_bf16 v[34:37], v[238:241], v[200:203], v[34:37]
	v_mfma_f32_16x16x32_bf16 v[22:25], v[230:233], v[214:217], v[22:25]
	v_mfma_f32_16x16x32_bf16 v[18:21], v[238:241], v[214:217], v[18:21]
	v_mfma_f32_16x16x32_bf16 v[4:7], v[230:233], v[222:225], v[4:7]
	v_mfma_f32_16x16x32_bf16 v[0:3], v[238:241], v[222:225], v[0:3]
	s_add_i32 s38, 0, 0x18000
	v_add_u32_e32 v142, s38, v193
	s_barrier
	ds_read_b128 v[130:133], v142
	ds_read_b128 v[134:137], v142 offset:1024
	ds_read_b128 v[138:141], v142 offset:2048
	ds_read_b128 v[142:145], v142 offset:3072
	s_add_u32 s26, s82, 0x40000
	s_addc_u32 s27, s83, 0
	s_mov_b32 m0, s87
	v_lshl_add_u64 v[226:227], s[26:27], 0, v[150:151]
	ds_read_b128 v[146:149], v198 offset:32768
	ds_read_b128 v[182:185], v198 offset:33792
	ds_read_b128 v[186:189], v198 offset:34816
	ds_read_b128 v[200:203], v198 offset:35840
	ds_read_b128 v[204:207], v198 offset:36864
	ds_read_b128 v[214:217], v198 offset:37888
	ds_read_b128 v[218:221], v198 offset:38912
	ds_read_b128 v[222:225], v198 offset:39936
	global_load_lds_dwordx4 v[226:227], off
	s_mov_b32 m0, s88
	v_lshl_add_u64 v[226:227], s[26:27], 0, v[152:153]
	global_load_lds_dwordx4 v[226:227], off
	s_waitcnt lgkmcnt(8)
	s_barrier
	s_waitcnt lgkmcnt(0)
	v_mfma_f32_16x16x32_bf16 v[126:129], v[130:133], v[146:149], v[126:129]
	v_mfma_f32_16x16x32_bf16 v[122:125], v[138:141], v[146:149], v[122:125]
	v_mfma_f32_16x16x32_bf16 v[110:113], v[130:133], v[186:189], v[110:113]
	v_mfma_f32_16x16x32_bf16 v[106:109], v[138:141], v[186:189], v[106:109]
	v_mfma_f32_16x16x32_bf16 v[94:97], v[130:133], v[204:207], v[94:97]
	v_mfma_f32_16x16x32_bf16 v[90:93], v[138:141], v[204:207], v[90:93]
	v_mfma_f32_16x16x32_bf16 v[78:81], v[130:133], v[218:221], v[78:81]
	v_mfma_f32_16x16x32_bf16 v[74:77], v[138:141], v[218:221], v[74:77]
	v_mfma_f32_16x16x32_bf16 v[126:129], v[134:137], v[182:185], v[126:129]
	v_mfma_f32_16x16x32_bf16 v[122:125], v[142:145], v[182:185], v[122:125]
	v_mfma_f32_16x16x32_bf16 v[110:113], v[134:137], v[200:203], v[110:113]
	v_mfma_f32_16x16x32_bf16 v[106:109], v[142:145], v[200:203], v[106:109]
	v_mfma_f32_16x16x32_bf16 v[94:97], v[134:137], v[214:217], v[94:97]
	v_mfma_f32_16x16x32_bf16 v[90:93], v[142:145], v[214:217], v[90:93]
	v_mfma_f32_16x16x32_bf16 v[78:81], v[134:137], v[222:225], v[78:81]
	v_mfma_f32_16x16x32_bf16 v[74:77], v[142:145], v[222:225], v[74:77]
	s_barrier
	s_add_i32 s39, 0, 0x1c000
	s_add_i32 s26, s38, s84
	v_add_u32_e32 v199, s39, v193
	v_lshl_add_u64 v[162:163], v[162:163], 0, s[70:71]
	s_mov_b32 m0, s26
	ds_read_b128 v[226:229], v199
	ds_read_b128 v[230:233], v199 offset:1024
	ds_read_b128 v[234:237], v199 offset:2048
	ds_read_b128 v[238:241], v199 offset:3072
	global_load_lds_dwordx4 v[162:163], off
	s_add_i32 m0, s26, 0x2000
	v_lshl_add_u64 v[162:163], v[164:165], 0, s[70:71]
	global_load_lds_dwordx4 v[162:163], off
	s_barrier
; #define PG8_STAGE(bufoff, gbase, voff) do { _Pragma("unroll") for (int _i = 0; _i < 2; ++_i) \
;         __builtin_amdgcn_global_load_lds((const unsigned*)((const char*)(gbase) + (voff)[_i]), (LAS unsigned*)(lds + (bufoff) + ldsw + _i * 8192), 16, 0, 0); } while (0)
; #define PG8_LDA(dst, b, h) do { _Pragma("unroll") for (int m = 0; m < 4; ++m) _Pragma("unroll") for (int k = 0; k < 2; ++k) dst[m][k] = *(const LAS bf16x8*)(lds + PG8_SA(b, h) + aoff + m * 2048 + k * 1024); } while (0)
; #define PG8_MMA(ai, bj, At, Bt) do { __builtin_amdgcn_s_setprio(1); _Pragma("unroll") for (int m = 0; m < 4; ++m) _Pragma("unroll") for (int n = 0; n < 2; ++n) _Pragma("unroll") for (int k = 0; k < 2; ++k) \
;         acc[ai][bj][m][n] = __builtin_amdgcn_mfma_f32_16x16x32_bf16(Bt[n][k], At[m][k], acc[ai][bj][m][n], 0, 0, 0); __builtin_amdgcn_s_setprio(0); } while (0)
; #define PG8_WAIT_V(n) asm volatile("s_waitcnt vmcnt(" #n ")" ::: "memory")
; #define PG8_WAIT_L(n) asm volatile("s_waitcnt lgkmcnt(" #n ")" ::: "memory")
; #define PG8_BAR __builtin_amdgcn_s_barrier()
; #define PG8_SCHED __builtin_amdgcn_sched_barrier(0)
; template <class Epi>
; DEVI void gemm_phase(LAS unsigned char* lds, const Gemm g, const Epi& E) {
;     ...
;             PG8_BAR; PG8_WAIT_L(0); PG8_MMA(0, 1, At, B1); PG8_BAR;
;             PG8_LDA(At, 1, 1); PG8_STAGE(PG8_SA(1, 0), a3, voffA);
;             PG8_BAR; PG8_WAIT_L(0); PG8_MMA(1, 0, At, B0); PG8_BAR; PG8_SCHED;
;             PG8_STAGE(PG8_SB(1, 1), b3 + hstepB, voffB);
;             PG8_WAIT_V(6); PG8_BAR; PG8_MMA(1, 1, At, B1); PG8_BAR;
;         }
	s_waitcnt lgkmcnt(0)
	v_mfma_f32_16x16x32_bf16 v[118:121], v[226:229], v[146:149], v[118:121]
	v_mfma_f32_16x16x32_bf16 v[114:117], v[234:237], v[146:149], v[114:117]
	v_mfma_f32_16x16x32_bf16 v[102:105], v[226:229], v[186:189], v[102:105]
	v_mfma_f32_16x16x32_bf16 v[98:101], v[234:237], v[186:189], v[98:101]
	v_mfma_f32_16x16x32_bf16 v[86:89], v[226:229], v[204:207], v[86:89]
	v_mfma_f32_16x16x32_bf16 v[82:85], v[234:237], v[204:207], v[82:85]
	v_mfma_f32_16x16x32_bf16 v[70:73], v[226:229], v[218:221], v[70:73]
	v_mfma_f32_16x16x32_bf16 v[66:69], v[234:237], v[218:221], v[66:69]
	v_mfma_f32_16x16x32_bf16 v[118:121], v[230:233], v[182:185], v[118:121]
	v_mfma_f32_16x16x32_bf16 v[114:117], v[238:241], v[182:185], v[114:117]
	v_mfma_f32_16x16x32_bf16 v[102:105], v[230:233], v[200:203], v[102:105]
	v_mfma_f32_16x16x32_bf16 v[98:101], v[238:241], v[200:203], v[98:101]
	v_mfma_f32_16x16x32_bf16 v[86:89], v[230:233], v[214:217], v[86:89]
	v_mfma_f32_16x16x32_bf16 v[82:85], v[238:241], v[214:217], v[82:85]
	v_mfma_f32_16x16x32_bf16 v[70:73], v[230:233], v[222:225], v[70:73]
	v_mfma_f32_16x16x32_bf16 v[66:69], v[238:241], v[222:225], v[66:69]
	s_mov_b32 m0, s89
	v_lshl_add_u64 v[162:163], v[190:191], 0, s[70:71]
	s_barrier
	ds_read_b128 v[146:149], v198 offset:49152
	ds_read_b128 v[182:185], v198 offset:50176
	ds_read_b128 v[186:189], v198 offset:51200
	ds_read_b128 v[200:203], v198 offset:52224
	ds_read_b128 v[204:207], v198 offset:53248
	ds_read_b128 v[214:217], v198 offset:54272
	ds_read_b128 v[218:221], v198 offset:55296
	ds_read_b128 v[222:225], v198 offset:56320
	global_load_lds_dwordx4 v[162:163], off
	s_mov_b32 m0, s90
	v_lshl_add_u64 v[162:163], v[208:209], 0, s[70:71]
	global_load_lds_dwordx4 v[162:163], off
	s_barrier
	s_waitcnt lgkmcnt(0)
	v_mfma_f32_16x16x32_bf16 v[62:65], v[130:133], v[146:149], v[62:65]
	v_mfma_f32_16x16x32_bf16 v[58:61], v[138:141], v[146:149], v[58:61]
	v_mfma_f32_16x16x32_bf16 v[46:49], v[130:133], v[186:189], v[46:49]
	v_mfma_f32_16x16x32_bf16 v[42:45], v[138:141], v[186:189], v[42:45]
	v_mfma_f32_16x16x32_bf16 v[30:33], v[130:133], v[204:207], v[30:33]
	v_mfma_f32_16x16x32_bf16 v[26:29], v[138:141], v[204:207], v[26:29]
	v_mfma_f32_16x16x32_bf16 v[14:17], v[130:133], v[218:221], v[14:17]
	v_mfma_f32_16x16x32_bf16 v[10:13], v[138:141], v[218:221], v[10:13]
	v_mfma_f32_16x16x32_bf16 v[62:65], v[134:137], v[182:185], v[62:65]
	v_mfma_f32_16x16x32_bf16 v[58:61], v[142:145], v[182:185], v[58:61]
	v_mfma_f32_16x16x32_bf16 v[46:49], v[134:137], v[200:203], v[46:49]
	v_mfma_f32_16x16x32_bf16 v[42:45], v[142:145], v[200:203], v[42:45]
	v_mfma_f32_16x16x32_bf16 v[30:33], v[134:137], v[214:217], v[30:33]
	v_mfma_f32_16x16x32_bf16 v[26:29], v[142:145], v[214:217], v[26:29]
	v_mfma_f32_16x16x32_bf16 v[14:17], v[134:137], v[222:225], v[14:17]
	v_mfma_f32_16x16x32_bf16 v[10:13], v[142:145], v[222:225], v[10:13]
	s_barrier
	s_add_u32 s26, s80, 0x40080
	s_addc_u32 s27, s81, 0
	s_add_i32 s38, s39, s84
	s_mov_b32 m0, s38
	v_lshl_add_u64 v[130:131], s[26:27], 0, v[8:9]
	global_load_lds_dwordx4 v[130:131], off
	s_add_i32 m0, s38, 0x2000
	v_lshl_add_u64 v[130:131], s[26:27], 0, v[176:177]
	global_load_lds_dwordx4 v[130:131], off
	s_waitcnt vmcnt(6)
	s_barrier
	v_mfma_f32_16x16x32_bf16 v[54:57], v[226:229], v[146:149], v[54:57]
	v_mfma_f32_16x16x32_bf16 v[50:53], v[234:237], v[146:149], v[50:53]
	v_mfma_f32_16x16x32_bf16 v[38:41], v[226:229], v[186:189], v[38:41]
	v_mfma_f32_16x16x32_bf16 v[34:37], v[234:237], v[186:189], v[34:37]
	v_mfma_f32_16x16x32_bf16 v[22:25], v[226:229], v[204:207], v[22:25]
	v_mfma_f32_16x16x32_bf16 v[18:21], v[234:237], v[204:207], v[18:21]
	v_mfma_f32_16x16x32_bf16 v[4:7], v[226:229], v[218:221], v[4:7]
	v_mfma_f32_16x16x32_bf16 v[0:3], v[234:237], v[218:221], v[0:3]
	v_mfma_f32_16x16x32_bf16 v[54:57], v[230:233], v[182:185], v[54:57]
	v_mfma_f32_16x16x32_bf16 v[50:53], v[238:241], v[182:185], v[50:53]
	v_mfma_f32_16x16x32_bf16 v[38:41], v[230:233], v[200:203], v[38:41]
	v_mfma_f32_16x16x32_bf16 v[34:37], v[238:241], v[200:203], v[34:37]
	v_mfma_f32_16x16x32_bf16 v[22:25], v[230:233], v[214:217], v[22:25]
	v_mfma_f32_16x16x32_bf16 v[18:21], v[238:241], v[214:217], v[18:21]
	v_mfma_f32_16x16x32_bf16 v[4:7], v[230:233], v[222:225], v[4:7]
	v_mfma_f32_16x16x32_bf16 v[0:3], v[238:241], v[222:225], v[0:3]
	s_add_i32 s19, s19, 2
	s_add_u32 s68, s68, 0x100
	s_addc_u32 s69, s69, 0
	s_add_u32 s15, s15, 0x100
	s_addc_u32 s18, s18, 0
	s_cmp_gt_u32 s19, 13
	s_barrier

; DEVI size_t gemm_offB(const Gemm& g, const Unit& u) { return (g.split ? (size_t)(u.b >> 2) * g.sB + (size_t)(u.b & 3) * g.sB_lo : (size_t)u.b * g.sB) + (size_t)(u.pm >> g.pmsh) * g.sBpm; }
; #define PG8_STAGE(bufoff, gbase, voff) do { _Pragma("unroll") for (int _i = 0; _i < 2; ++_i) \
;         __builtin_amdgcn_global_load_lds((const unsigned*)((const char*)(gbase) + (voff)[_i]), (LAS unsigned*)(lds + (bufoff) + ldsw + _i * 8192), 16, 0, 0); } while (0)
; #define PG8_LDA(dst, b, h) do { _Pragma("unroll") for (int m = 0; m < 4; ++m) _Pragma("unroll") for (int k = 0; k < 2; ++k) dst[m][k] = *(const LAS bf16x8*)(lds + PG8_SA(b, h) + aoff + m * 2048 + k * 1024); } while (0)
; #define PG8_WAIT_L(n) asm volatile("s_waitcnt lgkmcnt(" #n ")" ::: "memory")
; #define PG8_BAR __builtin_amdgcn_s_barrier()
; #define PG8_SCHED __builtin_amdgcn_sched_barrier(0)
; template <class Epi>
; DEVI void gemm_phase(LAS unsigned char* lds, const Gemm g, const Epi& E) {
;     ...
;         const char* nA = has_next ? (const char*)g.A + gemm_offA(g, nxt) * 2 + (size_t)nxt.pm * tstepA : cA;
;         const char* nB = has_next ? (const char*)g.Bt + gemm_offB(g, nxt) * 2 + (size_t)nxt.pn * tstepB : cB;
;         for (int t = 0; t < nt; t += 2) {
;             const bool last = (t == nt - 2);
;             const char* a1 = cA + (size_t)(t + 1) * kstep;
;             const char* a2 = last ? nA : cA + (size_t)(t + 2) * kstep; const char* b2 = last ? nB : cB + (size_t)(t + 2) * kstep;
;             const char* a3 = a2 + kstep; const char* b3 = b2 + kstep;
;             PG8_LDB(B0, 0, 0); PG8_SCHED; PG8_LDA(At, 0, 0); PG8_STAGE(PG8_SA(1, 1), a1 + hstepA, voffA);
;             PG8_WAIT_L(8); PG8_BAR; PG8_WAIT_L(0); PG8_MMA(0, 0, At, B0); PG8_BAR; PG8_SCHED;
;             PG8_LDB(B1, 0, 1); PG8_STAGE(PG8_SB(0, 0), b2, voffB);
;             PG8_BAR; PG8_WAIT_L(0); PG8_MMA(0, 1, At, B1); PG8_BAR;
;             PG8_LDA(At, 0, 1); PG8_STAGE(PG8_SA(0, 0), a2, voffA);
;             PG8_BAR; PG8_WAIT_L(0); PG8_MMA(1, 0, At, B0); PG8_BAR; PG8_SCHED;
;     ...
; #pragma unroll
;         for (int a = 0; a < 2; ++a)
; #pragma unroll
;             for (int b = 0; b < 2; ++b)
; #pragma unroll
;                 for (int m = 0; m < 4; ++m)
; #pragma unroll
;                     for (int n = 0; n < 2; ++n) acc[a][b][m][n] = (f32x4){0.f, 0.f, 0.f, 0.f};
;         cur = nxt; cA = nA; cB = nB; ++ui;
.LBB0_1506:
	s_ashr_i32 s13, s12, 31
	s_lshl_b64 s[0:1], s[12:13], 19
	s_add_u32 s16, s28, s0
	s_addc_u32 s17, s29, s1
	s_and_b64 s[0:1], s[6:7], exec
	s_cselect_b32 s0, s17, s69
	s_cselect_b32 s1, s16, s68
	s_add_u32 s6, s68, 0x40080
	s_addc_u32 s7, s69, 0
	s_add_u32 s11, s78, 0x100
	s_addc_u32 s13, s79, 0
	s_mov_b32 s18, -2
	s_add_u32 s19, s6, 0xfffc0080
	s_addc_u32 s26, s7, -1
	s_add_i32 s27, 0, 0x10000
	v_add_u32_e32 v142, s27, v199
	ds_read_b128 v[130:133], v142
	ds_read_b128 v[134:137], v142 offset:1024
	ds_read_b128 v[138:141], v142 offset:2048
	ds_read_b128 v[142:145], v142 offset:3072
	s_cmp_eq_u32 s18, 12
	s_cselect_b32 s79, s0, s26
	s_cselect_b32 s78, s1, s19
	s_cselect_b32 s69, s15, s13
	s_cselect_b32 s68, s14, s11
	v_lshl_add_u64 v[162:163], s[6:7], 0, v[182:183]
	s_add_i32 m0, s37, 0xc000
	ds_read_b128 v[146:149], v202
	ds_read_b128 v[150:153], v202 offset:1024
	ds_read_b128 v[186:189], v202 offset:2048
	ds_read_b128 v[190:193], v202 offset:3072
	ds_read_b128 v[194:197], v202 offset:4096
	ds_read_b128 v[204:207], v202 offset:5120
	ds_read_b128 v[214:217], v202 offset:6144
	ds_read_b128 v[218:221], v202 offset:7168
	global_load_lds_dwordx4 v[162:163], off
	s_add_i32 m0, s37, 0xe000
	v_lshl_add_u64 v[162:163], s[6:7], 0, v[184:185]
	global_load_lds_dwordx4 v[162:163], off
	s_waitcnt lgkmcnt(8)
	s_barrier
	s_waitcnt lgkmcnt(0)
	v_mfma_f32_16x16x32_bf16 v[126:129], v[130:133], v[146:149], 0
	v_mfma_f32_16x16x32_bf16 v[122:125], v[138:141], v[146:149], 0
	v_mfma_f32_16x16x32_bf16 v[110:113], v[130:133], v[186:189], 0
	v_mfma_f32_16x16x32_bf16 v[106:109], v[138:141], v[186:189], 0
	v_mfma_f32_16x16x32_bf16 v[94:97], v[130:133], v[194:197], 0
	v_mfma_f32_16x16x32_bf16 v[90:93], v[138:141], v[194:197], 0
	v_mfma_f32_16x16x32_bf16 v[78:81], v[130:133], v[214:217], 0
	v_mfma_f32_16x16x32_bf16 v[74:77], v[138:141], v[214:217], 0
	v_mfma_f32_16x16x32_bf16 v[126:129], v[134:137], v[150:153], v[126:129]
	v_mfma_f32_16x16x32_bf16 v[122:125], v[142:145], v[150:153], v[122:125]
	v_mfma_f32_16x16x32_bf16 v[110:113], v[134:137], v[190:193], v[110:113]
	v_mfma_f32_16x16x32_bf16 v[106:109], v[142:145], v[190:193], v[106:109]
	v_mfma_f32_16x16x32_bf16 v[94:97], v[134:137], v[204:207], v[94:97]
	v_mfma_f32_16x16x32_bf16 v[90:93], v[142:145], v[204:207], v[90:93]
	v_mfma_f32_16x16x32_bf16 v[78:81], v[134:137], v[218:221], v[78:81]
	v_mfma_f32_16x16x32_bf16 v[74:77], v[142:145], v[218:221], v[74:77]
	s_barrier
	s_add_i32 s19, 0, 0x14000
	v_add_u32_e32 v162, s19, v199
	s_add_i32 s26, s27, s80
	ds_read_b128 v[222:225], v162
	ds_read_b128 v[226:229], v162 offset:1024
	ds_read_b128 v[230:233], v162 offset:2048
	ds_read_b128 v[234:237], v162 offset:3072
	v_lshl_add_u64 v[162:163], s[68:69], 0, v[8:9]
	s_mov_b32 m0, s26
	v_lshl_add_u64 v[164:165], s[68:69], 0, v[180:181]
	global_load_lds_dwordx4 v[162:163], off
	s_add_i32 m0, s26, 0x2000
	s_nop 0
	global_load_lds_dwordx4 v[164:165], off
	s_barrier
	s_waitcnt lgkmcnt(0)
	v_mfma_f32_16x16x32_bf16 v[118:121], v[222:225], v[146:149], 0
	v_mfma_f32_16x16x32_bf16 v[114:117], v[230:233], v[146:149], 0
	v_mfma_f32_16x16x32_bf16 v[102:105], v[222:225], v[186:189], 0
	v_mfma_f32_16x16x32_bf16 v[98:101], v[230:233], v[186:189], 0
	v_mfma_f32_16x16x32_bf16 v[86:89], v[222:225], v[194:197], 0
	v_mfma_f32_16x16x32_bf16 v[82:85], v[230:233], v[194:197], 0
	v_mfma_f32_16x16x32_bf16 v[70:73], v[222:225], v[214:217], 0
	v_mfma_f32_16x16x32_bf16 v[62:65], v[230:233], v[214:217], 0
	v_mfma_f32_16x16x32_bf16 v[118:121], v[226:229], v[150:153], v[118:121]
	v_mfma_f32_16x16x32_bf16 v[114:117], v[234:237], v[150:153], v[114:117]
	v_mfma_f32_16x16x32_bf16 v[102:105], v[226:229], v[190:193], v[102:105]
	v_mfma_f32_16x16x32_bf16 v[98:101], v[234:237], v[190:193], v[98:101]
	v_mfma_f32_16x16x32_bf16 v[86:89], v[226:229], v[204:207], v[86:89]
	v_mfma_f32_16x16x32_bf16 v[82:85], v[234:237], v[204:207], v[82:85]
	v_mfma_f32_16x16x32_bf16 v[70:73], v[226:229], v[218:221], v[70:73]
	v_mfma_f32_16x16x32_bf16 v[62:65], v[234:237], v[218:221], v[62:65]
	s_mov_b32 m0, s37
	v_lshl_add_u64 v[208:209], s[78:79], 0, v[176:177]
	s_barrier
	ds_read_b128 v[146:149], v202 offset:16384
	ds_read_b128 v[150:153], v202 offset:17408
	ds_read_b128 v[186:189], v202 offset:18432
	ds_read_b128 v[190:193], v202 offset:19456
	ds_read_b128 v[194:197], v202 offset:20480
	ds_read_b128 v[204:207], v202 offset:21504
	ds_read_b128 v[214:217], v202 offset:22528
	ds_read_b128 v[218:221], v202 offset:23552
	global_load_lds_dwordx4 v[208:209], off
	s_mov_b32 m0, s47
	v_lshl_add_u64 v[238:239], s[78:79], 0, v[178:179]
	global_load_lds_dwordx4 v[238:239], off
	s_barrier
	s_waitcnt lgkmcnt(0)
	v_mfma_f32_16x16x32_bf16 v[66:69], v[130:133], v[146:149], 0
	v_mfma_f32_16x16x32_bf16 v[54:57], v[138:141], v[146:149], 0
	v_mfma_f32_16x16x32_bf16 v[46:49], v[130:133], v[186:189], 0
	v_mfma_f32_16x16x32_bf16 v[38:41], v[138:141], v[186:189], 0
	v_mfma_f32_16x16x32_bf16 v[30:33], v[130:133], v[194:197], 0
	v_mfma_f32_16x16x32_bf16 v[22:25], v[138:141], v[194:197], 0
	v_mfma_f32_16x16x32_bf16 v[14:17], v[130:133], v[214:217], 0
	v_mfma_f32_16x16x32_bf16 v[4:7], v[138:141], v[214:217], 0
	v_mfma_f32_16x16x32_bf16 v[66:69], v[134:137], v[150:153], v[66:69]
	v_mfma_f32_16x16x32_bf16 v[54:57], v[142:145], v[150:153], v[54:57]
	v_mfma_f32_16x16x32_bf16 v[46:49], v[134:137], v[190:193], v[46:49]
	v_mfma_f32_16x16x32_bf16 v[38:41], v[142:145], v[190:193], v[38:41]
	v_mfma_f32_16x16x32_bf16 v[30:33], v[134:137], v[204:207], v[30:33]
	v_mfma_f32_16x16x32_bf16 v[22:25], v[142:145], v[204:207], v[22:25]
	v_mfma_f32_16x16x32_bf16 v[14:17], v[134:137], v[218:221], v[14:17]
	v_mfma_f32_16x16x32_bf16 v[4:7], v[142:145], v[218:221], v[4:7]
	s_barrier
; #define PG8_STAGE(bufoff, gbase, voff) do { _Pragma("unroll") for (int _i = 0; _i < 2; ++_i) \
;         __builtin_amdgcn_global_load_lds((const unsigned*)((const char*)(gbase) + (voff)[_i]), (LAS unsigned*)(lds + (bufoff) + ldsw + _i * 8192), 16, 0, 0); } while (0)
; #define PG8_LDA(dst, b, h) do { _Pragma("unroll") for (int m = 0; m < 4; ++m) _Pragma("unroll") for (int k = 0; k < 2; ++k) dst[m][k] = *(const LAS bf16x8*)(lds + PG8_SA(b, h) + aoff + m * 2048 + k * 1024); } while (0)
; #define PG8_LDB(dst, b, h) do { _Pragma("unroll") for (int n = 0; n < 2; ++n) _Pragma("unroll") for (int k = 0; k < 2; ++k) dst[n][k] = *(const LAS bf16x8*)(lds + PG8_SB(b, h) + boff + n * 2048 + k * 1024); } while (0)
; #define PG8_MMA(ai, bj, At, Bt) do { __builtin_amdgcn_s_setprio(1); _Pragma("unroll") for (int m = 0; m < 4; ++m) _Pragma("unroll") for (int n = 0; n < 2; ++n) _Pragma("unroll") for (int k = 0; k < 2; ++k) \
;         acc[ai][bj][m][n] = __builtin_amdgcn_mfma_f32_16x16x32_bf16(Bt[n][k], At[m][k], acc[ai][bj][m][n], 0, 0, 0); __builtin_amdgcn_s_setprio(0); } while (0)
; #define PG8_WAIT_V(n) asm volatile("s_waitcnt vmcnt(" #n ")" ::: "memory")
; #define PG8_WAIT_L(n) asm volatile("s_waitcnt lgkmcnt(" #n ")" ::: "memory")
; #define PG8_BAR __builtin_amdgcn_s_barrier()
; #define PG8_SCHED __builtin_amdgcn_sched_barrier(0)
; template <class Epi>
; DEVI void gemm_phase(LAS unsigned char* lds, const Gemm g, const Epi& E) {
;     ...
;             PG8_STAGE(PG8_SB(0, 1), b2 + hstepB, voffB);
;             PG8_WAIT_V(6); PG8_BAR; PG8_MMA(1, 1, At, B1); PG8_BAR;
;             PG8_LDB(B0, 1, 0); PG8_SCHED; PG8_LDA(At, 1, 0); PG8_STAGE(PG8_SA(0, 1), a2 + hstepA, voffA);
;             PG8_WAIT_L(8); PG8_BAR; PG8_WAIT_L(0); PG8_MMA(0, 0, At, B0); PG8_BAR; PG8_SCHED;
;             PG8_LDB(B1, 1, 1); PG8_STAGE(PG8_SB(1, 0), b3, voffB);
	s_add_u32 s26, s68, 0x40000
	s_addc_u32 s27, s69, 0
	s_add_i32 s19, s19, s80
	s_mov_b32 m0, s19
	v_lshl_add_u64 v[130:131], s[26:27], 0, v[8:9]
	global_load_lds_dwordx4 v[130:131], off
	s_add_i32 m0, s19, 0x2000
	v_lshl_add_u64 v[130:131], s[26:27], 0, v[180:181]
	global_load_lds_dwordx4 v[130:131], off
	s_waitcnt vmcnt(6)
	s_barrier
	v_mfma_f32_16x16x32_bf16 v[58:61], v[222:225], v[146:149], 0
	v_mfma_f32_16x16x32_bf16 v[50:53], v[230:233], v[146:149], 0
	v_mfma_f32_16x16x32_bf16 v[42:45], v[222:225], v[186:189], 0
	v_mfma_f32_16x16x32_bf16 v[34:37], v[230:233], v[186:189], 0
	v_mfma_f32_16x16x32_bf16 v[26:29], v[222:225], v[194:197], 0
	v_mfma_f32_16x16x32_bf16 v[18:21], v[230:233], v[194:197], 0
	v_mfma_f32_16x16x32_bf16 v[10:13], v[222:225], v[214:217], 0
	v_mfma_f32_16x16x32_bf16 v[0:3], v[230:233], v[214:217], 0
	v_mfma_f32_16x16x32_bf16 v[58:61], v[226:229], v[150:153], v[58:61]
	v_mfma_f32_16x16x32_bf16 v[50:53], v[234:237], v[150:153], v[50:53]
	v_mfma_f32_16x16x32_bf16 v[42:45], v[226:229], v[190:193], v[42:45]
	v_mfma_f32_16x16x32_bf16 v[34:37], v[234:237], v[190:193], v[34:37]
	v_mfma_f32_16x16x32_bf16 v[26:29], v[226:229], v[204:207], v[26:29]
	v_mfma_f32_16x16x32_bf16 v[18:21], v[234:237], v[204:207], v[18:21]
	v_mfma_f32_16x16x32_bf16 v[10:13], v[226:229], v[218:221], v[10:13]
	v_mfma_f32_16x16x32_bf16 v[0:3], v[234:237], v[218:221], v[0:3]
	s_add_i32 s19, 0, 0x18000
	v_add_u32_e32 v142, s19, v199
	s_barrier
	ds_read_b128 v[130:133], v142
	ds_read_b128 v[134:137], v142 offset:1024
	ds_read_b128 v[138:141], v142 offset:2048
	ds_read_b128 v[142:145], v142 offset:3072
	s_add_u32 s26, s78, 0x40000
	s_addc_u32 s27, s79, 0
	s_mov_b32 m0, s81
	v_lshl_add_u64 v[222:223], s[26:27], 0, v[176:177]
	ds_read_b128 v[146:149], v202 offset:32768
	ds_read_b128 v[150:153], v202 offset:33792
	ds_read_b128 v[186:189], v202 offset:34816
	ds_read_b128 v[190:193], v202 offset:35840
	ds_read_b128 v[194:197], v202 offset:36864
	ds_read_b128 v[204:207], v202 offset:37888
	ds_read_b128 v[214:217], v202 offset:38912
	ds_read_b128 v[218:221], v202 offset:39936
	global_load_lds_dwordx4 v[222:223], off
	s_mov_b32 m0, s82
	v_lshl_add_u64 v[222:223], s[26:27], 0, v[178:179]
	global_load_lds_dwordx4 v[222:223], off
	s_waitcnt lgkmcnt(8)
	s_barrier
	s_waitcnt lgkmcnt(0)
	v_mfma_f32_16x16x32_bf16 v[126:129], v[130:133], v[146:149], v[126:129]
	v_mfma_f32_16x16x32_bf16 v[122:125], v[138:141], v[146:149], v[122:125]
	v_mfma_f32_16x16x32_bf16 v[110:113], v[130:133], v[186:189], v[110:113]
	v_mfma_f32_16x16x32_bf16 v[106:109], v[138:141], v[186:189], v[106:109]
	v_mfma_f32_16x16x32_bf16 v[94:97], v[130:133], v[194:197], v[94:97]
	v_mfma_f32_16x16x32_bf16 v[90:93], v[138:141], v[194:197], v[90:93]
	v_mfma_f32_16x16x32_bf16 v[78:81], v[130:133], v[214:217], v[78:81]
	v_mfma_f32_16x16x32_bf16 v[74:77], v[138:141], v[214:217], v[74:77]
	v_mfma_f32_16x16x32_bf16 v[126:129], v[134:137], v[150:153], v[126:129]
	v_mfma_f32_16x16x32_bf16 v[122:125], v[142:145], v[150:153], v[122:125]
	v_mfma_f32_16x16x32_bf16 v[110:113], v[134:137], v[190:193], v[110:113]
	v_mfma_f32_16x16x32_bf16 v[106:109], v[142:145], v[190:193], v[106:109]
	v_mfma_f32_16x16x32_bf16 v[94:97], v[134:137], v[204:207], v[94:97]
	v_mfma_f32_16x16x32_bf16 v[90:93], v[142:145], v[204:207], v[90:93]
	v_mfma_f32_16x16x32_bf16 v[78:81], v[134:137], v[218:221], v[78:81]
	v_mfma_f32_16x16x32_bf16 v[74:77], v[142:145], v[218:221], v[74:77]
	s_barrier
	s_add_i32 s38, 0, 0x1c000
	s_add_i32 s19, s19, s80
	v_add_u32_e32 v213, s38, v199
	v_lshl_add_u64 v[162:163], v[162:163], 0, s[70:71]
	s_mov_b32 m0, s19
	ds_read_b128 v[222:225], v213
	ds_read_b128 v[226:229], v213 offset:1024
	ds_read_b128 v[230:233], v213 offset:2048
	ds_read_b128 v[234:237], v213 offset:3072
	global_load_lds_dwordx4 v[162:163], off
	s_add_i32 m0, s19, 0x2000
	v_lshl_add_u64 v[162:163], v[164:165], 0, s[70:71]
	global_load_lds_dwordx4 v[162:163], off
	s_barrier
; #define PG8_STAGE(bufoff, gbase, voff) do { _Pragma("unroll") for (int _i = 0; _i < 2; ++_i) \
;         __builtin_amdgcn_global_load_lds((const unsigned*)((const char*)(gbase) + (voff)[_i]), (LAS unsigned*)(lds + (bufoff) + ldsw + _i * 8192), 16, 0, 0); } while (0)
; #define PG8_LDA(dst, b, h) do { _Pragma("unroll") for (int m = 0; m < 4; ++m) _Pragma("unroll") for (int k = 0; k < 2; ++k) dst[m][k] = *(const LAS bf16x8*)(lds + PG8_SA(b, h) + aoff + m * 2048 + k * 1024); } while (0)
; #define PG8_MMA(ai, bj, At, Bt) do { __builtin_amdgcn_s_setprio(1); _Pragma("unroll") for (int m = 0; m < 4; ++m) _Pragma("unroll") for (int n = 0; n < 2; ++n) _Pragma("unroll") for (int k = 0; k < 2; ++k) \
;         acc[ai][bj][m][n] = __builtin_amdgcn_mfma_f32_16x16x32_bf16(Bt[n][k], At[m][k], acc[ai][bj][m][n], 0, 0, 0); __builtin_amdgcn_s_setprio(0); } while (0)
; #define PG8_WAIT_V(n) asm volatile("s_waitcnt vmcnt(" #n ")" ::: "memory")
; #define PG8_WAIT_L(n) asm volatile("s_waitcnt lgkmcnt(" #n ")" ::: "memory")
; #define PG8_BAR __builtin_amdgcn_s_barrier()
; #define PG8_SCHED __builtin_amdgcn_sched_barrier(0)
; template <class Epi>
; DEVI void gemm_phase(LAS unsigned char* lds, const Gemm g, const Epi& E) {
;     ...
;             PG8_BAR; PG8_WAIT_L(0); PG8_MMA(0, 1, At, B1); PG8_BAR;
;             PG8_LDA(At, 1, 1); PG8_STAGE(PG8_SA(1, 0), a3, voffA);
;             PG8_BAR; PG8_WAIT_L(0); PG8_MMA(1, 0, At, B0); PG8_BAR; PG8_SCHED;
;             PG8_STAGE(PG8_SB(1, 1), b3 + hstepB, voffB);
;             PG8_WAIT_V(6); PG8_BAR; PG8_MMA(1, 1, At, B1); PG8_BAR;
;         }
	s_waitcnt lgkmcnt(0)
	v_mfma_f32_16x16x32_bf16 v[118:121], v[222:225], v[146:149], v[118:121]
	v_mfma_f32_16x16x32_bf16 v[114:117], v[230:233], v[146:149], v[114:117]
	v_mfma_f32_16x16x32_bf16 v[102:105], v[222:225], v[186:189], v[102:105]
	v_mfma_f32_16x16x32_bf16 v[98:101], v[230:233], v[186:189], v[98:101]
	v_mfma_f32_16x16x32_bf16 v[86:89], v[222:225], v[194:197], v[86:89]
	v_mfma_f32_16x16x32_bf16 v[82:85], v[230:233], v[194:197], v[82:85]
	v_mfma_f32_16x16x32_bf16 v[70:73], v[222:225], v[214:217], v[70:73]
	v_mfma_f32_16x16x32_bf16 v[62:65], v[230:233], v[214:217], v[62:65]
	v_mfma_f32_16x16x32_bf16 v[118:121], v[226:229], v[150:153], v[118:121]
	v_mfma_f32_16x16x32_bf16 v[114:117], v[234:237], v[150:153], v[114:117]
	v_mfma_f32_16x16x32_bf16 v[102:105], v[226:229], v[190:193], v[102:105]
	v_mfma_f32_16x16x32_bf16 v[98:101], v[234:237], v[190:193], v[98:101]
	v_mfma_f32_16x16x32_bf16 v[86:89], v[226:229], v[204:207], v[86:89]
	v_mfma_f32_16x16x32_bf16 v[82:85], v[234:237], v[204:207], v[82:85]
	v_mfma_f32_16x16x32_bf16 v[70:73], v[226:229], v[218:221], v[70:73]
	v_mfma_f32_16x16x32_bf16 v[62:65], v[234:237], v[218:221], v[62:65]
	s_mov_b32 m0, s83
	v_lshl_add_u64 v[162:163], v[208:209], 0, s[70:71]
	s_barrier
	ds_read_b128 v[146:149], v202 offset:49152
	ds_read_b128 v[150:153], v202 offset:50176
	ds_read_b128 v[186:189], v202 offset:51200
	ds_read_b128 v[190:193], v202 offset:52224
	ds_read_b128 v[194:197], v202 offset:53248
	ds_read_b128 v[204:207], v202 offset:54272
	ds_read_b128 v[214:217], v202 offset:55296
	ds_read_b128 v[218:221], v202 offset:56320
	global_load_lds_dwordx4 v[162:163], off
	s_mov_b32 m0, s84
	v_lshl_add_u64 v[162:163], v[238:239], 0, s[70:71]
	global_load_lds_dwordx4 v[162:163], off
	s_barrier
	s_waitcnt lgkmcnt(0)
	v_mfma_f32_16x16x32_bf16 v[66:69], v[130:133], v[146:149], v[66:69]
	v_mfma_f32_16x16x32_bf16 v[54:57], v[138:141], v[146:149], v[54:57]
	v_mfma_f32_16x16x32_bf16 v[46:49], v[130:133], v[186:189], v[46:49]
	v_mfma_f32_16x16x32_bf16 v[38:41], v[138:141], v[186:189], v[38:41]
	v_mfma_f32_16x16x32_bf16 v[30:33], v[130:133], v[194:197], v[30:33]
	v_mfma_f32_16x16x32_bf16 v[22:25], v[138:141], v[194:197], v[22:25]
	v_mfma_f32_16x16x32_bf16 v[14:17], v[130:133], v[214:217], v[14:17]
	v_mfma_f32_16x16x32_bf16 v[4:7], v[138:141], v[214:217], v[4:7]
	v_mfma_f32_16x16x32_bf16 v[66:69], v[134:137], v[150:153], v[66:69]
	v_mfma_f32_16x16x32_bf16 v[54:57], v[142:145], v[150:153], v[54:57]
	v_mfma_f32_16x16x32_bf16 v[46:49], v[134:137], v[190:193], v[46:49]
	v_mfma_f32_16x16x32_bf16 v[38:41], v[142:145], v[190:193], v[38:41]
	v_mfma_f32_16x16x32_bf16 v[30:33], v[134:137], v[204:207], v[30:33]
	v_mfma_f32_16x16x32_bf16 v[22:25], v[142:145], v[204:207], v[22:25]
	v_mfma_f32_16x16x32_bf16 v[14:17], v[134:137], v[218:221], v[14:17]
	v_mfma_f32_16x16x32_bf16 v[4:7], v[142:145], v[218:221], v[4:7]
	s_barrier
	s_add_u32 s26, s68, 0x40080
	s_addc_u32 s27, s69, 0
	s_add_i32 s19, s38, s80
	s_mov_b32 m0, s19
	v_lshl_add_u64 v[130:131], s[26:27], 0, v[8:9]
	global_load_lds_dwordx4 v[130:131], off
	s_add_i32 m0, s19, 0x2000
	v_lshl_add_u64 v[130:131], s[26:27], 0, v[180:181]
	global_load_lds_dwordx4 v[130:131], off
	s_waitcnt vmcnt(6)
	s_barrier
	v_mfma_f32_16x16x32_bf16 v[58:61], v[222:225], v[146:149], v[58:61]
	v_mfma_f32_16x16x32_bf16 v[50:53], v[230:233], v[146:149], v[50:53]
	v_mfma_f32_16x16x32_bf16 v[42:45], v[222:225], v[186:189], v[42:45]
	v_mfma_f32_16x16x32_bf16 v[34:37], v[230:233], v[186:189], v[34:37]
	v_mfma_f32_16x16x32_bf16 v[26:29], v[222:225], v[194:197], v[26:29]
	v_mfma_f32_16x16x32_bf16 v[18:21], v[230:233], v[194:197], v[18:21]
	v_mfma_f32_16x16x32_bf16 v[10:13], v[222:225], v[214:217], v[10:13]
	v_mfma_f32_16x16x32_bf16 v[0:3], v[230:233], v[214:217], v[0:3]
	v_mfma_f32_16x16x32_bf16 v[58:61], v[226:229], v[150:153], v[58:61]
	v_mfma_f32_16x16x32_bf16 v[50:53], v[234:237], v[150:153], v[50:53]
	v_mfma_f32_16x16x32_bf16 v[42:45], v[226:229], v[190:193], v[42:45]
	v_mfma_f32_16x16x32_bf16 v[34:37], v[234:237], v[190:193], v[34:37]
	v_mfma_f32_16x16x32_bf16 v[26:29], v[226:229], v[204:207], v[26:29]
	v_mfma_f32_16x16x32_bf16 v[18:21], v[234:237], v[204:207], v[18:21]
	v_mfma_f32_16x16x32_bf16 v[10:13], v[226:229], v[218:221], v[10:13]
	v_mfma_f32_16x16x32_bf16 v[0:3], v[234:237], v[218:221], v[0:3]
	s_add_i32 s18, s18, 2
	s_add_u32 s6, s6, 0x100
	s_addc_u32 s7, s7, 0
	s_add_u32 s11, s11, 0x100
	s_addc_u32 s13, s13, 0
	s_cmp_gt_u32 s18, 13
	s_barrier

; DEVI size_t gemm_offB(const Gemm& g, const Unit& u) { return (g.split ? (size_t)(u.b >> 2) * g.sB + (size_t)(u.b & 3) * g.sB_lo : (size_t)u.b * g.sB) + (size_t)(u.pm >> g.pmsh) * g.sBpm; }
; #define PG8_STAGE(bufoff, gbase, voff) do { _Pragma("unroll") for (int _i = 0; _i < 2; ++_i) \
;         __builtin_amdgcn_global_load_lds((const unsigned*)((const char*)(gbase) + (voff)[_i]), (LAS unsigned*)(lds + (bufoff) + ldsw + _i * 8192), 16, 0, 0); } while (0)
; #define PG8_LDA(dst, b, h) do { _Pragma("unroll") for (int m = 0; m < 4; ++m) _Pragma("unroll") for (int k = 0; k < 2; ++k) dst[m][k] = *(const LAS bf16x8*)(lds + PG8_SA(b, h) + aoff + m * 2048 + k * 1024); } while (0)
; #define PG8_WAIT_L(n) asm volatile("s_waitcnt lgkmcnt(" #n ")" ::: "memory")
; #define PG8_BAR __builtin_amdgcn_s_barrier()
; #define PG8_SCHED __builtin_amdgcn_sched_barrier(0)
; template <class Epi>
; DEVI void gemm_phase(LAS unsigned char* lds, const Gemm g, const Epi& E) {
;     ...
;         const char* nA = has_next ? (const char*)g.A + gemm_offA(g, nxt) * 2 + (size_t)nxt.pm * tstepA : cA;
;         const char* nB = has_next ? (const char*)g.Bt + gemm_offB(g, nxt) * 2 + (size_t)nxt.pn * tstepB : cB;
;         for (int t = 0; t < nt; t += 2) {
;             const bool last = (t == nt - 2);
;             const char* a1 = cA + (size_t)(t + 1) * kstep;
;             const char* a2 = last ? nA : cA + (size_t)(t + 2) * kstep; const char* b2 = last ? nB : cB + (size_t)(t + 2) * kstep;
;             const char* a3 = a2 + kstep; const char* b3 = b2 + kstep;
;             PG8_LDB(B0, 0, 0); PG8_SCHED; PG8_LDA(At, 0, 0); PG8_STAGE(PG8_SA(1, 1), a1 + hstepA, voffA);
;             PG8_WAIT_L(8); PG8_BAR; PG8_WAIT_L(0); PG8_MMA(0, 0, At, B0); PG8_BAR; PG8_SCHED;
;             PG8_LDB(B1, 0, 1); PG8_STAGE(PG8_SB(0, 0), b2, voffB);
;             PG8_BAR; PG8_WAIT_L(0); PG8_MMA(0, 1, At, B1); PG8_BAR;
;             PG8_LDA(At, 0, 1); PG8_STAGE(PG8_SA(0, 0), a2, voffA);
;             PG8_BAR; PG8_WAIT_L(0); PG8_MMA(1, 0, At, B0); PG8_BAR; PG8_SCHED;
;     ...
; #pragma unroll
;         for (int a = 0; a < 2; ++a)
; #pragma unroll
;             for (int b = 0; b < 2; ++b)
; #pragma unroll
;                 for (int m = 0; m < 4; ++m)
; #pragma unroll
;                     for (int n = 0; n < 2; ++n) acc[a][b][m][n] = (f32x4){0.f, 0.f, 0.f, 0.f};
;         cur = nxt; cA = nA; cB = nB; ++ui;
.LBB0_1594:
	s_ashr_i32 s17, s16, 31
	s_lshl_b64 s[0:1], s[16:17], 19
	v_readlane_b32 s18, v251, 2
	v_readlane_b32 s19, v251, 3
	s_add_u32 s46, s18, s0
	s_addc_u32 s47, s19, s1
	s_and_b64 s[0:1], s[8:9], exec
	s_cselect_b32 s0, s47, s79
	s_cselect_b32 s1, s46, s78
	s_add_u32 s8, s78, 0x40080
	s_addc_u32 s9, s79, 0
	s_add_u32 s13, s80, 0x100
	s_addc_u32 s15, s81, 0
	s_mov_b32 s17, -2
	s_waitcnt lgkmcnt(0)
	s_add_u32 s18, s8, 0xfffc0080
	s_addc_u32 s19, s9, -1
	s_add_i32 s26, 0, 0x10000
	v_add_u32_e32 v142, s26, v191
	ds_read_b128 v[130:133], v142
	ds_read_b128 v[134:137], v142 offset:1024
	ds_read_b128 v[138:141], v142 offset:2048
	ds_read_b128 v[142:145], v142 offset:3072
	s_cmp_eq_u32 s17, 12
	s_cselect_b32 s81, s0, s19
	s_cselect_b32 s80, s1, s18
	s_cselect_b32 s79, s37, s15
	s_cselect_b32 s78, s36, s13
	v_lshl_add_u64 v[162:163], s[8:9], 0, v[152:153]
	s_add_i32 m0, s69, 0xc000
	ds_read_b128 v[178:181], v196
	ds_read_b128 v[182:185], v196 offset:1024
	ds_read_b128 v[186:189], v196 offset:2048
	ds_read_b128 v[198:201], v196 offset:3072
	ds_read_b128 v[202:205], v196 offset:4096
	ds_read_b128 v[206:209], v196 offset:5120
	ds_read_b128 v[214:217], v196 offset:6144
	ds_read_b128 v[218:221], v196 offset:7168
	global_load_lds_dwordx4 v[162:163], off
	s_add_i32 m0, s69, 0xe000
	v_lshl_add_u64 v[162:163], s[8:9], 0, v[176:177]
	global_load_lds_dwordx4 v[162:163], off
	s_waitcnt lgkmcnt(8)
	s_barrier
	s_waitcnt lgkmcnt(0)
	v_mfma_f32_16x16x32_bf16 v[126:129], v[130:133], v[178:181], 0
	v_mfma_f32_16x16x32_bf16 v[122:125], v[138:141], v[178:181], 0
	v_mfma_f32_16x16x32_bf16 v[110:113], v[130:133], v[186:189], 0
	v_mfma_f32_16x16x32_bf16 v[106:109], v[138:141], v[186:189], 0
	v_mfma_f32_16x16x32_bf16 v[94:97], v[130:133], v[202:205], 0
	v_mfma_f32_16x16x32_bf16 v[90:93], v[138:141], v[202:205], 0
	v_mfma_f32_16x16x32_bf16 v[78:81], v[130:133], v[214:217], 0
	v_mfma_f32_16x16x32_bf16 v[74:77], v[138:141], v[214:217], 0
	v_mfma_f32_16x16x32_bf16 v[126:129], v[134:137], v[182:185], v[126:129]
	v_mfma_f32_16x16x32_bf16 v[122:125], v[142:145], v[182:185], v[122:125]
	v_mfma_f32_16x16x32_bf16 v[110:113], v[134:137], v[198:201], v[110:113]
	v_mfma_f32_16x16x32_bf16 v[106:109], v[142:145], v[198:201], v[106:109]
	v_mfma_f32_16x16x32_bf16 v[94:97], v[134:137], v[206:209], v[94:97]
	v_mfma_f32_16x16x32_bf16 v[90:93], v[142:145], v[206:209], v[90:93]
	v_mfma_f32_16x16x32_bf16 v[78:81], v[134:137], v[218:221], v[78:81]
	v_mfma_f32_16x16x32_bf16 v[74:77], v[142:145], v[218:221], v[74:77]
	s_barrier
	s_add_i32 s27, 0, 0x14000
	v_add_u32_e32 v162, s27, v191
	s_add_i32 s18, s26, s82
	ds_read_b128 v[222:225], v162
	ds_read_b128 v[226:229], v162 offset:1024
	ds_read_b128 v[230:233], v162 offset:2048
	ds_read_b128 v[234:237], v162 offset:3072
	v_lshl_add_u64 v[162:163], s[78:79], 0, v[8:9]
	s_mov_b32 m0, s18
	v_lshl_add_u64 v[164:165], s[78:79], 0, v[150:151]
	global_load_lds_dwordx4 v[162:163], off
	s_add_i32 m0, s18, 0x2000
	s_nop 0
	global_load_lds_dwordx4 v[164:165], off
	s_barrier
	s_waitcnt lgkmcnt(0)
	v_mfma_f32_16x16x32_bf16 v[118:121], v[222:225], v[178:181], 0
	v_mfma_f32_16x16x32_bf16 v[114:117], v[230:233], v[178:181], 0
	v_mfma_f32_16x16x32_bf16 v[102:105], v[222:225], v[186:189], 0
	v_mfma_f32_16x16x32_bf16 v[98:101], v[230:233], v[186:189], 0
	v_mfma_f32_16x16x32_bf16 v[86:89], v[222:225], v[202:205], 0
	v_mfma_f32_16x16x32_bf16 v[82:85], v[230:233], v[202:205], 0
	v_mfma_f32_16x16x32_bf16 v[70:73], v[222:225], v[214:217], 0
	v_mfma_f32_16x16x32_bf16 v[66:69], v[230:233], v[214:217], 0
	v_mfma_f32_16x16x32_bf16 v[118:121], v[226:229], v[182:185], v[118:121]
	v_mfma_f32_16x16x32_bf16 v[114:117], v[234:237], v[182:185], v[114:117]
	v_mfma_f32_16x16x32_bf16 v[102:105], v[226:229], v[198:201], v[102:105]
	v_mfma_f32_16x16x32_bf16 v[98:101], v[234:237], v[198:201], v[98:101]
	v_mfma_f32_16x16x32_bf16 v[86:89], v[226:229], v[206:209], v[86:89]
	v_mfma_f32_16x16x32_bf16 v[82:85], v[234:237], v[206:209], v[82:85]
	v_mfma_f32_16x16x32_bf16 v[70:73], v[226:229], v[218:221], v[70:73]
	v_mfma_f32_16x16x32_bf16 v[66:69], v[234:237], v[218:221], v[66:69]
	s_mov_b32 m0, s69
	v_lshl_add_u64 v[238:239], s[80:81], 0, v[146:147]
	s_barrier
	ds_read_b128 v[178:181], v196 offset:16384
	ds_read_b128 v[182:185], v196 offset:17408
	ds_read_b128 v[186:189], v196 offset:18432
	ds_read_b128 v[198:201], v196 offset:19456
	ds_read_b128 v[202:205], v196 offset:20480
	ds_read_b128 v[206:209], v196 offset:21504
	ds_read_b128 v[214:217], v196 offset:22528
	ds_read_b128 v[218:221], v196 offset:23552
	global_load_lds_dwordx4 v[238:239], off
	s_mov_b32 m0, s83
	v_lshl_add_u64 v[240:241], s[80:81], 0, v[148:149]
	global_load_lds_dwordx4 v[240:241], off
	s_barrier
	s_waitcnt lgkmcnt(0)
	v_mfma_f32_16x16x32_bf16 v[62:65], v[130:133], v[178:181], 0
	v_mfma_f32_16x16x32_bf16 v[58:61], v[138:141], v[178:181], 0
	v_mfma_f32_16x16x32_bf16 v[46:49], v[130:133], v[186:189], 0
	v_mfma_f32_16x16x32_bf16 v[42:45], v[138:141], v[186:189], 0
	v_mfma_f32_16x16x32_bf16 v[30:33], v[130:133], v[202:205], 0
	v_mfma_f32_16x16x32_bf16 v[26:29], v[138:141], v[202:205], 0
	v_mfma_f32_16x16x32_bf16 v[14:17], v[130:133], v[214:217], 0
	v_mfma_f32_16x16x32_bf16 v[10:13], v[138:141], v[214:217], 0
	v_mfma_f32_16x16x32_bf16 v[62:65], v[134:137], v[182:185], v[62:65]
	v_mfma_f32_16x16x32_bf16 v[58:61], v[142:145], v[182:185], v[58:61]
	v_mfma_f32_16x16x32_bf16 v[46:49], v[134:137], v[198:201], v[46:49]
	v_mfma_f32_16x16x32_bf16 v[42:45], v[142:145], v[198:201], v[42:45]
	v_mfma_f32_16x16x32_bf16 v[30:33], v[134:137], v[206:209], v[30:33]
	v_mfma_f32_16x16x32_bf16 v[26:29], v[142:145], v[206:209], v[26:29]
	v_mfma_f32_16x16x32_bf16 v[14:17], v[134:137], v[218:221], v[14:17]
	v_mfma_f32_16x16x32_bf16 v[10:13], v[142:145], v[218:221], v[10:13]
	s_barrier
; #define PG8_STAGE(bufoff, gbase, voff) do { _Pragma("unroll") for (int _i = 0; _i < 2; ++_i) \
;         __builtin_amdgcn_global_load_lds((const unsigned*)((const char*)(gbase) + (voff)[_i]), (LAS unsigned*)(lds + (bufoff) + ldsw + _i * 8192), 16, 0, 0); } while (0)
; #define PG8_LDA(dst, b, h) do { _Pragma("unroll") for (int m = 0; m < 4; ++m) _Pragma("unroll") for (int k = 0; k < 2; ++k) dst[m][k] = *(const LAS bf16x8*)(lds + PG8_SA(b, h) + aoff + m * 2048 + k * 1024); } while (0)
; #define PG8_LDB(dst, b, h) do { _Pragma("unroll") for (int n = 0; n < 2; ++n) _Pragma("unroll") for (int k = 0; k < 2; ++k) dst[n][k] = *(const LAS bf16x8*)(lds + PG8_SB(b, h) + boff + n * 2048 + k * 1024); } while (0)
; #define PG8_MMA(ai, bj, At, Bt) do { __builtin_amdgcn_s_setprio(1); _Pragma("unroll") for (int m = 0; m < 4; ++m) _Pragma("unroll") for (int n = 0; n < 2; ++n) _Pragma("unroll") for (int k = 0; k < 2; ++k) \
;         acc[ai][bj][m][n] = __builtin_amdgcn_mfma_f32_16x16x32_bf16(Bt[n][k], At[m][k], acc[ai][bj][m][n], 0, 0, 0); __builtin_amdgcn_s_setprio(0); } while (0)
; #define PG8_WAIT_V(n) asm volatile("s_waitcnt vmcnt(" #n ")" ::: "memory")
; #define PG8_WAIT_L(n) asm volatile("s_waitcnt lgkmcnt(" #n ")" ::: "memory")
; #define PG8_BAR __builtin_amdgcn_s_barrier()
; #define PG8_SCHED __builtin_amdgcn_sched_barrier(0)
; template <class Epi>
; DEVI void gemm_phase(LAS unsigned char* lds, const Gemm g, const Epi& E) {
;     ...
;             PG8_STAGE(PG8_SB(0, 1), b2 + hstepB, voffB);
;             PG8_WAIT_V(6); PG8_BAR; PG8_MMA(1, 1, At, B1); PG8_BAR;
;             PG8_LDB(B0, 1, 0); PG8_SCHED; PG8_LDA(At, 1, 0); PG8_STAGE(PG8_SA(0, 1), a2 + hstepA, voffA);
;             PG8_WAIT_L(8); PG8_BAR; PG8_WAIT_L(0); PG8_MMA(0, 0, At, B0); PG8_BAR; PG8_SCHED;
;             PG8_LDB(B1, 1, 1); PG8_STAGE(PG8_SB(1, 0), b3, voffB);
	s_add_u32 s18, s78, 0x40000
	s_addc_u32 s19, s79, 0
	s_add_i32 s26, s27, s82
	s_mov_b32 m0, s26
	v_lshl_add_u64 v[130:131], s[18:19], 0, v[8:9]
	global_load_lds_dwordx4 v[130:131], off
	s_add_i32 m0, s26, 0x2000
	v_lshl_add_u64 v[130:131], s[18:19], 0, v[150:151]
	global_load_lds_dwordx4 v[130:131], off
	s_waitcnt vmcnt(6)
	s_barrier
	v_mfma_f32_16x16x32_bf16 v[54:57], v[222:225], v[178:181], 0
	v_mfma_f32_16x16x32_bf16 v[50:53], v[230:233], v[178:181], 0
	v_mfma_f32_16x16x32_bf16 v[38:41], v[222:225], v[186:189], 0
	v_mfma_f32_16x16x32_bf16 v[34:37], v[230:233], v[186:189], 0
	v_mfma_f32_16x16x32_bf16 v[22:25], v[222:225], v[202:205], 0
	v_mfma_f32_16x16x32_bf16 v[18:21], v[230:233], v[202:205], 0
	v_mfma_f32_16x16x32_bf16 v[4:7], v[222:225], v[214:217], 0
	v_mfma_f32_16x16x32_bf16 v[0:3], v[230:233], v[214:217], 0
	v_mfma_f32_16x16x32_bf16 v[54:57], v[226:229], v[182:185], v[54:57]
	v_mfma_f32_16x16x32_bf16 v[50:53], v[234:237], v[182:185], v[50:53]
	v_mfma_f32_16x16x32_bf16 v[38:41], v[226:229], v[198:201], v[38:41]
	v_mfma_f32_16x16x32_bf16 v[34:37], v[234:237], v[198:201], v[34:37]
	v_mfma_f32_16x16x32_bf16 v[22:25], v[226:229], v[206:209], v[22:25]
	v_mfma_f32_16x16x32_bf16 v[18:21], v[234:237], v[206:209], v[18:21]
	v_mfma_f32_16x16x32_bf16 v[4:7], v[226:229], v[218:221], v[4:7]
	v_mfma_f32_16x16x32_bf16 v[0:3], v[234:237], v[218:221], v[0:3]
	s_add_i32 s26, 0, 0x18000
	v_add_u32_e32 v142, s26, v191
	s_barrier
	ds_read_b128 v[130:133], v142
	ds_read_b128 v[134:137], v142 offset:1024
	ds_read_b128 v[138:141], v142 offset:2048
	ds_read_b128 v[142:145], v142 offset:3072
	s_add_u32 s18, s80, 0x40000
	s_addc_u32 s19, s81, 0
	s_mov_b32 m0, s84
	v_lshl_add_u64 v[222:223], s[18:19], 0, v[146:147]
	ds_read_b128 v[178:181], v196 offset:32768
	ds_read_b128 v[182:185], v196 offset:33792
	ds_read_b128 v[186:189], v196 offset:34816
	ds_read_b128 v[198:201], v196 offset:35840
	ds_read_b128 v[202:205], v196 offset:36864
	ds_read_b128 v[206:209], v196 offset:37888
	ds_read_b128 v[214:217], v196 offset:38912
	ds_read_b128 v[218:221], v196 offset:39936
	global_load_lds_dwordx4 v[222:223], off
	s_mov_b32 m0, s85
	v_lshl_add_u64 v[222:223], s[18:19], 0, v[148:149]
	global_load_lds_dwordx4 v[222:223], off
	s_waitcnt lgkmcnt(8)
	s_barrier
	s_waitcnt lgkmcnt(0)
	v_mfma_f32_16x16x32_bf16 v[126:129], v[130:133], v[178:181], v[126:129]
	v_mfma_f32_16x16x32_bf16 v[122:125], v[138:141], v[178:181], v[122:125]
	v_mfma_f32_16x16x32_bf16 v[110:113], v[130:133], v[186:189], v[110:113]
	v_mfma_f32_16x16x32_bf16 v[106:109], v[138:141], v[186:189], v[106:109]
	v_mfma_f32_16x16x32_bf16 v[94:97], v[130:133], v[202:205], v[94:97]
	v_mfma_f32_16x16x32_bf16 v[90:93], v[138:141], v[202:205], v[90:93]
	v_mfma_f32_16x16x32_bf16 v[78:81], v[130:133], v[214:217], v[78:81]
	v_mfma_f32_16x16x32_bf16 v[74:77], v[138:141], v[214:217], v[74:77]
	v_mfma_f32_16x16x32_bf16 v[126:129], v[134:137], v[182:185], v[126:129]
	v_mfma_f32_16x16x32_bf16 v[122:125], v[142:145], v[182:185], v[122:125]
	v_mfma_f32_16x16x32_bf16 v[110:113], v[134:137], v[198:201], v[110:113]
	v_mfma_f32_16x16x32_bf16 v[106:109], v[142:145], v[198:201], v[106:109]
	v_mfma_f32_16x16x32_bf16 v[94:97], v[134:137], v[206:209], v[94:97]
	v_mfma_f32_16x16x32_bf16 v[90:93], v[142:145], v[206:209], v[90:93]
	v_mfma_f32_16x16x32_bf16 v[78:81], v[134:137], v[218:221], v[78:81]
	v_mfma_f32_16x16x32_bf16 v[74:77], v[142:145], v[218:221], v[74:77]
	s_barrier
	s_add_i32 s27, 0, 0x1c000
	s_add_i32 s18, s26, s82
	v_add_u32_e32 v197, s27, v191
	v_lshl_add_u64 v[162:163], v[162:163], 0, s[70:71]
	s_mov_b32 m0, s18
	ds_read_b128 v[222:225], v197
	ds_read_b128 v[226:229], v197 offset:1024
	ds_read_b128 v[230:233], v197 offset:2048
	ds_read_b128 v[234:237], v197 offset:3072
	global_load_lds_dwordx4 v[162:163], off
	s_add_i32 m0, s18, 0x2000
	v_lshl_add_u64 v[162:163], v[164:165], 0, s[70:71]
	global_load_lds_dwordx4 v[162:163], off
	s_barrier
; #define PG8_STAGE(bufoff, gbase, voff) do { _Pragma("unroll") for (int _i = 0; _i < 2; ++_i) \
;         __builtin_amdgcn_global_load_lds((const unsigned*)((const char*)(gbase) + (voff)[_i]), (LAS unsigned*)(lds + (bufoff) + ldsw + _i * 8192), 16, 0, 0); } while (0)
; #define PG8_LDA(dst, b, h) do { _Pragma("unroll") for (int m = 0; m < 4; ++m) _Pragma("unroll") for (int k = 0; k < 2; ++k) dst[m][k] = *(const LAS bf16x8*)(lds + PG8_SA(b, h) + aoff + m * 2048 + k * 1024); } while (0)
; #define PG8_MMA(ai, bj, At, Bt) do { __builtin_amdgcn_s_setprio(1); _Pragma("unroll") for (int m = 0; m < 4; ++m) _Pragma("unroll") for (int n = 0; n < 2; ++n) _Pragma("unroll") for (int k = 0; k < 2; ++k) \
;         acc[ai][bj][m][n] = __builtin_amdgcn_mfma_f32_16x16x32_bf16(Bt[n][k], At[m][k], acc[ai][bj][m][n], 0, 0, 0); __builtin_amdgcn_s_setprio(0); } while (0)
; #define PG8_WAIT_V(n) asm volatile("s_waitcnt vmcnt(" #n ")" ::: "memory")
; #define PG8_WAIT_L(n) asm volatile("s_waitcnt lgkmcnt(" #n ")" ::: "memory")
; #define PG8_BAR __builtin_amdgcn_s_barrier()
; #define PG8_SCHED __builtin_amdgcn_sched_barrier(0)
; template <class Epi>
; DEVI void gemm_phase(LAS unsigned char* lds, const Gemm g, const Epi& E) {
;     ...
;             PG8_BAR; PG8_WAIT_L(0); PG8_MMA(0, 1, At, B1); PG8_BAR;
;             PG8_LDA(At, 1, 1); PG8_STAGE(PG8_SA(1, 0), a3, voffA);
;             PG8_BAR; PG8_WAIT_L(0); PG8_MMA(1, 0, At, B0); PG8_BAR; PG8_SCHED;
;             PG8_STAGE(PG8_SB(1, 1), b3 + hstepB, voffB);
;             PG8_WAIT_V(6); PG8_BAR; PG8_MMA(1, 1, At, B1); PG8_BAR;
;         }
	s_waitcnt lgkmcnt(0)
	v_mfma_f32_16x16x32_bf16 v[118:121], v[222:225], v[178:181], v[118:121]
	v_mfma_f32_16x16x32_bf16 v[114:117], v[230:233], v[178:181], v[114:117]
	v_mfma_f32_16x16x32_bf16 v[102:105], v[222:225], v[186:189], v[102:105]
	v_mfma_f32_16x16x32_bf16 v[98:101], v[230:233], v[186:189], v[98:101]
	v_mfma_f32_16x16x32_bf16 v[86:89], v[222:225], v[202:205], v[86:89]
	v_mfma_f32_16x16x32_bf16 v[82:85], v[230:233], v[202:205], v[82:85]
	v_mfma_f32_16x16x32_bf16 v[70:73], v[222:225], v[214:217], v[70:73]
	v_mfma_f32_16x16x32_bf16 v[66:69], v[230:233], v[214:217], v[66:69]
	v_mfma_f32_16x16x32_bf16 v[118:121], v[226:229], v[182:185], v[118:121]
	v_mfma_f32_16x16x32_bf16 v[114:117], v[234:237], v[182:185], v[114:117]
	v_mfma_f32_16x16x32_bf16 v[102:105], v[226:229], v[198:201], v[102:105]
	v_mfma_f32_16x16x32_bf16 v[98:101], v[234:237], v[198:201], v[98:101]
	v_mfma_f32_16x16x32_bf16 v[86:89], v[226:229], v[206:209], v[86:89]
	v_mfma_f32_16x16x32_bf16 v[82:85], v[234:237], v[206:209], v[82:85]
	v_mfma_f32_16x16x32_bf16 v[70:73], v[226:229], v[218:221], v[70:73]
	v_mfma_f32_16x16x32_bf16 v[66:69], v[234:237], v[218:221], v[66:69]
	s_mov_b32 m0, s86
	v_lshl_add_u64 v[162:163], v[238:239], 0, s[70:71]
	s_barrier
	ds_read_b128 v[178:181], v196 offset:49152
	ds_read_b128 v[182:185], v196 offset:50176
	ds_read_b128 v[186:189], v196 offset:51200
	ds_read_b128 v[198:201], v196 offset:52224
	ds_read_b128 v[202:205], v196 offset:53248
	ds_read_b128 v[206:209], v196 offset:54272
	ds_read_b128 v[214:217], v196 offset:55296
	ds_read_b128 v[218:221], v196 offset:56320
	global_load_lds_dwordx4 v[162:163], off
	s_mov_b32 m0, s87
	v_lshl_add_u64 v[162:163], v[240:241], 0, s[70:71]
	global_load_lds_dwordx4 v[162:163], off
	s_barrier
	s_waitcnt lgkmcnt(0)
	v_mfma_f32_16x16x32_bf16 v[62:65], v[130:133], v[178:181], v[62:65]
	v_mfma_f32_16x16x32_bf16 v[58:61], v[138:141], v[178:181], v[58:61]
	v_mfma_f32_16x16x32_bf16 v[46:49], v[130:133], v[186:189], v[46:49]
	v_mfma_f32_16x16x32_bf16 v[42:45], v[138:141], v[186:189], v[42:45]
	v_mfma_f32_16x16x32_bf16 v[30:33], v[130:133], v[202:205], v[30:33]
	v_mfma_f32_16x16x32_bf16 v[26:29], v[138:141], v[202:205], v[26:29]
	v_mfma_f32_16x16x32_bf16 v[14:17], v[130:133], v[214:217], v[14:17]
	v_mfma_f32_16x16x32_bf16 v[10:13], v[138:141], v[214:217], v[10:13]
	v_mfma_f32_16x16x32_bf16 v[62:65], v[134:137], v[182:185], v[62:65]
	v_mfma_f32_16x16x32_bf16 v[58:61], v[142:145], v[182:185], v[58:61]
	v_mfma_f32_16x16x32_bf16 v[46:49], v[134:137], v[198:201], v[46:49]
	v_mfma_f32_16x16x32_bf16 v[42:45], v[142:145], v[198:201], v[42:45]
	v_mfma_f32_16x16x32_bf16 v[30:33], v[134:137], v[206:209], v[30:33]
	v_mfma_f32_16x16x32_bf16 v[26:29], v[142:145], v[206:209], v[26:29]
	v_mfma_f32_16x16x32_bf16 v[14:17], v[134:137], v[218:221], v[14:17]
	v_mfma_f32_16x16x32_bf16 v[10:13], v[142:145], v[218:221], v[10:13]
	s_barrier
	s_add_u32 s18, s78, 0x40080
	s_addc_u32 s19, s79, 0
	s_add_i32 s26, s27, s82
	s_mov_b32 m0, s26
	v_lshl_add_u64 v[130:131], s[18:19], 0, v[8:9]
	global_load_lds_dwordx4 v[130:131], off
	s_add_i32 m0, s26, 0x2000
	v_lshl_add_u64 v[130:131], s[18:19], 0, v[150:151]
	global_load_lds_dwordx4 v[130:131], off
	s_waitcnt vmcnt(6)
	s_barrier
	v_mfma_f32_16x16x32_bf16 v[54:57], v[222:225], v[178:181], v[54:57]
	v_mfma_f32_16x16x32_bf16 v[50:53], v[230:233], v[178:181], v[50:53]
	v_mfma_f32_16x16x32_bf16 v[38:41], v[222:225], v[186:189], v[38:41]
	v_mfma_f32_16x16x32_bf16 v[34:37], v[230:233], v[186:189], v[34:37]
	v_mfma_f32_16x16x32_bf16 v[22:25], v[222:225], v[202:205], v[22:25]
	v_mfma_f32_16x16x32_bf16 v[18:21], v[230:233], v[202:205], v[18:21]
	v_mfma_f32_16x16x32_bf16 v[4:7], v[222:225], v[214:217], v[4:7]
	v_mfma_f32_16x16x32_bf16 v[0:3], v[230:233], v[214:217], v[0:3]
	v_mfma_f32_16x16x32_bf16 v[54:57], v[226:229], v[182:185], v[54:57]
	v_mfma_f32_16x16x32_bf16 v[50:53], v[234:237], v[182:185], v[50:53]
	v_mfma_f32_16x16x32_bf16 v[38:41], v[226:229], v[198:201], v[38:41]
	v_mfma_f32_16x16x32_bf16 v[34:37], v[234:237], v[198:201], v[34:37]
	v_mfma_f32_16x16x32_bf16 v[22:25], v[226:229], v[206:209], v[22:25]
	v_mfma_f32_16x16x32_bf16 v[18:21], v[234:237], v[206:209], v[18:21]
	v_mfma_f32_16x16x32_bf16 v[4:7], v[226:229], v[218:221], v[4:7]
	v_mfma_f32_16x16x32_bf16 v[0:3], v[234:237], v[218:221], v[0:3]
	s_add_i32 s17, s17, 2
	s_add_u32 s8, s8, 0x100
	s_addc_u32 s9, s9, 0
	s_add_u32 s13, s13, 0x100
	s_addc_u32 s15, s15, 0
	s_cmp_gt_u32 s17, 13
	s_barrier

; DEVI size_t gemm_offB(const Gemm& g, const Unit& u) { return (g.split ? (size_t)(u.b >> 2) * g.sB + (size_t)(u.b & 3) * g.sB_lo : (size_t)u.b * g.sB) + (size_t)(u.pm >> g.pmsh) * g.sBpm; }
; #define PG8_STAGE(bufoff, gbase, voff) do { _Pragma("unroll") for (int _i = 0; _i < 2; ++_i) \
;         __builtin_amdgcn_global_load_lds((const unsigned*)((const char*)(gbase) + (voff)[_i]), (LAS unsigned*)(lds + (bufoff) + ldsw + _i * 8192), 16, 0, 0); } while (0)
; #define PG8_LDA(dst, b, h) do { _Pragma("unroll") for (int m = 0; m < 4; ++m) _Pragma("unroll") for (int k = 0; k < 2; ++k) dst[m][k] = *(const LAS bf16x8*)(lds + PG8_SA(b, h) + aoff + m * 2048 + k * 1024); } while (0)
; #define PG8_WAIT_L(n) asm volatile("s_waitcnt lgkmcnt(" #n ")" ::: "memory")
; #define PG8_BAR __builtin_amdgcn_s_barrier()
; #define PG8_SCHED __builtin_amdgcn_sched_barrier(0)
; template <class Epi>
; DEVI void gemm_phase(LAS unsigned char* lds, const Gemm g, const Epi& E) {
;     ...
;         const char* nA = has_next ? (const char*)g.A + gemm_offA(g, nxt) * 2 + (size_t)nxt.pm * tstepA : cA;
;         const char* nB = has_next ? (const char*)g.Bt + gemm_offB(g, nxt) * 2 + (size_t)nxt.pn * tstepB : cB;
;         for (int t = 0; t < nt; t += 2) {
;             const bool last = (t == nt - 2);
;             const char* a1 = cA + (size_t)(t + 1) * kstep;
;             const char* a2 = last ? nA : cA + (size_t)(t + 2) * kstep; const char* b2 = last ? nB : cB + (size_t)(t + 2) * kstep;
;             const char* a3 = a2 + kstep; const char* b3 = b2 + kstep;
;             PG8_LDB(B0, 0, 0); PG8_SCHED; PG8_LDA(At, 0, 0); PG8_STAGE(PG8_SA(1, 1), a1 + hstepA, voffA);
;             PG8_WAIT_L(8); PG8_BAR; PG8_WAIT_L(0); PG8_MMA(0, 0, At, B0); PG8_BAR; PG8_SCHED;
;             PG8_LDB(B1, 0, 1); PG8_STAGE(PG8_SB(0, 0), b2, voffB);
;             PG8_BAR; PG8_WAIT_L(0); PG8_MMA(0, 1, At, B1); PG8_BAR;
;             PG8_LDA(At, 0, 1); PG8_STAGE(PG8_SA(0, 0), a2, voffA);
;             PG8_BAR; PG8_WAIT_L(0); PG8_MMA(1, 0, At, B0); PG8_BAR; PG8_SCHED;
;     ...
; #pragma unroll
;         for (int a = 0; a < 2; ++a)
; #pragma unroll
;             for (int b = 0; b < 2; ++b)
; #pragma unroll
;                 for (int m = 0; m < 4; ++m)
; #pragma unroll
;                     for (int n = 0; n < 2; ++n) acc[a][b][m][n] = (f32x4){0.f, 0.f, 0.f, 0.f};
;         cur = nxt; cA = nA; cB = nB; ++ui;
.LBB0_1671:
	s_ashr_i32 s7, s6, 31
	s_lshl_b64 s[0:1], s[6:7], 19
	v_cmp_lt_i64_e32 vcc, s[12:13], v[174:175]
	s_add_u32 s12, s24, s0
	s_addc_u32 s13, s25, s1
	s_and_b64 s[0:1], vcc, exec
	s_cselect_b32 s0, s13, s17
	s_cselect_b32 s1, s12, s16
	s_ashr_i32 s9, s8, 31
	s_lshl_b64 s[14:15], s[8:9], 19
	s_add_u32 s14, s68, s14
	s_addc_u32 s15, s69, s15
	s_and_b64 s[18:19], vcc, exec
	s_cselect_b32 s5, s15, s37
	s_cselect_b32 s7, s14, s36
	s_add_u32 s16, s16, 0x40080
	s_addc_u32 s17, s17, 0
	s_add_u32 s9, s36, 0x100
	s_addc_u32 s18, s37, 0
	s_mov_b32 s19, -2
	s_add_u32 s26, s16, 0xfffc0080
	s_addc_u32 s27, s17, -1
	s_add_i32 s38, 0, 0x10000
	v_add_u32_e32 v142, s38, v197
	ds_read_b128 v[130:133], v142
	ds_read_b128 v[134:137], v142 offset:1024
	ds_read_b128 v[138:141], v142 offset:2048
	ds_read_b128 v[142:145], v142 offset:3072
	s_cmp_eq_u32 s19, 12
	s_cselect_b32 s47, s0, s27
	s_cselect_b32 s46, s1, s26
	s_cselect_b32 s37, s5, s18
	s_cselect_b32 s36, s7, s9
	v_lshl_add_u64 v[162:163], s[16:17], 0, v[152:153]
	s_add_i32 m0, s79, 0xc000
	ds_read_b128 v[178:181], v201
	ds_read_b128 v[182:185], v201 offset:1024
	ds_read_b128 v[186:189], v201 offset:2048
	ds_read_b128 v[202:205], v201 offset:3072
	ds_read_b128 v[206:209], v201 offset:4096
	ds_read_b128 v[214:217], v201 offset:5120
	ds_read_b128 v[218:221], v201 offset:6144
	ds_read_b128 v[222:225], v201 offset:7168
	global_load_lds_dwordx4 v[162:163], off
	s_add_i32 m0, s79, 0xe000
	v_lshl_add_u64 v[162:163], s[16:17], 0, v[176:177]
	global_load_lds_dwordx4 v[162:163], off
	s_waitcnt lgkmcnt(8)
	s_barrier
	s_waitcnt lgkmcnt(0)
	v_mfma_f32_16x16x32_bf16 v[126:129], v[130:133], v[178:181], 0
	v_mfma_f32_16x16x32_bf16 v[122:125], v[138:141], v[178:181], 0
	v_mfma_f32_16x16x32_bf16 v[110:113], v[130:133], v[186:189], 0
	v_mfma_f32_16x16x32_bf16 v[106:109], v[138:141], v[186:189], 0
	v_mfma_f32_16x16x32_bf16 v[94:97], v[130:133], v[206:209], 0
	v_mfma_f32_16x16x32_bf16 v[90:93], v[138:141], v[206:209], 0
	v_mfma_f32_16x16x32_bf16 v[78:81], v[130:133], v[218:221], 0
	v_mfma_f32_16x16x32_bf16 v[74:77], v[138:141], v[218:221], 0
	v_mfma_f32_16x16x32_bf16 v[126:129], v[134:137], v[182:185], v[126:129]
	v_mfma_f32_16x16x32_bf16 v[122:125], v[142:145], v[182:185], v[122:125]
	v_mfma_f32_16x16x32_bf16 v[110:113], v[134:137], v[202:205], v[110:113]
	v_mfma_f32_16x16x32_bf16 v[106:109], v[142:145], v[202:205], v[106:109]
	v_mfma_f32_16x16x32_bf16 v[94:97], v[134:137], v[214:217], v[94:97]
	v_mfma_f32_16x16x32_bf16 v[90:93], v[142:145], v[214:217], v[90:93]
	v_mfma_f32_16x16x32_bf16 v[78:81], v[134:137], v[222:225], v[78:81]
	v_mfma_f32_16x16x32_bf16 v[74:77], v[142:145], v[222:225], v[74:77]
	s_barrier
	s_add_i32 s39, 0, 0x14000
	v_add_u32_e32 v162, s39, v197
	s_add_i32 s26, s38, s78
	ds_read_b128 v[226:229], v162
	ds_read_b128 v[230:233], v162 offset:1024
	ds_read_b128 v[234:237], v162 offset:2048
	ds_read_b128 v[238:241], v162 offset:3072
	v_lshl_add_u64 v[162:163], s[36:37], 0, v[8:9]
	s_mov_b32 m0, s26
	v_lshl_add_u64 v[164:165], s[36:37], 0, v[146:147]
	global_load_lds_dwordx4 v[162:163], off
	s_add_i32 m0, s26, 0x2000
	s_nop 0
	global_load_lds_dwordx4 v[164:165], off
	s_barrier
	s_waitcnt lgkmcnt(0)
	v_mfma_f32_16x16x32_bf16 v[118:121], v[226:229], v[178:181], 0
	v_mfma_f32_16x16x32_bf16 v[114:117], v[234:237], v[178:181], 0
	v_mfma_f32_16x16x32_bf16 v[102:105], v[226:229], v[186:189], 0
	v_mfma_f32_16x16x32_bf16 v[98:101], v[234:237], v[186:189], 0
	v_mfma_f32_16x16x32_bf16 v[86:89], v[226:229], v[206:209], 0
	v_mfma_f32_16x16x32_bf16 v[82:85], v[234:237], v[206:209], 0
	v_mfma_f32_16x16x32_bf16 v[70:73], v[226:229], v[218:221], 0
	v_mfma_f32_16x16x32_bf16 v[66:69], v[234:237], v[218:221], 0
	v_mfma_f32_16x16x32_bf16 v[118:121], v[230:233], v[182:185], v[118:121]
	v_mfma_f32_16x16x32_bf16 v[114:117], v[238:241], v[182:185], v[114:117]
	v_mfma_f32_16x16x32_bf16 v[102:105], v[230:233], v[202:205], v[102:105]
	v_mfma_f32_16x16x32_bf16 v[98:101], v[238:241], v[202:205], v[98:101]
	v_mfma_f32_16x16x32_bf16 v[86:89], v[230:233], v[214:217], v[86:89]
	v_mfma_f32_16x16x32_bf16 v[82:85], v[238:241], v[214:217], v[82:85]
	v_mfma_f32_16x16x32_bf16 v[70:73], v[230:233], v[222:225], v[70:73]
	v_mfma_f32_16x16x32_bf16 v[66:69], v[238:241], v[222:225], v[66:69]
	s_mov_b32 m0, s79
	v_lshl_add_u64 v[190:191], s[46:47], 0, v[150:151]
	s_barrier
	ds_read_b128 v[178:181], v201 offset:16384
	ds_read_b128 v[182:185], v201 offset:17408
	ds_read_b128 v[186:189], v201 offset:18432
	ds_read_b128 v[202:205], v201 offset:19456
	ds_read_b128 v[206:209], v201 offset:20480
	ds_read_b128 v[214:217], v201 offset:21504
	ds_read_b128 v[218:221], v201 offset:22528
	ds_read_b128 v[222:225], v201 offset:23552
	global_load_lds_dwordx4 v[190:191], off
	s_mov_b32 m0, s80
	v_lshl_add_u64 v[194:195], s[46:47], 0, v[148:149]
	global_load_lds_dwordx4 v[194:195], off
	s_barrier
	s_waitcnt lgkmcnt(0)
	v_mfma_f32_16x16x32_bf16 v[50:53], v[130:133], v[178:181], 0
	v_mfma_f32_16x16x32_bf16 v[54:57], v[138:141], v[178:181], 0
	v_mfma_f32_16x16x32_bf16 v[34:37], v[130:133], v[186:189], 0
	v_mfma_f32_16x16x32_bf16 v[38:41], v[138:141], v[186:189], 0
	v_mfma_f32_16x16x32_bf16 v[18:21], v[130:133], v[206:209], 0
	v_mfma_f32_16x16x32_bf16 v[22:25], v[138:141], v[206:209], 0
	v_mfma_f32_16x16x32_bf16 v[0:3], v[130:133], v[218:221], 0
	v_mfma_f32_16x16x32_bf16 v[4:7], v[138:141], v[218:221], 0
	v_mfma_f32_16x16x32_bf16 v[50:53], v[134:137], v[182:185], v[50:53]
	v_mfma_f32_16x16x32_bf16 v[54:57], v[142:145], v[182:185], v[54:57]
	v_mfma_f32_16x16x32_bf16 v[34:37], v[134:137], v[202:205], v[34:37]
	v_mfma_f32_16x16x32_bf16 v[38:41], v[142:145], v[202:205], v[38:41]
	v_mfma_f32_16x16x32_bf16 v[18:21], v[134:137], v[214:217], v[18:21]
	v_mfma_f32_16x16x32_bf16 v[22:25], v[142:145], v[214:217], v[22:25]
	v_mfma_f32_16x16x32_bf16 v[0:3], v[134:137], v[222:225], v[0:3]
	v_mfma_f32_16x16x32_bf16 v[4:7], v[142:145], v[222:225], v[4:7]
	s_barrier
; #define PG8_STAGE(bufoff, gbase, voff) do { _Pragma("unroll") for (int _i = 0; _i < 2; ++_i) \
;         __builtin_amdgcn_global_load_lds((const unsigned*)((const char*)(gbase) + (voff)[_i]), (LAS unsigned*)(lds + (bufoff) + ldsw + _i * 8192), 16, 0, 0); } while (0)
; #define PG8_LDA(dst, b, h) do { _Pragma("unroll") for (int m = 0; m < 4; ++m) _Pragma("unroll") for (int k = 0; k < 2; ++k) dst[m][k] = *(const LAS bf16x8*)(lds + PG8_SA(b, h) + aoff + m * 2048 + k * 1024); } while (0)
; #define PG8_LDB(dst, b, h) do { _Pragma("unroll") for (int n = 0; n < 2; ++n) _Pragma("unroll") for (int k = 0; k < 2; ++k) dst[n][k] = *(const LAS bf16x8*)(lds + PG8_SB(b, h) + boff + n * 2048 + k * 1024); } while (0)
; #define PG8_MMA(ai, bj, At, Bt) do { __builtin_amdgcn_s_setprio(1); _Pragma("unroll") for (int m = 0; m < 4; ++m) _Pragma("unroll") for (int n = 0; n < 2; ++n) _Pragma("unroll") for (int k = 0; k < 2; ++k) \
;         acc[ai][bj][m][n] = __builtin_amdgcn_mfma_f32_16x16x32_bf16(Bt[n][k], At[m][k], acc[ai][bj][m][n], 0, 0, 0); __builtin_amdgcn_s_setprio(0); } while (0)
; #define PG8_WAIT_V(n) asm volatile("s_waitcnt vmcnt(" #n ")" ::: "memory")
; #define PG8_WAIT_L(n) asm volatile("s_waitcnt lgkmcnt(" #n ")" ::: "memory")
; #define PG8_BAR __builtin_amdgcn_s_barrier()
; #define PG8_SCHED __builtin_amdgcn_sched_barrier(0)
; template <class Epi>
; DEVI void gemm_phase(LAS unsigned char* lds, const Gemm g, const Epi& E) {
;     ...
;             PG8_STAGE(PG8_SB(0, 1), b2 + hstepB, voffB);
;             PG8_WAIT_V(6); PG8_BAR; PG8_MMA(1, 1, At, B1); PG8_BAR;
;             PG8_LDB(B0, 1, 0); PG8_SCHED; PG8_LDA(At, 1, 0); PG8_STAGE(PG8_SA(0, 1), a2 + hstepA, voffA);
;             PG8_WAIT_L(8); PG8_BAR; PG8_WAIT_L(0); PG8_MMA(0, 0, At, B0); PG8_BAR; PG8_SCHED;
;             PG8_LDB(B1, 1, 1); PG8_STAGE(PG8_SB(1, 0), b3, voffB);
	s_add_u32 s26, s36, 0x40000
	s_addc_u32 s27, s37, 0
	s_add_i32 s38, s39, s78
	s_mov_b32 m0, s38
	v_lshl_add_u64 v[130:131], s[26:27], 0, v[8:9]
	global_load_lds_dwordx4 v[130:131], off
	s_add_i32 m0, s38, 0x2000
	v_lshl_add_u64 v[130:131], s[26:27], 0, v[146:147]
	global_load_lds_dwordx4 v[130:131], off
	s_waitcnt vmcnt(6)
	s_barrier
	v_mfma_f32_16x16x32_bf16 v[58:61], v[226:229], v[178:181], 0
	v_mfma_f32_16x16x32_bf16 v[62:65], v[234:237], v[178:181], 0
	v_mfma_f32_16x16x32_bf16 v[42:45], v[226:229], v[186:189], 0
	v_mfma_f32_16x16x32_bf16 v[46:49], v[234:237], v[186:189], 0
	v_mfma_f32_16x16x32_bf16 v[26:29], v[226:229], v[206:209], 0
	v_mfma_f32_16x16x32_bf16 v[30:33], v[234:237], v[206:209], 0
	v_mfma_f32_16x16x32_bf16 v[10:13], v[226:229], v[218:221], 0
	v_mfma_f32_16x16x32_bf16 v[14:17], v[234:237], v[218:221], 0
	v_mfma_f32_16x16x32_bf16 v[58:61], v[230:233], v[182:185], v[58:61]
	v_mfma_f32_16x16x32_bf16 v[62:65], v[238:241], v[182:185], v[62:65]
	v_mfma_f32_16x16x32_bf16 v[42:45], v[230:233], v[202:205], v[42:45]
	v_mfma_f32_16x16x32_bf16 v[46:49], v[238:241], v[202:205], v[46:49]
	v_mfma_f32_16x16x32_bf16 v[26:29], v[230:233], v[214:217], v[26:29]
	v_mfma_f32_16x16x32_bf16 v[30:33], v[238:241], v[214:217], v[30:33]
	v_mfma_f32_16x16x32_bf16 v[10:13], v[230:233], v[222:225], v[10:13]
	v_mfma_f32_16x16x32_bf16 v[14:17], v[238:241], v[222:225], v[14:17]
	s_add_i32 s38, 0, 0x18000
	v_add_u32_e32 v142, s38, v197
	s_barrier
	ds_read_b128 v[130:133], v142
	ds_read_b128 v[134:137], v142 offset:1024
	ds_read_b128 v[138:141], v142 offset:2048
	ds_read_b128 v[142:145], v142 offset:3072
	s_add_u32 s26, s46, 0x40000
	s_addc_u32 s27, s47, 0
	s_mov_b32 m0, s81
	v_lshl_add_u64 v[226:227], s[26:27], 0, v[150:151]
	ds_read_b128 v[178:181], v201 offset:32768
	ds_read_b128 v[182:185], v201 offset:33792
	ds_read_b128 v[186:189], v201 offset:34816
	ds_read_b128 v[202:205], v201 offset:35840
	ds_read_b128 v[206:209], v201 offset:36864
	ds_read_b128 v[214:217], v201 offset:37888
	ds_read_b128 v[218:221], v201 offset:38912
	ds_read_b128 v[222:225], v201 offset:39936
	global_load_lds_dwordx4 v[226:227], off
	s_mov_b32 m0, s82
	v_lshl_add_u64 v[226:227], s[26:27], 0, v[148:149]
	global_load_lds_dwordx4 v[226:227], off
	s_waitcnt lgkmcnt(8)
	s_barrier
	s_waitcnt lgkmcnt(0)
	v_mfma_f32_16x16x32_bf16 v[126:129], v[130:133], v[178:181], v[126:129]
	v_mfma_f32_16x16x32_bf16 v[122:125], v[138:141], v[178:181], v[122:125]
	v_mfma_f32_16x16x32_bf16 v[110:113], v[130:133], v[186:189], v[110:113]
	v_mfma_f32_16x16x32_bf16 v[106:109], v[138:141], v[186:189], v[106:109]
	v_mfma_f32_16x16x32_bf16 v[94:97], v[130:133], v[206:209], v[94:97]
	v_mfma_f32_16x16x32_bf16 v[90:93], v[138:141], v[206:209], v[90:93]
	v_mfma_f32_16x16x32_bf16 v[78:81], v[130:133], v[218:221], v[78:81]
	v_mfma_f32_16x16x32_bf16 v[74:77], v[138:141], v[218:221], v[74:77]
	v_mfma_f32_16x16x32_bf16 v[126:129], v[134:137], v[182:185], v[126:129]
	v_mfma_f32_16x16x32_bf16 v[122:125], v[142:145], v[182:185], v[122:125]
	v_mfma_f32_16x16x32_bf16 v[110:113], v[134:137], v[202:205], v[110:113]
	v_mfma_f32_16x16x32_bf16 v[106:109], v[142:145], v[202:205], v[106:109]
	v_mfma_f32_16x16x32_bf16 v[94:97], v[134:137], v[214:217], v[94:97]
	v_mfma_f32_16x16x32_bf16 v[90:93], v[142:145], v[214:217], v[90:93]
	v_mfma_f32_16x16x32_bf16 v[78:81], v[134:137], v[222:225], v[78:81]
	v_mfma_f32_16x16x32_bf16 v[74:77], v[142:145], v[222:225], v[74:77]
	s_barrier
	s_add_i32 s39, 0, 0x1c000
	s_add_i32 s26, s38, s78
	v_add_u32_e32 v192, s39, v197
	v_lshl_add_u64 v[162:163], v[162:163], 0, s[70:71]
	s_mov_b32 m0, s26
	ds_read_b128 v[226:229], v192
	ds_read_b128 v[230:233], v192 offset:1024
	ds_read_b128 v[234:237], v192 offset:2048
	ds_read_b128 v[238:241], v192 offset:3072
	global_load_lds_dwordx4 v[162:163], off
	s_add_i32 m0, s26, 0x2000
	v_lshl_add_u64 v[162:163], v[164:165], 0, s[70:71]
	global_load_lds_dwordx4 v[162:163], off
	s_barrier
; #define PG8_STAGE(bufoff, gbase, voff) do { _Pragma("unroll") for (int _i = 0; _i < 2; ++_i) \
;         __builtin_amdgcn_global_load_lds((const unsigned*)((const char*)(gbase) + (voff)[_i]), (LAS unsigned*)(lds + (bufoff) + ldsw + _i * 8192), 16, 0, 0); } while (0)
; #define PG8_LDA(dst, b, h) do { _Pragma("unroll") for (int m = 0; m < 4; ++m) _Pragma("unroll") for (int k = 0; k < 2; ++k) dst[m][k] = *(const LAS bf16x8*)(lds + PG8_SA(b, h) + aoff + m * 2048 + k * 1024); } while (0)
; #define PG8_MMA(ai, bj, At, Bt) do { __builtin_amdgcn_s_setprio(1); _Pragma("unroll") for (int m = 0; m < 4; ++m) _Pragma("unroll") for (int n = 0; n < 2; ++n) _Pragma("unroll") for (int k = 0; k < 2; ++k) \
;         acc[ai][bj][m][n] = __builtin_amdgcn_mfma_f32_16x16x32_bf16(Bt[n][k], At[m][k], acc[ai][bj][m][n], 0, 0, 0); __builtin_amdgcn_s_setprio(0); } while (0)
; #define PG8_WAIT_V(n) asm volatile("s_waitcnt vmcnt(" #n ")" ::: "memory")
; #define PG8_WAIT_L(n) asm volatile("s_waitcnt lgkmcnt(" #n ")" ::: "memory")
; #define PG8_BAR __builtin_amdgcn_s_barrier()
; #define PG8_SCHED __builtin_amdgcn_sched_barrier(0)
; template <class Epi>
; DEVI void gemm_phase(LAS unsigned char* lds, const Gemm g, const Epi& E) {
;     ...
;             PG8_BAR; PG8_WAIT_L(0); PG8_MMA(0, 1, At, B1); PG8_BAR;
;             PG8_LDA(At, 1, 1); PG8_STAGE(PG8_SA(1, 0), a3, voffA);
;             PG8_BAR; PG8_WAIT_L(0); PG8_MMA(1, 0, At, B0); PG8_BAR; PG8_SCHED;
;             PG8_STAGE(PG8_SB(1, 1), b3 + hstepB, voffB);
;             PG8_WAIT_V(6); PG8_BAR; PG8_MMA(1, 1, At, B1); PG8_BAR;
;         }
	s_waitcnt lgkmcnt(0)
	v_mfma_f32_16x16x32_bf16 v[118:121], v[226:229], v[178:181], v[118:121]
	v_mfma_f32_16x16x32_bf16 v[114:117], v[234:237], v[178:181], v[114:117]
	v_mfma_f32_16x16x32_bf16 v[102:105], v[226:229], v[186:189], v[102:105]
	v_mfma_f32_16x16x32_bf16 v[98:101], v[234:237], v[186:189], v[98:101]
	v_mfma_f32_16x16x32_bf16 v[86:89], v[226:229], v[206:209], v[86:89]
	v_mfma_f32_16x16x32_bf16 v[82:85], v[234:237], v[206:209], v[82:85]
	v_mfma_f32_16x16x32_bf16 v[70:73], v[226:229], v[218:221], v[70:73]
	v_mfma_f32_16x16x32_bf16 v[66:69], v[234:237], v[218:221], v[66:69]
	v_mfma_f32_16x16x32_bf16 v[118:121], v[230:233], v[182:185], v[118:121]
	v_mfma_f32_16x16x32_bf16 v[114:117], v[238:241], v[182:185], v[114:117]
	v_mfma_f32_16x16x32_bf16 v[102:105], v[230:233], v[202:205], v[102:105]
	v_mfma_f32_16x16x32_bf16 v[98:101], v[238:241], v[202:205], v[98:101]
	v_mfma_f32_16x16x32_bf16 v[86:89], v[230:233], v[214:217], v[86:89]
	v_mfma_f32_16x16x32_bf16 v[82:85], v[238:241], v[214:217], v[82:85]
	v_mfma_f32_16x16x32_bf16 v[70:73], v[230:233], v[222:225], v[70:73]
	v_mfma_f32_16x16x32_bf16 v[66:69], v[238:241], v[222:225], v[66:69]
	s_mov_b32 m0, s83
	v_lshl_add_u64 v[162:163], v[190:191], 0, s[70:71]
	s_barrier
	ds_read_b128 v[178:181], v201 offset:49152
	ds_read_b128 v[182:185], v201 offset:50176
	ds_read_b128 v[186:189], v201 offset:51200
	ds_read_b128 v[202:205], v201 offset:52224
	ds_read_b128 v[206:209], v201 offset:53248
	ds_read_b128 v[214:217], v201 offset:54272
	ds_read_b128 v[218:221], v201 offset:55296
	ds_read_b128 v[222:225], v201 offset:56320
	global_load_lds_dwordx4 v[162:163], off
	s_mov_b32 m0, s84
	v_lshl_add_u64 v[162:163], v[194:195], 0, s[70:71]
	global_load_lds_dwordx4 v[162:163], off
	s_barrier
	s_waitcnt lgkmcnt(0)
	v_mfma_f32_16x16x32_bf16 v[50:53], v[130:133], v[178:181], v[50:53]
	v_mfma_f32_16x16x32_bf16 v[54:57], v[138:141], v[178:181], v[54:57]
	v_mfma_f32_16x16x32_bf16 v[34:37], v[130:133], v[186:189], v[34:37]
	v_mfma_f32_16x16x32_bf16 v[38:41], v[138:141], v[186:189], v[38:41]
	v_mfma_f32_16x16x32_bf16 v[18:21], v[130:133], v[206:209], v[18:21]
	v_mfma_f32_16x16x32_bf16 v[22:25], v[138:141], v[206:209], v[22:25]
	v_mfma_f32_16x16x32_bf16 v[0:3], v[130:133], v[218:221], v[0:3]
	v_mfma_f32_16x16x32_bf16 v[4:7], v[138:141], v[218:221], v[4:7]
	v_mfma_f32_16x16x32_bf16 v[50:53], v[134:137], v[182:185], v[50:53]
	v_mfma_f32_16x16x32_bf16 v[54:57], v[142:145], v[182:185], v[54:57]
	v_mfma_f32_16x16x32_bf16 v[34:37], v[134:137], v[202:205], v[34:37]
	v_mfma_f32_16x16x32_bf16 v[38:41], v[142:145], v[202:205], v[38:41]
	v_mfma_f32_16x16x32_bf16 v[18:21], v[134:137], v[214:217], v[18:21]
	v_mfma_f32_16x16x32_bf16 v[22:25], v[142:145], v[214:217], v[22:25]
	v_mfma_f32_16x16x32_bf16 v[0:3], v[134:137], v[222:225], v[0:3]
	v_mfma_f32_16x16x32_bf16 v[4:7], v[142:145], v[222:225], v[4:7]
	s_barrier
	s_add_u32 s26, s36, 0x40080
	s_addc_u32 s27, s37, 0
	s_add_i32 s36, s39, s78
	s_mov_b32 m0, s36
	v_lshl_add_u64 v[130:131], s[26:27], 0, v[8:9]
	global_load_lds_dwordx4 v[130:131], off
	s_add_i32 m0, s36, 0x2000
	v_lshl_add_u64 v[130:131], s[26:27], 0, v[146:147]
	global_load_lds_dwordx4 v[130:131], off
	s_waitcnt vmcnt(6)
	s_barrier
	v_mfma_f32_16x16x32_bf16 v[58:61], v[226:229], v[178:181], v[58:61]
	v_mfma_f32_16x16x32_bf16 v[62:65], v[234:237], v[178:181], v[62:65]
	v_mfma_f32_16x16x32_bf16 v[42:45], v[226:229], v[186:189], v[42:45]
	v_mfma_f32_16x16x32_bf16 v[46:49], v[234:237], v[186:189], v[46:49]
	v_mfma_f32_16x16x32_bf16 v[26:29], v[226:229], v[206:209], v[26:29]
	v_mfma_f32_16x16x32_bf16 v[30:33], v[234:237], v[206:209], v[30:33]
	v_mfma_f32_16x16x32_bf16 v[10:13], v[226:229], v[218:221], v[10:13]
	v_mfma_f32_16x16x32_bf16 v[14:17], v[234:237], v[218:221], v[14:17]
	v_mfma_f32_16x16x32_bf16 v[58:61], v[230:233], v[182:185], v[58:61]
	v_mfma_f32_16x16x32_bf16 v[62:65], v[238:241], v[182:185], v[62:65]
	v_mfma_f32_16x16x32_bf16 v[42:45], v[230:233], v[202:205], v[42:45]
	v_mfma_f32_16x16x32_bf16 v[46:49], v[238:241], v[202:205], v[46:49]
	v_mfma_f32_16x16x32_bf16 v[26:29], v[230:233], v[214:217], v[26:29]
	v_mfma_f32_16x16x32_bf16 v[30:33], v[238:241], v[214:217], v[30:33]
	v_mfma_f32_16x16x32_bf16 v[10:13], v[230:233], v[222:225], v[10:13]
	v_mfma_f32_16x16x32_bf16 v[14:17], v[238:241], v[222:225], v[14:17]
	s_add_i32 s19, s19, 2
	s_add_u32 s16, s16, 0x100
	s_addc_u32 s17, s17, 0
	s_add_u32 s9, s9, 0x100
	s_addc_u32 s18, s18, 0
	s_cmp_gt_u32 s19, 13
	s_barrier

; DEVI size_t gemm_offB(const Gemm& g, const Unit& u) { return (g.split ? (size_t)(u.b >> 2) * g.sB + (size_t)(u.b & 3) * g.sB_lo : (size_t)u.b * g.sB) + (size_t)(u.pm >> g.pmsh) * g.sBpm; }
; #define PG8_STAGE(bufoff, gbase, voff) do { _Pragma("unroll") for (int _i = 0; _i < 2; ++_i) \
;         __builtin_amdgcn_global_load_lds((const unsigned*)((const char*)(gbase) + (voff)[_i]), (LAS unsigned*)(lds + (bufoff) + ldsw + _i * 8192), 16, 0, 0); } while (0)
; #define PG8_LDA(dst, b, h) do { _Pragma("unroll") for (int m = 0; m < 4; ++m) _Pragma("unroll") for (int k = 0; k < 2; ++k) dst[m][k] = *(const LAS bf16x8*)(lds + PG8_SA(b, h) + aoff + m * 2048 + k * 1024); } while (0)
; #define PG8_WAIT_L(n) asm volatile("s_waitcnt lgkmcnt(" #n ")" ::: "memory")
; #define PG8_BAR __builtin_amdgcn_s_barrier()
; #define PG8_SCHED __builtin_amdgcn_sched_barrier(0)
; template <class Epi>
; DEVI void gemm_phase(LAS unsigned char* lds, const Gemm g, const Epi& E) {
;     ...
;         const char* nA = has_next ? (const char*)g.A + gemm_offA(g, nxt) * 2 + (size_t)nxt.pm * tstepA : cA;
;         const char* nB = has_next ? (const char*)g.Bt + gemm_offB(g, nxt) * 2 + (size_t)nxt.pn * tstepB : cB;
;         for (int t = 0; t < nt; t += 2) {
;             const bool last = (t == nt - 2);
;             const char* a1 = cA + (size_t)(t + 1) * kstep;
;             const char* a2 = last ? nA : cA + (size_t)(t + 2) * kstep; const char* b2 = last ? nB : cB + (size_t)(t + 2) * kstep;
;             const char* a3 = a2 + kstep; const char* b3 = b2 + kstep;
;             PG8_LDB(B0, 0, 0); PG8_SCHED; PG8_LDA(At, 0, 0); PG8_STAGE(PG8_SA(1, 1), a1 + hstepA, voffA);
;             PG8_WAIT_L(8); PG8_BAR; PG8_WAIT_L(0); PG8_MMA(0, 0, At, B0); PG8_BAR; PG8_SCHED;
;             PG8_LDB(B1, 0, 1); PG8_STAGE(PG8_SB(0, 0), b2, voffB);
;             PG8_BAR; PG8_WAIT_L(0); PG8_MMA(0, 1, At, B1); PG8_BAR;
;             PG8_LDA(At, 0, 1); PG8_STAGE(PG8_SA(0, 0), a2, voffA);
;             PG8_BAR; PG8_WAIT_L(0); PG8_MMA(1, 0, At, B0); PG8_BAR; PG8_SCHED;
;     ...
; #pragma unroll
;         for (int a = 0; a < 2; ++a)
; #pragma unroll
;             for (int b = 0; b < 2; ++b)
; #pragma unroll
;                 for (int m = 0; m < 4; ++m)
; #pragma unroll
;                     for (int n = 0; n < 2; ++n) acc[a][b][m][n] = (f32x4){0.f, 0.f, 0.f, 0.f};
;         cur = nxt; cA = nA; cB = nB; ++ui;
.LBB0_1746:
	s_add_u32 s1, s36, 0x100
	s_addc_u32 s13, s37, 0
	s_mov_b32 s18, -2
	s_waitcnt lgkmcnt(0)
	s_add_u32 s36, s16, 0x100
	s_addc_u32 s37, s17, 0
	s_add_i32 s19, 0, 0x10000
	v_add_u32_e32 v142, s19, v191
	ds_read_b128 v[130:133], v142
	ds_read_b128 v[134:137], v142 offset:1024
	ds_read_b128 v[138:141], v142 offset:2048
	ds_read_b128 v[142:145], v142 offset:3072
	s_cmp_eq_u32 s18, 40
	s_cselect_b32 s69, s9, s37
	s_cselect_b32 s68, s8, s36
	s_cselect_b32 s47, s11, s13
	s_cselect_b32 s46, s10, s1
	v_lshl_add_u64 v[162:163], s[16:17], 0, v[152:153]
	s_add_i32 m0, s81, 0xc000
	ds_read_b128 v[178:181], v196
	ds_read_b128 v[182:185], v196 offset:1024
	ds_read_b128 v[186:189], v196 offset:2048
	ds_read_b128 v[198:201], v196 offset:3072
	ds_read_b128 v[202:205], v196 offset:4096
	ds_read_b128 v[206:209], v196 offset:5120
	ds_read_b128 v[214:217], v196 offset:6144
	ds_read_b128 v[218:221], v196 offset:7168
	global_load_lds_dwordx4 v[162:163], off
	s_add_i32 m0, s81, 0xe000
	v_lshl_add_u64 v[162:163], s[16:17], 0, v[176:177]
	global_load_lds_dwordx4 v[162:163], off
	s_waitcnt lgkmcnt(8)
	s_barrier
	s_waitcnt lgkmcnt(0)
	v_mfma_f32_16x16x32_bf16 v[126:129], v[130:133], v[178:181], 0
	v_mfma_f32_16x16x32_bf16 v[122:125], v[138:141], v[178:181], 0
	v_mfma_f32_16x16x32_bf16 v[110:113], v[130:133], v[186:189], 0
	v_mfma_f32_16x16x32_bf16 v[106:109], v[138:141], v[186:189], 0
	v_mfma_f32_16x16x32_bf16 v[94:97], v[130:133], v[202:205], 0
	v_mfma_f32_16x16x32_bf16 v[90:93], v[138:141], v[202:205], 0
	v_mfma_f32_16x16x32_bf16 v[78:81], v[130:133], v[214:217], 0
	v_mfma_f32_16x16x32_bf16 v[74:77], v[138:141], v[214:217], 0
	v_mfma_f32_16x16x32_bf16 v[126:129], v[134:137], v[182:185], v[126:129]
	v_mfma_f32_16x16x32_bf16 v[122:125], v[142:145], v[182:185], v[122:125]
	v_mfma_f32_16x16x32_bf16 v[110:113], v[134:137], v[198:201], v[110:113]
	v_mfma_f32_16x16x32_bf16 v[106:109], v[142:145], v[198:201], v[106:109]
	v_mfma_f32_16x16x32_bf16 v[94:97], v[134:137], v[206:209], v[94:97]
	v_mfma_f32_16x16x32_bf16 v[90:93], v[142:145], v[206:209], v[90:93]
	v_mfma_f32_16x16x32_bf16 v[78:81], v[134:137], v[218:221], v[78:81]
	v_mfma_f32_16x16x32_bf16 v[74:77], v[142:145], v[218:221], v[74:77]
	s_barrier
	s_add_i32 s26, 0, 0x14000
	v_add_u32_e32 v162, s26, v191
	s_add_i32 s16, s19, s80
	ds_read_b128 v[222:225], v162
	ds_read_b128 v[226:229], v162 offset:1024
	ds_read_b128 v[230:233], v162 offset:2048
	ds_read_b128 v[234:237], v162 offset:3072
	v_lshl_add_u64 v[162:163], s[46:47], 0, v[8:9]
	s_mov_b32 m0, s16
	v_lshl_add_u64 v[164:165], s[46:47], 0, v[150:151]
	global_load_lds_dwordx4 v[162:163], off
	s_add_i32 m0, s16, 0x2000
	s_nop 0
	global_load_lds_dwordx4 v[164:165], off
	s_barrier
	s_waitcnt lgkmcnt(0)
	v_mfma_f32_16x16x32_bf16 v[118:121], v[222:225], v[178:181], 0
	v_mfma_f32_16x16x32_bf16 v[114:117], v[230:233], v[178:181], 0
	v_mfma_f32_16x16x32_bf16 v[102:105], v[222:225], v[186:189], 0
	v_mfma_f32_16x16x32_bf16 v[98:101], v[230:233], v[186:189], 0
	v_mfma_f32_16x16x32_bf16 v[86:89], v[222:225], v[202:205], 0
	v_mfma_f32_16x16x32_bf16 v[82:85], v[230:233], v[202:205], 0
	v_mfma_f32_16x16x32_bf16 v[70:73], v[222:225], v[214:217], 0
	v_mfma_f32_16x16x32_bf16 v[66:69], v[230:233], v[214:217], 0
	v_mfma_f32_16x16x32_bf16 v[118:121], v[226:229], v[182:185], v[118:121]
	v_mfma_f32_16x16x32_bf16 v[114:117], v[234:237], v[182:185], v[114:117]
	v_mfma_f32_16x16x32_bf16 v[102:105], v[226:229], v[198:201], v[102:105]
	v_mfma_f32_16x16x32_bf16 v[98:101], v[234:237], v[198:201], v[98:101]
	v_mfma_f32_16x16x32_bf16 v[86:89], v[226:229], v[206:209], v[86:89]
	v_mfma_f32_16x16x32_bf16 v[82:85], v[234:237], v[206:209], v[82:85]
	v_mfma_f32_16x16x32_bf16 v[70:73], v[226:229], v[218:221], v[70:73]
	v_mfma_f32_16x16x32_bf16 v[66:69], v[234:237], v[218:221], v[66:69]
	s_mov_b32 m0, s81
	v_lshl_add_u64 v[238:239], s[68:69], 0, v[146:147]
	s_barrier
	ds_read_b128 v[178:181], v196 offset:16384
	ds_read_b128 v[182:185], v196 offset:17408
	ds_read_b128 v[186:189], v196 offset:18432
	ds_read_b128 v[198:201], v196 offset:19456
	ds_read_b128 v[202:205], v196 offset:20480
	ds_read_b128 v[206:209], v196 offset:21504
	ds_read_b128 v[214:217], v196 offset:22528
	ds_read_b128 v[218:221], v196 offset:23552
	global_load_lds_dwordx4 v[238:239], off
	s_mov_b32 m0, s82
	v_lshl_add_u64 v[240:241], s[68:69], 0, v[148:149]
	global_load_lds_dwordx4 v[240:241], off
	s_barrier
	s_waitcnt lgkmcnt(0)
	v_mfma_f32_16x16x32_bf16 v[62:65], v[130:133], v[178:181], 0
	v_mfma_f32_16x16x32_bf16 v[58:61], v[138:141], v[178:181], 0
	v_mfma_f32_16x16x32_bf16 v[46:49], v[130:133], v[186:189], 0
	v_mfma_f32_16x16x32_bf16 v[42:45], v[138:141], v[186:189], 0
	v_mfma_f32_16x16x32_bf16 v[30:33], v[130:133], v[202:205], 0
	v_mfma_f32_16x16x32_bf16 v[26:29], v[138:141], v[202:205], 0
	v_mfma_f32_16x16x32_bf16 v[14:17], v[130:133], v[214:217], 0
	v_mfma_f32_16x16x32_bf16 v[10:13], v[138:141], v[214:217], 0
	v_mfma_f32_16x16x32_bf16 v[62:65], v[134:137], v[182:185], v[62:65]
	v_mfma_f32_16x16x32_bf16 v[58:61], v[142:145], v[182:185], v[58:61]
	v_mfma_f32_16x16x32_bf16 v[46:49], v[134:137], v[198:201], v[46:49]
	v_mfma_f32_16x16x32_bf16 v[42:45], v[142:145], v[198:201], v[42:45]
	v_mfma_f32_16x16x32_bf16 v[30:33], v[134:137], v[206:209], v[30:33]
	v_mfma_f32_16x16x32_bf16 v[26:29], v[142:145], v[206:209], v[26:29]
	v_mfma_f32_16x16x32_bf16 v[14:17], v[134:137], v[218:221], v[14:17]
	v_mfma_f32_16x16x32_bf16 v[10:13], v[142:145], v[218:221], v[10:13]
	s_barrier
; #define PG8_STAGE(bufoff, gbase, voff) do { _Pragma("unroll") for (int _i = 0; _i < 2; ++_i) \
;         __builtin_amdgcn_global_load_lds((const unsigned*)((const char*)(gbase) + (voff)[_i]), (LAS unsigned*)(lds + (bufoff) + ldsw + _i * 8192), 16, 0, 0); } while (0)
; #define PG8_LDA(dst, b, h) do { _Pragma("unroll") for (int m = 0; m < 4; ++m) _Pragma("unroll") for (int k = 0; k < 2; ++k) dst[m][k] = *(const LAS bf16x8*)(lds + PG8_SA(b, h) + aoff + m * 2048 + k * 1024); } while (0)
; #define PG8_LDB(dst, b, h) do { _Pragma("unroll") for (int n = 0; n < 2; ++n) _Pragma("unroll") for (int k = 0; k < 2; ++k) dst[n][k] = *(const LAS bf16x8*)(lds + PG8_SB(b, h) + boff + n * 2048 + k * 1024); } while (0)
; #define PG8_MMA(ai, bj, At, Bt) do { __builtin_amdgcn_s_setprio(1); _Pragma("unroll") for (int m = 0; m < 4; ++m) _Pragma("unroll") for (int n = 0; n < 2; ++n) _Pragma("unroll") for (int k = 0; k < 2; ++k) \
;         acc[ai][bj][m][n] = __builtin_amdgcn_mfma_f32_16x16x32_bf16(Bt[n][k], At[m][k], acc[ai][bj][m][n], 0, 0, 0); __builtin_amdgcn_s_setprio(0); } while (0)
; #define PG8_WAIT_V(n) asm volatile("s_waitcnt vmcnt(" #n ")" ::: "memory")
; #define PG8_WAIT_L(n) asm volatile("s_waitcnt lgkmcnt(" #n ")" ::: "memory")
; #define PG8_BAR __builtin_amdgcn_s_barrier()
; #define PG8_SCHED __builtin_amdgcn_sched_barrier(0)
; template <class Epi>
; DEVI void gemm_phase(LAS unsigned char* lds, const Gemm g, const Epi& E) {
;     ...
;             PG8_STAGE(PG8_SB(0, 1), b2 + hstepB, voffB);
;             PG8_WAIT_V(6); PG8_BAR; PG8_MMA(1, 1, At, B1); PG8_BAR;
;             PG8_LDB(B0, 1, 0); PG8_SCHED; PG8_LDA(At, 1, 0); PG8_STAGE(PG8_SA(0, 1), a2 + hstepA, voffA);
;             PG8_WAIT_L(8); PG8_BAR; PG8_WAIT_L(0); PG8_MMA(0, 0, At, B0); PG8_BAR; PG8_SCHED;
;             PG8_LDB(B1, 1, 1); PG8_STAGE(PG8_SB(1, 0), b3, voffB);
	s_add_u32 s16, s46, 0xb0000
	s_addc_u32 s17, s47, 0
	s_add_i32 s19, s26, s80
	s_mov_b32 m0, s19
	v_lshl_add_u64 v[130:131], s[16:17], 0, v[8:9]
	global_load_lds_dwordx4 v[130:131], off
	s_add_i32 m0, s19, 0x2000
	v_lshl_add_u64 v[130:131], s[16:17], 0, v[150:151]
	global_load_lds_dwordx4 v[130:131], off
	s_waitcnt vmcnt(6)
	s_barrier
	v_mfma_f32_16x16x32_bf16 v[54:57], v[222:225], v[178:181], 0
	v_mfma_f32_16x16x32_bf16 v[50:53], v[230:233], v[178:181], 0
	v_mfma_f32_16x16x32_bf16 v[38:41], v[222:225], v[186:189], 0
	v_mfma_f32_16x16x32_bf16 v[34:37], v[230:233], v[186:189], 0
	v_mfma_f32_16x16x32_bf16 v[22:25], v[222:225], v[202:205], 0
	v_mfma_f32_16x16x32_bf16 v[18:21], v[230:233], v[202:205], 0
	v_mfma_f32_16x16x32_bf16 v[4:7], v[222:225], v[214:217], 0
	v_mfma_f32_16x16x32_bf16 v[0:3], v[230:233], v[214:217], 0
	v_mfma_f32_16x16x32_bf16 v[54:57], v[226:229], v[182:185], v[54:57]
	v_mfma_f32_16x16x32_bf16 v[50:53], v[234:237], v[182:185], v[50:53]
	v_mfma_f32_16x16x32_bf16 v[38:41], v[226:229], v[198:201], v[38:41]
	v_mfma_f32_16x16x32_bf16 v[34:37], v[234:237], v[198:201], v[34:37]
	v_mfma_f32_16x16x32_bf16 v[22:25], v[226:229], v[206:209], v[22:25]
	v_mfma_f32_16x16x32_bf16 v[18:21], v[234:237], v[206:209], v[18:21]
	v_mfma_f32_16x16x32_bf16 v[4:7], v[226:229], v[218:221], v[4:7]
	v_mfma_f32_16x16x32_bf16 v[0:3], v[234:237], v[218:221], v[0:3]
	s_add_i32 s19, 0, 0x18000
	v_add_u32_e32 v142, s19, v191
	s_barrier
	ds_read_b128 v[130:133], v142
	ds_read_b128 v[134:137], v142 offset:1024
	ds_read_b128 v[138:141], v142 offset:2048
	ds_read_b128 v[142:145], v142 offset:3072
	s_add_u32 s16, s68, 0xb0000
	s_addc_u32 s17, s69, 0
	s_mov_b32 m0, s83
	v_lshl_add_u64 v[222:223], s[16:17], 0, v[146:147]
	ds_read_b128 v[178:181], v196 offset:32768
	ds_read_b128 v[182:185], v196 offset:33792
	ds_read_b128 v[186:189], v196 offset:34816
	ds_read_b128 v[198:201], v196 offset:35840
	ds_read_b128 v[202:205], v196 offset:36864
	ds_read_b128 v[206:209], v196 offset:37888
	ds_read_b128 v[214:217], v196 offset:38912
	ds_read_b128 v[218:221], v196 offset:39936
	global_load_lds_dwordx4 v[222:223], off
	s_mov_b32 m0, s84
	v_lshl_add_u64 v[222:223], s[16:17], 0, v[148:149]
	global_load_lds_dwordx4 v[222:223], off
	s_waitcnt lgkmcnt(8)
	s_barrier
	s_waitcnt lgkmcnt(0)
	v_mfma_f32_16x16x32_bf16 v[126:129], v[130:133], v[178:181], v[126:129]
	v_mfma_f32_16x16x32_bf16 v[122:125], v[138:141], v[178:181], v[122:125]
	v_mfma_f32_16x16x32_bf16 v[110:113], v[130:133], v[186:189], v[110:113]
	v_mfma_f32_16x16x32_bf16 v[106:109], v[138:141], v[186:189], v[106:109]
	v_mfma_f32_16x16x32_bf16 v[94:97], v[130:133], v[202:205], v[94:97]
	v_mfma_f32_16x16x32_bf16 v[90:93], v[138:141], v[202:205], v[90:93]
	v_mfma_f32_16x16x32_bf16 v[78:81], v[130:133], v[214:217], v[78:81]
	v_mfma_f32_16x16x32_bf16 v[74:77], v[138:141], v[214:217], v[74:77]
	v_mfma_f32_16x16x32_bf16 v[126:129], v[134:137], v[182:185], v[126:129]
	v_mfma_f32_16x16x32_bf16 v[122:125], v[142:145], v[182:185], v[122:125]
	v_mfma_f32_16x16x32_bf16 v[110:113], v[134:137], v[198:201], v[110:113]
	v_mfma_f32_16x16x32_bf16 v[106:109], v[142:145], v[198:201], v[106:109]
	v_mfma_f32_16x16x32_bf16 v[94:97], v[134:137], v[206:209], v[94:97]
	v_mfma_f32_16x16x32_bf16 v[90:93], v[142:145], v[206:209], v[90:93]
	v_mfma_f32_16x16x32_bf16 v[78:81], v[134:137], v[218:221], v[78:81]
	v_mfma_f32_16x16x32_bf16 v[74:77], v[142:145], v[218:221], v[74:77]
	s_barrier
	s_add_i32 s26, 0, 0x1c000
	s_add_i32 s16, s19, s80
	v_add_u32_e32 v197, s26, v191
	v_lshl_add_u64 v[162:163], v[162:163], 0, s[70:71]
	s_mov_b32 m0, s16
	ds_read_b128 v[222:225], v197
	ds_read_b128 v[226:229], v197 offset:1024
	ds_read_b128 v[230:233], v197 offset:2048
	ds_read_b128 v[234:237], v197 offset:3072
	global_load_lds_dwordx4 v[162:163], off
	s_add_i32 m0, s16, 0x2000
	v_lshl_add_u64 v[162:163], v[164:165], 0, s[70:71]
	global_load_lds_dwordx4 v[162:163], off
	s_barrier
; #define PG8_STAGE(bufoff, gbase, voff) do { _Pragma("unroll") for (int _i = 0; _i < 2; ++_i) \
;         __builtin_amdgcn_global_load_lds((const unsigned*)((const char*)(gbase) + (voff)[_i]), (LAS unsigned*)(lds + (bufoff) + ldsw + _i * 8192), 16, 0, 0); } while (0)
; #define PG8_LDA(dst, b, h) do { _Pragma("unroll") for (int m = 0; m < 4; ++m) _Pragma("unroll") for (int k = 0; k < 2; ++k) dst[m][k] = *(const LAS bf16x8*)(lds + PG8_SA(b, h) + aoff + m * 2048 + k * 1024); } while (0)
; #define PG8_MMA(ai, bj, At, Bt) do { __builtin_amdgcn_s_setprio(1); _Pragma("unroll") for (int m = 0; m < 4; ++m) _Pragma("unroll") for (int n = 0; n < 2; ++n) _Pragma("unroll") for (int k = 0; k < 2; ++k) \
;         acc[ai][bj][m][n] = __builtin_amdgcn_mfma_f32_16x16x32_bf16(Bt[n][k], At[m][k], acc[ai][bj][m][n], 0, 0, 0); __builtin_amdgcn_s_setprio(0); } while (0)
; #define PG8_WAIT_V(n) asm volatile("s_waitcnt vmcnt(" #n ")" ::: "memory")
; #define PG8_WAIT_L(n) asm volatile("s_waitcnt lgkmcnt(" #n ")" ::: "memory")
; #define PG8_BAR __builtin_amdgcn_s_barrier()
; #define PG8_SCHED __builtin_amdgcn_sched_barrier(0)
; template <class Epi>
; DEVI void gemm_phase(LAS unsigned char* lds, const Gemm g, const Epi& E) {
;     ...
;             PG8_BAR; PG8_WAIT_L(0); PG8_MMA(0, 1, At, B1); PG8_BAR;
;             PG8_LDA(At, 1, 1); PG8_STAGE(PG8_SA(1, 0), a3, voffA);
;             PG8_BAR; PG8_WAIT_L(0); PG8_MMA(1, 0, At, B0); PG8_BAR; PG8_SCHED;
;             PG8_STAGE(PG8_SB(1, 1), b3 + hstepB, voffB);
;             PG8_WAIT_V(6); PG8_BAR; PG8_MMA(1, 1, At, B1); PG8_BAR;
;         }
	s_waitcnt lgkmcnt(0)
	v_mfma_f32_16x16x32_bf16 v[118:121], v[222:225], v[178:181], v[118:121]
	v_mfma_f32_16x16x32_bf16 v[114:117], v[230:233], v[178:181], v[114:117]
	v_mfma_f32_16x16x32_bf16 v[102:105], v[222:225], v[186:189], v[102:105]
	v_mfma_f32_16x16x32_bf16 v[98:101], v[230:233], v[186:189], v[98:101]
	v_mfma_f32_16x16x32_bf16 v[86:89], v[222:225], v[202:205], v[86:89]
	v_mfma_f32_16x16x32_bf16 v[82:85], v[230:233], v[202:205], v[82:85]
	v_mfma_f32_16x16x32_bf16 v[70:73], v[222:225], v[214:217], v[70:73]
	v_mfma_f32_16x16x32_bf16 v[66:69], v[230:233], v[214:217], v[66:69]
	v_mfma_f32_16x16x32_bf16 v[118:121], v[226:229], v[182:185], v[118:121]
	v_mfma_f32_16x16x32_bf16 v[114:117], v[234:237], v[182:185], v[114:117]
	v_mfma_f32_16x16x32_bf16 v[102:105], v[226:229], v[198:201], v[102:105]
	v_mfma_f32_16x16x32_bf16 v[98:101], v[234:237], v[198:201], v[98:101]
	v_mfma_f32_16x16x32_bf16 v[86:89], v[226:229], v[206:209], v[86:89]
	v_mfma_f32_16x16x32_bf16 v[82:85], v[234:237], v[206:209], v[82:85]
	v_mfma_f32_16x16x32_bf16 v[70:73], v[226:229], v[218:221], v[70:73]
	v_mfma_f32_16x16x32_bf16 v[66:69], v[234:237], v[218:221], v[66:69]
	s_mov_b32 m0, s76
	v_lshl_add_u64 v[162:163], v[238:239], 0, s[70:71]
	s_barrier
	ds_read_b128 v[178:181], v196 offset:49152
	ds_read_b128 v[182:185], v196 offset:50176
	ds_read_b128 v[186:189], v196 offset:51200
	ds_read_b128 v[198:201], v196 offset:52224
	ds_read_b128 v[202:205], v196 offset:53248
	ds_read_b128 v[206:209], v196 offset:54272
	ds_read_b128 v[214:217], v196 offset:55296
	ds_read_b128 v[218:221], v196 offset:56320
	global_load_lds_dwordx4 v[162:163], off
	s_mov_b32 m0, s77
	v_lshl_add_u64 v[162:163], v[240:241], 0, s[70:71]
	global_load_lds_dwordx4 v[162:163], off
	s_barrier
	s_waitcnt lgkmcnt(0)
	v_mfma_f32_16x16x32_bf16 v[62:65], v[130:133], v[178:181], v[62:65]
	v_mfma_f32_16x16x32_bf16 v[58:61], v[138:141], v[178:181], v[58:61]
	v_mfma_f32_16x16x32_bf16 v[46:49], v[130:133], v[186:189], v[46:49]
	v_mfma_f32_16x16x32_bf16 v[42:45], v[138:141], v[186:189], v[42:45]
	v_mfma_f32_16x16x32_bf16 v[30:33], v[130:133], v[202:205], v[30:33]
	v_mfma_f32_16x16x32_bf16 v[26:29], v[138:141], v[202:205], v[26:29]
	v_mfma_f32_16x16x32_bf16 v[14:17], v[130:133], v[214:217], v[14:17]
	v_mfma_f32_16x16x32_bf16 v[10:13], v[138:141], v[214:217], v[10:13]
	v_mfma_f32_16x16x32_bf16 v[62:65], v[134:137], v[182:185], v[62:65]
	v_mfma_f32_16x16x32_bf16 v[58:61], v[142:145], v[182:185], v[58:61]
	v_mfma_f32_16x16x32_bf16 v[46:49], v[134:137], v[198:201], v[46:49]
	v_mfma_f32_16x16x32_bf16 v[42:45], v[142:145], v[198:201], v[42:45]
	v_mfma_f32_16x16x32_bf16 v[30:33], v[134:137], v[206:209], v[30:33]
	v_mfma_f32_16x16x32_bf16 v[26:29], v[142:145], v[206:209], v[26:29]
	v_mfma_f32_16x16x32_bf16 v[14:17], v[134:137], v[218:221], v[14:17]
	v_mfma_f32_16x16x32_bf16 v[10:13], v[142:145], v[218:221], v[10:13]
	s_barrier
	s_add_u32 s16, s46, 0xb0080
	s_addc_u32 s17, s47, 0
	s_add_i32 s19, s26, s80
	s_mov_b32 m0, s19
	v_lshl_add_u64 v[130:131], s[16:17], 0, v[8:9]
	global_load_lds_dwordx4 v[130:131], off
	s_add_i32 m0, s19, 0x2000
	v_lshl_add_u64 v[130:131], s[16:17], 0, v[150:151]
	global_load_lds_dwordx4 v[130:131], off
	s_waitcnt vmcnt(6)
	s_barrier
	v_mfma_f32_16x16x32_bf16 v[54:57], v[222:225], v[178:181], v[54:57]
	v_mfma_f32_16x16x32_bf16 v[50:53], v[230:233], v[178:181], v[50:53]
	v_mfma_f32_16x16x32_bf16 v[38:41], v[222:225], v[186:189], v[38:41]
	v_mfma_f32_16x16x32_bf16 v[34:37], v[230:233], v[186:189], v[34:37]
	v_mfma_f32_16x16x32_bf16 v[22:25], v[222:225], v[202:205], v[22:25]
	v_mfma_f32_16x16x32_bf16 v[18:21], v[230:233], v[202:205], v[18:21]
	v_mfma_f32_16x16x32_bf16 v[4:7], v[222:225], v[214:217], v[4:7]
	v_mfma_f32_16x16x32_bf16 v[0:3], v[230:233], v[214:217], v[0:3]
	v_mfma_f32_16x16x32_bf16 v[54:57], v[226:229], v[182:185], v[54:57]
	v_mfma_f32_16x16x32_bf16 v[50:53], v[234:237], v[182:185], v[50:53]
	v_mfma_f32_16x16x32_bf16 v[38:41], v[226:229], v[198:201], v[38:41]
	v_mfma_f32_16x16x32_bf16 v[34:37], v[234:237], v[198:201], v[34:37]
	v_mfma_f32_16x16x32_bf16 v[22:25], v[226:229], v[206:209], v[22:25]
	v_mfma_f32_16x16x32_bf16 v[18:21], v[234:237], v[206:209], v[18:21]
	v_mfma_f32_16x16x32_bf16 v[4:7], v[226:229], v[218:221], v[4:7]
	v_mfma_f32_16x16x32_bf16 v[0:3], v[234:237], v[218:221], v[0:3]
	s_add_i32 s18, s18, 2
	s_add_u32 s1, s1, 0x100
	s_addc_u32 s13, s13, 0
	s_cmp_gt_u32 s18, 41
	s_mov_b64 s[16:17], s[36:37]
	s_barrier
